# GEMM unit transitions: non-aligned epilogues (align / re-stagger barriers dropped, halves stay one barrier apart; one extra wr==0 barrier before the final one)
# baseline (speedup 1.0000x reference)
; #define PG8_STAGE(bufoff, gbase, voff) do { _Pragma("unroll") for (int _i = 0; _i < 2; ++_i) \
;         __builtin_amdgcn_global_load_lds((const unsigned*)((const char*)(gbase) + (voff)[_i]), (LAS unsigned*)(lds + (bufoff) + ldsw + _i * 8192), 16, 0, 0); } while (0)
; #define PG8_LDA(dst, b, h) do { _Pragma("unroll") for (int m = 0; m < 4; ++m) _Pragma("unroll") for (int k = 0; k < 2; ++k) dst[m][k] = *(const LAS bf16x8*)(lds + PG8_SA(b, h) + aoff + m * 2048 + k * 1024); } while (0)
; #define PG8_LDB(dst, b, h) do { _Pragma("unroll") for (int n = 0; n < 2; ++n) _Pragma("unroll") for (int k = 0; k < 2; ++k) dst[n][k] = *(const LAS bf16x8*)(lds + PG8_SB(b, h) + boff + n * 2048 + k * 1024); } while (0)
; #define PG8_MMA(ai, bj, At, Bt) do { __builtin_amdgcn_s_setprio(1); _Pragma("unroll") for (int m = 0; m < 4; ++m) _Pragma("unroll") for (int n = 0; n < 2; ++n) _Pragma("unroll") for (int k = 0; k < 2; ++k) \
;         acc[ai][bj][m][n] = __builtin_amdgcn_mfma_f32_16x16x32_bf16(Bt[n][k], At[m][k], acc[ai][bj][m][n], 0, 0, 0); __builtin_amdgcn_s_setprio(0); } while (0)
; #define PG8_WAIT_V(n) asm volatile("s_waitcnt vmcnt(" #n ")" ::: "memory")
; #define PG8_WAIT_L(n) asm volatile("s_waitcnt lgkmcnt(" #n ")" ::: "memory")
; #define PG8_BAR __builtin_amdgcn_s_barrier()
; #define PG8_SCHED __builtin_amdgcn_sched_barrier(0)
; template <class Epi, bool ALIGN_EPI>
; __device__ __forceinline__ void gemm_phase(LAS unsigned char* lds, const Gemm g, const StaticOrder& S, const Epi& E) {
;     ...
;         for (int t = 0; t < nt; t += 2) {
;             const bool last = (t == nt - 2);
;             const char* a1 = cA + (size_t)(t + 1) * kstep;
;             const char* a2 = last ? nA : cA + (size_t)(t + 2) * kstep; const char* b2 = last ? nB : cB + (size_t)(t + 2) * kstep;
;             const char* a3 = a2 + kstep; const char* b3 = b2 + kstep;
;             PG8_LDB(B0, 0, 0); PG8_LDB(B1, 0, 1); PG8_SCHED; PG8_LDA(At, 0, 0); PG8_STAGE(PG8_SA(1, 1), a1 + hA, voffA);
;             PG8_WAIT_V(8); PG8_WAIT_L(0); PG8_BAR; PG8_MMA(0, 0, At, B0); PG8_MMA(0, 1, At, B1); PG8_BAR; PG8_SCHED;
;             PG8_LDA(At, 0, 1); PG8_STAGE(PG8_SB(0, 0), b2, voffB); PG8_STAGE(PG8_SB(0, 1), b2 + hB, voffB); PG8_STAGE(PG8_SA(0, 0), a2, voffA);
;             PG8_WAIT_V(8); PG8_WAIT_L(0); PG8_BAR; PG8_MMA(1, 0, At, B0); PG8_MMA(1, 1, At, B1); PG8_BAR; PG8_SCHED;
.LBB0_252:
	ds_read_b128 v[168:171], v153
	ds_read_b128 v[172:175], v153 offset:1024
	ds_read_b128 v[176:179], v153 offset:2048
	ds_read_b128 v[180:183], v153 offset:3072
	ds_read_b128 v[184:187], v154
	ds_read_b128 v[188:191], v154 offset:1024
	ds_read_b128 v[194:197], v154 offset:2048
	ds_read_b128 v[198:201], v154 offset:3072
	s_add_u32 s8, s6, 0xfff80080
	s_addc_u32 s9, s7, -1
	s_cmp_eq_u32 s71, 28
	s_cselect_b32 s55, s47, s9
	s_cselect_b32 s54, s67, s8
	s_cselect_b32 s9, s45, s70
	s_cselect_b32 s8, s68, s69
	v_lshl_add_u64 v[234:235], s[6:7], 0, v[136:137]
	s_add_i32 m0, s39, 0xc000
	ds_read_b128 v[202:205], v155
	ds_read_b128 v[206:209], v155 offset:1024
	ds_read_b128 v[210:213], v155 offset:2048
	ds_read_b128 v[214:217], v155 offset:3072
	ds_read_b128 v[218:221], v155 offset:4096
	ds_read_b128 v[222:225], v155 offset:5120
	ds_read_b128 v[226:229], v155 offset:6144
	ds_read_b128 v[230:233], v155 offset:7168
	global_load_lds_dwordx4 v[234:235], off
	v_lshl_add_u64 v[234:235], s[6:7], 0, v[138:139]
	s_add_i32 m0, s39, 0xe000
	s_nop 0
	global_load_lds_dwordx4 v[234:235], off
	s_waitcnt vmcnt(8)
	s_waitcnt lgkmcnt(0)
	s_barrier
	s_setprio 1
	s_waitcnt lgkmcnt(0)
	v_mfma_f32_16x16x32_bf16 v[124:127], v[168:171], v[202:205], v[124:127]
	v_mfma_f32_16x16x32_bf16 v[124:127], v[172:175], v[206:209], v[124:127]
	v_mfma_f32_16x16x32_bf16 v[120:123], v[176:179], v[202:205], v[120:123]
	v_mfma_f32_16x16x32_bf16 v[120:123], v[180:183], v[206:209], v[120:123]
	v_mfma_f32_16x16x32_bf16 v[108:111], v[168:171], v[210:213], v[108:111]
	v_mfma_f32_16x16x32_bf16 v[108:111], v[172:175], v[214:217], v[108:111]
	v_mfma_f32_16x16x32_bf16 v[104:107], v[176:179], v[210:213], v[104:107]
	v_mfma_f32_16x16x32_bf16 v[104:107], v[180:183], v[214:217], v[104:107]
	v_mfma_f32_16x16x32_bf16 v[92:95], v[168:171], v[218:221], v[92:95]
	v_mfma_f32_16x16x32_bf16 v[92:95], v[172:175], v[222:225], v[92:95]
	v_mfma_f32_16x16x32_bf16 v[88:91], v[176:179], v[218:221], v[88:91]
	v_mfma_f32_16x16x32_bf16 v[88:91], v[180:183], v[222:225], v[88:91]
	v_mfma_f32_16x16x32_bf16 v[76:79], v[168:171], v[226:229], v[76:79]
	v_mfma_f32_16x16x32_bf16 v[76:79], v[172:175], v[230:233], v[76:79]
	v_mfma_f32_16x16x32_bf16 v[72:75], v[176:179], v[226:229], v[72:75]
	v_mfma_f32_16x16x32_bf16 v[72:75], v[180:183], v[230:233], v[72:75]
	s_setprio 0
	s_setprio 1
	v_mfma_f32_16x16x32_bf16 v[116:119], v[184:187], v[202:205], v[116:119]
	v_mfma_f32_16x16x32_bf16 v[116:119], v[188:191], v[206:209], v[116:119]
	v_mfma_f32_16x16x32_bf16 v[112:115], v[194:197], v[202:205], v[112:115]
	v_mfma_f32_16x16x32_bf16 v[112:115], v[198:201], v[206:209], v[112:115]
	v_mfma_f32_16x16x32_bf16 v[100:103], v[184:187], v[210:213], v[100:103]
	v_mfma_f32_16x16x32_bf16 v[100:103], v[188:191], v[214:217], v[100:103]
	v_mfma_f32_16x16x32_bf16 v[96:99], v[194:197], v[210:213], v[96:99]
	v_mfma_f32_16x16x32_bf16 v[96:99], v[198:201], v[214:217], v[96:99]
	v_mfma_f32_16x16x32_bf16 v[84:87], v[184:187], v[218:221], v[84:87]
	v_mfma_f32_16x16x32_bf16 v[84:87], v[188:191], v[222:225], v[84:87]
	v_mfma_f32_16x16x32_bf16 v[80:83], v[194:197], v[218:221], v[80:83]
	v_mfma_f32_16x16x32_bf16 v[80:83], v[198:201], v[222:225], v[80:83]
	v_mfma_f32_16x16x32_bf16 v[68:71], v[184:187], v[226:229], v[68:71]
	v_mfma_f32_16x16x32_bf16 v[68:71], v[188:191], v[230:233], v[68:71]
	v_mfma_f32_16x16x32_bf16 v[64:67], v[194:197], v[226:229], v[64:67]
	v_mfma_f32_16x16x32_bf16 v[64:67], v[198:201], v[230:233], v[64:67]
	s_setprio 0
	s_barrier
	s_add_i32 s72, s63, s33
	v_lshl_add_u64 v[234:235], s[8:9], 0, v[132:133]
	s_mov_b32 m0, s72
	ds_read_b128 v[202:205], v155 offset:16384
	ds_read_b128 v[206:209], v155 offset:17408
	ds_read_b128 v[210:213], v155 offset:18432
	ds_read_b128 v[214:217], v155 offset:19456
	ds_read_b128 v[218:221], v155 offset:20480
	ds_read_b128 v[222:225], v155 offset:21504
	ds_read_b128 v[226:229], v155 offset:22528
	ds_read_b128 v[230:233], v155 offset:23552
	global_load_lds_dwordx4 v[234:235], off
	s_add_i32 m0, s72, 0x2000
	s_add_u32 s72, s8, 0x80000
	v_lshl_add_u64 v[236:237], s[8:9], 0, v[128:129]
	s_addc_u32 s73, s9, 0
	s_add_i32 s74, s64, s33
	global_load_lds_dwordx4 v[236:237], off
	v_lshl_add_u64 v[238:239], s[72:73], 0, v[132:133]
	s_mov_b32 m0, s74
	v_lshl_add_u64 v[240:241], s[54:55], 0, v[130:131]
	global_load_lds_dwordx4 v[238:239], off
	v_lshl_add_u64 v[238:239], s[72:73], 0, v[128:129]
	s_add_i32 m0, s74, 0x2000
	s_nop 0
	global_load_lds_dwordx4 v[238:239], off
	v_lshl_add_u64 v[238:239], s[54:55], 0, v[134:135]
	s_mov_b32 m0, s39
	s_nop 0
	global_load_lds_dwordx4 v[238:239], off
	s_mov_b32 m0, s53
	s_nop 0
	global_load_lds_dwordx4 v[240:241], off
	s_waitcnt vmcnt(8)
	s_waitcnt lgkmcnt(0)
	s_barrier
; #define PG8_STAGE(bufoff, gbase, voff) do { _Pragma("unroll") for (int _i = 0; _i < 2; ++_i) \
;         __builtin_amdgcn_global_load_lds((const unsigned*)((const char*)(gbase) + (voff)[_i]), (LAS unsigned*)(lds + (bufoff) + ldsw + _i * 8192), 16, 0, 0); } while (0)
; #define PG8_LDA(dst, b, h) do { _Pragma("unroll") for (int m = 0; m < 4; ++m) _Pragma("unroll") for (int k = 0; k < 2; ++k) dst[m][k] = *(const LAS bf16x8*)(lds + PG8_SA(b, h) + aoff + m * 2048 + k * 1024); } while (0)
; #define PG8_LDB(dst, b, h) do { _Pragma("unroll") for (int n = 0; n < 2; ++n) _Pragma("unroll") for (int k = 0; k < 2; ++k) dst[n][k] = *(const LAS bf16x8*)(lds + PG8_SB(b, h) + boff + n * 2048 + k * 1024); } while (0)
; #define PG8_MMA(ai, bj, At, Bt) do { __builtin_amdgcn_s_setprio(1); _Pragma("unroll") for (int m = 0; m < 4; ++m) _Pragma("unroll") for (int n = 0; n < 2; ++n) _Pragma("unroll") for (int k = 0; k < 2; ++k) \
;         acc[ai][bj][m][n] = __builtin_amdgcn_mfma_f32_16x16x32_bf16(Bt[n][k], At[m][k], acc[ai][bj][m][n], 0, 0, 0); __builtin_amdgcn_s_setprio(0); } while (0)
; #define PG8_WAIT_V(n) asm volatile("s_waitcnt vmcnt(" #n ")" ::: "memory")
; #define PG8_WAIT_L(n) asm volatile("s_waitcnt lgkmcnt(" #n ")" ::: "memory")
; #define PG8_BAR __builtin_amdgcn_s_barrier()
; #define PG8_SCHED __builtin_amdgcn_sched_barrier(0)
; template <class Epi, bool ALIGN_EPI>
; __device__ __forceinline__ void gemm_phase(LAS unsigned char* lds, const Gemm g, const StaticOrder& S, const Epi& E) {
;     ...
;             PG8_WAIT_V(8); PG8_WAIT_L(0); PG8_BAR; PG8_MMA(1, 0, At, B0); PG8_MMA(1, 1, At, B1); PG8_BAR; PG8_SCHED;
;             PG8_LDB(B0, 1, 0); PG8_LDB(B1, 1, 1); PG8_SCHED; PG8_LDA(At, 1, 0); PG8_STAGE(PG8_SA(0, 1), a2 + hA, voffA);
;             PG8_WAIT_V(8); PG8_WAIT_L(0); PG8_BAR; PG8_MMA(0, 0, At, B0); PG8_MMA(0, 1, At, B1); PG8_BAR; PG8_SCHED;
;             PG8_LDA(At, 1, 1); PG8_STAGE(PG8_SB(1, 0), b3, voffB); PG8_STAGE(PG8_SB(1, 1), b3 + hB, voffB); PG8_STAGE(PG8_SA(1, 0), a3, voffA);
	s_setprio 1
	s_waitcnt lgkmcnt(0)
	v_mfma_f32_16x16x32_bf16 v[60:63], v[168:171], v[202:205], v[60:63]
	v_mfma_f32_16x16x32_bf16 v[60:63], v[172:175], v[206:209], v[60:63]
	v_mfma_f32_16x16x32_bf16 v[56:59], v[176:179], v[202:205], v[56:59]
	v_mfma_f32_16x16x32_bf16 v[56:59], v[180:183], v[206:209], v[56:59]
	v_mfma_f32_16x16x32_bf16 v[48:51], v[168:171], v[210:213], v[48:51]
	v_mfma_f32_16x16x32_bf16 v[48:51], v[172:175], v[214:217], v[48:51]
	v_mfma_f32_16x16x32_bf16 v[40:43], v[176:179], v[210:213], v[40:43]
	v_mfma_f32_16x16x32_bf16 v[40:43], v[180:183], v[214:217], v[40:43]
	v_mfma_f32_16x16x32_bf16 v[32:35], v[168:171], v[218:221], v[32:35]
	v_mfma_f32_16x16x32_bf16 v[32:35], v[172:175], v[222:225], v[32:35]
	v_mfma_f32_16x16x32_bf16 v[24:27], v[176:179], v[218:221], v[24:27]
	v_mfma_f32_16x16x32_bf16 v[24:27], v[180:183], v[222:225], v[24:27]
	v_mfma_f32_16x16x32_bf16 v[16:19], v[168:171], v[226:229], v[16:19]
	v_mfma_f32_16x16x32_bf16 v[16:19], v[172:175], v[230:233], v[16:19]
	v_mfma_f32_16x16x32_bf16 v[8:11], v[176:179], v[226:229], v[8:11]
	v_mfma_f32_16x16x32_bf16 v[8:11], v[180:183], v[230:233], v[8:11]
	s_setprio 0
	s_setprio 1
	v_mfma_f32_16x16x32_bf16 v[52:55], v[184:187], v[202:205], v[52:55]
	v_mfma_f32_16x16x32_bf16 v[52:55], v[188:191], v[206:209], v[52:55]
	v_mfma_f32_16x16x32_bf16 v[44:47], v[194:197], v[202:205], v[44:47]
	v_mfma_f32_16x16x32_bf16 v[44:47], v[198:201], v[206:209], v[44:47]
	v_mfma_f32_16x16x32_bf16 v[36:39], v[184:187], v[210:213], v[36:39]
	v_mfma_f32_16x16x32_bf16 v[36:39], v[188:191], v[214:217], v[36:39]
	v_mfma_f32_16x16x32_bf16 v[28:31], v[194:197], v[210:213], v[28:31]
	v_mfma_f32_16x16x32_bf16 v[28:31], v[198:201], v[214:217], v[28:31]
	v_mfma_f32_16x16x32_bf16 v[20:23], v[184:187], v[218:221], v[20:23]
	v_mfma_f32_16x16x32_bf16 v[20:23], v[188:191], v[222:225], v[20:23]
	v_mfma_f32_16x16x32_bf16 v[12:15], v[194:197], v[218:221], v[12:15]
	v_mfma_f32_16x16x32_bf16 v[12:15], v[198:201], v[222:225], v[12:15]
	v_mfma_f32_16x16x32_bf16 v[4:7], v[184:187], v[226:229], v[4:7]
	v_mfma_f32_16x16x32_bf16 v[4:7], v[188:191], v[230:233], v[4:7]
	v_mfma_f32_16x16x32_bf16 v[0:3], v[194:197], v[226:229], v[0:3]
	v_mfma_f32_16x16x32_bf16 v[0:3], v[198:201], v[230:233], v[0:3]
	s_setprio 0
	s_barrier
	s_add_i32 s72, 0, 0x18000
	v_add_u32_e32 v167, s72, v149
	s_add_i32 s73, 0, 0x1c000
	ds_read_b128 v[168:171], v167
	ds_read_b128 v[172:175], v167 offset:1024
	ds_read_b128 v[176:179], v167 offset:2048
	ds_read_b128 v[180:183], v167 offset:3072
	v_add_u32_e32 v167, s73, v149
	ds_read_b128 v[184:187], v167
	ds_read_b128 v[188:191], v167 offset:1024
	ds_read_b128 v[194:197], v167 offset:2048
	ds_read_b128 v[198:201], v167 offset:3072
	s_add_u32 s54, s54, 0x80000
	s_addc_u32 s55, s55, 0
	s_mov_b32 m0, s56
	v_lshl_add_u64 v[242:243], s[54:55], 0, v[134:135]
	ds_read_b128 v[202:205], v155 offset:32768
	ds_read_b128 v[206:209], v155 offset:33792
	ds_read_b128 v[210:213], v155 offset:34816
	ds_read_b128 v[214:217], v155 offset:35840
	ds_read_b128 v[218:221], v155 offset:36864
	ds_read_b128 v[222:225], v155 offset:37888
	ds_read_b128 v[226:229], v155 offset:38912
	ds_read_b128 v[230:233], v155 offset:39936
	global_load_lds_dwordx4 v[242:243], off
	v_lshl_add_u64 v[242:243], s[54:55], 0, v[130:131]
	s_mov_b32 m0, s57
	s_nop 0
	global_load_lds_dwordx4 v[242:243], off
	s_waitcnt vmcnt(8)
	s_waitcnt lgkmcnt(0)
	s_barrier
	s_setprio 1
	s_waitcnt lgkmcnt(0)
	v_mfma_f32_16x16x32_bf16 v[124:127], v[168:171], v[202:205], v[124:127]
	v_mfma_f32_16x16x32_bf16 v[124:127], v[172:175], v[206:209], v[124:127]
	v_mfma_f32_16x16x32_bf16 v[120:123], v[176:179], v[202:205], v[120:123]
	v_mfma_f32_16x16x32_bf16 v[120:123], v[180:183], v[206:209], v[120:123]
	v_mfma_f32_16x16x32_bf16 v[108:111], v[168:171], v[210:213], v[108:111]
	v_mfma_f32_16x16x32_bf16 v[108:111], v[172:175], v[214:217], v[108:111]
	v_mfma_f32_16x16x32_bf16 v[104:107], v[176:179], v[210:213], v[104:107]
	v_mfma_f32_16x16x32_bf16 v[104:107], v[180:183], v[214:217], v[104:107]
	v_mfma_f32_16x16x32_bf16 v[92:95], v[168:171], v[218:221], v[92:95]
	v_mfma_f32_16x16x32_bf16 v[92:95], v[172:175], v[222:225], v[92:95]
	v_mfma_f32_16x16x32_bf16 v[88:91], v[176:179], v[218:221], v[88:91]
	v_mfma_f32_16x16x32_bf16 v[88:91], v[180:183], v[222:225], v[88:91]
	v_mfma_f32_16x16x32_bf16 v[76:79], v[168:171], v[226:229], v[76:79]
	v_mfma_f32_16x16x32_bf16 v[76:79], v[172:175], v[230:233], v[76:79]
	v_mfma_f32_16x16x32_bf16 v[72:75], v[176:179], v[226:229], v[72:75]
	v_mfma_f32_16x16x32_bf16 v[72:75], v[180:183], v[230:233], v[72:75]
	s_setprio 0
	s_setprio 1
	v_mfma_f32_16x16x32_bf16 v[116:119], v[184:187], v[202:205], v[116:119]
	v_mfma_f32_16x16x32_bf16 v[116:119], v[188:191], v[206:209], v[116:119]
	v_mfma_f32_16x16x32_bf16 v[112:115], v[194:197], v[202:205], v[112:115]
	v_mfma_f32_16x16x32_bf16 v[112:115], v[198:201], v[206:209], v[112:115]
	v_mfma_f32_16x16x32_bf16 v[100:103], v[184:187], v[210:213], v[100:103]
	v_mfma_f32_16x16x32_bf16 v[100:103], v[188:191], v[214:217], v[100:103]
	v_mfma_f32_16x16x32_bf16 v[96:99], v[194:197], v[210:213], v[96:99]
	v_mfma_f32_16x16x32_bf16 v[96:99], v[198:201], v[214:217], v[96:99]
	v_mfma_f32_16x16x32_bf16 v[84:87], v[184:187], v[218:221], v[84:87]
	v_mfma_f32_16x16x32_bf16 v[84:87], v[188:191], v[222:225], v[84:87]
	v_mfma_f32_16x16x32_bf16 v[80:83], v[194:197], v[218:221], v[80:83]
	v_mfma_f32_16x16x32_bf16 v[80:83], v[198:201], v[222:225], v[80:83]
	v_mfma_f32_16x16x32_bf16 v[68:71], v[184:187], v[226:229], v[68:71]
	v_mfma_f32_16x16x32_bf16 v[68:71], v[188:191], v[230:233], v[68:71]
	v_mfma_f32_16x16x32_bf16 v[64:67], v[194:197], v[226:229], v[64:67]
	v_mfma_f32_16x16x32_bf16 v[64:67], v[198:201], v[230:233], v[64:67]
	s_setprio 0
	s_barrier
; #define PG8_STAGE(bufoff, gbase, voff) do { _Pragma("unroll") for (int _i = 0; _i < 2; ++_i) \
;         __builtin_amdgcn_global_load_lds((const unsigned*)((const char*)(gbase) + (voff)[_i]), (LAS unsigned*)(lds + (bufoff) + ldsw + _i * 8192), 16, 0, 0); } while (0)
; #define PG8_LDA(dst, b, h) do { _Pragma("unroll") for (int m = 0; m < 4; ++m) _Pragma("unroll") for (int k = 0; k < 2; ++k) dst[m][k] = *(const LAS bf16x8*)(lds + PG8_SA(b, h) + aoff + m * 2048 + k * 1024); } while (0)
; #define PG8_MMA(ai, bj, At, Bt) do { __builtin_amdgcn_s_setprio(1); _Pragma("unroll") for (int m = 0; m < 4; ++m) _Pragma("unroll") for (int n = 0; n < 2; ++n) _Pragma("unroll") for (int k = 0; k < 2; ++k) \
;         acc[ai][bj][m][n] = __builtin_amdgcn_mfma_f32_16x16x32_bf16(Bt[n][k], At[m][k], acc[ai][bj][m][n], 0, 0, 0); __builtin_amdgcn_s_setprio(0); } while (0)
; #define PG8_WAIT_V(n) asm volatile("s_waitcnt vmcnt(" #n ")" ::: "memory")
; #define PG8_WAIT_L(n) asm volatile("s_waitcnt lgkmcnt(" #n ")" ::: "memory")
; #define PG8_BAR __builtin_amdgcn_s_barrier()
; #define PG8_SCHED __builtin_amdgcn_sched_barrier(0)
; template <class Epi, bool ALIGN_EPI>
; __device__ __forceinline__ void gemm_phase(LAS unsigned char* lds, const Gemm g, const StaticOrder& S, const Epi& E) {
;     ...
;             PG8_WAIT_V(8); PG8_WAIT_L(0); PG8_BAR; PG8_MMA(0, 0, At, B0); PG8_MMA(0, 1, At, B1); PG8_BAR; PG8_SCHED;
;             PG8_LDA(At, 1, 1); PG8_STAGE(PG8_SB(1, 0), b3, voffB); PG8_STAGE(PG8_SB(1, 1), b3 + hB, voffB); PG8_STAGE(PG8_SA(1, 0), a3, voffA);
;             PG8_WAIT_V(8); PG8_WAIT_L(0); PG8_BAR; PG8_MMA(1, 0, At, B0); PG8_MMA(1, 1, At, B1); PG8_BAR; PG8_SCHED;
;         }
;         if constexpr (ALIGN_EPI) { if (wr == 0) PG8_BAR; }
	s_add_i32 s54, s72, s33
	v_lshl_add_u64 v[234:235], v[234:235], 0, s[20:21]
	s_mov_b32 m0, s54
	ds_read_b128 v[202:205], v155 offset:49152
	ds_read_b128 v[206:209], v155 offset:50176
	ds_read_b128 v[210:213], v155 offset:51200
	ds_read_b128 v[214:217], v155 offset:52224
	ds_read_b128 v[218:221], v155 offset:53248
	ds_read_b128 v[222:225], v155 offset:54272
	ds_read_b128 v[226:229], v155 offset:55296
	ds_read_b128 v[230:233], v155 offset:56320
	global_load_lds_dwordx4 v[234:235], off
	s_add_i32 m0, s54, 0x2000
	s_add_u32 s8, s8, 0x80080
	v_lshl_add_u64 v[234:235], v[236:237], 0, s[20:21]
	s_addc_u32 s9, s9, 0
	s_add_i32 s54, s73, s33
	global_load_lds_dwordx4 v[234:235], off
	v_lshl_add_u64 v[234:235], s[8:9], 0, v[132:133]
	s_mov_b32 m0, s54
	s_nop 0
	global_load_lds_dwordx4 v[234:235], off
	v_lshl_add_u64 v[234:235], s[8:9], 0, v[128:129]
	s_add_i32 m0, s54, 0x2000
	s_nop 0
	global_load_lds_dwordx4 v[234:235], off
	v_lshl_add_u64 v[234:235], v[238:239], 0, s[20:21]
	s_mov_b32 m0, s60
	s_nop 0
	global_load_lds_dwordx4 v[234:235], off
	v_lshl_add_u64 v[234:235], v[240:241], 0, s[20:21]
	s_mov_b32 m0, s61
	s_nop 0
	global_load_lds_dwordx4 v[234:235], off
	s_waitcnt vmcnt(8)
	s_waitcnt lgkmcnt(0)
	s_barrier
	s_setprio 1
	s_waitcnt lgkmcnt(0)
	v_mfma_f32_16x16x32_bf16 v[60:63], v[168:171], v[202:205], v[60:63]
	v_mfma_f32_16x16x32_bf16 v[60:63], v[172:175], v[206:209], v[60:63]
	v_mfma_f32_16x16x32_bf16 v[56:59], v[176:179], v[202:205], v[56:59]
	v_mfma_f32_16x16x32_bf16 v[56:59], v[180:183], v[206:209], v[56:59]
	v_mfma_f32_16x16x32_bf16 v[48:51], v[168:171], v[210:213], v[48:51]
	v_mfma_f32_16x16x32_bf16 v[48:51], v[172:175], v[214:217], v[48:51]
	v_mfma_f32_16x16x32_bf16 v[40:43], v[176:179], v[210:213], v[40:43]
	v_mfma_f32_16x16x32_bf16 v[40:43], v[180:183], v[214:217], v[40:43]
	v_mfma_f32_16x16x32_bf16 v[32:35], v[168:171], v[218:221], v[32:35]
	v_mfma_f32_16x16x32_bf16 v[32:35], v[172:175], v[222:225], v[32:35]
	v_mfma_f32_16x16x32_bf16 v[24:27], v[176:179], v[218:221], v[24:27]
	v_mfma_f32_16x16x32_bf16 v[24:27], v[180:183], v[222:225], v[24:27]
	v_mfma_f32_16x16x32_bf16 v[16:19], v[168:171], v[226:229], v[16:19]
	v_mfma_f32_16x16x32_bf16 v[16:19], v[172:175], v[230:233], v[16:19]
	v_mfma_f32_16x16x32_bf16 v[8:11], v[176:179], v[226:229], v[8:11]
	v_mfma_f32_16x16x32_bf16 v[8:11], v[180:183], v[230:233], v[8:11]
	s_setprio 0
	s_setprio 1
	v_mfma_f32_16x16x32_bf16 v[52:55], v[184:187], v[202:205], v[52:55]
	v_mfma_f32_16x16x32_bf16 v[52:55], v[188:191], v[206:209], v[52:55]
	v_mfma_f32_16x16x32_bf16 v[44:47], v[194:197], v[202:205], v[44:47]
	v_mfma_f32_16x16x32_bf16 v[44:47], v[198:201], v[206:209], v[44:47]
	v_mfma_f32_16x16x32_bf16 v[36:39], v[184:187], v[210:213], v[36:39]
	v_mfma_f32_16x16x32_bf16 v[36:39], v[188:191], v[214:217], v[36:39]
	v_mfma_f32_16x16x32_bf16 v[28:31], v[194:197], v[210:213], v[28:31]
	v_mfma_f32_16x16x32_bf16 v[28:31], v[198:201], v[214:217], v[28:31]
	v_mfma_f32_16x16x32_bf16 v[20:23], v[184:187], v[218:221], v[20:23]
	v_mfma_f32_16x16x32_bf16 v[20:23], v[188:191], v[222:225], v[20:23]
	v_mfma_f32_16x16x32_bf16 v[12:15], v[194:197], v[218:221], v[12:15]
	v_mfma_f32_16x16x32_bf16 v[12:15], v[198:201], v[222:225], v[12:15]
	v_mfma_f32_16x16x32_bf16 v[4:7], v[184:187], v[226:229], v[4:7]
	v_mfma_f32_16x16x32_bf16 v[4:7], v[188:191], v[230:233], v[4:7]
	v_mfma_f32_16x16x32_bf16 v[0:3], v[194:197], v[226:229], v[0:3]
	v_mfma_f32_16x16x32_bf16 v[0:3], v[198:201], v[230:233], v[0:3]
	s_setprio 0
	s_barrier
	s_add_i32 s71, s71, 2
	s_add_u32 s6, s6, 0x100
	s_addc_u32 s7, s7, 0
	s_add_u32 s69, s69, 0x100
	s_addc_u32 s70, s70, 0
	s_cmp_gt_u32 s71, 29
	s_cbranch_scc0 .LBB0_252
	s_and_b64 vcc, exec, s[22:23]
	s_cbranch_vccz .LBB0_255
	s_nop 0

; __device__ __forceinline__ unsigned cvt_pk_bf16(float lo, float hi) { unsigned r; asm volatile("v_cvt_pk_bf16_f32 %0, %1, %2" : "=v"(r) : "v"(lo), "v"(hi)); return r; }
;     __device__ __forceinline__ void operator()(const f32x4 (&acc)[2][2][4][2], const Unit& u, int wr, int wc, int fr, int fq, int, const float (&rsv_)[8]) const {
;     ...
;             for (int m = 0; m < 4; ++m) rsv[ai][m] = ss ? rsqrtf(rsv_[ai * 4 + m] * (1.f / 2048.f) + EPS) : 1.f;
; #pragma unroll
;         for (int ai = 0; ai < 2; ++ai)
; #pragma unroll
;             for (int m = 0; m < 4; ++m) { bf16_t* rowp = base + (size_t)(row0 + ai * HALF + m * 16) * ldc + col0;
;                 const float rs = rsv[ai][m];
; #pragma unroll
;                 for (int bj = 0; bj < 2; ++bj) { f32x4 v0 = acc[ai][bj][m][0] * rs, v1 = acc[ai][bj][m][1] * rs;
;                     if (ACT == 1) {
; #pragma unroll
;                         for (int j = 0; j < 4; ++j) { const float a = fmaxf(v0[j], 0.f), b = fmaxf(v1[j], 0.f); v0[j] = a * a; v1[j] = b * b; } }
;                     if (ACT == 2) { if (act2) {
; #pragma unroll
;                         for (int j = 0; j < 4; ++j) { float x = v0[j]; float z = 0.7978845608028654f * (x + 0.044715f * x * x * x); v0[j] = x / (1.f + __expf(-2.f * z));
;                                                       x = v1[j]; z = 0.7978845608028654f * (x + 0.044715f * x * x * x); v1[j] = x / (1.f + __expf(-2.f * z)); } } }
;                     u32x4 w; w.x = cvt_pk_bf16(v0[0], v0[1]); w.y = cvt_pk_bf16(v0[2], v0[3]); w.z = cvt_pk_bf16(v1[0], v1[1]); w.w = cvt_pk_bf16(v1[2], v1[3]);
;                     { u32x4* dp_ = (u32x4*)(rowp + bj * HALF); asm volatile("global_store_dwordx4 %0, %1, off sc1\n\ts_nop 1" :: "v"(dp_), "v"(w) : "memory"); } } }
.LBB0_257:
	s_waitcnt vmcnt(0)
	v_fmamk_f32 v166, v166, 0x3a000000, v156
	v_mul_f32_e32 v167, 0x4b800000, v166
	v_cmp_gt_f32_e32 vcc, s65, v166
	v_fmamk_f32 v165, v165, 0x3a000000, v156
	v_cmp_gt_f32_e64 s[4:5], s65, v165
	v_cndmask_b32_e32 v166, v166, v167, vcc
	v_rsq_f32_e32 v166, v166
	v_mul_f32_e32 v167, 0x4b800000, v165
	v_cndmask_b32_e64 v165, v165, v167, s[4:5]
	v_fmamk_f32 v152, v152, 0x3a000000, v156
	v_mul_f32_e32 v167, 0x45800000, v166
	v_cndmask_b32_e32 v166, v166, v167, vcc
	v_mul_f32_e32 v168, 0x4b800000, v152
	v_cmp_gt_f32_e32 vcc, s65, v152
	v_rsq_f32_e32 v165, v165
	v_fmamk_f32 v150, v150, 0x3a000000, v156
	v_cndmask_b32_e32 v152, v152, v168, vcc
	v_rsq_f32_e32 v152, v152
	v_mul_f32_e32 v167, 0x45800000, v165
	v_mul_f32_e32 v168, 0x4b800000, v150
	v_cmp_gt_f32_e64 s[8:9], s65, v150
	v_fmamk_f32 v148, v148, 0x3a000000, v156
	v_fmamk_f32 v146, v146, 0x3a000000, v156
	v_cndmask_b32_e64 v150, v150, v168, s[8:9]
	v_cndmask_b32_e64 v168, v165, v167, s[4:5]
	v_mul_f32_e32 v165, 0x45800000, v152
	v_cndmask_b32_e32 v170, v152, v165, vcc
	v_mul_f32_e32 v165, 0x4b800000, v148
	v_cmp_gt_f32_e32 vcc, s65, v148
	v_rsq_f32_e32 v150, v150
	v_cmp_gt_f32_e64 s[4:5], s65, v146
	v_cndmask_b32_e32 v148, v148, v165, vcc
	v_rsq_f32_e32 v148, v148
	v_mul_f32_e32 v152, 0x45800000, v150
	v_mul_f32_e32 v165, 0x4b800000, v146
	v_cndmask_b32_e64 v172, v150, v152, s[8:9]
	v_mul_f32_e32 v150, 0x45800000, v148
	v_fmamk_f32 v145, v145, 0x3a000000, v156
	v_cndmask_b32_e64 v146, v146, v165, s[4:5]
	v_cndmask_b32_e32 v152, v148, v150, vcc
	v_mul_f32_e32 v150, 0x4b800000, v145
	v_cmp_gt_f32_e32 vcc, s65, v145
	v_fmamk_f32 v144, v144, 0x3a000000, v156
	v_rsq_f32_e32 v146, v146
	v_cndmask_b32_e32 v145, v145, v150, vcc
	v_mul_f32_e32 v150, 0x4b800000, v144
	v_cmp_gt_f32_e64 s[8:9], s65, v144
	v_rsq_f32_e32 v145, v145
	v_mul_f32_e32 v148, 0x45800000, v146
	v_cndmask_b32_e64 v144, v144, v150, s[8:9]
	v_rsq_f32_e32 v144, v144
	v_cndmask_b32_e64 v150, v146, v148, s[4:5]
	v_mul_f32_e32 v146, 0x45800000, v145
	v_cndmask_b32_e32 v148, v145, v146, vcc
	v_mul_f32_e32 v145, 0x45800000, v144
	v_cndmask_b32_e64 v146, v144, v145, s[8:9]
	v_lshl_add_u32 v174, s52, 8, v147
	v_lshl_or_b32 v144, s66, 8, v151
	v_ashrrev_i32_e32 v145, 31, v144
	v_ashrrev_i32_e32 v175, 31, v174
	v_lshl_add_u64 v[176:177], v[144:145], 1, s[18:19]
	v_lshlrev_b64 v[144:145], 12, v[174:175]
	v_pk_mul_f32 v[126:127], v[166:167], v[126:127] op_sel_hi:[0,1]
	v_pk_mul_f32 v[124:125], v[166:167], v[124:125] op_sel_hi:[0,1]
	v_pk_mul_f32 v[178:179], v[166:167], v[122:123] op_sel_hi:[0,1]
	v_pk_mul_f32 v[122:123], v[166:167], v[120:121] op_sel_hi:[0,1]
	v_cvt_pk_bf16_f32 v120, v124, v125
	v_cvt_pk_bf16_f32 v121, v126, v127
	v_lshl_add_u64 v[144:145], v[176:177], 0, v[144:145]
	v_cvt_pk_bf16_f32 v122, v122, v123
	v_cvt_pk_bf16_f32 v123, v178, v179
	v_pk_mul_f32 v[116:117], v[166:167], v[116:117] op_sel_hi:[0,1]
	global_store_dwordx4 v[144:145], v[120:123], off sc1
	s_nop 1
	v_pk_mul_f32 v[120:121], v[166:167], v[114:115] op_sel_hi:[0,1]
	v_pk_mul_f32 v[114:115], v[166:167], v[112:113] op_sel_hi:[0,1]
	v_cvt_pk_bf16_f32 v112, v116, v117
	v_pk_mul_f32 v[118:119], v[166:167], v[118:119] op_sel_hi:[0,1]
	v_cvt_pk_bf16_f32 v113, v118, v119
	v_cvt_pk_bf16_f32 v114, v114, v115
	v_cvt_pk_bf16_f32 v115, v120, v121
	v_lshl_add_u64 v[116:117], v[144:145], 0, s[24:25]
	global_store_dwordx4 v[116:117], v[112:115], off sc1
	s_nop 1
	v_or_b32_e32 v112, 16, v174
	v_ashrrev_i32_e32 v113, 31, v112
	v_lshlrev_b64 v[112:113], 12, v[112:113]
	v_pk_mul_f32 v[110:111], v[168:169], v[110:111] op_sel_hi:[0,1]
	v_pk_mul_f32 v[108:109], v[168:169], v[108:109] op_sel_hi:[0,1]
	v_pk_mul_f32 v[114:115], v[168:169], v[106:107] op_sel_hi:[0,1]
	v_pk_mul_f32 v[106:107], v[168:169], v[104:105] op_sel_hi:[0,1]
	v_cvt_pk_bf16_f32 v104, v108, v109
	v_cvt_pk_bf16_f32 v105, v110, v111
	v_lshl_add_u64 v[112:113], v[176:177], 0, v[112:113]
	v_cvt_pk_bf16_f32 v106, v106, v107
	v_cvt_pk_bf16_f32 v107, v114, v115
	v_pk_mul_f32 v[100:101], v[168:169], v[100:101] op_sel_hi:[0,1]
	global_store_dwordx4 v[112:113], v[104:107], off sc1
	s_nop 1
	v_pk_mul_f32 v[104:105], v[168:169], v[98:99] op_sel_hi:[0,1]
	v_pk_mul_f32 v[98:99], v[168:169], v[96:97] op_sel_hi:[0,1]
	v_cvt_pk_bf16_f32 v96, v100, v101
	v_pk_mul_f32 v[102:103], v[168:169], v[102:103] op_sel_hi:[0,1]
	v_cvt_pk_bf16_f32 v97, v102, v103
	v_cvt_pk_bf16_f32 v98, v98, v99
	v_cvt_pk_bf16_f32 v99, v104, v105
	v_lshl_add_u64 v[100:101], v[112:113], 0, s[24:25]
	global_store_dwordx4 v[100:101], v[96:99], off sc1
	s_nop 1
	v_or_b32_e32 v96, 32, v174
	v_ashrrev_i32_e32 v97, 31, v96
	v_lshlrev_b64 v[96:97], 12, v[96:97]
	v_pk_mul_f32 v[94:95], v[170:171], v[94:95] op_sel_hi:[0,1]
	v_pk_mul_f32 v[92:93], v[170:171], v[92:93] op_sel_hi:[0,1]
	v_pk_mul_f32 v[98:99], v[170:171], v[90:91] op_sel_hi:[0,1]
	v_pk_mul_f32 v[90:91], v[170:171], v[88:89] op_sel_hi:[0,1]
	v_cvt_pk_bf16_f32 v88, v92, v93
	v_cvt_pk_bf16_f32 v89, v94, v95
	v_lshl_add_u64 v[96:97], v[176:177], 0, v[96:97]
	v_cvt_pk_bf16_f32 v90, v90, v91
	v_cvt_pk_bf16_f32 v91, v98, v99
	v_pk_mul_f32 v[84:85], v[170:171], v[84:85] op_sel_hi:[0,1]
	global_store_dwordx4 v[96:97], v[88:91], off sc1
	s_nop 1
	v_pk_mul_f32 v[88:89], v[170:171], v[82:83] op_sel_hi:[0,1]
	v_pk_mul_f32 v[82:83], v[170:171], v[80:81] op_sel_hi:[0,1]
	v_cvt_pk_bf16_f32 v80, v84, v85
	v_pk_mul_f32 v[86:87], v[170:171], v[86:87] op_sel_hi:[0,1]
; __device__ __forceinline__ unsigned cvt_pk_bf16(float lo, float hi) { unsigned r; asm volatile("v_cvt_pk_bf16_f32 %0, %1, %2" : "=v"(r) : "v"(lo), "v"(hi)); return r; }
; template <class Epi, bool ALIGN_EPI>
; __device__ __forceinline__ void gemm_phase(LAS unsigned char* lds, const Gemm g, const StaticOrder& S, const Epi& E) {
;     ...
;         if (!has_next) break;
;         E.post(ui + 1, rsn);
; #pragma unroll
;         for (int a = 0; a < 2; ++a)
; #pragma unroll
;             for (int b = 0; b < 2; ++b)
; #pragma unroll
;                 for (int m = 0; m < 4; ++m)
; #pragma unroll
;                     for (int n = 0; n < 2; ++n) acc[a][b][m][n] = (f32x4){0.f, 0.f, 0.f, 0.f};
;         cur = nxt; cA = nA; cB = nB; ++ui;
; #pragma unroll
;         for (int i_ = 0; i_ < 8; ++i_) rsv[i_] = rsn[i_];
;         if constexpr (ALIGN_EPI) { if (wr == 1) PG8_BAR; }
;     }
;     PG8_WAIT_V(0);
;     if constexpr (!ALIGN_EPI) { if (wr == 0) PG8_BAR; }
;     PG8_BAR;
;     __device__ __forceinline__ void operator()(const f32x4 (&acc)[2][2][4][2], const Unit& u, int wr, int wc, int fr, int fq, int, const float (&rsv_)[8]) const {
;     ...
;             for (int m = 0; m < 4; ++m) { bf16_t* rowp = base + (size_t)(row0 + ai * HALF + m * 16) * ldc + col0;
;                 const float rs = rsv[ai][m];
; #pragma unroll
;                 for (int bj = 0; bj < 2; ++bj) { f32x4 v0 = acc[ai][bj][m][0] * rs, v1 = acc[ai][bj][m][1] * rs;
;                     if (ACT == 1) {
; #pragma unroll
;                         for (int j = 0; j < 4; ++j) { const float a = fmaxf(v0[j], 0.f), b = fmaxf(v1[j], 0.f); v0[j] = a * a; v1[j] = b * b; } }
;                     if (ACT == 2) { if (act2) {
; #pragma unroll
;                         for (int j = 0; j < 4; ++j) { float x = v0[j]; float z = 0.7978845608028654f * (x + 0.044715f * x * x * x); v0[j] = x / (1.f + __expf(-2.f * z));
;                                                       x = v1[j]; z = 0.7978845608028654f * (x + 0.044715f * x * x * x); v1[j] = x / (1.f + __expf(-2.f * z)); } } }
;                     u32x4 w; w.x = cvt_pk_bf16(v0[0], v0[1]); w.y = cvt_pk_bf16(v0[2], v0[3]); w.z = cvt_pk_bf16(v1[0], v1[1]); w.w = cvt_pk_bf16(v1[2], v1[3]);
;                     { u32x4* dp_ = (u32x4*)(rowp + bj * HALF); asm volatile("global_store_dwordx4 %0, %1, off sc1\n\ts_nop 1" :: "v"(dp_), "v"(w) : "memory"); } } }
	v_cvt_pk_bf16_f32 v81, v86, v87
	v_cvt_pk_bf16_f32 v82, v82, v83
	v_cvt_pk_bf16_f32 v83, v88, v89
	v_lshl_add_u64 v[84:85], v[96:97], 0, s[24:25]
	global_store_dwordx4 v[84:85], v[80:83], off sc1
	s_nop 1
	v_or_b32_e32 v80, 48, v174
	v_ashrrev_i32_e32 v81, 31, v80
	v_lshlrev_b64 v[80:81], 12, v[80:81]
	v_pk_mul_f32 v[78:79], v[172:173], v[78:79] op_sel_hi:[0,1]
	v_pk_mul_f32 v[76:77], v[172:173], v[76:77] op_sel_hi:[0,1]
	v_pk_mul_f32 v[82:83], v[172:173], v[74:75] op_sel_hi:[0,1]
	v_pk_mul_f32 v[74:75], v[172:173], v[72:73] op_sel_hi:[0,1]
	v_cvt_pk_bf16_f32 v72, v76, v77
	v_cvt_pk_bf16_f32 v73, v78, v79
	v_lshl_add_u64 v[80:81], v[176:177], 0, v[80:81]
	v_cvt_pk_bf16_f32 v74, v74, v75
	v_cvt_pk_bf16_f32 v75, v82, v83
	v_pk_mul_f32 v[70:71], v[172:173], v[70:71] op_sel_hi:[0,1]
	global_store_dwordx4 v[80:81], v[72:75], off sc1
	s_nop 1
	v_pk_mul_f32 v[72:73], v[172:173], v[66:67] op_sel_hi:[0,1]
	v_pk_mul_f32 v[66:67], v[172:173], v[64:65] op_sel_hi:[0,1]
	v_pk_mul_f32 v[68:69], v[172:173], v[68:69] op_sel_hi:[0,1]
	v_cvt_pk_bf16_f32 v64, v68, v69
	v_cvt_pk_bf16_f32 v65, v70, v71
	v_cvt_pk_bf16_f32 v66, v66, v67
	v_cvt_pk_bf16_f32 v67, v72, v73
	v_lshl_add_u64 v[68:69], v[80:81], 0, s[24:25]
	global_store_dwordx4 v[68:69], v[64:67], off sc1
	s_nop 1
	v_pk_mul_f32 v[62:63], v[152:153], v[62:63] op_sel_hi:[0,1]
	v_pk_mul_f32 v[60:61], v[152:153], v[60:61] op_sel_hi:[0,1]
	v_pk_mul_f32 v[66:67], v[152:153], v[58:59] op_sel_hi:[0,1]
	v_pk_mul_f32 v[58:59], v[152:153], v[56:57] op_sel_hi:[0,1]
	v_cvt_pk_bf16_f32 v56, v60, v61
	v_cvt_pk_bf16_f32 v57, v62, v63
	v_lshl_add_u64 v[64:65], v[144:145], 0, s[14:15]
	v_cvt_pk_bf16_f32 v58, v58, v59
	v_cvt_pk_bf16_f32 v59, v66, v67
	v_pk_mul_f32 v[54:55], v[152:153], v[54:55] op_sel_hi:[0,1]
	global_store_dwordx4 v[64:65], v[56:59], off sc1
	s_nop 1
	v_pk_mul_f32 v[56:57], v[152:153], v[46:47] op_sel_hi:[0,1]
	v_pk_mul_f32 v[46:47], v[152:153], v[44:45] op_sel_hi:[0,1]
	v_pk_mul_f32 v[52:53], v[152:153], v[52:53] op_sel_hi:[0,1]
	v_cvt_pk_bf16_f32 v44, v52, v53
	v_cvt_pk_bf16_f32 v45, v54, v55
	v_cvt_pk_bf16_f32 v46, v46, v47
	v_cvt_pk_bf16_f32 v47, v56, v57
	v_lshl_add_u64 v[52:53], v[144:145], 0, s[26:27]
	global_store_dwordx4 v[52:53], v[44:47], off sc1
	s_nop 1
	v_pk_mul_f32 v[46:47], v[150:151], v[50:51] op_sel_hi:[0,1]
	v_pk_mul_f32 v[48:49], v[150:151], v[48:49] op_sel_hi:[0,1]
	v_pk_mul_f32 v[50:51], v[150:151], v[42:43] op_sel_hi:[0,1]
	v_pk_mul_f32 v[42:43], v[150:151], v[40:41] op_sel_hi:[0,1]
	v_cvt_pk_bf16_f32 v40, v48, v49
	v_cvt_pk_bf16_f32 v41, v46, v47
	v_lshl_add_u64 v[44:45], v[144:145], 0, s[28:29]
	v_cvt_pk_bf16_f32 v42, v42, v43
	v_cvt_pk_bf16_f32 v43, v50, v51
	v_pk_mul_f32 v[38:39], v[150:151], v[38:39] op_sel_hi:[0,1]
	global_store_dwordx4 v[44:45], v[40:43], off sc1
	s_nop 1
	v_pk_mul_f32 v[40:41], v[150:151], v[30:31] op_sel_hi:[0,1]
	v_pk_mul_f32 v[30:31], v[150:151], v[28:29] op_sel_hi:[0,1]
	v_pk_mul_f32 v[36:37], v[150:151], v[36:37] op_sel_hi:[0,1]
	v_cvt_pk_bf16_f32 v28, v36, v37
	v_cvt_pk_bf16_f32 v29, v38, v39
	v_cvt_pk_bf16_f32 v30, v30, v31
	v_cvt_pk_bf16_f32 v31, v40, v41
	v_lshl_add_u64 v[36:37], v[144:145], 0, s[30:31]
	global_store_dwordx4 v[36:37], v[28:31], off sc1
	s_nop 1
	v_pk_mul_f32 v[30:31], v[148:149], v[34:35] op_sel_hi:[0,1]
	v_pk_mul_f32 v[32:33], v[148:149], v[32:33] op_sel_hi:[0,1]
	v_pk_mul_f32 v[34:35], v[148:149], v[26:27] op_sel_hi:[0,1]
	v_pk_mul_f32 v[26:27], v[148:149], v[24:25] op_sel_hi:[0,1]
	v_cvt_pk_bf16_f32 v24, v32, v33
	v_cvt_pk_bf16_f32 v25, v30, v31
	v_lshl_add_u64 v[28:29], v[144:145], 0, s[34:35]
	v_cvt_pk_bf16_f32 v26, v26, v27
	v_cvt_pk_bf16_f32 v27, v34, v35
	v_pk_mul_f32 v[22:23], v[148:149], v[22:23] op_sel_hi:[0,1]
	global_store_dwordx4 v[28:29], v[24:27], off sc1
	s_nop 1
	v_pk_mul_f32 v[24:25], v[148:149], v[14:15] op_sel_hi:[0,1]
	v_pk_mul_f32 v[14:15], v[148:149], v[12:13] op_sel_hi:[0,1]
	v_pk_mul_f32 v[20:21], v[148:149], v[20:21] op_sel_hi:[0,1]
	v_cvt_pk_bf16_f32 v12, v20, v21
	v_cvt_pk_bf16_f32 v13, v22, v23
	v_cvt_pk_bf16_f32 v14, v14, v15
	v_cvt_pk_bf16_f32 v15, v24, v25
	v_lshl_add_u64 v[20:21], v[144:145], 0, s[36:37]
	global_store_dwordx4 v[20:21], v[12:15], off sc1
	s_nop 1
	v_pk_mul_f32 v[14:15], v[146:147], v[18:19] op_sel_hi:[0,1]
	v_pk_mul_f32 v[16:17], v[146:147], v[16:17] op_sel_hi:[0,1]
	v_pk_mul_f32 v[18:19], v[146:147], v[10:11] op_sel_hi:[0,1]
	v_pk_mul_f32 v[10:11], v[146:147], v[8:9] op_sel_hi:[0,1]
	v_cvt_pk_bf16_f32 v8, v16, v17
	v_cvt_pk_bf16_f32 v9, v14, v15
	v_lshl_add_u64 v[12:13], v[144:145], 0, s[40:41]
	v_cvt_pk_bf16_f32 v10, v10, v11
	v_cvt_pk_bf16_f32 v11, v18, v19
	v_pk_mul_f32 v[4:5], v[146:147], v[4:5] op_sel_hi:[0,1]
	global_store_dwordx4 v[12:13], v[8:11], off sc1
	s_nop 1
	v_pk_mul_f32 v[8:9], v[146:147], v[2:3] op_sel_hi:[0,1]
	v_pk_mul_f32 v[2:3], v[146:147], v[0:1] op_sel_hi:[0,1]
	v_pk_mul_f32 v[6:7], v[146:147], v[6:7] op_sel_hi:[0,1]
	v_cvt_pk_bf16_f32 v0, v4, v5
	v_cvt_pk_bf16_f32 v1, v6, v7
	v_cvt_pk_bf16_f32 v2, v2, v3
	v_cvt_pk_bf16_f32 v3, v8, v9
	v_lshl_add_u64 v[4:5], v[144:145], 0, s[42:43]
	global_store_dwordx4 v[4:5], v[0:3], off sc1
	s_nop 1
	s_and_b64 vcc, exec, s[6:7]
	s_mov_b64 s[4:5], -1
	s_cbranch_vccnz .LBB0_244
	s_andn2_b64 vcc, exec, s[16:17]
	s_cbranch_vccnz .LBB0_243
	s_nop 0
	s_branch .LBB0_243
.LBB0_260:
	s_waitcnt vmcnt(0)
	s_and_b64 vcc, exec, s[22:23]
	s_cbranch_vccz .Lnoalign_skip_1
	s_barrier
.Lnoalign_skip_1:
	s_barrier

; #define PG8_STAGE(bufoff, gbase, voff) do { _Pragma("unroll") for (int _i = 0; _i < 2; ++_i) \
;         __builtin_amdgcn_global_load_lds((const unsigned*)((const char*)(gbase) + (voff)[_i]), (LAS unsigned*)(lds + (bufoff) + ldsw + _i * 8192), 16, 0, 0); } while (0)
; #define PG8_LDA(dst, b, h) do { _Pragma("unroll") for (int m = 0; m < 4; ++m) _Pragma("unroll") for (int k = 0; k < 2; ++k) dst[m][k] = *(const LAS bf16x8*)(lds + PG8_SA(b, h) + aoff + m * 2048 + k * 1024); } while (0)
; #define PG8_LDB(dst, b, h) do { _Pragma("unroll") for (int n = 0; n < 2; ++n) _Pragma("unroll") for (int k = 0; k < 2; ++k) dst[n][k] = *(const LAS bf16x8*)(lds + PG8_SB(b, h) + boff + n * 2048 + k * 1024); } while (0)
; #define PG8_MMA(ai, bj, At, Bt) do { __builtin_amdgcn_s_setprio(1); _Pragma("unroll") for (int m = 0; m < 4; ++m) _Pragma("unroll") for (int n = 0; n < 2; ++n) _Pragma("unroll") for (int k = 0; k < 2; ++k) \
;         acc[ai][bj][m][n] = __builtin_amdgcn_mfma_f32_16x16x32_bf16(Bt[n][k], At[m][k], acc[ai][bj][m][n], 0, 0, 0); __builtin_amdgcn_s_setprio(0); } while (0)
; #define PG8_WAIT_V(n) asm volatile("s_waitcnt vmcnt(" #n ")" ::: "memory")
; #define PG8_WAIT_L(n) asm volatile("s_waitcnt lgkmcnt(" #n ")" ::: "memory")
; #define PG8_BAR __builtin_amdgcn_s_barrier()
; #define PG8_SCHED __builtin_amdgcn_sched_barrier(0)
; template <class Epi, bool ALIGN_EPI>
; __device__ __forceinline__ void gemm_phase(LAS unsigned char* lds, const Gemm g, const StaticOrder& S, const Epi& E) {
;     ...
;             const char* a1 = cA + (size_t)(t + 1) * kstep;
;             const char* a2 = last ? nA : cA + (size_t)(t + 2) * kstep; const char* b2 = last ? nB : cB + (size_t)(t + 2) * kstep;
;             const char* a3 = a2 + kstep; const char* b3 = b2 + kstep;
;             PG8_LDB(B0, 0, 0); PG8_LDB(B1, 0, 1); PG8_SCHED; PG8_LDA(At, 0, 0); PG8_STAGE(PG8_SA(1, 1), a1 + hA, voffA);
;             PG8_WAIT_V(8); PG8_WAIT_L(0); PG8_BAR; PG8_MMA(0, 0, At, B0); PG8_MMA(0, 1, At, B1); PG8_BAR; PG8_SCHED;
;             PG8_LDA(At, 0, 1); PG8_STAGE(PG8_SB(0, 0), b2, voffB); PG8_STAGE(PG8_SB(0, 1), b2 + hB, voffB); PG8_STAGE(PG8_SA(0, 0), a2, voffA);
;             PG8_WAIT_V(8); PG8_WAIT_L(0); PG8_BAR; PG8_MMA(1, 0, At, B0); PG8_MMA(1, 1, At, B1); PG8_BAR; PG8_SCHED;
.LBB0_385:
	ds_read_b128 v[152:155], v149
	ds_read_b128 v[156:159], v149 offset:1024
	ds_read_b128 v[160:163], v149 offset:2048
	ds_read_b128 v[164:167], v149 offset:3072
	ds_read_b128 v[168:171], v150
	ds_read_b128 v[172:175], v150 offset:1024
	ds_read_b128 v[176:179], v150 offset:2048
	ds_read_b128 v[180:183], v150 offset:3072
	s_add_u32 s40, s36, 0xfff80080
	s_addc_u32 s41, s37, -1
	s_cmp_eq_u32 s61, 4
	s_cselect_b32 s43, s27, s41
	s_cselect_b32 s42, s57, s40
	s_cselect_b32 s41, s25, s60
	s_cselect_b32 s40, s58, s59
	v_lshl_add_u64 v[144:145], s[36:37], 0, v[136:137]
	s_add_i32 m0, s35, 0xc000
	ds_read_b128 v[184:187], v151
	ds_read_b128 v[188:191], v151 offset:1024
	ds_read_b128 v[194:197], v151 offset:2048
	ds_read_b128 v[198:201], v151 offset:3072
	ds_read_b128 v[202:205], v151 offset:4096
	ds_read_b128 v[206:209], v151 offset:5120
	ds_read_b128 v[210:213], v151 offset:6144
	ds_read_b128 v[214:217], v151 offset:7168
	global_load_lds_dwordx4 v[144:145], off
	v_lshl_add_u64 v[144:145], s[36:37], 0, v[138:139]
	s_add_i32 m0, s35, 0xe000
	s_nop 0
	global_load_lds_dwordx4 v[144:145], off
	s_waitcnt vmcnt(8)
	s_waitcnt lgkmcnt(0)
	s_barrier
	s_setprio 1
	s_waitcnt lgkmcnt(0)
	v_mfma_f32_16x16x32_bf16 v[124:127], v[152:155], v[184:187], v[124:127]
	v_mfma_f32_16x16x32_bf16 v[124:127], v[156:159], v[188:191], v[124:127]
	v_mfma_f32_16x16x32_bf16 v[120:123], v[160:163], v[184:187], v[120:123]
	v_mfma_f32_16x16x32_bf16 v[120:123], v[164:167], v[188:191], v[120:123]
	v_mfma_f32_16x16x32_bf16 v[116:119], v[152:155], v[194:197], v[116:119]
	v_mfma_f32_16x16x32_bf16 v[116:119], v[156:159], v[198:201], v[116:119]
	v_mfma_f32_16x16x32_bf16 v[108:111], v[160:163], v[194:197], v[108:111]
	v_mfma_f32_16x16x32_bf16 v[108:111], v[164:167], v[198:201], v[108:111]
	v_mfma_f32_16x16x32_bf16 v[100:103], v[152:155], v[202:205], v[100:103]
	v_mfma_f32_16x16x32_bf16 v[100:103], v[156:159], v[206:209], v[100:103]
	v_mfma_f32_16x16x32_bf16 v[92:95], v[160:163], v[202:205], v[92:95]
	v_mfma_f32_16x16x32_bf16 v[92:95], v[164:167], v[206:209], v[92:95]
	v_mfma_f32_16x16x32_bf16 v[84:87], v[152:155], v[210:213], v[84:87]
	v_mfma_f32_16x16x32_bf16 v[84:87], v[156:159], v[214:217], v[84:87]
	v_mfma_f32_16x16x32_bf16 v[76:79], v[160:163], v[210:213], v[76:79]
	v_mfma_f32_16x16x32_bf16 v[76:79], v[164:167], v[214:217], v[76:79]
	s_setprio 0
	s_setprio 1
	v_mfma_f32_16x16x32_bf16 v[112:115], v[168:171], v[184:187], v[112:115]
	v_mfma_f32_16x16x32_bf16 v[112:115], v[172:175], v[188:191], v[112:115]
	v_mfma_f32_16x16x32_bf16 v[104:107], v[176:179], v[184:187], v[104:107]
	v_mfma_f32_16x16x32_bf16 v[104:107], v[180:183], v[188:191], v[104:107]
	v_mfma_f32_16x16x32_bf16 v[96:99], v[168:171], v[194:197], v[96:99]
	v_mfma_f32_16x16x32_bf16 v[96:99], v[172:175], v[198:201], v[96:99]
	v_mfma_f32_16x16x32_bf16 v[88:91], v[176:179], v[194:197], v[88:91]
	v_mfma_f32_16x16x32_bf16 v[88:91], v[180:183], v[198:201], v[88:91]
	v_mfma_f32_16x16x32_bf16 v[80:83], v[168:171], v[202:205], v[80:83]
	v_mfma_f32_16x16x32_bf16 v[80:83], v[172:175], v[206:209], v[80:83]
	v_mfma_f32_16x16x32_bf16 v[72:75], v[176:179], v[202:205], v[72:75]
	v_mfma_f32_16x16x32_bf16 v[72:75], v[180:183], v[206:209], v[72:75]
	v_mfma_f32_16x16x32_bf16 v[68:71], v[168:171], v[210:213], v[68:71]
	v_mfma_f32_16x16x32_bf16 v[68:71], v[172:175], v[214:217], v[68:71]
	v_mfma_f32_16x16x32_bf16 v[64:67], v[176:179], v[210:213], v[64:67]
	v_mfma_f32_16x16x32_bf16 v[64:67], v[180:183], v[214:217], v[64:67]
	s_setprio 0
	s_barrier
	s_add_i32 s62, s53, s45
	v_lshl_add_u64 v[144:145], s[40:41], 0, v[132:133]
	s_mov_b32 m0, s62
	ds_read_b128 v[184:187], v151 offset:16384
	ds_read_b128 v[188:191], v151 offset:17408
	ds_read_b128 v[194:197], v151 offset:18432
	ds_read_b128 v[198:201], v151 offset:19456
	ds_read_b128 v[202:205], v151 offset:20480
	ds_read_b128 v[206:209], v151 offset:21504
	ds_read_b128 v[210:213], v151 offset:22528
	ds_read_b128 v[214:217], v151 offset:23552
	global_load_lds_dwordx4 v[144:145], off
	s_add_i32 m0, s62, 0x2000
	s_add_u32 s62, s40, 0x20000
	v_lshl_add_u64 v[218:219], s[40:41], 0, v[128:129]
	s_addc_u32 s63, s41, 0
	s_add_i32 s64, s54, s45
	global_load_lds_dwordx4 v[218:219], off
	v_lshl_add_u64 v[220:221], s[62:63], 0, v[132:133]
	s_mov_b32 m0, s64
	v_lshl_add_u64 v[222:223], s[42:43], 0, v[130:131]
	global_load_lds_dwordx4 v[220:221], off
	v_lshl_add_u64 v[220:221], s[62:63], 0, v[128:129]
	s_add_i32 m0, s64, 0x2000
	s_nop 0
	global_load_lds_dwordx4 v[220:221], off
	v_lshl_add_u64 v[220:221], s[42:43], 0, v[134:135]
	s_mov_b32 m0, s35
	s_nop 0
	global_load_lds_dwordx4 v[220:221], off
	s_mov_b32 m0, s47
	s_nop 0
	global_load_lds_dwordx4 v[222:223], off
	s_waitcnt vmcnt(8)
	s_waitcnt lgkmcnt(0)
	s_barrier
; #define PG8_STAGE(bufoff, gbase, voff) do { _Pragma("unroll") for (int _i = 0; _i < 2; ++_i) \
;         __builtin_amdgcn_global_load_lds((const unsigned*)((const char*)(gbase) + (voff)[_i]), (LAS unsigned*)(lds + (bufoff) + ldsw + _i * 8192), 16, 0, 0); } while (0)
; #define PG8_LDA(dst, b, h) do { _Pragma("unroll") for (int m = 0; m < 4; ++m) _Pragma("unroll") for (int k = 0; k < 2; ++k) dst[m][k] = *(const LAS bf16x8*)(lds + PG8_SA(b, h) + aoff + m * 2048 + k * 1024); } while (0)
; #define PG8_LDB(dst, b, h) do { _Pragma("unroll") for (int n = 0; n < 2; ++n) _Pragma("unroll") for (int k = 0; k < 2; ++k) dst[n][k] = *(const LAS bf16x8*)(lds + PG8_SB(b, h) + boff + n * 2048 + k * 1024); } while (0)
; #define PG8_MMA(ai, bj, At, Bt) do { __builtin_amdgcn_s_setprio(1); _Pragma("unroll") for (int m = 0; m < 4; ++m) _Pragma("unroll") for (int n = 0; n < 2; ++n) _Pragma("unroll") for (int k = 0; k < 2; ++k) \
;         acc[ai][bj][m][n] = __builtin_amdgcn_mfma_f32_16x16x32_bf16(Bt[n][k], At[m][k], acc[ai][bj][m][n], 0, 0, 0); __builtin_amdgcn_s_setprio(0); } while (0)
; #define PG8_WAIT_V(n) asm volatile("s_waitcnt vmcnt(" #n ")" ::: "memory")
; #define PG8_WAIT_L(n) asm volatile("s_waitcnt lgkmcnt(" #n ")" ::: "memory")
; #define PG8_BAR __builtin_amdgcn_s_barrier()
; #define PG8_SCHED __builtin_amdgcn_sched_barrier(0)
; template <class Epi, bool ALIGN_EPI>
; __device__ __forceinline__ void gemm_phase(LAS unsigned char* lds, const Gemm g, const StaticOrder& S, const Epi& E) {
;     ...
;             PG8_WAIT_V(8); PG8_WAIT_L(0); PG8_BAR; PG8_MMA(1, 0, At, B0); PG8_MMA(1, 1, At, B1); PG8_BAR; PG8_SCHED;
;             PG8_LDB(B0, 1, 0); PG8_LDB(B1, 1, 1); PG8_SCHED; PG8_LDA(At, 1, 0); PG8_STAGE(PG8_SA(0, 1), a2 + hA, voffA);
;             PG8_WAIT_V(8); PG8_WAIT_L(0); PG8_BAR; PG8_MMA(0, 0, At, B0); PG8_MMA(0, 1, At, B1); PG8_BAR; PG8_SCHED;
	s_setprio 1
	s_waitcnt lgkmcnt(0)
	v_mfma_f32_16x16x32_bf16 v[60:63], v[152:155], v[184:187], v[60:63]
	v_mfma_f32_16x16x32_bf16 v[60:63], v[156:159], v[188:191], v[60:63]
	v_mfma_f32_16x16x32_bf16 v[56:59], v[160:163], v[184:187], v[56:59]
	v_mfma_f32_16x16x32_bf16 v[56:59], v[164:167], v[188:191], v[56:59]
	v_mfma_f32_16x16x32_bf16 v[52:55], v[152:155], v[194:197], v[52:55]
	v_mfma_f32_16x16x32_bf16 v[52:55], v[156:159], v[198:201], v[52:55]
	v_mfma_f32_16x16x32_bf16 v[44:47], v[160:163], v[194:197], v[44:47]
	v_mfma_f32_16x16x32_bf16 v[44:47], v[164:167], v[198:201], v[44:47]
	v_mfma_f32_16x16x32_bf16 v[36:39], v[152:155], v[202:205], v[36:39]
	v_mfma_f32_16x16x32_bf16 v[36:39], v[156:159], v[206:209], v[36:39]
	v_mfma_f32_16x16x32_bf16 v[28:31], v[160:163], v[202:205], v[28:31]
	v_mfma_f32_16x16x32_bf16 v[28:31], v[164:167], v[206:209], v[28:31]
	v_mfma_f32_16x16x32_bf16 v[20:23], v[152:155], v[210:213], v[20:23]
	v_mfma_f32_16x16x32_bf16 v[20:23], v[156:159], v[214:217], v[20:23]
	v_mfma_f32_16x16x32_bf16 v[12:15], v[160:163], v[210:213], v[12:15]
	v_mfma_f32_16x16x32_bf16 v[12:15], v[164:167], v[214:217], v[12:15]
	s_setprio 0
	s_setprio 1
	v_mfma_f32_16x16x32_bf16 v[48:51], v[168:171], v[184:187], v[48:51]
	v_mfma_f32_16x16x32_bf16 v[48:51], v[172:175], v[188:191], v[48:51]
	v_mfma_f32_16x16x32_bf16 v[40:43], v[176:179], v[184:187], v[40:43]
	v_mfma_f32_16x16x32_bf16 v[40:43], v[180:183], v[188:191], v[40:43]
	v_mfma_f32_16x16x32_bf16 v[32:35], v[168:171], v[194:197], v[32:35]
	v_mfma_f32_16x16x32_bf16 v[32:35], v[172:175], v[198:201], v[32:35]
	v_mfma_f32_16x16x32_bf16 v[24:27], v[176:179], v[194:197], v[24:27]
	v_mfma_f32_16x16x32_bf16 v[24:27], v[180:183], v[198:201], v[24:27]
	v_mfma_f32_16x16x32_bf16 v[16:19], v[168:171], v[202:205], v[16:19]
	v_mfma_f32_16x16x32_bf16 v[16:19], v[172:175], v[206:209], v[16:19]
	v_mfma_f32_16x16x32_bf16 v[8:11], v[176:179], v[202:205], v[8:11]
	v_mfma_f32_16x16x32_bf16 v[8:11], v[180:183], v[206:209], v[8:11]
	v_mfma_f32_16x16x32_bf16 v[4:7], v[168:171], v[210:213], v[4:7]
	v_mfma_f32_16x16x32_bf16 v[4:7], v[172:175], v[214:217], v[4:7]
	v_mfma_f32_16x16x32_bf16 v[0:3], v[176:179], v[210:213], v[0:3]
	v_mfma_f32_16x16x32_bf16 v[0:3], v[180:183], v[214:217], v[0:3]
	s_setprio 0
	s_barrier
	s_add_i32 s62, 0, 0x18000
	s_add_i32 s63, 0, 0x1c000
	v_add_u32_e32 v164, s62, v147
	v_add_u32_e32 v180, s63, v147
	ds_read_b128 v[152:155], v164
	ds_read_b128 v[156:159], v164 offset:1024
	ds_read_b128 v[160:163], v164 offset:2048
	ds_read_b128 v[164:167], v164 offset:3072
	ds_read_b128 v[168:171], v180
	ds_read_b128 v[172:175], v180 offset:1024
	ds_read_b128 v[176:179], v180 offset:2048
	ds_read_b128 v[180:183], v180 offset:3072
	s_add_u32 s42, s42, 0x80000
	s_addc_u32 s43, s43, 0
	s_mov_b32 m0, s48
	v_lshl_add_u64 v[224:225], s[42:43], 0, v[134:135]
	ds_read_b128 v[184:187], v151 offset:32768
	ds_read_b128 v[188:191], v151 offset:33792
	ds_read_b128 v[194:197], v151 offset:34816
	ds_read_b128 v[198:201], v151 offset:35840
	ds_read_b128 v[202:205], v151 offset:36864
	ds_read_b128 v[206:209], v151 offset:37888
	ds_read_b128 v[210:213], v151 offset:38912
	ds_read_b128 v[214:217], v151 offset:39936
	global_load_lds_dwordx4 v[224:225], off
	v_lshl_add_u64 v[224:225], s[42:43], 0, v[130:131]
	s_mov_b32 m0, s49
	s_nop 0
	global_load_lds_dwordx4 v[224:225], off
	s_waitcnt vmcnt(8)
	s_waitcnt lgkmcnt(0)
	s_barrier
	s_setprio 1
	s_waitcnt lgkmcnt(0)
	v_mfma_f32_16x16x32_bf16 v[124:127], v[152:155], v[184:187], v[124:127]
	v_mfma_f32_16x16x32_bf16 v[124:127], v[156:159], v[188:191], v[124:127]
	v_mfma_f32_16x16x32_bf16 v[120:123], v[160:163], v[184:187], v[120:123]
	v_mfma_f32_16x16x32_bf16 v[120:123], v[164:167], v[188:191], v[120:123]
	v_mfma_f32_16x16x32_bf16 v[116:119], v[152:155], v[194:197], v[116:119]
	v_mfma_f32_16x16x32_bf16 v[116:119], v[156:159], v[198:201], v[116:119]
	v_mfma_f32_16x16x32_bf16 v[108:111], v[160:163], v[194:197], v[108:111]
	v_mfma_f32_16x16x32_bf16 v[108:111], v[164:167], v[198:201], v[108:111]
	v_mfma_f32_16x16x32_bf16 v[100:103], v[152:155], v[202:205], v[100:103]
	v_mfma_f32_16x16x32_bf16 v[100:103], v[156:159], v[206:209], v[100:103]
	v_mfma_f32_16x16x32_bf16 v[92:95], v[160:163], v[202:205], v[92:95]
	v_mfma_f32_16x16x32_bf16 v[92:95], v[164:167], v[206:209], v[92:95]
	v_mfma_f32_16x16x32_bf16 v[84:87], v[152:155], v[210:213], v[84:87]
	v_mfma_f32_16x16x32_bf16 v[84:87], v[156:159], v[214:217], v[84:87]
	v_mfma_f32_16x16x32_bf16 v[76:79], v[160:163], v[210:213], v[76:79]
	v_mfma_f32_16x16x32_bf16 v[76:79], v[164:167], v[214:217], v[76:79]
	s_setprio 0
	s_setprio 1
	v_mfma_f32_16x16x32_bf16 v[112:115], v[168:171], v[184:187], v[112:115]
	v_mfma_f32_16x16x32_bf16 v[112:115], v[172:175], v[188:191], v[112:115]
	v_mfma_f32_16x16x32_bf16 v[104:107], v[176:179], v[184:187], v[104:107]
	v_mfma_f32_16x16x32_bf16 v[104:107], v[180:183], v[188:191], v[104:107]
	v_mfma_f32_16x16x32_bf16 v[96:99], v[168:171], v[194:197], v[96:99]
	v_mfma_f32_16x16x32_bf16 v[96:99], v[172:175], v[198:201], v[96:99]
	v_mfma_f32_16x16x32_bf16 v[88:91], v[176:179], v[194:197], v[88:91]
	v_mfma_f32_16x16x32_bf16 v[88:91], v[180:183], v[198:201], v[88:91]
	v_mfma_f32_16x16x32_bf16 v[80:83], v[168:171], v[202:205], v[80:83]
	v_mfma_f32_16x16x32_bf16 v[80:83], v[172:175], v[206:209], v[80:83]
	v_mfma_f32_16x16x32_bf16 v[72:75], v[176:179], v[202:205], v[72:75]
	v_mfma_f32_16x16x32_bf16 v[72:75], v[180:183], v[206:209], v[72:75]
	v_mfma_f32_16x16x32_bf16 v[68:71], v[168:171], v[210:213], v[68:71]
	v_mfma_f32_16x16x32_bf16 v[68:71], v[172:175], v[214:217], v[68:71]
	v_mfma_f32_16x16x32_bf16 v[64:67], v[176:179], v[210:213], v[64:67]
	v_mfma_f32_16x16x32_bf16 v[64:67], v[180:183], v[214:217], v[64:67]
	s_setprio 0
	s_barrier
; #define PG8_STAGE(bufoff, gbase, voff) do { _Pragma("unroll") for (int _i = 0; _i < 2; ++_i) \
;         __builtin_amdgcn_global_load_lds((const unsigned*)((const char*)(gbase) + (voff)[_i]), (LAS unsigned*)(lds + (bufoff) + ldsw + _i * 8192), 16, 0, 0); } while (0)
; #define PG8_LDA(dst, b, h) do { _Pragma("unroll") for (int m = 0; m < 4; ++m) _Pragma("unroll") for (int k = 0; k < 2; ++k) dst[m][k] = *(const LAS bf16x8*)(lds + PG8_SA(b, h) + aoff + m * 2048 + k * 1024); } while (0)
; #define PG8_MMA(ai, bj, At, Bt) do { __builtin_amdgcn_s_setprio(1); _Pragma("unroll") for (int m = 0; m < 4; ++m) _Pragma("unroll") for (int n = 0; n < 2; ++n) _Pragma("unroll") for (int k = 0; k < 2; ++k) \
;         acc[ai][bj][m][n] = __builtin_amdgcn_mfma_f32_16x16x32_bf16(Bt[n][k], At[m][k], acc[ai][bj][m][n], 0, 0, 0); __builtin_amdgcn_s_setprio(0); } while (0)
; #define PG8_WAIT_V(n) asm volatile("s_waitcnt vmcnt(" #n ")" ::: "memory")
; #define PG8_WAIT_L(n) asm volatile("s_waitcnt lgkmcnt(" #n ")" ::: "memory")
; #define PG8_BAR __builtin_amdgcn_s_barrier()
; #define PG8_SCHED __builtin_amdgcn_sched_barrier(0)
; template <class Epi, bool ALIGN_EPI>
; __device__ __forceinline__ void gemm_phase(LAS unsigned char* lds, const Gemm g, const StaticOrder& S, const Epi& E) {
;     ...
;             PG8_WAIT_V(8); PG8_WAIT_L(0); PG8_BAR; PG8_MMA(0, 0, At, B0); PG8_MMA(0, 1, At, B1); PG8_BAR; PG8_SCHED;
;             PG8_LDA(At, 1, 1); PG8_STAGE(PG8_SB(1, 0), b3, voffB); PG8_STAGE(PG8_SB(1, 1), b3 + hB, voffB); PG8_STAGE(PG8_SA(1, 0), a3, voffA);
;             PG8_WAIT_V(8); PG8_WAIT_L(0); PG8_BAR; PG8_MMA(1, 0, At, B0); PG8_MMA(1, 1, At, B1); PG8_BAR; PG8_SCHED;
;         }
;         if constexpr (ALIGN_EPI) { if (wr == 0) PG8_BAR; }
	s_add_i32 s42, s62, s45
	v_lshl_add_u64 v[144:145], v[144:145], 0, s[18:19]
	s_mov_b32 m0, s42
	ds_read_b128 v[184:187], v151 offset:49152
	ds_read_b128 v[188:191], v151 offset:50176
	ds_read_b128 v[194:197], v151 offset:51200
	ds_read_b128 v[198:201], v151 offset:52224
	ds_read_b128 v[202:205], v151 offset:53248
	ds_read_b128 v[206:209], v151 offset:54272
	ds_read_b128 v[210:213], v151 offset:55296
	ds_read_b128 v[214:217], v151 offset:56320
	global_load_lds_dwordx4 v[144:145], off
	s_add_i32 m0, s42, 0x2000
	s_add_u32 s40, s40, 0x20080
	v_lshl_add_u64 v[144:145], v[218:219], 0, s[18:19]
	s_addc_u32 s41, s41, 0
	s_add_i32 s42, s63, s45
	global_load_lds_dwordx4 v[144:145], off
	v_lshl_add_u64 v[144:145], s[40:41], 0, v[132:133]
	s_mov_b32 m0, s42
	s_nop 0
	global_load_lds_dwordx4 v[144:145], off
	v_lshl_add_u64 v[144:145], s[40:41], 0, v[128:129]
	s_add_i32 m0, s42, 0x2000
	s_nop 0
	global_load_lds_dwordx4 v[144:145], off
	v_lshl_add_u64 v[144:145], v[220:221], 0, s[18:19]
	s_mov_b32 m0, s50
	s_nop 0
	global_load_lds_dwordx4 v[144:145], off
	v_lshl_add_u64 v[144:145], v[222:223], 0, s[18:19]
	s_mov_b32 m0, s51
	s_nop 0
	global_load_lds_dwordx4 v[144:145], off
	s_waitcnt vmcnt(8)
	s_waitcnt lgkmcnt(0)
	s_barrier
	s_setprio 1
	s_waitcnt lgkmcnt(0)
	v_mfma_f32_16x16x32_bf16 v[60:63], v[152:155], v[184:187], v[60:63]
	v_mfma_f32_16x16x32_bf16 v[60:63], v[156:159], v[188:191], v[60:63]
	v_mfma_f32_16x16x32_bf16 v[56:59], v[160:163], v[184:187], v[56:59]
	v_mfma_f32_16x16x32_bf16 v[56:59], v[164:167], v[188:191], v[56:59]
	v_mfma_f32_16x16x32_bf16 v[52:55], v[152:155], v[194:197], v[52:55]
	v_mfma_f32_16x16x32_bf16 v[52:55], v[156:159], v[198:201], v[52:55]
	v_mfma_f32_16x16x32_bf16 v[44:47], v[160:163], v[194:197], v[44:47]
	v_mfma_f32_16x16x32_bf16 v[44:47], v[164:167], v[198:201], v[44:47]
	v_mfma_f32_16x16x32_bf16 v[36:39], v[152:155], v[202:205], v[36:39]
	v_mfma_f32_16x16x32_bf16 v[36:39], v[156:159], v[206:209], v[36:39]
	v_mfma_f32_16x16x32_bf16 v[28:31], v[160:163], v[202:205], v[28:31]
	v_mfma_f32_16x16x32_bf16 v[28:31], v[164:167], v[206:209], v[28:31]
	v_mfma_f32_16x16x32_bf16 v[20:23], v[152:155], v[210:213], v[20:23]
	v_mfma_f32_16x16x32_bf16 v[20:23], v[156:159], v[214:217], v[20:23]
	v_mfma_f32_16x16x32_bf16 v[12:15], v[160:163], v[210:213], v[12:15]
	v_mfma_f32_16x16x32_bf16 v[12:15], v[164:167], v[214:217], v[12:15]
	s_setprio 0
	s_setprio 1
	v_mfma_f32_16x16x32_bf16 v[48:51], v[168:171], v[184:187], v[48:51]
	v_mfma_f32_16x16x32_bf16 v[48:51], v[172:175], v[188:191], v[48:51]
	v_mfma_f32_16x16x32_bf16 v[40:43], v[176:179], v[184:187], v[40:43]
	v_mfma_f32_16x16x32_bf16 v[40:43], v[180:183], v[188:191], v[40:43]
	v_mfma_f32_16x16x32_bf16 v[32:35], v[168:171], v[194:197], v[32:35]
	v_mfma_f32_16x16x32_bf16 v[32:35], v[172:175], v[198:201], v[32:35]
	v_mfma_f32_16x16x32_bf16 v[24:27], v[176:179], v[194:197], v[24:27]
	v_mfma_f32_16x16x32_bf16 v[24:27], v[180:183], v[198:201], v[24:27]
	v_mfma_f32_16x16x32_bf16 v[16:19], v[168:171], v[202:205], v[16:19]
	v_mfma_f32_16x16x32_bf16 v[16:19], v[172:175], v[206:209], v[16:19]
	v_mfma_f32_16x16x32_bf16 v[8:11], v[176:179], v[202:205], v[8:11]
	v_mfma_f32_16x16x32_bf16 v[8:11], v[180:183], v[206:209], v[8:11]
	v_mfma_f32_16x16x32_bf16 v[4:7], v[168:171], v[210:213], v[4:7]
	v_mfma_f32_16x16x32_bf16 v[4:7], v[172:175], v[214:217], v[4:7]
	v_mfma_f32_16x16x32_bf16 v[0:3], v[176:179], v[210:213], v[0:3]
	v_mfma_f32_16x16x32_bf16 v[0:3], v[180:183], v[214:217], v[0:3]
	s_setprio 0
	s_barrier
	s_add_i32 s61, s61, 2
	s_add_u32 s36, s36, 0x100
	s_addc_u32 s37, s37, 0
	s_add_u32 s59, s59, 0x100
	s_addc_u32 s60, s60, 0
	s_cmp_gt_u32 s61, 5
	s_cbranch_scc0 .LBB0_385
	s_and_b64 vcc, exec, s[20:21]
	s_cbranch_vccz .LBB0_388
	s_nop 0
; __device__ __forceinline__ unsigned cvt_pk_bf16(float lo, float hi) { unsigned r; asm volatile("v_cvt_pk_bf16_f32 %0, %1, %2" : "=v"(r) : "v"(lo), "v"(hi)); return r; }
; template <class Epi, bool ALIGN_EPI>
; __device__ __forceinline__ void gemm_phase(LAS unsigned char* lds, const Gemm g, const StaticOrder& S, const Epi& E) {
;     ...
;         if (!has_next) break;
;         E.post(ui + 1, rsn);
; #pragma unroll
;         for (int a = 0; a < 2; ++a)
; #pragma unroll
;             for (int b = 0; b < 2; ++b)
; #pragma unroll
;                 for (int m = 0; m < 4; ++m)
; #pragma unroll
;                     for (int n = 0; n < 2; ++n) acc[a][b][m][n] = (f32x4){0.f, 0.f, 0.f, 0.f};
;         cur = nxt; cA = nA; cB = nB; ++ui;
; #pragma unroll
;         for (int i_ = 0; i_ < 8; ++i_) rsv[i_] = rsn[i_];
;         if constexpr (ALIGN_EPI) { if (wr == 1) PG8_BAR; }
;     }
;     PG8_WAIT_V(0);
;     if constexpr (!ALIGN_EPI) { if (wr == 0) PG8_BAR; }
;     PG8_BAR;
;     __device__ __forceinline__ void operator()(const f32x4 (&acc)[2][2][4][2], const Unit& u, int wr, int wc, int fr, int fq, int, const float (&rsv_)[8]) const {
;     ...
;             for (int m = 0; m < 4; ++m) { bf16_t* rowp = base + (size_t)(row0 + ai * HALF + m * 16) * ldc + col0;
;                 const float rs = rsv[ai][m];
; #pragma unroll
;                 for (int bj = 0; bj < 2; ++bj) { f32x4 v0 = acc[ai][bj][m][0] * rs, v1 = acc[ai][bj][m][1] * rs;
;                     if (ACT == 1) {
; #pragma unroll
;                         for (int j = 0; j < 4; ++j) { const float a = fmaxf(v0[j], 0.f), b = fmaxf(v1[j], 0.f); v0[j] = a * a; v1[j] = b * b; } }
;                     if (ACT == 2) { if (act2) {
; #pragma unroll
;                         for (int j = 0; j < 4; ++j) { float x = v0[j]; float z = 0.7978845608028654f * (x + 0.044715f * x * x * x); v0[j] = x / (1.f + __expf(-2.f * z));
;                                                       x = v1[j]; z = 0.7978845608028654f * (x + 0.044715f * x * x * x); v1[j] = x / (1.f + __expf(-2.f * z)); } } }
;                     u32x4 w; w.x = cvt_pk_bf16(v0[0], v0[1]); w.y = cvt_pk_bf16(v0[2], v0[3]); w.z = cvt_pk_bf16(v1[0], v1[1]); w.w = cvt_pk_bf16(v1[2], v1[3]);
;                     { u32x4* dp_ = (u32x4*)(rowp + bj * HALF); asm volatile("global_store_dwordx4 %0, %1, off sc1\n\ts_nop 1" :: "v"(dp_), "v"(w) : "memory"); } } }
.LBB0_388:
	v_lshl_or_b32 v144, s56, 8, v148
	v_ashrrev_i32_e32 v145, 31, v144
	v_lshl_add_u32 v154, s34, 8, v146
	v_lshl_add_u64 v[144:145], v[144:145], 1, s[16:17]
	v_mad_i64_i32 v[152:153], s[36:37], v154, s55, v[144:145]
	v_cvt_pk_bf16_f32 v124, v124, v125
	v_cvt_pk_bf16_f32 v125, v126, v127
	v_cvt_pk_bf16_f32 v126, v120, v121
	v_cvt_pk_bf16_f32 v127, v122, v123
	s_andn2_b64 vcc, exec, s[4:5]
	global_store_dwordx4 v[152:153], v[124:127], off sc1
	s_nop 1
	v_cvt_pk_bf16_f32 v112, v112, v113
	v_cvt_pk_bf16_f32 v113, v114, v115
	v_cvt_pk_bf16_f32 v114, v104, v105
	v_lshl_add_u64 v[104:105], v[152:153], 0, s[22:23]
	v_cvt_pk_bf16_f32 v115, v106, v107
	s_mov_b64 s[4:5], -1
	global_store_dwordx4 v[104:105], v[112:115], off sc1
	s_nop 1
	v_or_b32_e32 v104, 16, v154
	v_mad_i64_i32 v[112:113], s[36:37], v104, s55, v[144:145]
	v_cvt_pk_bf16_f32 v104, v116, v117
	v_cvt_pk_bf16_f32 v105, v118, v119
	v_cvt_pk_bf16_f32 v106, v108, v109
	v_cvt_pk_bf16_f32 v107, v110, v111
	s_nop 0
	global_store_dwordx4 v[112:113], v[104:107], off sc1
	s_nop 1
	v_cvt_pk_bf16_f32 v96, v96, v97
	v_cvt_pk_bf16_f32 v97, v98, v99
	v_cvt_pk_bf16_f32 v98, v88, v89
	v_lshl_add_u64 v[88:89], v[112:113], 0, s[22:23]
	v_cvt_pk_bf16_f32 v99, v90, v91
	s_nop 0
	global_store_dwordx4 v[88:89], v[96:99], off sc1
	s_nop 1
	v_or_b32_e32 v88, 32, v154
	v_mad_i64_i32 v[96:97], s[36:37], v88, s55, v[144:145]
	v_cvt_pk_bf16_f32 v88, v100, v101
	v_cvt_pk_bf16_f32 v89, v102, v103
	v_cvt_pk_bf16_f32 v90, v92, v93
	v_cvt_pk_bf16_f32 v91, v94, v95
	s_nop 0
	global_store_dwordx4 v[96:97], v[88:91], off sc1
	s_nop 1
	v_cvt_pk_bf16_f32 v80, v80, v81
	v_cvt_pk_bf16_f32 v81, v82, v83
	v_cvt_pk_bf16_f32 v82, v72, v73
	v_lshl_add_u64 v[72:73], v[96:97], 0, s[22:23]
	v_cvt_pk_bf16_f32 v83, v74, v75
	s_nop 0
	global_store_dwordx4 v[72:73], v[80:83], off sc1
	s_nop 1
	v_or_b32_e32 v72, 48, v154
	v_mad_i64_i32 v[80:81], s[36:37], v72, s55, v[144:145]
	v_cvt_pk_bf16_f32 v72, v84, v85
	v_cvt_pk_bf16_f32 v73, v86, v87
	v_cvt_pk_bf16_f32 v74, v76, v77
	v_cvt_pk_bf16_f32 v75, v78, v79
	s_nop 0
	global_store_dwordx4 v[80:81], v[72:75], off sc1
	s_nop 1
	v_cvt_pk_bf16_f32 v68, v68, v69
	v_cvt_pk_bf16_f32 v69, v70, v71
	v_cvt_pk_bf16_f32 v70, v64, v65
	v_lshl_add_u64 v[64:65], v[80:81], 0, s[22:23]
	v_cvt_pk_bf16_f32 v71, v66, v67
	s_nop 0
	global_store_dwordx4 v[64:65], v[68:71], off sc1
	s_nop 1
	v_add_u32_e32 v64, 0x80, v154
	v_mad_i64_i32 v[64:65], s[36:37], v64, s55, v[144:145]
	v_cvt_pk_bf16_f32 v60, v60, v61
	v_cvt_pk_bf16_f32 v61, v62, v63
	v_cvt_pk_bf16_f32 v62, v56, v57
	v_cvt_pk_bf16_f32 v63, v58, v59
	s_nop 0
	global_store_dwordx4 v[64:65], v[60:63], off sc1
	s_nop 1
	v_cvt_pk_bf16_f32 v48, v48, v49
	v_cvt_pk_bf16_f32 v49, v50, v51
	v_cvt_pk_bf16_f32 v50, v40, v41
	v_lshl_add_u64 v[40:41], v[64:65], 0, s[22:23]
	v_cvt_pk_bf16_f32 v51, v42, v43
	s_nop 0
	global_store_dwordx4 v[40:41], v[48:51], off sc1
	s_nop 1
	v_add_u32_e32 v40, 0x90, v154
	v_mad_i64_i32 v[48:49], s[36:37], v40, s55, v[144:145]
	v_cvt_pk_bf16_f32 v40, v52, v53
	v_cvt_pk_bf16_f32 v41, v54, v55
	v_cvt_pk_bf16_f32 v42, v44, v45
	v_cvt_pk_bf16_f32 v43, v46, v47
	s_nop 0
	global_store_dwordx4 v[48:49], v[40:43], off sc1
	s_nop 1
	v_cvt_pk_bf16_f32 v32, v32, v33
	v_cvt_pk_bf16_f32 v33, v34, v35
	v_cvt_pk_bf16_f32 v34, v24, v25
	v_lshl_add_u64 v[24:25], v[48:49], 0, s[22:23]
	v_cvt_pk_bf16_f32 v35, v26, v27
	s_nop 0
	global_store_dwordx4 v[24:25], v[32:35], off sc1
	s_nop 1
	v_add_u32_e32 v24, 0xa0, v154
	v_mad_i64_i32 v[32:33], s[36:37], v24, s55, v[144:145]
	v_cvt_pk_bf16_f32 v24, v36, v37
	v_cvt_pk_bf16_f32 v25, v38, v39
	v_cvt_pk_bf16_f32 v26, v28, v29
	v_cvt_pk_bf16_f32 v27, v30, v31
	s_nop 0
	global_store_dwordx4 v[32:33], v[24:27], off sc1
	s_nop 1
	v_cvt_pk_bf16_f32 v16, v16, v17
	v_cvt_pk_bf16_f32 v17, v18, v19
	v_cvt_pk_bf16_f32 v18, v8, v9
	v_lshl_add_u64 v[8:9], v[32:33], 0, s[22:23]
	v_cvt_pk_bf16_f32 v19, v10, v11
	s_nop 0
	global_store_dwordx4 v[8:9], v[16:19], off sc1
	s_nop 1
	v_add_u32_e32 v8, 0xb0, v154
	v_mad_i64_i32 v[16:17], s[36:37], v8, s55, v[144:145]
	v_cvt_pk_bf16_f32 v8, v20, v21
	v_cvt_pk_bf16_f32 v9, v22, v23
	v_cvt_pk_bf16_f32 v10, v12, v13
	v_cvt_pk_bf16_f32 v11, v14, v15
	s_nop 0
	global_store_dwordx4 v[16:17], v[8:11], off sc1
	s_nop 1
	v_cvt_pk_bf16_f32 v4, v4, v5
	v_cvt_pk_bf16_f32 v5, v6, v7
	v_cvt_pk_bf16_f32 v6, v0, v1
	v_cvt_pk_bf16_f32 v7, v2, v3
	v_lshl_add_u64 v[0:1], v[16:17], 0, s[22:23]
	global_store_dwordx4 v[0:1], v[4:7], off sc1
	s_nop 1
	s_cbranch_vccnz .LBB0_381
	s_andn2_b64 vcc, exec, s[14:15]
	s_cbranch_vccnz .LBB0_380
	s_nop 0
	s_branch .LBB0_380
.LBB0_391:
	s_waitcnt vmcnt(0)
	s_and_b64 vcc, exec, s[20:21]
	s_cbranch_vccz .Lnoalign_skip_2
	s_barrier

; #define PG8_STAGE(bufoff, gbase, voff) do { _Pragma("unroll") for (int _i = 0; _i < 2; ++_i) \
;         __builtin_amdgcn_global_load_lds((const unsigned*)((const char*)(gbase) + (voff)[_i]), (LAS unsigned*)(lds + (bufoff) + ldsw + _i * 8192), 16, 0, 0); } while (0)
; #define PG8_LDA(dst, b, h) do { _Pragma("unroll") for (int m = 0; m < 4; ++m) _Pragma("unroll") for (int k = 0; k < 2; ++k) dst[m][k] = *(const LAS bf16x8*)(lds + PG8_SA(b, h) + aoff + m * 2048 + k * 1024); } while (0)
; #define PG8_LDB(dst, b, h) do { _Pragma("unroll") for (int n = 0; n < 2; ++n) _Pragma("unroll") for (int k = 0; k < 2; ++k) dst[n][k] = *(const LAS bf16x8*)(lds + PG8_SB(b, h) + boff + n * 2048 + k * 1024); } while (0)
; #define PG8_MMA(ai, bj, At, Bt) do { __builtin_amdgcn_s_setprio(1); _Pragma("unroll") for (int m = 0; m < 4; ++m) _Pragma("unroll") for (int n = 0; n < 2; ++n) _Pragma("unroll") for (int k = 0; k < 2; ++k) \
;         acc[ai][bj][m][n] = __builtin_amdgcn_mfma_f32_16x16x32_bf16(Bt[n][k], At[m][k], acc[ai][bj][m][n], 0, 0, 0); __builtin_amdgcn_s_setprio(0); } while (0)
; #define PG8_WAIT_V(n) asm volatile("s_waitcnt vmcnt(" #n ")" ::: "memory")
; #define PG8_WAIT_L(n) asm volatile("s_waitcnt lgkmcnt(" #n ")" ::: "memory")
; #define PG8_BAR __builtin_amdgcn_s_barrier()
; #define PG8_SCHED __builtin_amdgcn_sched_barrier(0)
; template <class Epi, bool ALIGN_EPI>
; __device__ __forceinline__ void gemm_phase(LAS unsigned char* lds, const Gemm g, const StaticOrder& S, const Epi& E) {
;     ...
;             const char* a1 = cA + (size_t)(t + 1) * kstep;
;             const char* a2 = last ? nA : cA + (size_t)(t + 2) * kstep; const char* b2 = last ? nB : cB + (size_t)(t + 2) * kstep;
;             const char* a3 = a2 + kstep; const char* b3 = b2 + kstep;
;             PG8_LDB(B0, 0, 0); PG8_LDB(B1, 0, 1); PG8_SCHED; PG8_LDA(At, 0, 0); PG8_STAGE(PG8_SA(1, 1), a1 + hA, voffA);
;             PG8_WAIT_V(8); PG8_WAIT_L(0); PG8_BAR; PG8_MMA(0, 0, At, B0); PG8_MMA(0, 1, At, B1); PG8_BAR; PG8_SCHED;
;             PG8_LDA(At, 0, 1); PG8_STAGE(PG8_SB(0, 0), b2, voffB); PG8_STAGE(PG8_SB(0, 1), b2 + hB, voffB); PG8_STAGE(PG8_SA(0, 0), a2, voffA);
;             PG8_WAIT_V(8); PG8_WAIT_L(0); PG8_BAR; PG8_MMA(1, 0, At, B0); PG8_MMA(1, 1, At, B1); PG8_BAR; PG8_SCHED;
.LBB0_403:
	ds_read_b128 v[152:155], v149
	ds_read_b128 v[156:159], v149 offset:1024
	ds_read_b128 v[160:163], v149 offset:2048
	ds_read_b128 v[164:167], v149 offset:3072
	ds_read_b128 v[168:171], v150
	ds_read_b128 v[172:175], v150 offset:1024
	ds_read_b128 v[176:179], v150 offset:2048
	ds_read_b128 v[180:183], v150 offset:3072
	s_add_u32 s30, s6, 0xfff80080
	s_addc_u32 s31, s7, -1
	s_cmp_eq_u32 s53, 8
	s_cselect_b32 s35, s23, s31
	s_cselect_b32 s34, s50, s30
	s_cselect_b32 s31, s25, s52
	s_cselect_b32 s30, s24, s51
	v_lshl_add_u64 v[144:145], s[6:7], 0, v[136:137]
	s_add_i32 m0, s0, 0xc000
	ds_read_b128 v[184:187], v151
	ds_read_b128 v[188:191], v151 offset:1024
	ds_read_b128 v[194:197], v151 offset:2048
	ds_read_b128 v[198:201], v151 offset:3072
	ds_read_b128 v[202:205], v151 offset:4096
	ds_read_b128 v[206:209], v151 offset:5120
	ds_read_b128 v[210:213], v151 offset:6144
	ds_read_b128 v[214:217], v151 offset:7168
	global_load_lds_dwordx4 v[144:145], off
	v_lshl_add_u64 v[144:145], s[6:7], 0, v[138:139]
	s_add_i32 m0, s0, 0xe000
	s_nop 0
	global_load_lds_dwordx4 v[144:145], off
	s_waitcnt vmcnt(8)
	s_waitcnt lgkmcnt(0)
	s_barrier
	s_setprio 1
	s_waitcnt lgkmcnt(0)
	v_mfma_f32_16x16x32_bf16 v[124:127], v[152:155], v[184:187], v[124:127]
	v_mfma_f32_16x16x32_bf16 v[124:127], v[156:159], v[188:191], v[124:127]
	v_mfma_f32_16x16x32_bf16 v[120:123], v[160:163], v[184:187], v[120:123]
	v_mfma_f32_16x16x32_bf16 v[120:123], v[164:167], v[188:191], v[120:123]
	v_mfma_f32_16x16x32_bf16 v[116:119], v[152:155], v[194:197], v[116:119]
	v_mfma_f32_16x16x32_bf16 v[116:119], v[156:159], v[198:201], v[116:119]
	v_mfma_f32_16x16x32_bf16 v[108:111], v[160:163], v[194:197], v[108:111]
	v_mfma_f32_16x16x32_bf16 v[108:111], v[164:167], v[198:201], v[108:111]
	v_mfma_f32_16x16x32_bf16 v[100:103], v[152:155], v[202:205], v[100:103]
	v_mfma_f32_16x16x32_bf16 v[100:103], v[156:159], v[206:209], v[100:103]
	v_mfma_f32_16x16x32_bf16 v[92:95], v[160:163], v[202:205], v[92:95]
	v_mfma_f32_16x16x32_bf16 v[92:95], v[164:167], v[206:209], v[92:95]
	v_mfma_f32_16x16x32_bf16 v[84:87], v[152:155], v[210:213], v[84:87]
	v_mfma_f32_16x16x32_bf16 v[84:87], v[156:159], v[214:217], v[84:87]
	v_mfma_f32_16x16x32_bf16 v[76:79], v[160:163], v[210:213], v[76:79]
	v_mfma_f32_16x16x32_bf16 v[76:79], v[164:167], v[214:217], v[76:79]
	s_setprio 0
	s_setprio 1
	v_mfma_f32_16x16x32_bf16 v[112:115], v[168:171], v[184:187], v[112:115]
	v_mfma_f32_16x16x32_bf16 v[112:115], v[172:175], v[188:191], v[112:115]
	v_mfma_f32_16x16x32_bf16 v[104:107], v[176:179], v[184:187], v[104:107]
	v_mfma_f32_16x16x32_bf16 v[104:107], v[180:183], v[188:191], v[104:107]
	v_mfma_f32_16x16x32_bf16 v[96:99], v[168:171], v[194:197], v[96:99]
	v_mfma_f32_16x16x32_bf16 v[96:99], v[172:175], v[198:201], v[96:99]
	v_mfma_f32_16x16x32_bf16 v[88:91], v[176:179], v[194:197], v[88:91]
	v_mfma_f32_16x16x32_bf16 v[88:91], v[180:183], v[198:201], v[88:91]
	v_mfma_f32_16x16x32_bf16 v[80:83], v[168:171], v[202:205], v[80:83]
	v_mfma_f32_16x16x32_bf16 v[80:83], v[172:175], v[206:209], v[80:83]
	v_mfma_f32_16x16x32_bf16 v[72:75], v[176:179], v[202:205], v[72:75]
	v_mfma_f32_16x16x32_bf16 v[72:75], v[180:183], v[206:209], v[72:75]
	v_mfma_f32_16x16x32_bf16 v[68:71], v[168:171], v[210:213], v[68:71]
	v_mfma_f32_16x16x32_bf16 v[68:71], v[172:175], v[214:217], v[68:71]
	v_mfma_f32_16x16x32_bf16 v[64:67], v[176:179], v[210:213], v[64:67]
	v_mfma_f32_16x16x32_bf16 v[64:67], v[180:183], v[214:217], v[64:67]
	s_setprio 0
	s_barrier
	s_add_i32 s54, s45, s2
	v_lshl_add_u64 v[144:145], s[30:31], 0, v[132:133]
	s_mov_b32 m0, s54
	ds_read_b128 v[184:187], v151 offset:16384
	ds_read_b128 v[188:191], v151 offset:17408
	ds_read_b128 v[194:197], v151 offset:18432
	ds_read_b128 v[198:201], v151 offset:19456
	ds_read_b128 v[202:205], v151 offset:20480
	ds_read_b128 v[206:209], v151 offset:21504
	ds_read_b128 v[210:213], v151 offset:22528
	ds_read_b128 v[214:217], v151 offset:23552
	global_load_lds_dwordx4 v[144:145], off
	s_add_i32 m0, s54, 0x2000
	s_add_u32 s54, s30, 0x30000
	v_lshl_add_u64 v[218:219], s[30:31], 0, v[128:129]
	s_addc_u32 s55, s31, 0
	s_add_i32 s56, s46, s2
	global_load_lds_dwordx4 v[218:219], off
	v_lshl_add_u64 v[220:221], s[54:55], 0, v[132:133]
	s_mov_b32 m0, s56
	v_lshl_add_u64 v[222:223], s[34:35], 0, v[130:131]
	global_load_lds_dwordx4 v[220:221], off
	v_lshl_add_u64 v[220:221], s[54:55], 0, v[128:129]
	s_add_i32 m0, s56, 0x2000
	s_nop 0
	global_load_lds_dwordx4 v[220:221], off
	v_lshl_add_u64 v[220:221], s[34:35], 0, v[134:135]
	s_mov_b32 m0, s0
	s_nop 0
	global_load_lds_dwordx4 v[220:221], off
	s_mov_b32 m0, s1
	s_nop 0
	global_load_lds_dwordx4 v[222:223], off
	s_waitcnt vmcnt(8)
	s_waitcnt lgkmcnt(0)
	s_barrier
; #define PG8_STAGE(bufoff, gbase, voff) do { _Pragma("unroll") for (int _i = 0; _i < 2; ++_i) \
;         __builtin_amdgcn_global_load_lds((const unsigned*)((const char*)(gbase) + (voff)[_i]), (LAS unsigned*)(lds + (bufoff) + ldsw + _i * 8192), 16, 0, 0); } while (0)
; #define PG8_LDA(dst, b, h) do { _Pragma("unroll") for (int m = 0; m < 4; ++m) _Pragma("unroll") for (int k = 0; k < 2; ++k) dst[m][k] = *(const LAS bf16x8*)(lds + PG8_SA(b, h) + aoff + m * 2048 + k * 1024); } while (0)
; #define PG8_LDB(dst, b, h) do { _Pragma("unroll") for (int n = 0; n < 2; ++n) _Pragma("unroll") for (int k = 0; k < 2; ++k) dst[n][k] = *(const LAS bf16x8*)(lds + PG8_SB(b, h) + boff + n * 2048 + k * 1024); } while (0)
; #define PG8_MMA(ai, bj, At, Bt) do { __builtin_amdgcn_s_setprio(1); _Pragma("unroll") for (int m = 0; m < 4; ++m) _Pragma("unroll") for (int n = 0; n < 2; ++n) _Pragma("unroll") for (int k = 0; k < 2; ++k) \
;         acc[ai][bj][m][n] = __builtin_amdgcn_mfma_f32_16x16x32_bf16(Bt[n][k], At[m][k], acc[ai][bj][m][n], 0, 0, 0); __builtin_amdgcn_s_setprio(0); } while (0)
; #define PG8_WAIT_V(n) asm volatile("s_waitcnt vmcnt(" #n ")" ::: "memory")
; #define PG8_WAIT_L(n) asm volatile("s_waitcnt lgkmcnt(" #n ")" ::: "memory")
; #define PG8_BAR __builtin_amdgcn_s_barrier()
; #define PG8_SCHED __builtin_amdgcn_sched_barrier(0)
; template <class Epi, bool ALIGN_EPI>
; __device__ __forceinline__ void gemm_phase(LAS unsigned char* lds, const Gemm g, const StaticOrder& S, const Epi& E) {
;     ...
;             PG8_WAIT_V(8); PG8_WAIT_L(0); PG8_BAR; PG8_MMA(1, 0, At, B0); PG8_MMA(1, 1, At, B1); PG8_BAR; PG8_SCHED;
;             PG8_LDB(B0, 1, 0); PG8_LDB(B1, 1, 1); PG8_SCHED; PG8_LDA(At, 1, 0); PG8_STAGE(PG8_SA(0, 1), a2 + hA, voffA);
;             PG8_WAIT_V(8); PG8_WAIT_L(0); PG8_BAR; PG8_MMA(0, 0, At, B0); PG8_MMA(0, 1, At, B1); PG8_BAR; PG8_SCHED;
	s_setprio 1
	s_waitcnt lgkmcnt(0)
	v_mfma_f32_16x16x32_bf16 v[60:63], v[152:155], v[184:187], v[60:63]
	v_mfma_f32_16x16x32_bf16 v[60:63], v[156:159], v[188:191], v[60:63]
	v_mfma_f32_16x16x32_bf16 v[56:59], v[160:163], v[184:187], v[56:59]
	v_mfma_f32_16x16x32_bf16 v[56:59], v[164:167], v[188:191], v[56:59]
	v_mfma_f32_16x16x32_bf16 v[52:55], v[152:155], v[194:197], v[52:55]
	v_mfma_f32_16x16x32_bf16 v[52:55], v[156:159], v[198:201], v[52:55]
	v_mfma_f32_16x16x32_bf16 v[44:47], v[160:163], v[194:197], v[44:47]
	v_mfma_f32_16x16x32_bf16 v[44:47], v[164:167], v[198:201], v[44:47]
	v_mfma_f32_16x16x32_bf16 v[36:39], v[152:155], v[202:205], v[36:39]
	v_mfma_f32_16x16x32_bf16 v[36:39], v[156:159], v[206:209], v[36:39]
	v_mfma_f32_16x16x32_bf16 v[28:31], v[160:163], v[202:205], v[28:31]
	v_mfma_f32_16x16x32_bf16 v[28:31], v[164:167], v[206:209], v[28:31]
	v_mfma_f32_16x16x32_bf16 v[20:23], v[152:155], v[210:213], v[20:23]
	v_mfma_f32_16x16x32_bf16 v[20:23], v[156:159], v[214:217], v[20:23]
	v_mfma_f32_16x16x32_bf16 v[12:15], v[160:163], v[210:213], v[12:15]
	v_mfma_f32_16x16x32_bf16 v[12:15], v[164:167], v[214:217], v[12:15]
	s_setprio 0
	s_setprio 1
	v_mfma_f32_16x16x32_bf16 v[48:51], v[168:171], v[184:187], v[48:51]
	v_mfma_f32_16x16x32_bf16 v[48:51], v[172:175], v[188:191], v[48:51]
	v_mfma_f32_16x16x32_bf16 v[40:43], v[176:179], v[184:187], v[40:43]
	v_mfma_f32_16x16x32_bf16 v[40:43], v[180:183], v[188:191], v[40:43]
	v_mfma_f32_16x16x32_bf16 v[32:35], v[168:171], v[194:197], v[32:35]
	v_mfma_f32_16x16x32_bf16 v[32:35], v[172:175], v[198:201], v[32:35]
	v_mfma_f32_16x16x32_bf16 v[24:27], v[176:179], v[194:197], v[24:27]
	v_mfma_f32_16x16x32_bf16 v[24:27], v[180:183], v[198:201], v[24:27]
	v_mfma_f32_16x16x32_bf16 v[16:19], v[168:171], v[202:205], v[16:19]
	v_mfma_f32_16x16x32_bf16 v[16:19], v[172:175], v[206:209], v[16:19]
	v_mfma_f32_16x16x32_bf16 v[8:11], v[176:179], v[202:205], v[8:11]
	v_mfma_f32_16x16x32_bf16 v[8:11], v[180:183], v[206:209], v[8:11]
	v_mfma_f32_16x16x32_bf16 v[4:7], v[168:171], v[210:213], v[4:7]
	v_mfma_f32_16x16x32_bf16 v[4:7], v[172:175], v[214:217], v[4:7]
	v_mfma_f32_16x16x32_bf16 v[0:3], v[176:179], v[210:213], v[0:3]
	v_mfma_f32_16x16x32_bf16 v[0:3], v[180:183], v[214:217], v[0:3]
	s_setprio 0
	s_barrier
	s_add_i32 s54, 0, 0x18000
	s_add_i32 s55, 0, 0x1c000
	v_add_u32_e32 v164, s54, v147
	v_add_u32_e32 v180, s55, v147
	ds_read_b128 v[152:155], v164
	ds_read_b128 v[156:159], v164 offset:1024
	ds_read_b128 v[160:163], v164 offset:2048
	ds_read_b128 v[164:167], v164 offset:3072
	ds_read_b128 v[168:171], v180
	ds_read_b128 v[172:175], v180 offset:1024
	ds_read_b128 v[176:179], v180 offset:2048
	ds_read_b128 v[180:183], v180 offset:3072
	s_add_u32 s34, s34, 0x80000
	s_addc_u32 s35, s35, 0
	s_mov_b32 m0, s29
	v_lshl_add_u64 v[224:225], s[34:35], 0, v[134:135]
	ds_read_b128 v[184:187], v151 offset:32768
	ds_read_b128 v[188:191], v151 offset:33792
	ds_read_b128 v[194:197], v151 offset:34816
	ds_read_b128 v[198:201], v151 offset:35840
	ds_read_b128 v[202:205], v151 offset:36864
	ds_read_b128 v[206:209], v151 offset:37888
	ds_read_b128 v[210:213], v151 offset:38912
	ds_read_b128 v[214:217], v151 offset:39936
	global_load_lds_dwordx4 v[224:225], off
	v_lshl_add_u64 v[224:225], s[34:35], 0, v[130:131]
	s_mov_b32 m0, s40
	s_nop 0
	global_load_lds_dwordx4 v[224:225], off
	s_waitcnt vmcnt(8)
	s_waitcnt lgkmcnt(0)
	s_barrier
	s_setprio 1
	s_waitcnt lgkmcnt(0)
	v_mfma_f32_16x16x32_bf16 v[124:127], v[152:155], v[184:187], v[124:127]
	v_mfma_f32_16x16x32_bf16 v[124:127], v[156:159], v[188:191], v[124:127]
	v_mfma_f32_16x16x32_bf16 v[120:123], v[160:163], v[184:187], v[120:123]
	v_mfma_f32_16x16x32_bf16 v[120:123], v[164:167], v[188:191], v[120:123]
	v_mfma_f32_16x16x32_bf16 v[116:119], v[152:155], v[194:197], v[116:119]
	v_mfma_f32_16x16x32_bf16 v[116:119], v[156:159], v[198:201], v[116:119]
	v_mfma_f32_16x16x32_bf16 v[108:111], v[160:163], v[194:197], v[108:111]
	v_mfma_f32_16x16x32_bf16 v[108:111], v[164:167], v[198:201], v[108:111]
	v_mfma_f32_16x16x32_bf16 v[100:103], v[152:155], v[202:205], v[100:103]
	v_mfma_f32_16x16x32_bf16 v[100:103], v[156:159], v[206:209], v[100:103]
	v_mfma_f32_16x16x32_bf16 v[92:95], v[160:163], v[202:205], v[92:95]
	v_mfma_f32_16x16x32_bf16 v[92:95], v[164:167], v[206:209], v[92:95]
	v_mfma_f32_16x16x32_bf16 v[84:87], v[152:155], v[210:213], v[84:87]
	v_mfma_f32_16x16x32_bf16 v[84:87], v[156:159], v[214:217], v[84:87]
	v_mfma_f32_16x16x32_bf16 v[76:79], v[160:163], v[210:213], v[76:79]
	v_mfma_f32_16x16x32_bf16 v[76:79], v[164:167], v[214:217], v[76:79]
	s_setprio 0
	s_setprio 1
	v_mfma_f32_16x16x32_bf16 v[112:115], v[168:171], v[184:187], v[112:115]
	v_mfma_f32_16x16x32_bf16 v[112:115], v[172:175], v[188:191], v[112:115]
	v_mfma_f32_16x16x32_bf16 v[104:107], v[176:179], v[184:187], v[104:107]
	v_mfma_f32_16x16x32_bf16 v[104:107], v[180:183], v[188:191], v[104:107]
	v_mfma_f32_16x16x32_bf16 v[96:99], v[168:171], v[194:197], v[96:99]
	v_mfma_f32_16x16x32_bf16 v[96:99], v[172:175], v[198:201], v[96:99]
	v_mfma_f32_16x16x32_bf16 v[88:91], v[176:179], v[194:197], v[88:91]
	v_mfma_f32_16x16x32_bf16 v[88:91], v[180:183], v[198:201], v[88:91]
	v_mfma_f32_16x16x32_bf16 v[80:83], v[168:171], v[202:205], v[80:83]
	v_mfma_f32_16x16x32_bf16 v[80:83], v[172:175], v[206:209], v[80:83]
	v_mfma_f32_16x16x32_bf16 v[72:75], v[176:179], v[202:205], v[72:75]
	v_mfma_f32_16x16x32_bf16 v[72:75], v[180:183], v[206:209], v[72:75]
	v_mfma_f32_16x16x32_bf16 v[68:71], v[168:171], v[210:213], v[68:71]
	v_mfma_f32_16x16x32_bf16 v[68:71], v[172:175], v[214:217], v[68:71]
	v_mfma_f32_16x16x32_bf16 v[64:67], v[176:179], v[210:213], v[64:67]
	v_mfma_f32_16x16x32_bf16 v[64:67], v[180:183], v[214:217], v[64:67]
	s_setprio 0
	s_barrier
; #define PG8_STAGE(bufoff, gbase, voff) do { _Pragma("unroll") for (int _i = 0; _i < 2; ++_i) \
;         __builtin_amdgcn_global_load_lds((const unsigned*)((const char*)(gbase) + (voff)[_i]), (LAS unsigned*)(lds + (bufoff) + ldsw + _i * 8192), 16, 0, 0); } while (0)
; #define PG8_LDA(dst, b, h) do { _Pragma("unroll") for (int m = 0; m < 4; ++m) _Pragma("unroll") for (int k = 0; k < 2; ++k) dst[m][k] = *(const LAS bf16x8*)(lds + PG8_SA(b, h) + aoff + m * 2048 + k * 1024); } while (0)
; #define PG8_MMA(ai, bj, At, Bt) do { __builtin_amdgcn_s_setprio(1); _Pragma("unroll") for (int m = 0; m < 4; ++m) _Pragma("unroll") for (int n = 0; n < 2; ++n) _Pragma("unroll") for (int k = 0; k < 2; ++k) \
;         acc[ai][bj][m][n] = __builtin_amdgcn_mfma_f32_16x16x32_bf16(Bt[n][k], At[m][k], acc[ai][bj][m][n], 0, 0, 0); __builtin_amdgcn_s_setprio(0); } while (0)
; #define PG8_WAIT_V(n) asm volatile("s_waitcnt vmcnt(" #n ")" ::: "memory")
; #define PG8_WAIT_L(n) asm volatile("s_waitcnt lgkmcnt(" #n ")" ::: "memory")
; #define PG8_BAR __builtin_amdgcn_s_barrier()
; #define PG8_SCHED __builtin_amdgcn_sched_barrier(0)
; template <class Epi, bool ALIGN_EPI>
; __device__ __forceinline__ void gemm_phase(LAS unsigned char* lds, const Gemm g, const StaticOrder& S, const Epi& E) {
;     ...
;             PG8_WAIT_V(8); PG8_WAIT_L(0); PG8_BAR; PG8_MMA(0, 0, At, B0); PG8_MMA(0, 1, At, B1); PG8_BAR; PG8_SCHED;
;             PG8_LDA(At, 1, 1); PG8_STAGE(PG8_SB(1, 0), b3, voffB); PG8_STAGE(PG8_SB(1, 1), b3 + hB, voffB); PG8_STAGE(PG8_SA(1, 0), a3, voffA);
;             PG8_WAIT_V(8); PG8_WAIT_L(0); PG8_BAR; PG8_MMA(1, 0, At, B0); PG8_MMA(1, 1, At, B1); PG8_BAR; PG8_SCHED;
;         }
;         if constexpr (ALIGN_EPI) { if (wr == 0) PG8_BAR; }
	s_add_i32 s34, s54, s2
	v_lshl_add_u64 v[144:145], v[144:145], 0, s[16:17]
	s_mov_b32 m0, s34
	ds_read_b128 v[184:187], v151 offset:49152
	ds_read_b128 v[188:191], v151 offset:50176
	ds_read_b128 v[194:197], v151 offset:51200
	ds_read_b128 v[198:201], v151 offset:52224
	ds_read_b128 v[202:205], v151 offset:53248
	ds_read_b128 v[206:209], v151 offset:54272
	ds_read_b128 v[210:213], v151 offset:55296
	ds_read_b128 v[214:217], v151 offset:56320
	global_load_lds_dwordx4 v[144:145], off
	s_add_i32 m0, s34, 0x2000
	s_add_u32 s30, s30, 0x30080
	v_lshl_add_u64 v[144:145], v[218:219], 0, s[16:17]
	s_addc_u32 s31, s31, 0
	s_add_i32 s34, s55, s2
	global_load_lds_dwordx4 v[144:145], off
	v_lshl_add_u64 v[144:145], s[30:31], 0, v[132:133]
	s_mov_b32 m0, s34
	s_nop 0
	global_load_lds_dwordx4 v[144:145], off
	v_lshl_add_u64 v[144:145], s[30:31], 0, v[128:129]
	s_add_i32 m0, s34, 0x2000
	s_nop 0
	global_load_lds_dwordx4 v[144:145], off
	v_lshl_add_u64 v[144:145], v[220:221], 0, s[16:17]
	s_mov_b32 m0, s42
	s_nop 0
	global_load_lds_dwordx4 v[144:145], off
	v_lshl_add_u64 v[144:145], v[222:223], 0, s[16:17]
	s_mov_b32 m0, s43
	s_nop 0
	global_load_lds_dwordx4 v[144:145], off
	s_waitcnt vmcnt(8)
	s_waitcnt lgkmcnt(0)
	s_barrier
	s_setprio 1
	s_waitcnt lgkmcnt(0)
	v_mfma_f32_16x16x32_bf16 v[60:63], v[152:155], v[184:187], v[60:63]
	v_mfma_f32_16x16x32_bf16 v[60:63], v[156:159], v[188:191], v[60:63]
	v_mfma_f32_16x16x32_bf16 v[56:59], v[160:163], v[184:187], v[56:59]
	v_mfma_f32_16x16x32_bf16 v[56:59], v[164:167], v[188:191], v[56:59]
	v_mfma_f32_16x16x32_bf16 v[52:55], v[152:155], v[194:197], v[52:55]
	v_mfma_f32_16x16x32_bf16 v[52:55], v[156:159], v[198:201], v[52:55]
	v_mfma_f32_16x16x32_bf16 v[44:47], v[160:163], v[194:197], v[44:47]
	v_mfma_f32_16x16x32_bf16 v[44:47], v[164:167], v[198:201], v[44:47]
	v_mfma_f32_16x16x32_bf16 v[36:39], v[152:155], v[202:205], v[36:39]
	v_mfma_f32_16x16x32_bf16 v[36:39], v[156:159], v[206:209], v[36:39]
	v_mfma_f32_16x16x32_bf16 v[28:31], v[160:163], v[202:205], v[28:31]
	v_mfma_f32_16x16x32_bf16 v[28:31], v[164:167], v[206:209], v[28:31]
	v_mfma_f32_16x16x32_bf16 v[20:23], v[152:155], v[210:213], v[20:23]
	v_mfma_f32_16x16x32_bf16 v[20:23], v[156:159], v[214:217], v[20:23]
	v_mfma_f32_16x16x32_bf16 v[12:15], v[160:163], v[210:213], v[12:15]
	v_mfma_f32_16x16x32_bf16 v[12:15], v[164:167], v[214:217], v[12:15]
	s_setprio 0
	s_setprio 1
	v_mfma_f32_16x16x32_bf16 v[48:51], v[168:171], v[184:187], v[48:51]
	v_mfma_f32_16x16x32_bf16 v[48:51], v[172:175], v[188:191], v[48:51]
	v_mfma_f32_16x16x32_bf16 v[40:43], v[176:179], v[184:187], v[40:43]
	v_mfma_f32_16x16x32_bf16 v[40:43], v[180:183], v[188:191], v[40:43]
	v_mfma_f32_16x16x32_bf16 v[32:35], v[168:171], v[194:197], v[32:35]
	v_mfma_f32_16x16x32_bf16 v[32:35], v[172:175], v[198:201], v[32:35]
	v_mfma_f32_16x16x32_bf16 v[24:27], v[176:179], v[194:197], v[24:27]
	v_mfma_f32_16x16x32_bf16 v[24:27], v[180:183], v[198:201], v[24:27]
	v_mfma_f32_16x16x32_bf16 v[16:19], v[168:171], v[202:205], v[16:19]
	v_mfma_f32_16x16x32_bf16 v[16:19], v[172:175], v[206:209], v[16:19]
	v_mfma_f32_16x16x32_bf16 v[8:11], v[176:179], v[202:205], v[8:11]
	v_mfma_f32_16x16x32_bf16 v[8:11], v[180:183], v[206:209], v[8:11]
	v_mfma_f32_16x16x32_bf16 v[4:7], v[168:171], v[210:213], v[4:7]
	v_mfma_f32_16x16x32_bf16 v[4:7], v[172:175], v[214:217], v[4:7]
	v_mfma_f32_16x16x32_bf16 v[0:3], v[176:179], v[210:213], v[0:3]
	v_mfma_f32_16x16x32_bf16 v[0:3], v[180:183], v[214:217], v[0:3]
	s_setprio 0
	s_barrier
	s_add_i32 s53, s53, 2
	s_add_u32 s6, s6, 0x100
	s_addc_u32 s7, s7, 0
	s_add_u32 s51, s51, 0x100
	s_addc_u32 s52, s52, 0
	s_cmp_gt_u32 s53, 9
	s_cbranch_scc0 .LBB0_403
	s_and_b64 vcc, exec, s[18:19]
	s_cbranch_vccz .LBB0_406
	s_nop 0
; __device__ __forceinline__ unsigned cvt_pk_bf16(float lo, float hi) { unsigned r; asm volatile("v_cvt_pk_bf16_f32 %0, %1, %2" : "=v"(r) : "v"(lo), "v"(hi)); return r; }
; template <class Epi, bool ALIGN_EPI>
; __device__ __forceinline__ void gemm_phase(LAS unsigned char* lds, const Gemm g, const StaticOrder& S, const Epi& E) {
;     ...
;         if (!has_next) break;
;         E.post(ui + 1, rsn);
; #pragma unroll
;         for (int a = 0; a < 2; ++a)
; #pragma unroll
;             for (int b = 0; b < 2; ++b)
; #pragma unroll
;                 for (int m = 0; m < 4; ++m)
; #pragma unroll
;                     for (int n = 0; n < 2; ++n) acc[a][b][m][n] = (f32x4){0.f, 0.f, 0.f, 0.f};
;         cur = nxt; cA = nA; cB = nB; ++ui;
; #pragma unroll
;         for (int i_ = 0; i_ < 8; ++i_) rsv[i_] = rsn[i_];
;         if constexpr (ALIGN_EPI) { if (wr == 1) PG8_BAR; }
;     }
;     PG8_WAIT_V(0);
;     if constexpr (!ALIGN_EPI) { if (wr == 0) PG8_BAR; }
;     PG8_BAR;
;     __device__ __forceinline__ void operator()(const f32x4 (&acc)[2][2][4][2], const Unit& u, int wr, int wc, int fr, int fq, int, const float (&rsv_)[8]) const {
;     ...
;             for (int m = 0; m < 4; ++m) { bf16_t* rowp = base + (size_t)(row0 + ai * HALF + m * 16) * ldc + col0;
;                 const float rs = rsv[ai][m];
; #pragma unroll
;                 for (int bj = 0; bj < 2; ++bj) { f32x4 v0 = acc[ai][bj][m][0] * rs, v1 = acc[ai][bj][m][1] * rs;
;                     if (ACT == 1) {
; #pragma unroll
;                         for (int j = 0; j < 4; ++j) { const float a = fmaxf(v0[j], 0.f), b = fmaxf(v1[j], 0.f); v0[j] = a * a; v1[j] = b * b; } }
;                     if (ACT == 2) { if (act2) {
; #pragma unroll
;                         for (int j = 0; j < 4; ++j) { float x = v0[j]; float z = 0.7978845608028654f * (x + 0.044715f * x * x * x); v0[j] = x / (1.f + __expf(-2.f * z));
;                                                       x = v1[j]; z = 0.7978845608028654f * (x + 0.044715f * x * x * x); v1[j] = x / (1.f + __expf(-2.f * z)); } } }
;                     u32x4 w; w.x = cvt_pk_bf16(v0[0], v0[1]); w.y = cvt_pk_bf16(v0[2], v0[3]); w.z = cvt_pk_bf16(v1[0], v1[1]); w.w = cvt_pk_bf16(v1[2], v1[3]);
;                     { u32x4* dp_ = (u32x4*)(rowp + bj * HALF); asm volatile("global_store_dwordx4 %0, %1, off sc1\n\ts_nop 1" :: "v"(dp_), "v"(w) : "memory"); } } }
.LBB0_406:
	v_lshl_or_b32 v144, s49, 8, v148
	v_ashrrev_i32_e32 v145, 31, v144
	v_lshl_add_u32 v154, s28, 8, v146
	v_lshl_add_u64 v[144:145], v[144:145], 1, s[8:9]
	v_mad_i64_i32 v[152:153], s[6:7], v154, s47, v[144:145]
	v_cvt_pk_bf16_f32 v124, v124, v125
	v_cvt_pk_bf16_f32 v125, v126, v127
	v_cvt_pk_bf16_f32 v126, v120, v121
	v_cvt_pk_bf16_f32 v127, v122, v123
	s_and_b64 vcc, exec, s[4:5]
	global_store_dwordx4 v[152:153], v[124:127], off sc1
	s_nop 1
	v_cvt_pk_bf16_f32 v112, v112, v113
	v_cvt_pk_bf16_f32 v113, v114, v115
	v_cvt_pk_bf16_f32 v114, v104, v105
	v_lshl_add_u64 v[104:105], v[152:153], 0, s[20:21]
	v_cvt_pk_bf16_f32 v115, v106, v107
	s_mov_b64 s[4:5], -1
	global_store_dwordx4 v[104:105], v[112:115], off sc1
	s_nop 1
	v_or_b32_e32 v104, 16, v154
	v_mad_i64_i32 v[112:113], s[6:7], v104, s47, v[144:145]
	v_cvt_pk_bf16_f32 v104, v116, v117
	v_cvt_pk_bf16_f32 v105, v118, v119
	v_cvt_pk_bf16_f32 v106, v108, v109
	v_cvt_pk_bf16_f32 v107, v110, v111
	s_nop 0
	global_store_dwordx4 v[112:113], v[104:107], off sc1
	s_nop 1
	v_cvt_pk_bf16_f32 v96, v96, v97
	v_cvt_pk_bf16_f32 v97, v98, v99
	v_cvt_pk_bf16_f32 v98, v88, v89
	v_lshl_add_u64 v[88:89], v[112:113], 0, s[20:21]
	v_cvt_pk_bf16_f32 v99, v90, v91
	s_nop 0
	global_store_dwordx4 v[88:89], v[96:99], off sc1
	s_nop 1
	v_or_b32_e32 v88, 32, v154
	v_mad_i64_i32 v[96:97], s[6:7], v88, s47, v[144:145]
	v_cvt_pk_bf16_f32 v88, v100, v101
	v_cvt_pk_bf16_f32 v89, v102, v103
	v_cvt_pk_bf16_f32 v90, v92, v93
	v_cvt_pk_bf16_f32 v91, v94, v95
	s_nop 0
	global_store_dwordx4 v[96:97], v[88:91], off sc1
	s_nop 1
	v_cvt_pk_bf16_f32 v80, v80, v81
	v_cvt_pk_bf16_f32 v81, v82, v83
	v_cvt_pk_bf16_f32 v82, v72, v73
	v_lshl_add_u64 v[72:73], v[96:97], 0, s[20:21]
	v_cvt_pk_bf16_f32 v83, v74, v75
	s_nop 0
	global_store_dwordx4 v[72:73], v[80:83], off sc1
	s_nop 1
	v_or_b32_e32 v72, 48, v154
	v_mad_i64_i32 v[80:81], s[6:7], v72, s47, v[144:145]
	v_cvt_pk_bf16_f32 v72, v84, v85
	v_cvt_pk_bf16_f32 v73, v86, v87
	v_cvt_pk_bf16_f32 v74, v76, v77
	v_cvt_pk_bf16_f32 v75, v78, v79
	s_nop 0
	global_store_dwordx4 v[80:81], v[72:75], off sc1
	s_nop 1
	v_cvt_pk_bf16_f32 v68, v68, v69
	v_cvt_pk_bf16_f32 v69, v70, v71
	v_cvt_pk_bf16_f32 v70, v64, v65
	v_lshl_add_u64 v[64:65], v[80:81], 0, s[20:21]
	v_cvt_pk_bf16_f32 v71, v66, v67
	s_nop 0
	global_store_dwordx4 v[64:65], v[68:71], off sc1
	s_nop 1
	v_add_u32_e32 v64, 0x80, v154
	v_mad_i64_i32 v[64:65], s[6:7], v64, s47, v[144:145]
	v_cvt_pk_bf16_f32 v60, v60, v61
	v_cvt_pk_bf16_f32 v61, v62, v63
	v_cvt_pk_bf16_f32 v62, v56, v57
	v_cvt_pk_bf16_f32 v63, v58, v59
	s_nop 0
	global_store_dwordx4 v[64:65], v[60:63], off sc1
	s_nop 1
	v_cvt_pk_bf16_f32 v48, v48, v49
	v_cvt_pk_bf16_f32 v49, v50, v51
	v_cvt_pk_bf16_f32 v50, v40, v41
	v_lshl_add_u64 v[40:41], v[64:65], 0, s[20:21]
	v_cvt_pk_bf16_f32 v51, v42, v43
	s_nop 0
	global_store_dwordx4 v[40:41], v[48:51], off sc1
	s_nop 1
	v_add_u32_e32 v40, 0x90, v154
	v_mad_i64_i32 v[48:49], s[6:7], v40, s47, v[144:145]
	v_cvt_pk_bf16_f32 v40, v52, v53
	v_cvt_pk_bf16_f32 v41, v54, v55
	v_cvt_pk_bf16_f32 v42, v44, v45
	v_cvt_pk_bf16_f32 v43, v46, v47
	s_nop 0
	global_store_dwordx4 v[48:49], v[40:43], off sc1
	s_nop 1
	v_cvt_pk_bf16_f32 v32, v32, v33
	v_cvt_pk_bf16_f32 v33, v34, v35
	v_cvt_pk_bf16_f32 v34, v24, v25
	v_lshl_add_u64 v[24:25], v[48:49], 0, s[20:21]
	v_cvt_pk_bf16_f32 v35, v26, v27
	s_nop 0
	global_store_dwordx4 v[24:25], v[32:35], off sc1
	s_nop 1
	v_add_u32_e32 v24, 0xa0, v154
	v_mad_i64_i32 v[32:33], s[6:7], v24, s47, v[144:145]
	v_cvt_pk_bf16_f32 v24, v36, v37
	v_cvt_pk_bf16_f32 v25, v38, v39
	v_cvt_pk_bf16_f32 v26, v28, v29
	v_cvt_pk_bf16_f32 v27, v30, v31
	s_nop 0
	global_store_dwordx4 v[32:33], v[24:27], off sc1
	s_nop 1
	v_cvt_pk_bf16_f32 v16, v16, v17
	v_cvt_pk_bf16_f32 v17, v18, v19
	v_cvt_pk_bf16_f32 v18, v8, v9
	v_lshl_add_u64 v[8:9], v[32:33], 0, s[20:21]
	v_cvt_pk_bf16_f32 v19, v10, v11
	s_nop 0
	global_store_dwordx4 v[8:9], v[16:19], off sc1
	s_nop 1
	v_add_u32_e32 v8, 0xb0, v154
	v_mad_i64_i32 v[16:17], s[6:7], v8, s47, v[144:145]
	v_cvt_pk_bf16_f32 v8, v20, v21
	v_cvt_pk_bf16_f32 v9, v22, v23
	v_cvt_pk_bf16_f32 v10, v12, v13
	v_cvt_pk_bf16_f32 v11, v14, v15
	s_nop 0
	global_store_dwordx4 v[16:17], v[8:11], off sc1
	s_nop 1
	v_cvt_pk_bf16_f32 v4, v4, v5
	v_cvt_pk_bf16_f32 v5, v6, v7
	v_cvt_pk_bf16_f32 v6, v0, v1
	v_cvt_pk_bf16_f32 v7, v2, v3
	v_lshl_add_u64 v[0:1], v[16:17], 0, s[20:21]
	global_store_dwordx4 v[0:1], v[4:7], off sc1
	s_nop 1
	s_cbranch_vccnz .LBB0_397
	s_andn2_b64 vcc, exec, s[14:15]
	s_cbranch_vccnz .LBB0_396
	s_nop 0
	s_branch .LBB0_396
.LBB0_409:
	s_waitcnt vmcnt(0)
	s_and_b64 vcc, exec, s[18:19]
	s_cbranch_vccz .Lnoalign_skip_3
	s_barrier

; #define PG8_STAGE(bufoff, gbase, voff) do { _Pragma("unroll") for (int _i = 0; _i < 2; ++_i) \
;         __builtin_amdgcn_global_load_lds((const unsigned*)((const char*)(gbase) + (voff)[_i]), (LAS unsigned*)(lds + (bufoff) + ldsw + _i * 8192), 16, 0, 0); } while (0)
; #define PG8_LDA(dst, b, h) do { _Pragma("unroll") for (int m = 0; m < 4; ++m) _Pragma("unroll") for (int k = 0; k < 2; ++k) dst[m][k] = *(const LAS bf16x8*)(lds + PG8_SA(b, h) + aoff + m * 2048 + k * 1024); } while (0)
; #define PG8_LDB(dst, b, h) do { _Pragma("unroll") for (int n = 0; n < 2; ++n) _Pragma("unroll") for (int k = 0; k < 2; ++k) dst[n][k] = *(const LAS bf16x8*)(lds + PG8_SB(b, h) + boff + n * 2048 + k * 1024); } while (0)
; #define PG8_MMA(ai, bj, At, Bt) do { __builtin_amdgcn_s_setprio(1); _Pragma("unroll") for (int m = 0; m < 4; ++m) _Pragma("unroll") for (int n = 0; n < 2; ++n) _Pragma("unroll") for (int k = 0; k < 2; ++k) \
;         acc[ai][bj][m][n] = __builtin_amdgcn_mfma_f32_16x16x32_bf16(Bt[n][k], At[m][k], acc[ai][bj][m][n], 0, 0, 0); __builtin_amdgcn_s_setprio(0); } while (0)
; #define PG8_WAIT_V(n) asm volatile("s_waitcnt vmcnt(" #n ")" ::: "memory")
; #define PG8_WAIT_L(n) asm volatile("s_waitcnt lgkmcnt(" #n ")" ::: "memory")
; #define PG8_BAR __builtin_amdgcn_s_barrier()
; #define PG8_SCHED __builtin_amdgcn_sched_barrier(0)
; template <class Epi, bool ALIGN_EPI>
; __device__ __forceinline__ void gemm_phase(LAS unsigned char* lds, const Gemm g, const StaticOrder& S, const Epi& E) {
;     ...
;             const char* a1 = cA + (size_t)(t + 1) * kstep;
;             const char* a2 = last ? nA : cA + (size_t)(t + 2) * kstep; const char* b2 = last ? nB : cB + (size_t)(t + 2) * kstep;
;             const char* a3 = a2 + kstep; const char* b3 = b2 + kstep;
;             PG8_LDB(B0, 0, 0); PG8_LDB(B1, 0, 1); PG8_SCHED; PG8_LDA(At, 0, 0); PG8_STAGE(PG8_SA(1, 1), a1 + hA, voffA);
;             PG8_WAIT_V(8); PG8_WAIT_L(0); PG8_BAR; PG8_MMA(0, 0, At, B0); PG8_MMA(0, 1, At, B1); PG8_BAR; PG8_SCHED;
;             PG8_LDA(At, 0, 1); PG8_STAGE(PG8_SB(0, 0), b2, voffB); PG8_STAGE(PG8_SB(0, 1), b2 + hB, voffB); PG8_STAGE(PG8_SA(0, 0), a2, voffA);
;             PG8_WAIT_V(8); PG8_WAIT_L(0); PG8_BAR; PG8_MMA(1, 0, At, B0); PG8_MMA(1, 1, At, B1); PG8_BAR; PG8_SCHED;
.LBB0_419:
	ds_read_b128 v[148:151], v145
	ds_read_b128 v[152:155], v145 offset:1024
	ds_read_b128 v[156:159], v145 offset:2048
	ds_read_b128 v[160:163], v145 offset:3072
	ds_read_b128 v[164:167], v146
	ds_read_b128 v[168:171], v146 offset:1024
	ds_read_b128 v[172:175], v146 offset:2048
	ds_read_b128 v[176:179], v146 offset:3072
	s_add_u32 s30, s28, 0xfff80080
	s_addc_u32 s31, s29, -1
	s_cmp_eq_u32 s53, 28
	s_cselect_b32 s35, s19, s31
	s_cselect_b32 s34, s49, s30
	s_cselect_b32 s31, s17, s52
	s_cselect_b32 s30, s50, s51
	v_lshl_add_u64 v[140:141], s[28:29], 0, v[136:137]
	s_add_i32 m0, s27, 0xc000
	ds_read_b128 v[180:183], v147
	ds_read_b128 v[184:187], v147 offset:1024
	ds_read_b128 v[188:191], v147 offset:2048
	ds_read_b128 v[194:197], v147 offset:3072
	ds_read_b128 v[198:201], v147 offset:4096
	ds_read_b128 v[202:205], v147 offset:5120
	ds_read_b128 v[206:209], v147 offset:6144
	ds_read_b128 v[210:213], v147 offset:7168
	global_load_lds_dwordx4 v[140:141], off
	v_lshl_add_u64 v[140:141], s[28:29], 0, v[138:139]
	s_add_i32 m0, s27, 0xe000
	s_nop 0
	global_load_lds_dwordx4 v[140:141], off
	s_waitcnt vmcnt(8)
	s_waitcnt lgkmcnt(0)
	s_barrier
	s_setprio 1
	s_waitcnt lgkmcnt(0)
	v_mfma_f32_16x16x32_bf16 v[124:127], v[148:151], v[180:183], v[124:127]
	v_mfma_f32_16x16x32_bf16 v[124:127], v[152:155], v[184:187], v[124:127]
	v_mfma_f32_16x16x32_bf16 v[120:123], v[156:159], v[180:183], v[120:123]
	v_mfma_f32_16x16x32_bf16 v[120:123], v[160:163], v[184:187], v[120:123]
	v_mfma_f32_16x16x32_bf16 v[116:119], v[148:151], v[188:191], v[116:119]
	v_mfma_f32_16x16x32_bf16 v[116:119], v[152:155], v[194:197], v[116:119]
	v_mfma_f32_16x16x32_bf16 v[108:111], v[156:159], v[188:191], v[108:111]
	v_mfma_f32_16x16x32_bf16 v[108:111], v[160:163], v[194:197], v[108:111]
	v_mfma_f32_16x16x32_bf16 v[100:103], v[148:151], v[198:201], v[100:103]
	v_mfma_f32_16x16x32_bf16 v[100:103], v[152:155], v[202:205], v[100:103]
	v_mfma_f32_16x16x32_bf16 v[92:95], v[156:159], v[198:201], v[92:95]
	v_mfma_f32_16x16x32_bf16 v[92:95], v[160:163], v[202:205], v[92:95]
	v_mfma_f32_16x16x32_bf16 v[84:87], v[148:151], v[206:209], v[84:87]
	v_mfma_f32_16x16x32_bf16 v[84:87], v[152:155], v[210:213], v[84:87]
	v_mfma_f32_16x16x32_bf16 v[76:79], v[156:159], v[206:209], v[76:79]
	v_mfma_f32_16x16x32_bf16 v[76:79], v[160:163], v[210:213], v[76:79]
	s_setprio 0
	s_setprio 1
	v_mfma_f32_16x16x32_bf16 v[112:115], v[164:167], v[180:183], v[112:115]
	v_mfma_f32_16x16x32_bf16 v[112:115], v[168:171], v[184:187], v[112:115]
	v_mfma_f32_16x16x32_bf16 v[104:107], v[172:175], v[180:183], v[104:107]
	v_mfma_f32_16x16x32_bf16 v[104:107], v[176:179], v[184:187], v[104:107]
	v_mfma_f32_16x16x32_bf16 v[96:99], v[164:167], v[188:191], v[96:99]
	v_mfma_f32_16x16x32_bf16 v[96:99], v[168:171], v[194:197], v[96:99]
	v_mfma_f32_16x16x32_bf16 v[88:91], v[172:175], v[188:191], v[88:91]
	v_mfma_f32_16x16x32_bf16 v[88:91], v[176:179], v[194:197], v[88:91]
	v_mfma_f32_16x16x32_bf16 v[80:83], v[164:167], v[198:201], v[80:83]
	v_mfma_f32_16x16x32_bf16 v[80:83], v[168:171], v[202:205], v[80:83]
	v_mfma_f32_16x16x32_bf16 v[72:75], v[172:175], v[198:201], v[72:75]
	v_mfma_f32_16x16x32_bf16 v[72:75], v[176:179], v[202:205], v[72:75]
	v_mfma_f32_16x16x32_bf16 v[68:71], v[164:167], v[206:209], v[68:71]
	v_mfma_f32_16x16x32_bf16 v[68:71], v[168:171], v[210:213], v[68:71]
	v_mfma_f32_16x16x32_bf16 v[64:67], v[172:175], v[206:209], v[64:67]
	v_mfma_f32_16x16x32_bf16 v[64:67], v[176:179], v[210:213], v[64:67]
	s_setprio 0
	s_barrier
	s_add_i32 s54, s45, s1
	v_lshl_add_u64 v[140:141], s[30:31], 0, v[132:133]
	s_mov_b32 m0, s54
	ds_read_b128 v[180:183], v147 offset:16384
	ds_read_b128 v[184:187], v147 offset:17408
	ds_read_b128 v[188:191], v147 offset:18432
	ds_read_b128 v[194:197], v147 offset:19456
	ds_read_b128 v[198:201], v147 offset:20480
	ds_read_b128 v[202:205], v147 offset:21504
	ds_read_b128 v[206:209], v147 offset:22528
	ds_read_b128 v[210:213], v147 offset:23552
	global_load_lds_dwordx4 v[140:141], off
	s_add_i32 m0, s54, 0x2000
	s_add_u32 s54, s30, 0x80000
	v_lshl_add_u64 v[214:215], s[30:31], 0, v[128:129]
	s_addc_u32 s55, s31, 0
	s_add_i32 s56, s46, s1
	global_load_lds_dwordx4 v[214:215], off
	v_lshl_add_u64 v[216:217], s[54:55], 0, v[132:133]
	s_mov_b32 m0, s56
	v_lshl_add_u64 v[218:219], s[34:35], 0, v[130:131]
	global_load_lds_dwordx4 v[216:217], off
	v_lshl_add_u64 v[216:217], s[54:55], 0, v[128:129]
	s_add_i32 m0, s56, 0x2000
	s_nop 0
	global_load_lds_dwordx4 v[216:217], off
	v_lshl_add_u64 v[216:217], s[34:35], 0, v[134:135]
	s_mov_b32 m0, s27
	s_nop 0
	global_load_lds_dwordx4 v[216:217], off
	s_mov_b32 m0, s39
	s_nop 0
	global_load_lds_dwordx4 v[218:219], off
	s_waitcnt vmcnt(8)
	s_waitcnt lgkmcnt(0)
	s_barrier
; #define PG8_STAGE(bufoff, gbase, voff) do { _Pragma("unroll") for (int _i = 0; _i < 2; ++_i) \
;         __builtin_amdgcn_global_load_lds((const unsigned*)((const char*)(gbase) + (voff)[_i]), (LAS unsigned*)(lds + (bufoff) + ldsw + _i * 8192), 16, 0, 0); } while (0)
; #define PG8_LDA(dst, b, h) do { _Pragma("unroll") for (int m = 0; m < 4; ++m) _Pragma("unroll") for (int k = 0; k < 2; ++k) dst[m][k] = *(const LAS bf16x8*)(lds + PG8_SA(b, h) + aoff + m * 2048 + k * 1024); } while (0)
; #define PG8_LDB(dst, b, h) do { _Pragma("unroll") for (int n = 0; n < 2; ++n) _Pragma("unroll") for (int k = 0; k < 2; ++k) dst[n][k] = *(const LAS bf16x8*)(lds + PG8_SB(b, h) + boff + n * 2048 + k * 1024); } while (0)
; #define PG8_MMA(ai, bj, At, Bt) do { __builtin_amdgcn_s_setprio(1); _Pragma("unroll") for (int m = 0; m < 4; ++m) _Pragma("unroll") for (int n = 0; n < 2; ++n) _Pragma("unroll") for (int k = 0; k < 2; ++k) \
;         acc[ai][bj][m][n] = __builtin_amdgcn_mfma_f32_16x16x32_bf16(Bt[n][k], At[m][k], acc[ai][bj][m][n], 0, 0, 0); __builtin_amdgcn_s_setprio(0); } while (0)
; #define PG8_WAIT_V(n) asm volatile("s_waitcnt vmcnt(" #n ")" ::: "memory")
; #define PG8_WAIT_L(n) asm volatile("s_waitcnt lgkmcnt(" #n ")" ::: "memory")
; #define PG8_BAR __builtin_amdgcn_s_barrier()
; #define PG8_SCHED __builtin_amdgcn_sched_barrier(0)
; template <class Epi, bool ALIGN_EPI>
; __device__ __forceinline__ void gemm_phase(LAS unsigned char* lds, const Gemm g, const StaticOrder& S, const Epi& E) {
;     ...
;             PG8_WAIT_V(8); PG8_WAIT_L(0); PG8_BAR; PG8_MMA(1, 0, At, B0); PG8_MMA(1, 1, At, B1); PG8_BAR; PG8_SCHED;
;             PG8_LDB(B0, 1, 0); PG8_LDB(B1, 1, 1); PG8_SCHED; PG8_LDA(At, 1, 0); PG8_STAGE(PG8_SA(0, 1), a2 + hA, voffA);
;             PG8_WAIT_V(8); PG8_WAIT_L(0); PG8_BAR; PG8_MMA(0, 0, At, B0); PG8_MMA(0, 1, At, B1); PG8_BAR; PG8_SCHED;
	s_setprio 1
	s_waitcnt lgkmcnt(0)
	v_mfma_f32_16x16x32_bf16 v[60:63], v[148:151], v[180:183], v[60:63]
	v_mfma_f32_16x16x32_bf16 v[60:63], v[152:155], v[184:187], v[60:63]
	v_mfma_f32_16x16x32_bf16 v[56:59], v[156:159], v[180:183], v[56:59]
	v_mfma_f32_16x16x32_bf16 v[56:59], v[160:163], v[184:187], v[56:59]
	v_mfma_f32_16x16x32_bf16 v[52:55], v[148:151], v[188:191], v[52:55]
	v_mfma_f32_16x16x32_bf16 v[52:55], v[152:155], v[194:197], v[52:55]
	v_mfma_f32_16x16x32_bf16 v[44:47], v[156:159], v[188:191], v[44:47]
	v_mfma_f32_16x16x32_bf16 v[44:47], v[160:163], v[194:197], v[44:47]
	v_mfma_f32_16x16x32_bf16 v[36:39], v[148:151], v[198:201], v[36:39]
	v_mfma_f32_16x16x32_bf16 v[36:39], v[152:155], v[202:205], v[36:39]
	v_mfma_f32_16x16x32_bf16 v[28:31], v[156:159], v[198:201], v[28:31]
	v_mfma_f32_16x16x32_bf16 v[28:31], v[160:163], v[202:205], v[28:31]
	v_mfma_f32_16x16x32_bf16 v[20:23], v[148:151], v[206:209], v[20:23]
	v_mfma_f32_16x16x32_bf16 v[20:23], v[152:155], v[210:213], v[20:23]
	v_mfma_f32_16x16x32_bf16 v[12:15], v[156:159], v[206:209], v[12:15]
	v_mfma_f32_16x16x32_bf16 v[12:15], v[160:163], v[210:213], v[12:15]
	s_setprio 0
	s_setprio 1
	v_mfma_f32_16x16x32_bf16 v[48:51], v[164:167], v[180:183], v[48:51]
	v_mfma_f32_16x16x32_bf16 v[48:51], v[168:171], v[184:187], v[48:51]
	v_mfma_f32_16x16x32_bf16 v[40:43], v[172:175], v[180:183], v[40:43]
	v_mfma_f32_16x16x32_bf16 v[40:43], v[176:179], v[184:187], v[40:43]
	v_mfma_f32_16x16x32_bf16 v[32:35], v[164:167], v[188:191], v[32:35]
	v_mfma_f32_16x16x32_bf16 v[32:35], v[168:171], v[194:197], v[32:35]
	v_mfma_f32_16x16x32_bf16 v[24:27], v[172:175], v[188:191], v[24:27]
	v_mfma_f32_16x16x32_bf16 v[24:27], v[176:179], v[194:197], v[24:27]
	v_mfma_f32_16x16x32_bf16 v[16:19], v[164:167], v[198:201], v[16:19]
	v_mfma_f32_16x16x32_bf16 v[16:19], v[168:171], v[202:205], v[16:19]
	v_mfma_f32_16x16x32_bf16 v[8:11], v[172:175], v[198:201], v[8:11]
	v_mfma_f32_16x16x32_bf16 v[8:11], v[176:179], v[202:205], v[8:11]
	v_mfma_f32_16x16x32_bf16 v[4:7], v[164:167], v[206:209], v[4:7]
	v_mfma_f32_16x16x32_bf16 v[4:7], v[168:171], v[210:213], v[4:7]
	v_mfma_f32_16x16x32_bf16 v[0:3], v[172:175], v[206:209], v[0:3]
	v_mfma_f32_16x16x32_bf16 v[0:3], v[176:179], v[210:213], v[0:3]
	s_setprio 0
	s_barrier
	s_add_i32 s54, 0, 0x18000
	s_add_i32 s55, 0, 0x1c000
	v_add_u32_e32 v160, s54, v143
	v_add_u32_e32 v176, s55, v143
	ds_read_b128 v[148:151], v160
	ds_read_b128 v[152:155], v160 offset:1024
	ds_read_b128 v[156:159], v160 offset:2048
	ds_read_b128 v[160:163], v160 offset:3072
	ds_read_b128 v[164:167], v176
	ds_read_b128 v[168:171], v176 offset:1024
	ds_read_b128 v[172:175], v176 offset:2048
	ds_read_b128 v[176:179], v176 offset:3072
	s_add_u32 s34, s34, 0x80000
	s_addc_u32 s35, s35, 0
	s_mov_b32 m0, s40
	v_lshl_add_u64 v[220:221], s[34:35], 0, v[134:135]
	ds_read_b128 v[180:183], v147 offset:32768
	ds_read_b128 v[184:187], v147 offset:33792
	ds_read_b128 v[188:191], v147 offset:34816
	ds_read_b128 v[194:197], v147 offset:35840
	ds_read_b128 v[198:201], v147 offset:36864
	ds_read_b128 v[202:205], v147 offset:37888
	ds_read_b128 v[206:209], v147 offset:38912
	ds_read_b128 v[210:213], v147 offset:39936
	global_load_lds_dwordx4 v[220:221], off
	v_lshl_add_u64 v[220:221], s[34:35], 0, v[130:131]
	s_mov_b32 m0, s41
	s_nop 0
	global_load_lds_dwordx4 v[220:221], off
	s_waitcnt vmcnt(8)
	s_waitcnt lgkmcnt(0)
	s_barrier
	s_setprio 1
	s_waitcnt lgkmcnt(0)
	v_mfma_f32_16x16x32_bf16 v[124:127], v[148:151], v[180:183], v[124:127]
	v_mfma_f32_16x16x32_bf16 v[124:127], v[152:155], v[184:187], v[124:127]
	v_mfma_f32_16x16x32_bf16 v[120:123], v[156:159], v[180:183], v[120:123]
	v_mfma_f32_16x16x32_bf16 v[120:123], v[160:163], v[184:187], v[120:123]
	v_mfma_f32_16x16x32_bf16 v[116:119], v[148:151], v[188:191], v[116:119]
	v_mfma_f32_16x16x32_bf16 v[116:119], v[152:155], v[194:197], v[116:119]
	v_mfma_f32_16x16x32_bf16 v[108:111], v[156:159], v[188:191], v[108:111]
	v_mfma_f32_16x16x32_bf16 v[108:111], v[160:163], v[194:197], v[108:111]
	v_mfma_f32_16x16x32_bf16 v[100:103], v[148:151], v[198:201], v[100:103]
	v_mfma_f32_16x16x32_bf16 v[100:103], v[152:155], v[202:205], v[100:103]
	v_mfma_f32_16x16x32_bf16 v[92:95], v[156:159], v[198:201], v[92:95]
	v_mfma_f32_16x16x32_bf16 v[92:95], v[160:163], v[202:205], v[92:95]
	v_mfma_f32_16x16x32_bf16 v[84:87], v[148:151], v[206:209], v[84:87]
	v_mfma_f32_16x16x32_bf16 v[84:87], v[152:155], v[210:213], v[84:87]
	v_mfma_f32_16x16x32_bf16 v[76:79], v[156:159], v[206:209], v[76:79]
	v_mfma_f32_16x16x32_bf16 v[76:79], v[160:163], v[210:213], v[76:79]
	s_setprio 0
	s_setprio 1
	v_mfma_f32_16x16x32_bf16 v[112:115], v[164:167], v[180:183], v[112:115]
	v_mfma_f32_16x16x32_bf16 v[112:115], v[168:171], v[184:187], v[112:115]
	v_mfma_f32_16x16x32_bf16 v[104:107], v[172:175], v[180:183], v[104:107]
	v_mfma_f32_16x16x32_bf16 v[104:107], v[176:179], v[184:187], v[104:107]
	v_mfma_f32_16x16x32_bf16 v[96:99], v[164:167], v[188:191], v[96:99]
	v_mfma_f32_16x16x32_bf16 v[96:99], v[168:171], v[194:197], v[96:99]
	v_mfma_f32_16x16x32_bf16 v[88:91], v[172:175], v[188:191], v[88:91]
	v_mfma_f32_16x16x32_bf16 v[88:91], v[176:179], v[194:197], v[88:91]
	v_mfma_f32_16x16x32_bf16 v[80:83], v[164:167], v[198:201], v[80:83]
	v_mfma_f32_16x16x32_bf16 v[80:83], v[168:171], v[202:205], v[80:83]
	v_mfma_f32_16x16x32_bf16 v[72:75], v[172:175], v[198:201], v[72:75]
	v_mfma_f32_16x16x32_bf16 v[72:75], v[176:179], v[202:205], v[72:75]
	v_mfma_f32_16x16x32_bf16 v[68:71], v[164:167], v[206:209], v[68:71]
	v_mfma_f32_16x16x32_bf16 v[68:71], v[168:171], v[210:213], v[68:71]
	v_mfma_f32_16x16x32_bf16 v[64:67], v[172:175], v[206:209], v[64:67]
	v_mfma_f32_16x16x32_bf16 v[64:67], v[176:179], v[210:213], v[64:67]
	s_setprio 0
	s_barrier
; #define PG8_STAGE(bufoff, gbase, voff) do { _Pragma("unroll") for (int _i = 0; _i < 2; ++_i) \
;         __builtin_amdgcn_global_load_lds((const unsigned*)((const char*)(gbase) + (voff)[_i]), (LAS unsigned*)(lds + (bufoff) + ldsw + _i * 8192), 16, 0, 0); } while (0)
; #define PG8_LDA(dst, b, h) do { _Pragma("unroll") for (int m = 0; m < 4; ++m) _Pragma("unroll") for (int k = 0; k < 2; ++k) dst[m][k] = *(const LAS bf16x8*)(lds + PG8_SA(b, h) + aoff + m * 2048 + k * 1024); } while (0)
; #define PG8_MMA(ai, bj, At, Bt) do { __builtin_amdgcn_s_setprio(1); _Pragma("unroll") for (int m = 0; m < 4; ++m) _Pragma("unroll") for (int n = 0; n < 2; ++n) _Pragma("unroll") for (int k = 0; k < 2; ++k) \
;         acc[ai][bj][m][n] = __builtin_amdgcn_mfma_f32_16x16x32_bf16(Bt[n][k], At[m][k], acc[ai][bj][m][n], 0, 0, 0); __builtin_amdgcn_s_setprio(0); } while (0)
; #define PG8_WAIT_V(n) asm volatile("s_waitcnt vmcnt(" #n ")" ::: "memory")
; #define PG8_WAIT_L(n) asm volatile("s_waitcnt lgkmcnt(" #n ")" ::: "memory")
; #define PG8_BAR __builtin_amdgcn_s_barrier()
; #define PG8_SCHED __builtin_amdgcn_sched_barrier(0)
; template <class Epi, bool ALIGN_EPI>
; __device__ __forceinline__ void gemm_phase(LAS unsigned char* lds, const Gemm g, const StaticOrder& S, const Epi& E) {
;     ...
;             PG8_WAIT_V(8); PG8_WAIT_L(0); PG8_BAR; PG8_MMA(0, 0, At, B0); PG8_MMA(0, 1, At, B1); PG8_BAR; PG8_SCHED;
;             PG8_LDA(At, 1, 1); PG8_STAGE(PG8_SB(1, 0), b3, voffB); PG8_STAGE(PG8_SB(1, 1), b3 + hB, voffB); PG8_STAGE(PG8_SA(1, 0), a3, voffA);
;             PG8_WAIT_V(8); PG8_WAIT_L(0); PG8_BAR; PG8_MMA(1, 0, At, B0); PG8_MMA(1, 1, At, B1); PG8_BAR; PG8_SCHED;
;         }
;         if constexpr (ALIGN_EPI) { if (wr == 0) PG8_BAR; }
	s_add_i32 s34, s54, s1
	v_lshl_add_u64 v[140:141], v[140:141], 0, s[10:11]
	s_mov_b32 m0, s34
	ds_read_b128 v[180:183], v147 offset:49152
	ds_read_b128 v[184:187], v147 offset:50176
	ds_read_b128 v[188:191], v147 offset:51200
	ds_read_b128 v[194:197], v147 offset:52224
	ds_read_b128 v[198:201], v147 offset:53248
	ds_read_b128 v[202:205], v147 offset:54272
	ds_read_b128 v[206:209], v147 offset:55296
	ds_read_b128 v[210:213], v147 offset:56320
	global_load_lds_dwordx4 v[140:141], off
	s_add_i32 m0, s34, 0x2000
	s_add_u32 s30, s30, 0x80080
	v_lshl_add_u64 v[140:141], v[214:215], 0, s[10:11]
	s_addc_u32 s31, s31, 0
	s_add_i32 s34, s55, s1
	global_load_lds_dwordx4 v[140:141], off
	v_lshl_add_u64 v[140:141], s[30:31], 0, v[132:133]
	s_mov_b32 m0, s34
	s_nop 0
	global_load_lds_dwordx4 v[140:141], off
	v_lshl_add_u64 v[140:141], s[30:31], 0, v[128:129]
	s_add_i32 m0, s34, 0x2000
	s_nop 0
	global_load_lds_dwordx4 v[140:141], off
	v_lshl_add_u64 v[140:141], v[216:217], 0, s[10:11]
	s_mov_b32 m0, s42
	s_nop 0
	global_load_lds_dwordx4 v[140:141], off
	v_lshl_add_u64 v[140:141], v[218:219], 0, s[10:11]
	s_mov_b32 m0, s43
	s_nop 0
	global_load_lds_dwordx4 v[140:141], off
	s_waitcnt vmcnt(8)
	s_waitcnt lgkmcnt(0)
	s_barrier
	s_setprio 1
	s_waitcnt lgkmcnt(0)
	v_mfma_f32_16x16x32_bf16 v[60:63], v[148:151], v[180:183], v[60:63]
	v_mfma_f32_16x16x32_bf16 v[60:63], v[152:155], v[184:187], v[60:63]
	v_mfma_f32_16x16x32_bf16 v[56:59], v[156:159], v[180:183], v[56:59]
	v_mfma_f32_16x16x32_bf16 v[56:59], v[160:163], v[184:187], v[56:59]
	v_mfma_f32_16x16x32_bf16 v[52:55], v[148:151], v[188:191], v[52:55]
	v_mfma_f32_16x16x32_bf16 v[52:55], v[152:155], v[194:197], v[52:55]
	v_mfma_f32_16x16x32_bf16 v[44:47], v[156:159], v[188:191], v[44:47]
	v_mfma_f32_16x16x32_bf16 v[44:47], v[160:163], v[194:197], v[44:47]
	v_mfma_f32_16x16x32_bf16 v[36:39], v[148:151], v[198:201], v[36:39]
	v_mfma_f32_16x16x32_bf16 v[36:39], v[152:155], v[202:205], v[36:39]
	v_mfma_f32_16x16x32_bf16 v[28:31], v[156:159], v[198:201], v[28:31]
	v_mfma_f32_16x16x32_bf16 v[28:31], v[160:163], v[202:205], v[28:31]
	v_mfma_f32_16x16x32_bf16 v[20:23], v[148:151], v[206:209], v[20:23]
	v_mfma_f32_16x16x32_bf16 v[20:23], v[152:155], v[210:213], v[20:23]
	v_mfma_f32_16x16x32_bf16 v[12:15], v[156:159], v[206:209], v[12:15]
	v_mfma_f32_16x16x32_bf16 v[12:15], v[160:163], v[210:213], v[12:15]
	s_setprio 0
	s_setprio 1
	v_mfma_f32_16x16x32_bf16 v[48:51], v[164:167], v[180:183], v[48:51]
	v_mfma_f32_16x16x32_bf16 v[48:51], v[168:171], v[184:187], v[48:51]
	v_mfma_f32_16x16x32_bf16 v[40:43], v[172:175], v[180:183], v[40:43]
	v_mfma_f32_16x16x32_bf16 v[40:43], v[176:179], v[184:187], v[40:43]
	v_mfma_f32_16x16x32_bf16 v[32:35], v[164:167], v[188:191], v[32:35]
	v_mfma_f32_16x16x32_bf16 v[32:35], v[168:171], v[194:197], v[32:35]
	v_mfma_f32_16x16x32_bf16 v[24:27], v[172:175], v[188:191], v[24:27]
	v_mfma_f32_16x16x32_bf16 v[24:27], v[176:179], v[194:197], v[24:27]
	v_mfma_f32_16x16x32_bf16 v[16:19], v[164:167], v[198:201], v[16:19]
	v_mfma_f32_16x16x32_bf16 v[16:19], v[168:171], v[202:205], v[16:19]
	v_mfma_f32_16x16x32_bf16 v[8:11], v[172:175], v[198:201], v[8:11]
	v_mfma_f32_16x16x32_bf16 v[8:11], v[176:179], v[202:205], v[8:11]
	v_mfma_f32_16x16x32_bf16 v[4:7], v[164:167], v[206:209], v[4:7]
	v_mfma_f32_16x16x32_bf16 v[4:7], v[168:171], v[210:213], v[4:7]
	v_mfma_f32_16x16x32_bf16 v[0:3], v[172:175], v[206:209], v[0:3]
	v_mfma_f32_16x16x32_bf16 v[0:3], v[176:179], v[210:213], v[0:3]
	s_setprio 0
	s_barrier
	s_add_i32 s53, s53, 2
	s_add_u32 s28, s28, 0x100
	s_addc_u32 s29, s29, 0
	s_add_u32 s51, s51, 0x100
	s_addc_u32 s52, s52, 0
	s_cmp_gt_u32 s53, 29
	s_cbranch_scc0 .LBB0_419
	s_and_b64 vcc, exec, s[14:15]
	s_cbranch_vccz .LBB0_422
	s_nop 0
; #define PG8_WAIT_V(n) asm volatile("s_waitcnt vmcnt(" #n ")" ::: "memory")
; #define PG8_BAR __builtin_amdgcn_s_barrier()
; template <class Epi, bool ALIGN_EPI>
; __device__ __forceinline__ void gemm_phase(LAS unsigned char* lds, const Gemm g, const StaticOrder& S, const Epi& E) {
;     ...
;         if (!has_next) break;
;         E.post(ui + 1, rsn);
; #pragma unroll
;         for (int a = 0; a < 2; ++a)
; #pragma unroll
;             for (int b = 0; b < 2; ++b)
; #pragma unroll
;                 for (int m = 0; m < 4; ++m)
; #pragma unroll
;                     for (int n = 0; n < 2; ++n) acc[a][b][m][n] = (f32x4){0.f, 0.f, 0.f, 0.f};
;         cur = nxt; cA = nA; cB = nB; ++ui;
; #pragma unroll
;         for (int i_ = 0; i_ < 8; ++i_) rsv[i_] = rsn[i_];
;         if constexpr (ALIGN_EPI) { if (wr == 1) PG8_BAR; }
;     }
;     PG8_WAIT_V(0);
;     if constexpr (!ALIGN_EPI) { if (wr == 0) PG8_BAR; }
;     PG8_BAR;
;     __device__ __forceinline__ void operator()(const f32x4 (&acc)[2][2][4][2], const Unit& u, int wr, int wc, int fr, int fq, int, const float (&)[8]) const {
;         const int col0 = u.pn * BM + wc * 32 + 8 * fq; const int row0 = u.pm * BM + wr * 64 + fr;
;         float part[2][4];
;         f32x4 c0[2], c1[2], n0[2], n1[2];
;     ...
;         ER_LOAD(c0, c1, 0);
; #pragma unroll
;         for (int aim = 0; aim < 8; ++aim) { const int ai = aim >> 2, m = aim & 3;
;             if (aim < 7) ER_LOAD(n0, n1, aim + 1);
;             asm volatile("" ::: "memory");
;             float pp = 0.f;
; #pragma unroll
;             for (int bj = 0; bj < 2; ++bj) { const size_t off = (size_t)(row0 + ai * HALF + m * 16) * ldc + col0 + bj * HALF;
;                 const f32x4 v0 = acc[ai][bj][m][0] + c0[bj], v1 = acc[ai][bj][m][1] + c1[bj];
;                 if (outf) { *(f32x4*)(outf + off) = v0; *(f32x4*)(outf + off + 4) = v1; }
;                 if (outb) { u32x4 w; w.x = cvt_pk_bf16(v0[0], v0[1]); w.y = cvt_pk_bf16(v0[2], v0[3]); w.z = cvt_pk_bf16(v1[0], v1[1]); w.w = cvt_pk_bf16(v1[2], v1[3]); *(u32x4*)(outb + off) = w; }
;                 pp += (v0[0] * v0[0] + v0[1] * v0[1]) + (v0[2] * v0[2] + v0[3] * v0[3]) + (v1[0] * v1[0] + v1[1] * v1[1]) + (v1[2] * v1[2] + v1[3] * v1[3]); }
;             part[ai][m] = pp;
;             asm volatile("" ::: "memory");
; #pragma unroll
;             for (int bj = 0; bj < 2; ++bj) { c0[bj] = n0[bj]; c1[bj] = n1[bj]; } }
.LBB0_422:
	v_lshl_add_u32 v140, s26, 8, v142
	v_lshl_or_b32 v152, s48, 8, v144
	v_ashrrev_i32_e32 v141, 31, v140
	v_ashrrev_i32_e32 v153, 31, v152
	v_pk_add_f32 v[148:149], v[120:121], 0 op_sel_hi:[1,0]
	v_lshlrev_b64 v[120:121], 12, v[140:141]
	v_or_b32_e32 v154, 16, v140
	v_pk_add_f32 v[150:151], v[122:123], 0 op_sel_hi:[1,0]
	v_lshl_add_u64 v[122:123], s[8:9], 0, v[120:121]
	v_lshlrev_b64 v[120:121], 2, v[152:153]
	v_ashrrev_i32_e32 v155, 31, v154
	v_pk_add_f32 v[126:127], v[126:127], 0 op_sel_hi:[1,0]
	v_pk_add_f32 v[124:125], v[124:125], 0 op_sel_hi:[1,0]
	v_lshl_add_u64 v[122:123], v[122:123], 0, v[120:121]
	v_pk_add_f32 v[114:115], v[114:115], 0 op_sel_hi:[1,0]
	v_pk_add_f32 v[112:113], v[112:113], 0 op_sel_hi:[1,0]
	global_store_dwordx4 v[122:123], v[124:127], off
	global_store_dwordx4 v[122:123], v[148:151], off offset:16
	v_pk_add_f32 v[106:107], v[106:107], 0 op_sel_hi:[1,0]
	v_pk_add_f32 v[104:105], v[104:105], 0 op_sel_hi:[1,0]
	global_store_dwordx4 v[122:123], v[112:115], off offset:512
	global_store_dwordx4 v[122:123], v[104:107], off offset:528
	v_pk_add_f32 v[98:99], v[98:99], 0 op_sel_hi:[1,0]
	v_lshlrev_b64 v[114:115], 12, v[154:155]
	v_or_b32_e32 v112, 32, v140
	v_lshl_add_u64 v[114:115], s[8:9], 0, v[114:115]
	v_ashrrev_i32_e32 v113, 31, v112
	v_pk_add_f32 v[106:107], v[118:119], 0 op_sel_hi:[1,0]
	v_pk_add_f32 v[104:105], v[116:117], 0 op_sel_hi:[1,0]
	v_lshl_add_u64 v[114:115], v[114:115], 0, v[120:121]
	v_pk_add_f32 v[96:97], v[96:97], 0 op_sel_hi:[1,0]
	v_pk_add_f32 v[110:111], v[110:111], 0 op_sel_hi:[1,0]
	v_pk_add_f32 v[108:109], v[108:109], 0 op_sel_hi:[1,0]
	global_store_dwordx4 v[114:115], v[104:107], off
	global_store_dwordx4 v[114:115], v[108:111], off offset:16
	v_pk_add_f32 v[90:91], v[90:91], 0 op_sel_hi:[1,0]
	v_pk_add_f32 v[88:89], v[88:89], 0 op_sel_hi:[1,0]
	global_store_dwordx4 v[114:115], v[96:99], off offset:512
	global_store_dwordx4 v[114:115], v[88:91], off offset:528
	v_pk_add_f32 v[82:83], v[82:83], 0 op_sel_hi:[1,0]
	v_lshlrev_b64 v[98:99], 12, v[112:113]
	v_or_b32_e32 v96, 48, v140
	v_lshl_add_u64 v[98:99], s[8:9], 0, v[98:99]
	v_ashrrev_i32_e32 v97, 31, v96
	v_pk_add_f32 v[90:91], v[102:103], 0 op_sel_hi:[1,0]
	v_pk_add_f32 v[88:89], v[100:101], 0 op_sel_hi:[1,0]
	v_lshl_add_u64 v[98:99], v[98:99], 0, v[120:121]
	v_pk_add_f32 v[80:81], v[80:81], 0 op_sel_hi:[1,0]
	v_pk_add_f32 v[94:95], v[94:95], 0 op_sel_hi:[1,0]
	v_pk_add_f32 v[92:93], v[92:93], 0 op_sel_hi:[1,0]
	global_store_dwordx4 v[98:99], v[88:91], off
	global_store_dwordx4 v[98:99], v[92:95], off offset:16
	v_pk_add_f32 v[74:75], v[74:75], 0 op_sel_hi:[1,0]
	v_pk_add_f32 v[72:73], v[72:73], 0 op_sel_hi:[1,0]
	global_store_dwordx4 v[98:99], v[80:83], off offset:512
	global_store_dwordx4 v[98:99], v[72:75], off offset:528
	v_pk_add_f32 v[70:71], v[70:71], 0 op_sel_hi:[1,0]
	v_lshlrev_b64 v[80:81], 12, v[96:97]
	v_lshl_add_u64 v[80:81], s[8:9], 0, v[80:81]
	v_pk_add_f32 v[74:75], v[86:87], 0 op_sel_hi:[1,0]
	v_pk_add_f32 v[72:73], v[84:85], 0 op_sel_hi:[1,0]
	v_lshl_add_u64 v[80:81], v[80:81], 0, v[120:121]
	v_pk_add_f32 v[68:69], v[68:69], 0 op_sel_hi:[1,0]
	v_pk_add_f32 v[64:65], v[64:65], 0 op_sel_hi:[1,0]
	v_pk_add_f32 v[78:79], v[78:79], 0 op_sel_hi:[1,0]
	v_pk_add_f32 v[76:77], v[76:77], 0 op_sel_hi:[1,0]
	global_store_dwordx4 v[80:81], v[72:75], off
	global_store_dwordx4 v[80:81], v[76:79], off offset:16
	v_pk_add_f32 v[66:67], v[66:67], 0 op_sel_hi:[1,0]
	global_store_dwordx4 v[80:81], v[68:71], off offset:512
	global_store_dwordx4 v[80:81], v[64:67], off offset:528
	v_pk_add_f32 v[62:63], v[62:63], 0 op_sel_hi:[1,0]
	v_add_co_u32_e32 v68, vcc, s47, v122
	v_add_u32_e32 v64, 0x90, v140
	v_ashrrev_i32_e32 v65, 31, v64
	v_pk_add_f32 v[60:61], v[60:61], 0 op_sel_hi:[1,0]
	v_lshl_add_u64 v[66:67], v[122:123], 0, s[4:5]
	v_addc_co_u32_e32 v69, vcc, 0, v123, vcc
	v_pk_add_f32 v[50:51], v[50:51], 0 op_sel_hi:[1,0]
	v_pk_add_f32 v[48:49], v[48:49], 0 op_sel_hi:[1,0]
	v_pk_add_f32 v[58:59], v[58:59], 0 op_sel_hi:[1,0]
	v_pk_add_f32 v[56:57], v[56:57], 0 op_sel_hi:[1,0]
	global_store_dwordx4 v[68:69], v[60:63], off
	global_store_dwordx4 v[66:67], v[56:59], off offset:16
	v_pk_add_f32 v[42:43], v[42:43], 0 op_sel_hi:[1,0]
	v_pk_add_f32 v[40:41], v[40:41], 0 op_sel_hi:[1,0]
	global_store_dwordx4 v[66:67], v[48:51], off offset:512
	global_store_dwordx4 v[66:67], v[40:43], off offset:528
	v_pk_add_f32 v[34:35], v[34:35], 0 op_sel_hi:[1,0]
	v_lshlrev_b64 v[50:51], 12, v[64:65]
	v_add_u32_e32 v48, 0xa0, v140
	v_lshl_add_u64 v[50:51], s[8:9], 0, v[50:51]
	v_ashrrev_i32_e32 v49, 31, v48
	v_pk_add_f32 v[42:43], v[54:55], 0 op_sel_hi:[1,0]
	v_pk_add_f32 v[40:41], v[52:53], 0 op_sel_hi:[1,0]
	v_lshl_add_u64 v[50:51], v[50:51], 0, v[120:121]
	v_pk_add_f32 v[32:33], v[32:33], 0 op_sel_hi:[1,0]
	v_pk_add_f32 v[46:47], v[46:47], 0 op_sel_hi:[1,0]
	v_pk_add_f32 v[44:45], v[44:45], 0 op_sel_hi:[1,0]
	global_store_dwordx4 v[50:51], v[40:43], off
	global_store_dwordx4 v[50:51], v[44:47], off offset:16
	v_pk_add_f32 v[26:27], v[26:27], 0 op_sel_hi:[1,0]
	v_pk_add_f32 v[24:25], v[24:25], 0 op_sel_hi:[1,0]
	global_store_dwordx4 v[50:51], v[32:35], off offset:512
	global_store_dwordx4 v[50:51], v[24:27], off offset:528
	v_pk_add_f32 v[18:19], v[18:19], 0 op_sel_hi:[1,0]
	v_lshlrev_b64 v[34:35], 12, v[48:49]
	v_add_u32_e32 v32, 0xb0, v140
	v_lshl_add_u64 v[34:35], s[8:9], 0, v[34:35]
	v_ashrrev_i32_e32 v33, 31, v32
	v_pk_add_f32 v[26:27], v[38:39], 0 op_sel_hi:[1,0]
	v_pk_add_f32 v[24:25], v[36:37], 0 op_sel_hi:[1,0]
	v_lshl_add_u64 v[34:35], v[34:35], 0, v[120:121]
	v_pk_add_f32 v[16:17], v[16:17], 0 op_sel_hi:[1,0]
	v_pk_add_f32 v[30:31], v[30:31], 0 op_sel_hi:[1,0]
	v_pk_add_f32 v[28:29], v[28:29], 0 op_sel_hi:[1,0]
	global_store_dwordx4 v[34:35], v[24:27], off
	global_store_dwordx4 v[34:35], v[28:31], off offset:16
	v_pk_add_f32 v[10:11], v[10:11], 0 op_sel_hi:[1,0]
	v_pk_add_f32 v[8:9], v[8:9], 0 op_sel_hi:[1,0]
	global_store_dwordx4 v[34:35], v[16:19], off offset:512
	global_store_dwordx4 v[34:35], v[8:11], off offset:528
	v_pk_add_f32 v[6:7], v[6:7], 0 op_sel_hi:[1,0]
	v_lshlrev_b64 v[16:17], 12, v[32:33]
	v_lshl_add_u64 v[16:17], s[8:9], 0, v[16:17]
	v_pk_add_f32 v[10:11], v[22:23], 0 op_sel_hi:[1,0]
	v_pk_add_f32 v[8:9], v[20:21], 0 op_sel_hi:[1,0]
	v_lshl_add_u64 v[16:17], v[16:17], 0, v[120:121]
	v_pk_add_f32 v[4:5], v[4:5], 0 op_sel_hi:[1,0]
	v_pk_add_f32 v[14:15], v[14:15], 0 op_sel_hi:[1,0]
	v_pk_add_f32 v[12:13], v[12:13], 0 op_sel_hi:[1,0]
	global_store_dwordx4 v[16:17], v[8:11], off
	global_store_dwordx4 v[16:17], v[12:15], off offset:16
	v_pk_add_f32 v[2:3], v[2:3], 0 op_sel_hi:[1,0]
	v_pk_add_f32 v[0:1], v[0:1], 0 op_sel_hi:[1,0]
	global_store_dwordx4 v[16:17], v[4:7], off offset:512
	global_store_dwordx4 v[16:17], v[0:3], off offset:528
	s_andn2_b64 vcc, exec, s[20:21]
	s_mov_b64 s[20:21], -1
	s_cbranch_vccnz .LBB0_415
	s_andn2_b64 vcc, exec, s[6:7]
	s_cbranch_vccnz .LBB0_414
	s_nop 0
	s_branch .LBB0_414
.LBB0_425:
	s_waitcnt vmcnt(0)
	s_and_b64 vcc, exec, s[14:15]
	s_cbranch_vccz .Lnoalign_skip_4
	s_barrier

; #define PG8_STAGE(bufoff, gbase, voff) do { _Pragma("unroll") for (int _i = 0; _i < 2; ++_i) \
;         __builtin_amdgcn_global_load_lds((const unsigned*)((const char*)(gbase) + (voff)[_i]), (LAS unsigned*)(lds + (bufoff) + ldsw + _i * 8192), 16, 0, 0); } while (0)
; #define PG8_LDA(dst, b, h) do { _Pragma("unroll") for (int m = 0; m < 4; ++m) _Pragma("unroll") for (int k = 0; k < 2; ++k) dst[m][k] = *(const LAS bf16x8*)(lds + PG8_SA(b, h) + aoff + m * 2048 + k * 1024); } while (0)
; #define PG8_LDB(dst, b, h) do { _Pragma("unroll") for (int n = 0; n < 2; ++n) _Pragma("unroll") for (int k = 0; k < 2; ++k) dst[n][k] = *(const LAS bf16x8*)(lds + PG8_SB(b, h) + boff + n * 2048 + k * 1024); } while (0)
; #define PG8_MMA(ai, bj, At, Bt) do { __builtin_amdgcn_s_setprio(1); _Pragma("unroll") for (int m = 0; m < 4; ++m) _Pragma("unroll") for (int n = 0; n < 2; ++n) _Pragma("unroll") for (int k = 0; k < 2; ++k) \
;         acc[ai][bj][m][n] = __builtin_amdgcn_mfma_f32_16x16x32_bf16(Bt[n][k], At[m][k], acc[ai][bj][m][n], 0, 0, 0); __builtin_amdgcn_s_setprio(0); } while (0)
; #define PG8_WAIT_V(n) asm volatile("s_waitcnt vmcnt(" #n ")" ::: "memory")
; #define PG8_WAIT_L(n) asm volatile("s_waitcnt lgkmcnt(" #n ")" ::: "memory")
; #define PG8_BAR __builtin_amdgcn_s_barrier()
; #define PG8_SCHED __builtin_amdgcn_sched_barrier(0)
; template <class Epi, bool ALIGN_EPI>
; __device__ __forceinline__ void gemm_phase(LAS unsigned char* lds, const Gemm g, const StaticOrder& S, const Epi& E) {
;     ...
;             const char* a1 = cA + (size_t)(t + 1) * kstep;
;             const char* a2 = last ? nA : cA + (size_t)(t + 2) * kstep; const char* b2 = last ? nB : cB + (size_t)(t + 2) * kstep;
;             const char* a3 = a2 + kstep; const char* b3 = b2 + kstep;
;             PG8_LDB(B0, 0, 0); PG8_LDB(B1, 0, 1); PG8_SCHED; PG8_LDA(At, 0, 0); PG8_STAGE(PG8_SA(1, 1), a1 + hA, voffA);
;             PG8_WAIT_V(8); PG8_WAIT_L(0); PG8_BAR; PG8_MMA(0, 0, At, B0); PG8_MMA(0, 1, At, B1); PG8_BAR; PG8_SCHED;
;             PG8_LDA(At, 0, 1); PG8_STAGE(PG8_SB(0, 0), b2, voffB); PG8_STAGE(PG8_SB(0, 1), b2 + hB, voffB); PG8_STAGE(PG8_SA(0, 0), a2, voffA);
;             PG8_WAIT_V(8); PG8_WAIT_L(0); PG8_BAR; PG8_MMA(1, 0, At, B0); PG8_MMA(1, 1, At, B1); PG8_BAR; PG8_SCHED;
.LBB0_775:
	ds_read_b128 v[128:131], v196
	ds_read_b128 v[132:135], v196 offset:1024
	ds_read_b128 v[136:139], v196 offset:2048
	ds_read_b128 v[140:143], v196 offset:3072
	ds_read_b128 v[144:147], v197
	ds_read_b128 v[148:151], v197 offset:1024
	ds_read_b128 v[152:155], v197 offset:2048
	ds_read_b128 v[156:159], v197 offset:3072
	s_add_u32 s37, s40, 0xfff80080
	s_addc_u32 s38, s41, -1
	s_cmp_eq_u32 s29, 28
	s_cselect_b32 s45, s0, s38
	s_cselect_b32 s44, s1, s37
	s_cselect_b32 s43, s2, s27
	s_cselect_b32 s42, s3, s9
	v_lshl_add_u64 v[216:217], s[40:41], 0, v[168:169]
	s_add_i32 m0, s50, 0xc000
	ds_read_b128 v[176:179], v198
	ds_read_b128 v[180:183], v198 offset:1024
	ds_read_b128 v[184:187], v198 offset:2048
	ds_read_b128 v[188:191], v198 offset:3072
	ds_read_b128 v[200:203], v198 offset:4096
	ds_read_b128 v[204:207], v198 offset:5120
	ds_read_b128 v[208:211], v198 offset:6144
	ds_read_b128 v[212:215], v198 offset:7168
	global_load_lds_dwordx4 v[216:217], off
	v_lshl_add_u64 v[216:217], s[40:41], 0, v[170:171]
	s_add_i32 m0, s50, 0xe000
	s_nop 0
	global_load_lds_dwordx4 v[216:217], off
	s_waitcnt vmcnt(8)
	s_waitcnt lgkmcnt(0)
	s_barrier
	s_setprio 1
	s_waitcnt lgkmcnt(0)
	v_mfma_f32_16x16x32_bf16 v[124:127], v[128:131], v[176:179], v[124:127]
	v_mfma_f32_16x16x32_bf16 v[124:127], v[132:135], v[180:183], v[124:127]
	v_mfma_f32_16x16x32_bf16 v[120:123], v[136:139], v[176:179], v[120:123]
	v_mfma_f32_16x16x32_bf16 v[120:123], v[140:143], v[180:183], v[120:123]
	v_mfma_f32_16x16x32_bf16 v[108:111], v[128:131], v[184:187], v[108:111]
	v_mfma_f32_16x16x32_bf16 v[108:111], v[132:135], v[188:191], v[108:111]
	v_mfma_f32_16x16x32_bf16 v[104:107], v[136:139], v[184:187], v[104:107]
	v_mfma_f32_16x16x32_bf16 v[104:107], v[140:143], v[188:191], v[104:107]
	v_mfma_f32_16x16x32_bf16 v[92:95], v[128:131], v[200:203], v[92:95]
	v_mfma_f32_16x16x32_bf16 v[92:95], v[132:135], v[204:207], v[92:95]
	v_mfma_f32_16x16x32_bf16 v[88:91], v[136:139], v[200:203], v[88:91]
	v_mfma_f32_16x16x32_bf16 v[88:91], v[140:143], v[204:207], v[88:91]
	v_mfma_f32_16x16x32_bf16 v[76:79], v[128:131], v[208:211], v[76:79]
	v_mfma_f32_16x16x32_bf16 v[76:79], v[132:135], v[212:215], v[76:79]
	v_mfma_f32_16x16x32_bf16 v[72:75], v[136:139], v[208:211], v[72:75]
	v_mfma_f32_16x16x32_bf16 v[72:75], v[140:143], v[212:215], v[72:75]
	s_setprio 0
	s_setprio 1
	v_mfma_f32_16x16x32_bf16 v[116:119], v[144:147], v[176:179], v[116:119]
	v_mfma_f32_16x16x32_bf16 v[116:119], v[148:151], v[180:183], v[116:119]
	v_mfma_f32_16x16x32_bf16 v[112:115], v[152:155], v[176:179], v[112:115]
	v_mfma_f32_16x16x32_bf16 v[112:115], v[156:159], v[180:183], v[112:115]
	v_mfma_f32_16x16x32_bf16 v[100:103], v[144:147], v[184:187], v[100:103]
	v_mfma_f32_16x16x32_bf16 v[100:103], v[148:151], v[188:191], v[100:103]
	v_mfma_f32_16x16x32_bf16 v[96:99], v[152:155], v[184:187], v[96:99]
	v_mfma_f32_16x16x32_bf16 v[96:99], v[156:159], v[188:191], v[96:99]
	v_mfma_f32_16x16x32_bf16 v[84:87], v[144:147], v[200:203], v[84:87]
	v_mfma_f32_16x16x32_bf16 v[84:87], v[148:151], v[204:207], v[84:87]
	v_mfma_f32_16x16x32_bf16 v[80:83], v[152:155], v[200:203], v[80:83]
	v_mfma_f32_16x16x32_bf16 v[80:83], v[156:159], v[204:207], v[80:83]
	v_mfma_f32_16x16x32_bf16 v[68:71], v[144:147], v[208:211], v[68:71]
	v_mfma_f32_16x16x32_bf16 v[68:71], v[148:151], v[212:215], v[68:71]
	v_mfma_f32_16x16x32_bf16 v[64:67], v[152:155], v[208:211], v[64:67]
	v_mfma_f32_16x16x32_bf16 v[64:67], v[156:159], v[212:215], v[64:67]
	s_setprio 0
	s_barrier
	s_add_i32 s37, s60, s49
	v_lshl_add_u64 v[216:217], s[42:43], 0, v[162:163]
	s_mov_b32 m0, s37
	ds_read_b128 v[176:179], v198 offset:16384
	ds_read_b128 v[180:183], v198 offset:17408
	ds_read_b128 v[184:187], v198 offset:18432
	ds_read_b128 v[188:191], v198 offset:19456
	ds_read_b128 v[200:203], v198 offset:20480
	ds_read_b128 v[204:207], v198 offset:21504
	ds_read_b128 v[208:211], v198 offset:22528
	ds_read_b128 v[212:215], v198 offset:23552
	global_load_lds_dwordx4 v[216:217], off
	s_add_i32 m0, s37, 0x2000
	s_add_u32 s38, s42, 0x80000
	v_lshl_add_u64 v[218:219], s[42:43], 0, v[166:167]
	s_addc_u32 s39, s43, 0
	s_add_i32 s37, s61, s49
	global_load_lds_dwordx4 v[218:219], off
	v_lshl_add_u64 v[220:221], s[38:39], 0, v[162:163]
	s_mov_b32 m0, s37
	v_lshl_add_u64 v[222:223], s[44:45], 0, v[164:165]
	global_load_lds_dwordx4 v[220:221], off
	v_lshl_add_u64 v[220:221], s[38:39], 0, v[166:167]
	s_add_i32 m0, s37, 0x2000
	s_nop 0
	global_load_lds_dwordx4 v[220:221], off
	v_lshl_add_u64 v[220:221], s[44:45], 0, v[160:161]
	s_mov_b32 m0, s50
	s_nop 0
	global_load_lds_dwordx4 v[220:221], off
	s_mov_b32 m0, s51
	s_nop 0
	global_load_lds_dwordx4 v[222:223], off
	s_waitcnt vmcnt(8)
	s_waitcnt lgkmcnt(0)
	s_barrier
; #define PG8_STAGE(bufoff, gbase, voff) do { _Pragma("unroll") for (int _i = 0; _i < 2; ++_i) \
;         __builtin_amdgcn_global_load_lds((const unsigned*)((const char*)(gbase) + (voff)[_i]), (LAS unsigned*)(lds + (bufoff) + ldsw + _i * 8192), 16, 0, 0); } while (0)
; #define PG8_LDA(dst, b, h) do { _Pragma("unroll") for (int m = 0; m < 4; ++m) _Pragma("unroll") for (int k = 0; k < 2; ++k) dst[m][k] = *(const LAS bf16x8*)(lds + PG8_SA(b, h) + aoff + m * 2048 + k * 1024); } while (0)
; #define PG8_LDB(dst, b, h) do { _Pragma("unroll") for (int n = 0; n < 2; ++n) _Pragma("unroll") for (int k = 0; k < 2; ++k) dst[n][k] = *(const LAS bf16x8*)(lds + PG8_SB(b, h) + boff + n * 2048 + k * 1024); } while (0)
; #define PG8_MMA(ai, bj, At, Bt) do { __builtin_amdgcn_s_setprio(1); _Pragma("unroll") for (int m = 0; m < 4; ++m) _Pragma("unroll") for (int n = 0; n < 2; ++n) _Pragma("unroll") for (int k = 0; k < 2; ++k) \
;         acc[ai][bj][m][n] = __builtin_amdgcn_mfma_f32_16x16x32_bf16(Bt[n][k], At[m][k], acc[ai][bj][m][n], 0, 0, 0); __builtin_amdgcn_s_setprio(0); } while (0)
; #define PG8_WAIT_V(n) asm volatile("s_waitcnt vmcnt(" #n ")" ::: "memory")
; #define PG8_WAIT_L(n) asm volatile("s_waitcnt lgkmcnt(" #n ")" ::: "memory")
; #define PG8_BAR __builtin_amdgcn_s_barrier()
; #define PG8_SCHED __builtin_amdgcn_sched_barrier(0)
; template <class Epi, bool ALIGN_EPI>
; __device__ __forceinline__ void gemm_phase(LAS unsigned char* lds, const Gemm g, const StaticOrder& S, const Epi& E) {
;     ...
;             PG8_WAIT_V(8); PG8_WAIT_L(0); PG8_BAR; PG8_MMA(1, 0, At, B0); PG8_MMA(1, 1, At, B1); PG8_BAR; PG8_SCHED;
;             PG8_LDB(B0, 1, 0); PG8_LDB(B1, 1, 1); PG8_SCHED; PG8_LDA(At, 1, 0); PG8_STAGE(PG8_SA(0, 1), a2 + hA, voffA);
;             PG8_WAIT_V(8); PG8_WAIT_L(0); PG8_BAR; PG8_MMA(0, 0, At, B0); PG8_MMA(0, 1, At, B1); PG8_BAR; PG8_SCHED;
	s_setprio 1
	s_waitcnt lgkmcnt(0)
	v_mfma_f32_16x16x32_bf16 v[60:63], v[128:131], v[176:179], v[60:63]
	v_mfma_f32_16x16x32_bf16 v[60:63], v[132:135], v[180:183], v[60:63]
	v_mfma_f32_16x16x32_bf16 v[56:59], v[136:139], v[176:179], v[56:59]
	v_mfma_f32_16x16x32_bf16 v[56:59], v[140:143], v[180:183], v[56:59]
	v_mfma_f32_16x16x32_bf16 v[44:47], v[128:131], v[184:187], v[44:47]
	v_mfma_f32_16x16x32_bf16 v[44:47], v[132:135], v[188:191], v[44:47]
	v_mfma_f32_16x16x32_bf16 v[40:43], v[136:139], v[184:187], v[40:43]
	v_mfma_f32_16x16x32_bf16 v[40:43], v[140:143], v[188:191], v[40:43]
	v_mfma_f32_16x16x32_bf16 v[28:31], v[128:131], v[200:203], v[28:31]
	v_mfma_f32_16x16x32_bf16 v[28:31], v[132:135], v[204:207], v[28:31]
	v_mfma_f32_16x16x32_bf16 v[24:27], v[136:139], v[200:203], v[24:27]
	v_mfma_f32_16x16x32_bf16 v[24:27], v[140:143], v[204:207], v[24:27]
	v_mfma_f32_16x16x32_bf16 v[16:19], v[128:131], v[208:211], v[16:19]
	v_mfma_f32_16x16x32_bf16 v[16:19], v[132:135], v[212:215], v[16:19]
	v_mfma_f32_16x16x32_bf16 v[8:11], v[136:139], v[208:211], v[8:11]
	v_mfma_f32_16x16x32_bf16 v[8:11], v[140:143], v[212:215], v[8:11]
	s_setprio 0
	s_setprio 1
	v_mfma_f32_16x16x32_bf16 v[52:55], v[144:147], v[176:179], v[52:55]
	v_mfma_f32_16x16x32_bf16 v[52:55], v[148:151], v[180:183], v[52:55]
	v_mfma_f32_16x16x32_bf16 v[48:51], v[152:155], v[176:179], v[48:51]
	v_mfma_f32_16x16x32_bf16 v[48:51], v[156:159], v[180:183], v[48:51]
	v_mfma_f32_16x16x32_bf16 v[36:39], v[144:147], v[184:187], v[36:39]
	v_mfma_f32_16x16x32_bf16 v[36:39], v[148:151], v[188:191], v[36:39]
	v_mfma_f32_16x16x32_bf16 v[32:35], v[152:155], v[184:187], v[32:35]
	v_mfma_f32_16x16x32_bf16 v[32:35], v[156:159], v[188:191], v[32:35]
	v_mfma_f32_16x16x32_bf16 v[20:23], v[144:147], v[200:203], v[20:23]
	v_mfma_f32_16x16x32_bf16 v[20:23], v[148:151], v[204:207], v[20:23]
	v_mfma_f32_16x16x32_bf16 v[12:15], v[152:155], v[200:203], v[12:15]
	v_mfma_f32_16x16x32_bf16 v[12:15], v[156:159], v[204:207], v[12:15]
	v_mfma_f32_16x16x32_bf16 v[4:7], v[144:147], v[208:211], v[4:7]
	v_mfma_f32_16x16x32_bf16 v[4:7], v[148:151], v[212:215], v[4:7]
	v_mfma_f32_16x16x32_bf16 v[0:3], v[152:155], v[208:211], v[0:3]
	v_mfma_f32_16x16x32_bf16 v[0:3], v[156:159], v[212:215], v[0:3]
	s_setprio 0
	s_barrier
	s_add_i32 s37, 0, 0x18000
	s_add_i32 s63, 0, 0x1c000
	v_add_u32_e32 v140, s37, v194
	v_add_u32_e32 v156, s63, v194
	ds_read_b128 v[128:131], v140
	ds_read_b128 v[132:135], v140 offset:1024
	ds_read_b128 v[136:139], v140 offset:2048
	ds_read_b128 v[140:143], v140 offset:3072
	ds_read_b128 v[144:147], v156
	ds_read_b128 v[148:151], v156 offset:1024
	ds_read_b128 v[152:155], v156 offset:2048
	ds_read_b128 v[156:159], v156 offset:3072
	s_add_u32 s38, s44, 0x80000
	s_addc_u32 s39, s45, 0
	s_mov_b32 m0, s52
	v_lshl_add_u64 v[224:225], s[38:39], 0, v[160:161]
	ds_read_b128 v[176:179], v198 offset:32768
	ds_read_b128 v[180:183], v198 offset:33792
	ds_read_b128 v[184:187], v198 offset:34816
	ds_read_b128 v[188:191], v198 offset:35840
	ds_read_b128 v[200:203], v198 offset:36864
	ds_read_b128 v[204:207], v198 offset:37888
	ds_read_b128 v[208:211], v198 offset:38912
	ds_read_b128 v[212:215], v198 offset:39936
	global_load_lds_dwordx4 v[224:225], off
	v_lshl_add_u64 v[224:225], s[38:39], 0, v[164:165]
	s_mov_b32 m0, s53
	s_nop 0
	global_load_lds_dwordx4 v[224:225], off
	s_waitcnt vmcnt(8)
	s_waitcnt lgkmcnt(0)
	s_barrier
	s_setprio 1
	s_waitcnt lgkmcnt(0)
	v_mfma_f32_16x16x32_bf16 v[124:127], v[128:131], v[176:179], v[124:127]
	v_mfma_f32_16x16x32_bf16 v[124:127], v[132:135], v[180:183], v[124:127]
	v_mfma_f32_16x16x32_bf16 v[120:123], v[136:139], v[176:179], v[120:123]
	v_mfma_f32_16x16x32_bf16 v[120:123], v[140:143], v[180:183], v[120:123]
	v_mfma_f32_16x16x32_bf16 v[108:111], v[128:131], v[184:187], v[108:111]
	v_mfma_f32_16x16x32_bf16 v[108:111], v[132:135], v[188:191], v[108:111]
	v_mfma_f32_16x16x32_bf16 v[104:107], v[136:139], v[184:187], v[104:107]
	v_mfma_f32_16x16x32_bf16 v[104:107], v[140:143], v[188:191], v[104:107]
	v_mfma_f32_16x16x32_bf16 v[92:95], v[128:131], v[200:203], v[92:95]
	v_mfma_f32_16x16x32_bf16 v[92:95], v[132:135], v[204:207], v[92:95]
	v_mfma_f32_16x16x32_bf16 v[88:91], v[136:139], v[200:203], v[88:91]
	v_mfma_f32_16x16x32_bf16 v[88:91], v[140:143], v[204:207], v[88:91]
	v_mfma_f32_16x16x32_bf16 v[76:79], v[128:131], v[208:211], v[76:79]
	v_mfma_f32_16x16x32_bf16 v[76:79], v[132:135], v[212:215], v[76:79]
	v_mfma_f32_16x16x32_bf16 v[72:75], v[136:139], v[208:211], v[72:75]
	v_mfma_f32_16x16x32_bf16 v[72:75], v[140:143], v[212:215], v[72:75]
	s_setprio 0
	s_setprio 1
	v_mfma_f32_16x16x32_bf16 v[116:119], v[144:147], v[176:179], v[116:119]
	v_mfma_f32_16x16x32_bf16 v[116:119], v[148:151], v[180:183], v[116:119]
	v_mfma_f32_16x16x32_bf16 v[112:115], v[152:155], v[176:179], v[112:115]
	v_mfma_f32_16x16x32_bf16 v[112:115], v[156:159], v[180:183], v[112:115]
	v_mfma_f32_16x16x32_bf16 v[100:103], v[144:147], v[184:187], v[100:103]
	v_mfma_f32_16x16x32_bf16 v[100:103], v[148:151], v[188:191], v[100:103]
	v_mfma_f32_16x16x32_bf16 v[96:99], v[152:155], v[184:187], v[96:99]
	v_mfma_f32_16x16x32_bf16 v[96:99], v[156:159], v[188:191], v[96:99]
	v_mfma_f32_16x16x32_bf16 v[84:87], v[144:147], v[200:203], v[84:87]
	v_mfma_f32_16x16x32_bf16 v[84:87], v[148:151], v[204:207], v[84:87]
	v_mfma_f32_16x16x32_bf16 v[80:83], v[152:155], v[200:203], v[80:83]
	v_mfma_f32_16x16x32_bf16 v[80:83], v[156:159], v[204:207], v[80:83]
	v_mfma_f32_16x16x32_bf16 v[68:71], v[144:147], v[208:211], v[68:71]
	v_mfma_f32_16x16x32_bf16 v[68:71], v[148:151], v[212:215], v[68:71]
	v_mfma_f32_16x16x32_bf16 v[64:67], v[152:155], v[208:211], v[64:67]
	v_mfma_f32_16x16x32_bf16 v[64:67], v[156:159], v[212:215], v[64:67]
	s_setprio 0
	s_barrier
; #define PG8_STAGE(bufoff, gbase, voff) do { _Pragma("unroll") for (int _i = 0; _i < 2; ++_i) \
;         __builtin_amdgcn_global_load_lds((const unsigned*)((const char*)(gbase) + (voff)[_i]), (LAS unsigned*)(lds + (bufoff) + ldsw + _i * 8192), 16, 0, 0); } while (0)
; #define PG8_LDA(dst, b, h) do { _Pragma("unroll") for (int m = 0; m < 4; ++m) _Pragma("unroll") for (int k = 0; k < 2; ++k) dst[m][k] = *(const LAS bf16x8*)(lds + PG8_SA(b, h) + aoff + m * 2048 + k * 1024); } while (0)
; #define PG8_MMA(ai, bj, At, Bt) do { __builtin_amdgcn_s_setprio(1); _Pragma("unroll") for (int m = 0; m < 4; ++m) _Pragma("unroll") for (int n = 0; n < 2; ++n) _Pragma("unroll") for (int k = 0; k < 2; ++k) \
;         acc[ai][bj][m][n] = __builtin_amdgcn_mfma_f32_16x16x32_bf16(Bt[n][k], At[m][k], acc[ai][bj][m][n], 0, 0, 0); __builtin_amdgcn_s_setprio(0); } while (0)
; #define PG8_WAIT_V(n) asm volatile("s_waitcnt vmcnt(" #n ")" ::: "memory")
; #define PG8_WAIT_L(n) asm volatile("s_waitcnt lgkmcnt(" #n ")" ::: "memory")
; #define PG8_BAR __builtin_amdgcn_s_barrier()
; #define PG8_SCHED __builtin_amdgcn_sched_barrier(0)
; template <class Epi, bool ALIGN_EPI>
; __device__ __forceinline__ void gemm_phase(LAS unsigned char* lds, const Gemm g, const StaticOrder& S, const Epi& E) {
;     ...
;             PG8_WAIT_V(8); PG8_WAIT_L(0); PG8_BAR; PG8_MMA(0, 0, At, B0); PG8_MMA(0, 1, At, B1); PG8_BAR; PG8_SCHED;
;             PG8_LDA(At, 1, 1); PG8_STAGE(PG8_SB(1, 0), b3, voffB); PG8_STAGE(PG8_SB(1, 1), b3 + hB, voffB); PG8_STAGE(PG8_SA(1, 0), a3, voffA);
;             PG8_WAIT_V(8); PG8_WAIT_L(0); PG8_BAR; PG8_MMA(1, 0, At, B0); PG8_MMA(1, 1, At, B1); PG8_BAR; PG8_SCHED;
;         }
;         if constexpr (ALIGN_EPI) { if (wr == 0) PG8_BAR; }
	s_add_i32 s37, s37, s49
	v_lshl_add_u64 v[216:217], v[216:217], 0, s[20:21]
	s_mov_b32 m0, s37
	ds_read_b128 v[176:179], v198 offset:49152
	ds_read_b128 v[180:183], v198 offset:50176
	ds_read_b128 v[184:187], v198 offset:51200
	ds_read_b128 v[188:191], v198 offset:52224
	ds_read_b128 v[200:203], v198 offset:53248
	ds_read_b128 v[204:207], v198 offset:54272
	ds_read_b128 v[208:211], v198 offset:55296
	ds_read_b128 v[212:215], v198 offset:56320
	global_load_lds_dwordx4 v[216:217], off
	s_add_i32 m0, s37, 0x2000
	s_add_u32 s38, s42, 0x80080
	v_lshl_add_u64 v[216:217], v[218:219], 0, s[20:21]
	s_addc_u32 s39, s43, 0
	s_add_i32 s37, s63, s49
	global_load_lds_dwordx4 v[216:217], off
	v_lshl_add_u64 v[216:217], s[38:39], 0, v[162:163]
	s_mov_b32 m0, s37
	s_nop 0
	global_load_lds_dwordx4 v[216:217], off
	v_lshl_add_u64 v[216:217], s[38:39], 0, v[166:167]
	s_add_i32 m0, s37, 0x2000
	s_nop 0
	global_load_lds_dwordx4 v[216:217], off
	v_lshl_add_u64 v[216:217], v[220:221], 0, s[20:21]
	s_mov_b32 m0, s57
	s_nop 0
	global_load_lds_dwordx4 v[216:217], off
	v_lshl_add_u64 v[216:217], v[222:223], 0, s[20:21]
	s_mov_b32 m0, s58
	s_nop 0
	global_load_lds_dwordx4 v[216:217], off
	s_waitcnt vmcnt(8)
	s_waitcnt lgkmcnt(0)
	s_barrier
	s_setprio 1
	s_waitcnt lgkmcnt(0)
	v_mfma_f32_16x16x32_bf16 v[60:63], v[128:131], v[176:179], v[60:63]
	v_mfma_f32_16x16x32_bf16 v[60:63], v[132:135], v[180:183], v[60:63]
	v_mfma_f32_16x16x32_bf16 v[56:59], v[136:139], v[176:179], v[56:59]
	v_mfma_f32_16x16x32_bf16 v[56:59], v[140:143], v[180:183], v[56:59]
	v_mfma_f32_16x16x32_bf16 v[44:47], v[128:131], v[184:187], v[44:47]
	v_mfma_f32_16x16x32_bf16 v[44:47], v[132:135], v[188:191], v[44:47]
	v_mfma_f32_16x16x32_bf16 v[40:43], v[136:139], v[184:187], v[40:43]
	v_mfma_f32_16x16x32_bf16 v[40:43], v[140:143], v[188:191], v[40:43]
	v_mfma_f32_16x16x32_bf16 v[28:31], v[128:131], v[200:203], v[28:31]
	v_mfma_f32_16x16x32_bf16 v[28:31], v[132:135], v[204:207], v[28:31]
	v_mfma_f32_16x16x32_bf16 v[24:27], v[136:139], v[200:203], v[24:27]
	v_mfma_f32_16x16x32_bf16 v[24:27], v[140:143], v[204:207], v[24:27]
	v_mfma_f32_16x16x32_bf16 v[16:19], v[128:131], v[208:211], v[16:19]
	v_mfma_f32_16x16x32_bf16 v[16:19], v[132:135], v[212:215], v[16:19]
	v_mfma_f32_16x16x32_bf16 v[8:11], v[136:139], v[208:211], v[8:11]
	v_mfma_f32_16x16x32_bf16 v[8:11], v[140:143], v[212:215], v[8:11]
	s_setprio 0
	s_setprio 1
	v_mfma_f32_16x16x32_bf16 v[52:55], v[144:147], v[176:179], v[52:55]
	v_mfma_f32_16x16x32_bf16 v[52:55], v[148:151], v[180:183], v[52:55]
	v_mfma_f32_16x16x32_bf16 v[48:51], v[152:155], v[176:179], v[48:51]
	v_mfma_f32_16x16x32_bf16 v[48:51], v[156:159], v[180:183], v[48:51]
	v_mfma_f32_16x16x32_bf16 v[36:39], v[144:147], v[184:187], v[36:39]
	v_mfma_f32_16x16x32_bf16 v[36:39], v[148:151], v[188:191], v[36:39]
	v_mfma_f32_16x16x32_bf16 v[32:35], v[152:155], v[184:187], v[32:35]
	v_mfma_f32_16x16x32_bf16 v[32:35], v[156:159], v[188:191], v[32:35]
	v_mfma_f32_16x16x32_bf16 v[20:23], v[144:147], v[200:203], v[20:23]
	v_mfma_f32_16x16x32_bf16 v[20:23], v[148:151], v[204:207], v[20:23]
	v_mfma_f32_16x16x32_bf16 v[12:15], v[152:155], v[200:203], v[12:15]
	v_mfma_f32_16x16x32_bf16 v[12:15], v[156:159], v[204:207], v[12:15]
	v_mfma_f32_16x16x32_bf16 v[4:7], v[144:147], v[208:211], v[4:7]
	v_mfma_f32_16x16x32_bf16 v[4:7], v[148:151], v[212:215], v[4:7]
	v_mfma_f32_16x16x32_bf16 v[0:3], v[152:155], v[208:211], v[0:3]
	v_mfma_f32_16x16x32_bf16 v[0:3], v[156:159], v[212:215], v[0:3]
	s_setprio 0
	s_barrier
	s_add_i32 s29, s29, 2
	s_add_u32 s40, s40, 0x100
	s_addc_u32 s41, s41, 0
	s_add_u32 s9, s9, 0x100
	s_addc_u32 s27, s27, 0
	s_cmp_gt_u32 s29, 29
	s_cbranch_scc0 .LBB0_775
	s_and_b64 vcc, exec, s[22:23]
	s_cbranch_vccz .LBB0_778
	s_nop 0

; #define PG8_BAR __builtin_amdgcn_s_barrier()
;     __device__ __forceinline__ void post(int ui, const float (&r)[8]) const { const int t = my_tid(); if (t < 384) cbuf[(ui & 1) * 384 + t] = r[0]; }
; template <class Epi, bool ALIGN_EPI>
; __device__ __forceinline__ void gemm_phase(LAS unsigned char* lds, const Gemm g, const StaticOrder& S, const Epi& E) {
;     ...
;         if (!has_next) break;
;         E.post(ui + 1, rsn);
; #pragma unroll
;         for (int a = 0; a < 2; ++a)
; #pragma unroll
;             for (int b = 0; b < 2; ++b)
; #pragma unroll
;                 for (int m = 0; m < 4; ++m)
; #pragma unroll
;                     for (int n = 0; n < 2; ++n) acc[a][b][m][n] = (f32x4){0.f, 0.f, 0.f, 0.f};
;         cur = nxt; cA = nA; cB = nB; ++ui;
; #pragma unroll
;         for (int i_ = 0; i_ < 8; ++i_) rsv[i_] = rsn[i_];
;         if constexpr (ALIGN_EPI) { if (wr == 1) PG8_BAR; }
;     __device__ __forceinline__ void operator()(const f32x4 (&acc)[2][2][4][2], const Unit& u, int wr, int wc, int fr, int fq, int, const float (&)[8]) const {
;     ...
;         if (ss) {
; #pragma unroll
;             for (int ai = 0; ai < 2; ++ai)
; #pragma unroll
;                 for (int m = 0; m < 4; ++m) { float pp = part[ai][m]; pp += __shfl_xor(pp, 16); pp += __shfl_xor(pp, 32); if (fq == 0) unsafeAtomicAdd(ss + row0 + ai * HALF + m * 16, pp); } }
;     }
.LBB0_838:
	s_or_b64 exec, exec, s[8:9]
	s_andn2_b64 vcc, exec, s[6:7]
	s_mov_b64 s[6:7], -1
	s_cbranch_vccnz .LBB0_767
	s_andn2_b64 vcc, exec, s[14:15]
	s_cbranch_vccnz .LBB0_766
	s_nop 0
	s_branch .LBB0_766

; #define PG8_STAGE(bufoff, gbase, voff) do { _Pragma("unroll") for (int _i = 0; _i < 2; ++_i) \
;         __builtin_amdgcn_global_load_lds((const unsigned*)((const char*)(gbase) + (voff)[_i]), (LAS unsigned*)(lds + (bufoff) + ldsw + _i * 8192), 16, 0, 0); } while (0)
; #define PG8_LDA(dst, b, h) do { _Pragma("unroll") for (int m = 0; m < 4; ++m) _Pragma("unroll") for (int k = 0; k < 2; ++k) dst[m][k] = *(const LAS bf16x8*)(lds + PG8_SA(b, h) + aoff + m * 2048 + k * 1024); } while (0)
; #define PG8_LDB(dst, b, h) do { _Pragma("unroll") for (int n = 0; n < 2; ++n) _Pragma("unroll") for (int k = 0; k < 2; ++k) dst[n][k] = *(const LAS bf16x8*)(lds + PG8_SB(b, h) + boff + n * 2048 + k * 1024); } while (0)
; #define PG8_MMA(ai, bj, At, Bt) do { __builtin_amdgcn_s_setprio(1); _Pragma("unroll") for (int m = 0; m < 4; ++m) _Pragma("unroll") for (int n = 0; n < 2; ++n) _Pragma("unroll") for (int k = 0; k < 2; ++k) \
;         acc[ai][bj][m][n] = __builtin_amdgcn_mfma_f32_16x16x32_bf16(Bt[n][k], At[m][k], acc[ai][bj][m][n], 0, 0, 0); __builtin_amdgcn_s_setprio(0); } while (0)
; #define PG8_WAIT_V(n) asm volatile("s_waitcnt vmcnt(" #n ")" ::: "memory")
; #define PG8_WAIT_L(n) asm volatile("s_waitcnt lgkmcnt(" #n ")" ::: "memory")
; #define PG8_BAR __builtin_amdgcn_s_barrier()
; #define PG8_SCHED __builtin_amdgcn_sched_barrier(0)
; template <class Epi, bool ALIGN_EPI>
; __device__ __forceinline__ void gemm_phase(LAS unsigned char* lds, const Gemm g, const StaticOrder& S, const Epi& E) {
;     ...
;             const char* a1 = cA + (size_t)(t + 1) * kstep;
;             const char* a2 = last ? nA : cA + (size_t)(t + 2) * kstep; const char* b2 = last ? nB : cB + (size_t)(t + 2) * kstep;
;             const char* a3 = a2 + kstep; const char* b3 = b2 + kstep;
;             PG8_LDB(B0, 0, 0); PG8_LDB(B1, 0, 1); PG8_SCHED; PG8_LDA(At, 0, 0); PG8_STAGE(PG8_SA(1, 1), a1 + hA, voffA);
;             PG8_WAIT_V(8); PG8_WAIT_L(0); PG8_BAR; PG8_MMA(0, 0, At, B0); PG8_MMA(0, 1, At, B1); PG8_BAR; PG8_SCHED;
;             PG8_LDA(At, 0, 1); PG8_STAGE(PG8_SB(0, 0), b2, voffB); PG8_STAGE(PG8_SB(0, 1), b2 + hB, voffB); PG8_STAGE(PG8_SA(0, 0), a2, voffA);
;             PG8_WAIT_V(8); PG8_WAIT_L(0); PG8_BAR; PG8_MMA(1, 0, At, B0); PG8_MMA(1, 1, At, B1); PG8_BAR; PG8_SCHED;
.LBB0_926:
	ds_read_b128 v[168:171], v153
	ds_read_b128 v[172:175], v153 offset:1024
	ds_read_b128 v[176:179], v153 offset:2048
	ds_read_b128 v[180:183], v153 offset:3072
	ds_read_b128 v[184:187], v155
	ds_read_b128 v[188:191], v155 offset:1024
	ds_read_b128 v[194:197], v155 offset:2048
	ds_read_b128 v[198:201], v155 offset:3072
	s_add_u32 s8, s6, 0xfff80080
	s_addc_u32 s9, s7, -1
	s_cmp_eq_u32 s71, 28
	s_cselect_b32 s55, s47, s9
	s_cselect_b32 s54, s67, s8
	s_cselect_b32 s9, s45, s70
	s_cselect_b32 s8, s68, s69
	v_lshl_add_u64 v[234:235], s[6:7], 0, v[136:137]
	s_add_i32 m0, s39, 0xc000
	ds_read_b128 v[202:205], v156
	ds_read_b128 v[206:209], v156 offset:1024
	ds_read_b128 v[210:213], v156 offset:2048
	ds_read_b128 v[214:217], v156 offset:3072
	ds_read_b128 v[218:221], v156 offset:4096
	ds_read_b128 v[222:225], v156 offset:5120
	ds_read_b128 v[226:229], v156 offset:6144
	ds_read_b128 v[230:233], v156 offset:7168
	global_load_lds_dwordx4 v[234:235], off
	v_lshl_add_u64 v[234:235], s[6:7], 0, v[138:139]
	s_add_i32 m0, s39, 0xe000
	s_nop 0
	global_load_lds_dwordx4 v[234:235], off
	s_waitcnt vmcnt(8)
	s_waitcnt lgkmcnt(0)
	s_barrier
	s_setprio 1
	s_waitcnt lgkmcnt(0)
	v_mfma_f32_16x16x32_bf16 v[124:127], v[168:171], v[202:205], v[124:127]
	v_mfma_f32_16x16x32_bf16 v[124:127], v[172:175], v[206:209], v[124:127]
	v_mfma_f32_16x16x32_bf16 v[120:123], v[176:179], v[202:205], v[120:123]
	v_mfma_f32_16x16x32_bf16 v[120:123], v[180:183], v[206:209], v[120:123]
	v_mfma_f32_16x16x32_bf16 v[108:111], v[168:171], v[210:213], v[108:111]
	v_mfma_f32_16x16x32_bf16 v[108:111], v[172:175], v[214:217], v[108:111]
	v_mfma_f32_16x16x32_bf16 v[104:107], v[176:179], v[210:213], v[104:107]
	v_mfma_f32_16x16x32_bf16 v[104:107], v[180:183], v[214:217], v[104:107]
	v_mfma_f32_16x16x32_bf16 v[92:95], v[168:171], v[218:221], v[92:95]
	v_mfma_f32_16x16x32_bf16 v[92:95], v[172:175], v[222:225], v[92:95]
	v_mfma_f32_16x16x32_bf16 v[88:91], v[176:179], v[218:221], v[88:91]
	v_mfma_f32_16x16x32_bf16 v[88:91], v[180:183], v[222:225], v[88:91]
	v_mfma_f32_16x16x32_bf16 v[76:79], v[168:171], v[226:229], v[76:79]
	v_mfma_f32_16x16x32_bf16 v[76:79], v[172:175], v[230:233], v[76:79]
	v_mfma_f32_16x16x32_bf16 v[72:75], v[176:179], v[226:229], v[72:75]
	v_mfma_f32_16x16x32_bf16 v[72:75], v[180:183], v[230:233], v[72:75]
	s_setprio 0
	s_setprio 1
	v_mfma_f32_16x16x32_bf16 v[116:119], v[184:187], v[202:205], v[116:119]
	v_mfma_f32_16x16x32_bf16 v[116:119], v[188:191], v[206:209], v[116:119]
	v_mfma_f32_16x16x32_bf16 v[112:115], v[194:197], v[202:205], v[112:115]
	v_mfma_f32_16x16x32_bf16 v[112:115], v[198:201], v[206:209], v[112:115]
	v_mfma_f32_16x16x32_bf16 v[100:103], v[184:187], v[210:213], v[100:103]
	v_mfma_f32_16x16x32_bf16 v[100:103], v[188:191], v[214:217], v[100:103]
	v_mfma_f32_16x16x32_bf16 v[96:99], v[194:197], v[210:213], v[96:99]
	v_mfma_f32_16x16x32_bf16 v[96:99], v[198:201], v[214:217], v[96:99]
	v_mfma_f32_16x16x32_bf16 v[84:87], v[184:187], v[218:221], v[84:87]
	v_mfma_f32_16x16x32_bf16 v[84:87], v[188:191], v[222:225], v[84:87]
	v_mfma_f32_16x16x32_bf16 v[80:83], v[194:197], v[218:221], v[80:83]
	v_mfma_f32_16x16x32_bf16 v[80:83], v[198:201], v[222:225], v[80:83]
	v_mfma_f32_16x16x32_bf16 v[68:71], v[184:187], v[226:229], v[68:71]
	v_mfma_f32_16x16x32_bf16 v[68:71], v[188:191], v[230:233], v[68:71]
	v_mfma_f32_16x16x32_bf16 v[64:67], v[194:197], v[226:229], v[64:67]
	v_mfma_f32_16x16x32_bf16 v[64:67], v[198:201], v[230:233], v[64:67]
	s_setprio 0
	s_barrier
	s_add_i32 s72, s63, s33
	v_lshl_add_u64 v[234:235], s[8:9], 0, v[132:133]
	s_mov_b32 m0, s72
	ds_read_b128 v[202:205], v156 offset:16384
	ds_read_b128 v[206:209], v156 offset:17408
	ds_read_b128 v[210:213], v156 offset:18432
	ds_read_b128 v[214:217], v156 offset:19456
	ds_read_b128 v[218:221], v156 offset:20480
	ds_read_b128 v[222:225], v156 offset:21504
	ds_read_b128 v[226:229], v156 offset:22528
	ds_read_b128 v[230:233], v156 offset:23552
	global_load_lds_dwordx4 v[234:235], off
	s_add_i32 m0, s72, 0x2000
	s_add_u32 s72, s8, 0x80000
	v_lshl_add_u64 v[236:237], s[8:9], 0, v[128:129]
	s_addc_u32 s73, s9, 0
	s_add_i32 s74, s64, s33
	global_load_lds_dwordx4 v[236:237], off
	v_lshl_add_u64 v[238:239], s[72:73], 0, v[132:133]
	s_mov_b32 m0, s74
	v_lshl_add_u64 v[240:241], s[54:55], 0, v[130:131]
	global_load_lds_dwordx4 v[238:239], off
	v_lshl_add_u64 v[238:239], s[72:73], 0, v[128:129]
	s_add_i32 m0, s74, 0x2000
	s_nop 0
	global_load_lds_dwordx4 v[238:239], off
	v_lshl_add_u64 v[238:239], s[54:55], 0, v[134:135]
	s_mov_b32 m0, s39
	s_nop 0
	global_load_lds_dwordx4 v[238:239], off
	s_mov_b32 m0, s53
	s_nop 0
	global_load_lds_dwordx4 v[240:241], off
	s_waitcnt vmcnt(8)
	s_waitcnt lgkmcnt(0)
	s_barrier
; #define PG8_STAGE(bufoff, gbase, voff) do { _Pragma("unroll") for (int _i = 0; _i < 2; ++_i) \
;         __builtin_amdgcn_global_load_lds((const unsigned*)((const char*)(gbase) + (voff)[_i]), (LAS unsigned*)(lds + (bufoff) + ldsw + _i * 8192), 16, 0, 0); } while (0)
; #define PG8_LDA(dst, b, h) do { _Pragma("unroll") for (int m = 0; m < 4; ++m) _Pragma("unroll") for (int k = 0; k < 2; ++k) dst[m][k] = *(const LAS bf16x8*)(lds + PG8_SA(b, h) + aoff + m * 2048 + k * 1024); } while (0)
; #define PG8_LDB(dst, b, h) do { _Pragma("unroll") for (int n = 0; n < 2; ++n) _Pragma("unroll") for (int k = 0; k < 2; ++k) dst[n][k] = *(const LAS bf16x8*)(lds + PG8_SB(b, h) + boff + n * 2048 + k * 1024); } while (0)
; #define PG8_MMA(ai, bj, At, Bt) do { __builtin_amdgcn_s_setprio(1); _Pragma("unroll") for (int m = 0; m < 4; ++m) _Pragma("unroll") for (int n = 0; n < 2; ++n) _Pragma("unroll") for (int k = 0; k < 2; ++k) \
;         acc[ai][bj][m][n] = __builtin_amdgcn_mfma_f32_16x16x32_bf16(Bt[n][k], At[m][k], acc[ai][bj][m][n], 0, 0, 0); __builtin_amdgcn_s_setprio(0); } while (0)
; #define PG8_WAIT_V(n) asm volatile("s_waitcnt vmcnt(" #n ")" ::: "memory")
; #define PG8_WAIT_L(n) asm volatile("s_waitcnt lgkmcnt(" #n ")" ::: "memory")
; #define PG8_BAR __builtin_amdgcn_s_barrier()
; #define PG8_SCHED __builtin_amdgcn_sched_barrier(0)
; template <class Epi, bool ALIGN_EPI>
; __device__ __forceinline__ void gemm_phase(LAS unsigned char* lds, const Gemm g, const StaticOrder& S, const Epi& E) {
;     ...
;             PG8_WAIT_V(8); PG8_WAIT_L(0); PG8_BAR; PG8_MMA(1, 0, At, B0); PG8_MMA(1, 1, At, B1); PG8_BAR; PG8_SCHED;
;             PG8_LDB(B0, 1, 0); PG8_LDB(B1, 1, 1); PG8_SCHED; PG8_LDA(At, 1, 0); PG8_STAGE(PG8_SA(0, 1), a2 + hA, voffA);
;             PG8_WAIT_V(8); PG8_WAIT_L(0); PG8_BAR; PG8_MMA(0, 0, At, B0); PG8_MMA(0, 1, At, B1); PG8_BAR; PG8_SCHED;
	s_setprio 1
	s_waitcnt lgkmcnt(0)
	v_mfma_f32_16x16x32_bf16 v[60:63], v[168:171], v[202:205], v[60:63]
	v_mfma_f32_16x16x32_bf16 v[60:63], v[172:175], v[206:209], v[60:63]
	v_mfma_f32_16x16x32_bf16 v[56:59], v[176:179], v[202:205], v[56:59]
	v_mfma_f32_16x16x32_bf16 v[56:59], v[180:183], v[206:209], v[56:59]
	v_mfma_f32_16x16x32_bf16 v[44:47], v[168:171], v[210:213], v[44:47]
	v_mfma_f32_16x16x32_bf16 v[44:47], v[172:175], v[214:217], v[44:47]
	v_mfma_f32_16x16x32_bf16 v[40:43], v[176:179], v[210:213], v[40:43]
	v_mfma_f32_16x16x32_bf16 v[40:43], v[180:183], v[214:217], v[40:43]
	v_mfma_f32_16x16x32_bf16 v[28:31], v[168:171], v[218:221], v[28:31]
	v_mfma_f32_16x16x32_bf16 v[28:31], v[172:175], v[222:225], v[28:31]
	v_mfma_f32_16x16x32_bf16 v[24:27], v[176:179], v[218:221], v[24:27]
	v_mfma_f32_16x16x32_bf16 v[24:27], v[180:183], v[222:225], v[24:27]
	v_mfma_f32_16x16x32_bf16 v[12:15], v[168:171], v[226:229], v[12:15]
	v_mfma_f32_16x16x32_bf16 v[12:15], v[172:175], v[230:233], v[12:15]
	v_mfma_f32_16x16x32_bf16 v[8:11], v[176:179], v[226:229], v[8:11]
	v_mfma_f32_16x16x32_bf16 v[8:11], v[180:183], v[230:233], v[8:11]
	s_setprio 0
	s_setprio 1
	v_mfma_f32_16x16x32_bf16 v[52:55], v[184:187], v[202:205], v[52:55]
	v_mfma_f32_16x16x32_bf16 v[52:55], v[188:191], v[206:209], v[52:55]
	v_mfma_f32_16x16x32_bf16 v[48:51], v[194:197], v[202:205], v[48:51]
	v_mfma_f32_16x16x32_bf16 v[48:51], v[198:201], v[206:209], v[48:51]
	v_mfma_f32_16x16x32_bf16 v[36:39], v[184:187], v[210:213], v[36:39]
	v_mfma_f32_16x16x32_bf16 v[36:39], v[188:191], v[214:217], v[36:39]
	v_mfma_f32_16x16x32_bf16 v[32:35], v[194:197], v[210:213], v[32:35]
	v_mfma_f32_16x16x32_bf16 v[32:35], v[198:201], v[214:217], v[32:35]
	v_mfma_f32_16x16x32_bf16 v[20:23], v[184:187], v[218:221], v[20:23]
	v_mfma_f32_16x16x32_bf16 v[20:23], v[188:191], v[222:225], v[20:23]
	v_mfma_f32_16x16x32_bf16 v[16:19], v[194:197], v[218:221], v[16:19]
	v_mfma_f32_16x16x32_bf16 v[16:19], v[198:201], v[222:225], v[16:19]
	v_mfma_f32_16x16x32_bf16 v[4:7], v[184:187], v[226:229], v[4:7]
	v_mfma_f32_16x16x32_bf16 v[4:7], v[188:191], v[230:233], v[4:7]
	v_mfma_f32_16x16x32_bf16 v[0:3], v[194:197], v[226:229], v[0:3]
	v_mfma_f32_16x16x32_bf16 v[0:3], v[198:201], v[230:233], v[0:3]
	s_setprio 0
	s_barrier
	s_add_i32 s72, 0, 0x18000
	v_add_u32_e32 v167, s72, v149
	s_add_i32 s73, 0, 0x1c000
	ds_read_b128 v[168:171], v167
	ds_read_b128 v[172:175], v167 offset:1024
	ds_read_b128 v[176:179], v167 offset:2048
	ds_read_b128 v[180:183], v167 offset:3072
	v_add_u32_e32 v167, s73, v149
	ds_read_b128 v[184:187], v167
	ds_read_b128 v[188:191], v167 offset:1024
	ds_read_b128 v[194:197], v167 offset:2048
	ds_read_b128 v[198:201], v167 offset:3072
	s_add_u32 s54, s54, 0x80000
	s_addc_u32 s55, s55, 0
	s_mov_b32 m0, s56
	v_lshl_add_u64 v[242:243], s[54:55], 0, v[134:135]
	ds_read_b128 v[202:205], v156 offset:32768
	ds_read_b128 v[206:209], v156 offset:33792
	ds_read_b128 v[210:213], v156 offset:34816
	ds_read_b128 v[214:217], v156 offset:35840
	ds_read_b128 v[218:221], v156 offset:36864
	ds_read_b128 v[222:225], v156 offset:37888
	ds_read_b128 v[226:229], v156 offset:38912
	ds_read_b128 v[230:233], v156 offset:39936
	global_load_lds_dwordx4 v[242:243], off
	v_lshl_add_u64 v[242:243], s[54:55], 0, v[130:131]
	s_mov_b32 m0, s57
	s_nop 0
	global_load_lds_dwordx4 v[242:243], off
	s_waitcnt vmcnt(8)
	s_waitcnt lgkmcnt(0)
	s_barrier
	s_setprio 1
	s_waitcnt lgkmcnt(0)
	v_mfma_f32_16x16x32_bf16 v[124:127], v[168:171], v[202:205], v[124:127]
	v_mfma_f32_16x16x32_bf16 v[124:127], v[172:175], v[206:209], v[124:127]
	v_mfma_f32_16x16x32_bf16 v[120:123], v[176:179], v[202:205], v[120:123]
	v_mfma_f32_16x16x32_bf16 v[120:123], v[180:183], v[206:209], v[120:123]
	v_mfma_f32_16x16x32_bf16 v[108:111], v[168:171], v[210:213], v[108:111]
	v_mfma_f32_16x16x32_bf16 v[108:111], v[172:175], v[214:217], v[108:111]
	v_mfma_f32_16x16x32_bf16 v[104:107], v[176:179], v[210:213], v[104:107]
	v_mfma_f32_16x16x32_bf16 v[104:107], v[180:183], v[214:217], v[104:107]
	v_mfma_f32_16x16x32_bf16 v[92:95], v[168:171], v[218:221], v[92:95]
	v_mfma_f32_16x16x32_bf16 v[92:95], v[172:175], v[222:225], v[92:95]
	v_mfma_f32_16x16x32_bf16 v[88:91], v[176:179], v[218:221], v[88:91]
	v_mfma_f32_16x16x32_bf16 v[88:91], v[180:183], v[222:225], v[88:91]
	v_mfma_f32_16x16x32_bf16 v[76:79], v[168:171], v[226:229], v[76:79]
	v_mfma_f32_16x16x32_bf16 v[76:79], v[172:175], v[230:233], v[76:79]
	v_mfma_f32_16x16x32_bf16 v[72:75], v[176:179], v[226:229], v[72:75]
	v_mfma_f32_16x16x32_bf16 v[72:75], v[180:183], v[230:233], v[72:75]
	s_setprio 0
	s_setprio 1
	v_mfma_f32_16x16x32_bf16 v[116:119], v[184:187], v[202:205], v[116:119]
	v_mfma_f32_16x16x32_bf16 v[116:119], v[188:191], v[206:209], v[116:119]
	v_mfma_f32_16x16x32_bf16 v[112:115], v[194:197], v[202:205], v[112:115]
	v_mfma_f32_16x16x32_bf16 v[112:115], v[198:201], v[206:209], v[112:115]
	v_mfma_f32_16x16x32_bf16 v[100:103], v[184:187], v[210:213], v[100:103]
	v_mfma_f32_16x16x32_bf16 v[100:103], v[188:191], v[214:217], v[100:103]
	v_mfma_f32_16x16x32_bf16 v[96:99], v[194:197], v[210:213], v[96:99]
	v_mfma_f32_16x16x32_bf16 v[96:99], v[198:201], v[214:217], v[96:99]
	v_mfma_f32_16x16x32_bf16 v[84:87], v[184:187], v[218:221], v[84:87]
	v_mfma_f32_16x16x32_bf16 v[84:87], v[188:191], v[222:225], v[84:87]
	v_mfma_f32_16x16x32_bf16 v[80:83], v[194:197], v[218:221], v[80:83]
	v_mfma_f32_16x16x32_bf16 v[80:83], v[198:201], v[222:225], v[80:83]
	v_mfma_f32_16x16x32_bf16 v[68:71], v[184:187], v[226:229], v[68:71]
	v_mfma_f32_16x16x32_bf16 v[68:71], v[188:191], v[230:233], v[68:71]
	v_mfma_f32_16x16x32_bf16 v[64:67], v[194:197], v[226:229], v[64:67]
	v_mfma_f32_16x16x32_bf16 v[64:67], v[198:201], v[230:233], v[64:67]
	s_setprio 0
	s_barrier
; #define PG8_STAGE(bufoff, gbase, voff) do { _Pragma("unroll") for (int _i = 0; _i < 2; ++_i) \
;         __builtin_amdgcn_global_load_lds((const unsigned*)((const char*)(gbase) + (voff)[_i]), (LAS unsigned*)(lds + (bufoff) + ldsw + _i * 8192), 16, 0, 0); } while (0)
; #define PG8_LDA(dst, b, h) do { _Pragma("unroll") for (int m = 0; m < 4; ++m) _Pragma("unroll") for (int k = 0; k < 2; ++k) dst[m][k] = *(const LAS bf16x8*)(lds + PG8_SA(b, h) + aoff + m * 2048 + k * 1024); } while (0)
; #define PG8_MMA(ai, bj, At, Bt) do { __builtin_amdgcn_s_setprio(1); _Pragma("unroll") for (int m = 0; m < 4; ++m) _Pragma("unroll") for (int n = 0; n < 2; ++n) _Pragma("unroll") for (int k = 0; k < 2; ++k) \
;         acc[ai][bj][m][n] = __builtin_amdgcn_mfma_f32_16x16x32_bf16(Bt[n][k], At[m][k], acc[ai][bj][m][n], 0, 0, 0); __builtin_amdgcn_s_setprio(0); } while (0)
; #define PG8_WAIT_V(n) asm volatile("s_waitcnt vmcnt(" #n ")" ::: "memory")
; #define PG8_WAIT_L(n) asm volatile("s_waitcnt lgkmcnt(" #n ")" ::: "memory")
; #define PG8_BAR __builtin_amdgcn_s_barrier()
; #define PG8_SCHED __builtin_amdgcn_sched_barrier(0)
; template <class Epi, bool ALIGN_EPI>
; __device__ __forceinline__ void gemm_phase(LAS unsigned char* lds, const Gemm g, const StaticOrder& S, const Epi& E) {
;     ...
;             PG8_WAIT_V(8); PG8_WAIT_L(0); PG8_BAR; PG8_MMA(0, 0, At, B0); PG8_MMA(0, 1, At, B1); PG8_BAR; PG8_SCHED;
;             PG8_LDA(At, 1, 1); PG8_STAGE(PG8_SB(1, 0), b3, voffB); PG8_STAGE(PG8_SB(1, 1), b3 + hB, voffB); PG8_STAGE(PG8_SA(1, 0), a3, voffA);
;             PG8_WAIT_V(8); PG8_WAIT_L(0); PG8_BAR; PG8_MMA(1, 0, At, B0); PG8_MMA(1, 1, At, B1); PG8_BAR; PG8_SCHED;
;         }
;         if constexpr (ALIGN_EPI) { if (wr == 0) PG8_BAR; }
	s_add_i32 s54, s72, s33
	v_lshl_add_u64 v[234:235], v[234:235], 0, s[18:19]
	s_mov_b32 m0, s54
	ds_read_b128 v[202:205], v156 offset:49152
	ds_read_b128 v[206:209], v156 offset:50176
	ds_read_b128 v[210:213], v156 offset:51200
	ds_read_b128 v[214:217], v156 offset:52224
	ds_read_b128 v[218:221], v156 offset:53248
	ds_read_b128 v[222:225], v156 offset:54272
	ds_read_b128 v[226:229], v156 offset:55296
	ds_read_b128 v[230:233], v156 offset:56320
	global_load_lds_dwordx4 v[234:235], off
	s_add_i32 m0, s54, 0x2000
	s_add_u32 s8, s8, 0x80080
	v_lshl_add_u64 v[234:235], v[236:237], 0, s[18:19]
	s_addc_u32 s9, s9, 0
	s_add_i32 s54, s73, s33
	global_load_lds_dwordx4 v[234:235], off
	v_lshl_add_u64 v[234:235], s[8:9], 0, v[132:133]
	s_mov_b32 m0, s54
	s_nop 0
	global_load_lds_dwordx4 v[234:235], off
	v_lshl_add_u64 v[234:235], s[8:9], 0, v[128:129]
	s_add_i32 m0, s54, 0x2000
	s_nop 0
	global_load_lds_dwordx4 v[234:235], off
	v_lshl_add_u64 v[234:235], v[238:239], 0, s[18:19]
	s_mov_b32 m0, s60
	s_nop 0
	global_load_lds_dwordx4 v[234:235], off
	v_lshl_add_u64 v[234:235], v[240:241], 0, s[18:19]
	s_mov_b32 m0, s61
	s_nop 0
	global_load_lds_dwordx4 v[234:235], off
	s_waitcnt vmcnt(8)
	s_waitcnt lgkmcnt(0)
	s_barrier
	s_setprio 1
	s_waitcnt lgkmcnt(0)
	v_mfma_f32_16x16x32_bf16 v[60:63], v[168:171], v[202:205], v[60:63]
	v_mfma_f32_16x16x32_bf16 v[60:63], v[172:175], v[206:209], v[60:63]
	v_mfma_f32_16x16x32_bf16 v[56:59], v[176:179], v[202:205], v[56:59]
	v_mfma_f32_16x16x32_bf16 v[56:59], v[180:183], v[206:209], v[56:59]
	v_mfma_f32_16x16x32_bf16 v[44:47], v[168:171], v[210:213], v[44:47]
	v_mfma_f32_16x16x32_bf16 v[44:47], v[172:175], v[214:217], v[44:47]
	v_mfma_f32_16x16x32_bf16 v[40:43], v[176:179], v[210:213], v[40:43]
	v_mfma_f32_16x16x32_bf16 v[40:43], v[180:183], v[214:217], v[40:43]
	v_mfma_f32_16x16x32_bf16 v[28:31], v[168:171], v[218:221], v[28:31]
	v_mfma_f32_16x16x32_bf16 v[28:31], v[172:175], v[222:225], v[28:31]
	v_mfma_f32_16x16x32_bf16 v[24:27], v[176:179], v[218:221], v[24:27]
	v_mfma_f32_16x16x32_bf16 v[24:27], v[180:183], v[222:225], v[24:27]
	v_mfma_f32_16x16x32_bf16 v[12:15], v[168:171], v[226:229], v[12:15]
	v_mfma_f32_16x16x32_bf16 v[12:15], v[172:175], v[230:233], v[12:15]
	v_mfma_f32_16x16x32_bf16 v[8:11], v[176:179], v[226:229], v[8:11]
	v_mfma_f32_16x16x32_bf16 v[8:11], v[180:183], v[230:233], v[8:11]
	s_setprio 0
	s_setprio 1
	v_mfma_f32_16x16x32_bf16 v[52:55], v[184:187], v[202:205], v[52:55]
	v_mfma_f32_16x16x32_bf16 v[52:55], v[188:191], v[206:209], v[52:55]
	v_mfma_f32_16x16x32_bf16 v[48:51], v[194:197], v[202:205], v[48:51]
	v_mfma_f32_16x16x32_bf16 v[48:51], v[198:201], v[206:209], v[48:51]
	v_mfma_f32_16x16x32_bf16 v[36:39], v[184:187], v[210:213], v[36:39]
	v_mfma_f32_16x16x32_bf16 v[36:39], v[188:191], v[214:217], v[36:39]
	v_mfma_f32_16x16x32_bf16 v[32:35], v[194:197], v[210:213], v[32:35]
	v_mfma_f32_16x16x32_bf16 v[32:35], v[198:201], v[214:217], v[32:35]
	v_mfma_f32_16x16x32_bf16 v[20:23], v[184:187], v[218:221], v[20:23]
	v_mfma_f32_16x16x32_bf16 v[20:23], v[188:191], v[222:225], v[20:23]
	v_mfma_f32_16x16x32_bf16 v[16:19], v[194:197], v[218:221], v[16:19]
	v_mfma_f32_16x16x32_bf16 v[16:19], v[198:201], v[222:225], v[16:19]
	v_mfma_f32_16x16x32_bf16 v[4:7], v[184:187], v[226:229], v[4:7]
	v_mfma_f32_16x16x32_bf16 v[4:7], v[188:191], v[230:233], v[4:7]
	v_mfma_f32_16x16x32_bf16 v[0:3], v[194:197], v[226:229], v[0:3]
	v_mfma_f32_16x16x32_bf16 v[0:3], v[198:201], v[230:233], v[0:3]
	s_setprio 0
	s_barrier
	s_add_i32 s71, s71, 2
	s_add_u32 s6, s6, 0x100
	s_addc_u32 s7, s7, 0
	s_add_u32 s69, s69, 0x100
	s_addc_u32 s70, s70, 0
	s_cmp_gt_u32 s71, 29
	s_cbranch_scc0 .LBB0_926
	s_and_b64 vcc, exec, s[20:21]
	s_cbranch_vccz .LBB0_929
	s_nop 0

;     __device__ __forceinline__ void operator()(const f32x4 (&acc)[2][2][4][2], const Unit& u, int wr, int wc, int fr, int fq, int, const float (&rsv_)[8]) const {
;     ...
;             for (int m = 0; m < 4; ++m) rsv[ai][m] = ss ? rsqrtf(rsv_[ai * 4 + m] * (1.f / 2048.f) + EPS) : 1.f;
; #pragma unroll
;         for (int ai = 0; ai < 2; ++ai)
; #pragma unroll
;             for (int m = 0; m < 4; ++m) { bf16_t* rowp = base + (size_t)(row0 + ai * HALF + m * 16) * ldc + col0;
;                 const float rs = rsv[ai][m];
; #pragma unroll
;                 for (int bj = 0; bj < 2; ++bj) { f32x4 v0 = acc[ai][bj][m][0] * rs, v1 = acc[ai][bj][m][1] * rs;
;                     if (ACT == 1) {
; #pragma unroll
;                         for (int j = 0; j < 4; ++j) { const float a = fmaxf(v0[j], 0.f), b = fmaxf(v1[j], 0.f); v0[j] = a * a; v1[j] = b * b; } }
.LBB0_931:
	s_waitcnt vmcnt(0)
	v_fmamk_f32 v166, v166, 0x3a000000, v157
	v_mul_f32_e32 v167, 0x4b800000, v166
	v_cmp_gt_f32_e32 vcc, s65, v166
	v_fmamk_f32 v154, v154, 0x3a000000, v157
	v_cmp_gt_f32_e64 s[4:5], s65, v154
	v_cndmask_b32_e32 v166, v166, v167, vcc
	v_rsq_f32_e32 v166, v166
	v_mul_f32_e32 v167, 0x4b800000, v154
	v_cndmask_b32_e64 v154, v154, v167, s[4:5]
	v_fmamk_f32 v152, v152, 0x3a000000, v157
	v_mul_f32_e32 v167, 0x45800000, v166
	v_cndmask_b32_e32 v166, v166, v167, vcc
	v_mul_f32_e32 v168, 0x4b800000, v152
	v_cmp_gt_f32_e32 vcc, s65, v152
	v_rsq_f32_e32 v154, v154
	v_fmamk_f32 v150, v150, 0x3a000000, v157
	v_cndmask_b32_e32 v152, v152, v168, vcc
	v_rsq_f32_e32 v152, v152
	v_mul_f32_e32 v167, 0x45800000, v154
	v_mul_f32_e32 v168, 0x4b800000, v150
	v_cmp_gt_f32_e64 s[8:9], s65, v150
	v_fmamk_f32 v148, v148, 0x3a000000, v157
	v_fmamk_f32 v146, v146, 0x3a000000, v157
	v_cndmask_b32_e64 v150, v150, v168, s[8:9]
	v_cndmask_b32_e64 v168, v154, v167, s[4:5]
	v_mul_f32_e32 v154, 0x45800000, v152
	v_cndmask_b32_e32 v170, v152, v154, vcc
	v_mul_f32_e32 v154, 0x4b800000, v148
	v_cmp_gt_f32_e32 vcc, s65, v148
	v_rsq_f32_e32 v150, v150
	v_cmp_gt_f32_e64 s[4:5], s65, v146
	v_cndmask_b32_e32 v148, v148, v154, vcc
	v_rsq_f32_e32 v148, v148
	v_mul_f32_e32 v152, 0x45800000, v150
	v_mul_f32_e32 v154, 0x4b800000, v146
	v_cndmask_b32_e64 v146, v146, v154, s[4:5]
	v_cndmask_b32_e64 v154, v150, v152, s[8:9]
	v_mul_f32_e32 v150, 0x45800000, v148
	v_fmamk_f32 v145, v145, 0x3a000000, v157
	v_cndmask_b32_e32 v152, v148, v150, vcc
	v_mul_f32_e32 v150, 0x4b800000, v145
	v_cmp_gt_f32_e32 vcc, s65, v145
	v_fmamk_f32 v144, v144, 0x3a000000, v157
	v_rsq_f32_e32 v146, v146
	v_cndmask_b32_e32 v145, v145, v150, vcc
	v_mul_f32_e32 v150, 0x4b800000, v144
	v_cmp_gt_f32_e64 s[8:9], s65, v144
	v_rsq_f32_e32 v145, v145
	v_mul_f32_e32 v148, 0x45800000, v146
	v_cndmask_b32_e64 v144, v144, v150, s[8:9]
	v_rsq_f32_e32 v144, v144
	v_cndmask_b32_e64 v150, v146, v148, s[4:5]
	v_mul_f32_e32 v146, 0x45800000, v145
	v_pk_mul_f32 v[120:121], v[166:167], v[120:121] op_sel_hi:[0,1]
	v_cndmask_b32_e32 v148, v145, v146, vcc
	v_mul_f32_e32 v145, 0x45800000, v144
	v_pk_mul_f32 v[124:125], v[166:167], v[124:125] op_sel_hi:[0,1]
	v_pk_mul_f32 v[122:123], v[166:167], v[122:123] op_sel_hi:[0,1]
	v_max_f32_e32 v120, 0, v120
	v_cndmask_b32_e64 v146, v144, v145, s[8:9]
	v_lshl_add_u32 v172, s52, 8, v147
	v_lshl_or_b32 v144, s66, 8, v151
	v_pk_mul_f32 v[126:127], v[166:167], v[126:127] op_sel_hi:[0,1]
	v_mul_f32_e32 v167, v120, v120
	v_max_f32_e32 v120, 0, v125
	v_max_f32_e32 v121, 0, v121
	v_max_f32_e32 v122, 0, v122
	v_ashrrev_i32_e32 v145, 31, v144
	v_ashrrev_i32_e32 v173, 31, v172
	v_max_f32_e32 v124, 0, v124
	v_mul_f32_e32 v120, v120, v120
	v_mul_f32_e32 v125, v121, v121
	v_max_f32_e32 v121, 0, v126
	v_mul_f32_e32 v126, v122, v122
	v_max_f32_e32 v122, 0, v127
	v_max_f32_e32 v123, 0, v123
	v_pk_mul_f32 v[114:115], v[166:167], v[114:115] op_sel_hi:[0,1]
	v_pk_mul_f32 v[112:113], v[166:167], v[112:113] op_sel_hi:[0,1]
	v_lshl_add_u64 v[174:175], v[144:145], 1, s[16:17]
	v_lshlrev_b64 v[144:145], 14, v[172:173]
	v_mul_f32_e32 v124, v124, v124
	v_mul_f32_e32 v121, v121, v121
	v_mul_f32_e32 v122, v122, v122
	v_mul_f32_e32 v123, v123, v123
	v_cvt_pk_bf16_f32 v120, v124, v120
	v_pk_mul_f32 v[118:119], v[166:167], v[118:119] op_sel_hi:[0,1]
	v_pk_mul_f32 v[116:117], v[166:167], v[116:117] op_sel_hi:[0,1]
	v_max_f32_e32 v112, 0, v112
	v_max_f32_e32 v113, 0, v113
	v_max_f32_e32 v114, 0, v114
	v_lshl_add_u64 v[144:145], v[174:175], 0, v[144:145]
	v_cvt_pk_bf16_f32 v121, v121, v122
	v_cvt_pk_bf16_f32 v122, v167, v125
	v_cvt_pk_bf16_f32 v123, v126, v123
	v_max_f32_e32 v116, 0, v116
	global_store_dwordx4 v[144:145], v[120:123], off sc1
	s_nop 1
	v_mul_f32_e32 v120, v112, v112
	v_max_f32_e32 v112, 0, v117
	v_mul_f32_e32 v117, v113, v113
	v_max_f32_e32 v113, 0, v118
	v_mul_f32_e32 v118, v114, v114
	v_max_f32_e32 v114, 0, v119
	v_mul_f32_e32 v112, v112, v112
	v_mul_f32_e32 v113, v113, v113
	v_max_f32_e32 v115, 0, v115
	v_mul_f32_e32 v114, v114, v114
	v_pk_mul_f32 v[104:105], v[168:169], v[104:105] op_sel_hi:[0,1]
	v_mul_f32_e32 v116, v116, v116
	v_mul_f32_e32 v115, v115, v115
	v_cvt_pk_bf16_f32 v112, v116, v112
	v_cvt_pk_bf16_f32 v113, v113, v114
	v_cvt_pk_bf16_f32 v114, v120, v117
	v_pk_mul_f32 v[108:109], v[168:169], v[108:109] op_sel_hi:[0,1]
	v_pk_mul_f32 v[106:107], v[168:169], v[106:107] op_sel_hi:[0,1]
	v_max_f32_e32 v104, 0, v104
	v_cvt_pk_bf16_f32 v115, v118, v115
	v_lshl_add_u64 v[116:117], v[144:145], 0, s[22:23]
	global_store_dwordx4 v[116:117], v[112:115], off sc1
	s_nop 1
	v_or_b32_e32 v112, 16, v172
	v_pk_mul_f32 v[110:111], v[168:169], v[110:111] op_sel_hi:[0,1]
	v_mul_f32_e32 v114, v104, v104
	v_max_f32_e32 v104, 0, v109
	v_max_f32_e32 v105, 0, v105
	v_max_f32_e32 v106, 0, v106
	v_ashrrev_i32_e32 v113, 31, v112
	v_max_f32_e32 v108, 0, v108
	v_mul_f32_e32 v104, v104, v104
	v_mul_f32_e32 v109, v105, v105
	v_max_f32_e32 v105, 0, v110
	v_mul_f32_e32 v110, v106, v106
	v_max_f32_e32 v106, 0, v111
	v_max_f32_e32 v107, 0, v107
	v_pk_mul_f32 v[98:99], v[168:169], v[98:99] op_sel_hi:[0,1]
	v_pk_mul_f32 v[96:97], v[168:169], v[96:97] op_sel_hi:[0,1]
	v_lshlrev_b64 v[112:113], 14, v[112:113]
	v_mul_f32_e32 v108, v108, v108
	v_mul_f32_e32 v105, v105, v105
	v_mul_f32_e32 v106, v106, v106
	v_mul_f32_e32 v107, v107, v107
	v_cvt_pk_bf16_f32 v104, v108, v104
	v_pk_mul_f32 v[102:103], v[168:169], v[102:103] op_sel_hi:[0,1]
	v_pk_mul_f32 v[100:101], v[168:169], v[100:101] op_sel_hi:[0,1]
	v_max_f32_e32 v96, 0, v96
	v_max_f32_e32 v97, 0, v97
	v_max_f32_e32 v98, 0, v98
	v_lshl_add_u64 v[112:113], v[174:175], 0, v[112:113]
; __device__ __forceinline__ unsigned cvt_pk_bf16(float lo, float hi) { unsigned r; asm volatile("v_cvt_pk_bf16_f32 %0, %1, %2" : "=v"(r) : "v"(lo), "v"(hi)); return r; }
;     __device__ __forceinline__ void operator()(const f32x4 (&acc)[2][2][4][2], const Unit& u, int wr, int wc, int fr, int fq, int, const float (&rsv_)[8]) const {
;     ...
;             for (int m = 0; m < 4; ++m) { bf16_t* rowp = base + (size_t)(row0 + ai * HALF + m * 16) * ldc + col0;
;                 const float rs = rsv[ai][m];
; #pragma unroll
;                 for (int bj = 0; bj < 2; ++bj) { f32x4 v0 = acc[ai][bj][m][0] * rs, v1 = acc[ai][bj][m][1] * rs;
;                     if (ACT == 1) {
; #pragma unroll
;                         for (int j = 0; j < 4; ++j) { const float a = fmaxf(v0[j], 0.f), b = fmaxf(v1[j], 0.f); v0[j] = a * a; v1[j] = b * b; } }
;                     if (ACT == 2) { if (act2) {
; #pragma unroll
;                         for (int j = 0; j < 4; ++j) { float x = v0[j]; float z = 0.7978845608028654f * (x + 0.044715f * x * x * x); v0[j] = x / (1.f + __expf(-2.f * z));
;                                                       x = v1[j]; z = 0.7978845608028654f * (x + 0.044715f * x * x * x); v1[j] = x / (1.f + __expf(-2.f * z)); } } }
;                     u32x4 w; w.x = cvt_pk_bf16(v0[0], v0[1]); w.y = cvt_pk_bf16(v0[2], v0[3]); w.z = cvt_pk_bf16(v1[0], v1[1]); w.w = cvt_pk_bf16(v1[2], v1[3]);
;                     { u32x4* dp_ = (u32x4*)(rowp + bj * HALF); asm volatile("global_store_dwordx4 %0, %1, off sc1\n\ts_nop 1" :: "v"(dp_), "v"(w) : "memory"); } } }
	v_cvt_pk_bf16_f32 v105, v105, v106
	v_cvt_pk_bf16_f32 v106, v114, v109
	v_cvt_pk_bf16_f32 v107, v110, v107
	v_max_f32_e32 v100, 0, v100
	global_store_dwordx4 v[112:113], v[104:107], off sc1
	s_nop 1
	v_mul_f32_e32 v104, v96, v96
	v_max_f32_e32 v96, 0, v101
	v_mul_f32_e32 v101, v97, v97
	v_max_f32_e32 v97, 0, v102
	v_mul_f32_e32 v102, v98, v98
	v_max_f32_e32 v98, 0, v103
	v_mul_f32_e32 v96, v96, v96
	v_mul_f32_e32 v97, v97, v97
	v_max_f32_e32 v99, 0, v99
	v_mul_f32_e32 v98, v98, v98
	v_pk_mul_f32 v[88:89], v[170:171], v[88:89] op_sel_hi:[0,1]
	v_mul_f32_e32 v100, v100, v100
	v_mul_f32_e32 v99, v99, v99
	v_cvt_pk_bf16_f32 v96, v100, v96
	v_cvt_pk_bf16_f32 v97, v97, v98
	v_cvt_pk_bf16_f32 v98, v104, v101
	v_pk_mul_f32 v[92:93], v[170:171], v[92:93] op_sel_hi:[0,1]
	v_pk_mul_f32 v[90:91], v[170:171], v[90:91] op_sel_hi:[0,1]
	v_max_f32_e32 v88, 0, v88
	v_cvt_pk_bf16_f32 v99, v102, v99
	v_lshl_add_u64 v[100:101], v[112:113], 0, s[22:23]
	global_store_dwordx4 v[100:101], v[96:99], off sc1
	s_nop 1
	v_or_b32_e32 v96, 32, v172
	v_pk_mul_f32 v[94:95], v[170:171], v[94:95] op_sel_hi:[0,1]
	v_mul_f32_e32 v98, v88, v88
	v_max_f32_e32 v88, 0, v93
	v_max_f32_e32 v89, 0, v89
	v_max_f32_e32 v90, 0, v90
	v_ashrrev_i32_e32 v97, 31, v96
	v_max_f32_e32 v92, 0, v92
	v_mul_f32_e32 v88, v88, v88
	v_mul_f32_e32 v93, v89, v89
	v_max_f32_e32 v89, 0, v94
	v_mul_f32_e32 v94, v90, v90
	v_max_f32_e32 v90, 0, v95
	v_max_f32_e32 v91, 0, v91
	v_pk_mul_f32 v[82:83], v[170:171], v[82:83] op_sel_hi:[0,1]
	v_pk_mul_f32 v[80:81], v[170:171], v[80:81] op_sel_hi:[0,1]
	v_lshlrev_b64 v[96:97], 14, v[96:97]
	v_mul_f32_e32 v92, v92, v92
	v_mul_f32_e32 v89, v89, v89
	v_mul_f32_e32 v90, v90, v90
	v_mul_f32_e32 v91, v91, v91
	v_cvt_pk_bf16_f32 v88, v92, v88
	v_pk_mul_f32 v[86:87], v[170:171], v[86:87] op_sel_hi:[0,1]
	v_pk_mul_f32 v[84:85], v[170:171], v[84:85] op_sel_hi:[0,1]
	v_max_f32_e32 v80, 0, v80
	v_max_f32_e32 v81, 0, v81
	v_max_f32_e32 v82, 0, v82
	v_lshl_add_u64 v[96:97], v[174:175], 0, v[96:97]
	v_cvt_pk_bf16_f32 v89, v89, v90
	v_cvt_pk_bf16_f32 v90, v98, v93
	v_cvt_pk_bf16_f32 v91, v94, v91
	v_max_f32_e32 v84, 0, v84
	global_store_dwordx4 v[96:97], v[88:91], off sc1
	s_nop 1
	v_mul_f32_e32 v88, v80, v80
	v_max_f32_e32 v80, 0, v85
	v_mul_f32_e32 v85, v81, v81
	v_max_f32_e32 v81, 0, v86
	v_mul_f32_e32 v86, v82, v82
	v_max_f32_e32 v82, 0, v87
	v_mul_f32_e32 v80, v80, v80
	v_mul_f32_e32 v81, v81, v81
	v_max_f32_e32 v83, 0, v83
	v_mul_f32_e32 v82, v82, v82
	v_pk_mul_f32 v[72:73], v[154:155], v[72:73] op_sel_hi:[0,1]
	v_mul_f32_e32 v84, v84, v84
	v_mul_f32_e32 v83, v83, v83
	v_cvt_pk_bf16_f32 v80, v84, v80
	v_cvt_pk_bf16_f32 v81, v81, v82
	v_cvt_pk_bf16_f32 v82, v88, v85
	v_pk_mul_f32 v[76:77], v[154:155], v[76:77] op_sel_hi:[0,1]
	v_pk_mul_f32 v[74:75], v[154:155], v[74:75] op_sel_hi:[0,1]
	v_max_f32_e32 v72, 0, v72
	v_cvt_pk_bf16_f32 v83, v86, v83
	v_lshl_add_u64 v[84:85], v[96:97], 0, s[22:23]
	global_store_dwordx4 v[84:85], v[80:83], off sc1
	s_nop 1
	v_or_b32_e32 v80, 48, v172
	v_pk_mul_f32 v[78:79], v[154:155], v[78:79] op_sel_hi:[0,1]
	v_mul_f32_e32 v82, v72, v72
	v_max_f32_e32 v72, 0, v77
	v_max_f32_e32 v73, 0, v73
	v_max_f32_e32 v74, 0, v74
	v_ashrrev_i32_e32 v81, 31, v80
	v_max_f32_e32 v76, 0, v76
	v_mul_f32_e32 v72, v72, v72
	v_mul_f32_e32 v77, v73, v73
	v_max_f32_e32 v73, 0, v78
	v_mul_f32_e32 v78, v74, v74
	v_max_f32_e32 v74, 0, v79
	v_max_f32_e32 v75, 0, v75
	v_pk_mul_f32 v[66:67], v[154:155], v[66:67] op_sel_hi:[0,1]
	v_pk_mul_f32 v[64:65], v[154:155], v[64:65] op_sel_hi:[0,1]
	v_lshlrev_b64 v[80:81], 14, v[80:81]
	v_mul_f32_e32 v76, v76, v76
	v_mul_f32_e32 v73, v73, v73
	v_mul_f32_e32 v74, v74, v74
	v_mul_f32_e32 v75, v75, v75
	v_cvt_pk_bf16_f32 v72, v76, v72
	v_pk_mul_f32 v[70:71], v[154:155], v[70:71] op_sel_hi:[0,1]
	v_pk_mul_f32 v[68:69], v[154:155], v[68:69] op_sel_hi:[0,1]
	v_max_f32_e32 v64, 0, v64
	v_max_f32_e32 v65, 0, v65
	v_max_f32_e32 v66, 0, v66
	v_lshl_add_u64 v[80:81], v[174:175], 0, v[80:81]
	v_cvt_pk_bf16_f32 v73, v73, v74
	v_cvt_pk_bf16_f32 v74, v82, v77
	v_cvt_pk_bf16_f32 v75, v78, v75
	v_max_f32_e32 v68, 0, v68
	global_store_dwordx4 v[80:81], v[72:75], off sc1
	s_nop 1
	v_mul_f32_e32 v72, v64, v64
	v_max_f32_e32 v64, 0, v69
	v_mul_f32_e32 v69, v65, v65
	v_max_f32_e32 v65, 0, v70
	v_mul_f32_e32 v70, v66, v66
	v_max_f32_e32 v66, 0, v71
	v_mul_f32_e32 v64, v64, v64
	v_mul_f32_e32 v65, v65, v65
	v_max_f32_e32 v67, 0, v67
	v_mul_f32_e32 v66, v66, v66
	v_pk_mul_f32 v[56:57], v[152:153], v[56:57] op_sel_hi:[0,1]
	v_mul_f32_e32 v68, v68, v68
	v_mul_f32_e32 v67, v67, v67
	v_cvt_pk_bf16_f32 v64, v68, v64
	v_cvt_pk_bf16_f32 v65, v65, v66
	v_cvt_pk_bf16_f32 v66, v72, v69
	v_pk_mul_f32 v[60:61], v[152:153], v[60:61] op_sel_hi:[0,1]
	v_pk_mul_f32 v[58:59], v[152:153], v[58:59] op_sel_hi:[0,1]
	v_max_f32_e32 v56, 0, v56
	v_cvt_pk_bf16_f32 v67, v70, v67
	v_lshl_add_u64 v[68:69], v[80:81], 0, s[22:23]
	global_store_dwordx4 v[68:69], v[64:67], off sc1
	s_nop 1
	v_pk_mul_f32 v[62:63], v[152:153], v[62:63] op_sel_hi:[0,1]
	v_mul_f32_e32 v66, v56, v56
	v_max_f32_e32 v56, 0, v61
	v_max_f32_e32 v57, 0, v57
	v_max_f32_e32 v58, 0, v58
	v_max_f32_e32 v60, 0, v60
	v_mul_f32_e32 v56, v56, v56
	v_mul_f32_e32 v61, v57, v57
	v_max_f32_e32 v57, 0, v62
	v_mul_f32_e32 v62, v58, v58
	v_max_f32_e32 v58, 0, v63
	v_max_f32_e32 v59, 0, v59
	v_pk_mul_f32 v[50:51], v[152:153], v[50:51] op_sel_hi:[0,1]
	v_pk_mul_f32 v[48:49], v[152:153], v[48:49] op_sel_hi:[0,1]
	v_mul_f32_e32 v60, v60, v60
	v_mul_f32_e32 v57, v57, v57
	v_mul_f32_e32 v58, v58, v58
	v_mul_f32_e32 v59, v59, v59
	v_cvt_pk_bf16_f32 v56, v60, v56
	v_pk_mul_f32 v[54:55], v[152:153], v[54:55] op_sel_hi:[0,1]
; __device__ __forceinline__ unsigned cvt_pk_bf16(float lo, float hi) { unsigned r; asm volatile("v_cvt_pk_bf16_f32 %0, %1, %2" : "=v"(r) : "v"(lo), "v"(hi)); return r; }
; #define PG8_BAR __builtin_amdgcn_s_barrier()
; template <class Epi, bool ALIGN_EPI>
; __device__ __forceinline__ void gemm_phase(LAS unsigned char* lds, const Gemm g, const StaticOrder& S, const Epi& E) {
;     ...
;         if (!has_next) break;
;         E.post(ui + 1, rsn);
; #pragma unroll
;         for (int a = 0; a < 2; ++a)
; #pragma unroll
;             for (int b = 0; b < 2; ++b)
; #pragma unroll
;                 for (int m = 0; m < 4; ++m)
; #pragma unroll
;                     for (int n = 0; n < 2; ++n) acc[a][b][m][n] = (f32x4){0.f, 0.f, 0.f, 0.f};
;         cur = nxt; cA = nA; cB = nB; ++ui;
; #pragma unroll
;         for (int i_ = 0; i_ < 8; ++i_) rsv[i_] = rsn[i_];
;         if constexpr (ALIGN_EPI) { if (wr == 1) PG8_BAR; }
;     __device__ __forceinline__ void operator()(const f32x4 (&acc)[2][2][4][2], const Unit& u, int wr, int wc, int fr, int fq, int, const float (&rsv_)[8]) const {
;     ...
;             for (int m = 0; m < 4; ++m) { bf16_t* rowp = base + (size_t)(row0 + ai * HALF + m * 16) * ldc + col0;
;                 const float rs = rsv[ai][m];
; #pragma unroll
;                 for (int bj = 0; bj < 2; ++bj) { f32x4 v0 = acc[ai][bj][m][0] * rs, v1 = acc[ai][bj][m][1] * rs;
;                     if (ACT == 1) {
; #pragma unroll
;                         for (int j = 0; j < 4; ++j) { const float a = fmaxf(v0[j], 0.f), b = fmaxf(v1[j], 0.f); v0[j] = a * a; v1[j] = b * b; } }
;                     if (ACT == 2) { if (act2) {
; #pragma unroll
;                         for (int j = 0; j < 4; ++j) { float x = v0[j]; float z = 0.7978845608028654f * (x + 0.044715f * x * x * x); v0[j] = x / (1.f + __expf(-2.f * z));
;                                                       x = v1[j]; z = 0.7978845608028654f * (x + 0.044715f * x * x * x); v1[j] = x / (1.f + __expf(-2.f * z)); } } }
;                     u32x4 w; w.x = cvt_pk_bf16(v0[0], v0[1]); w.y = cvt_pk_bf16(v0[2], v0[3]); w.z = cvt_pk_bf16(v1[0], v1[1]); w.w = cvt_pk_bf16(v1[2], v1[3]);
;                     { u32x4* dp_ = (u32x4*)(rowp + bj * HALF); asm volatile("global_store_dwordx4 %0, %1, off sc1\n\ts_nop 1" :: "v"(dp_), "v"(w) : "memory"); } } }
	v_pk_mul_f32 v[52:53], v[152:153], v[52:53] op_sel_hi:[0,1]
	v_max_f32_e32 v48, 0, v48
	v_max_f32_e32 v49, 0, v49
	v_max_f32_e32 v50, 0, v50
	v_lshl_add_u64 v[64:65], v[144:145], 0, s[24:25]
	v_cvt_pk_bf16_f32 v57, v57, v58
	v_cvt_pk_bf16_f32 v58, v66, v61
	v_cvt_pk_bf16_f32 v59, v62, v59
	v_max_f32_e32 v52, 0, v52
	global_store_dwordx4 v[64:65], v[56:59], off sc1
	s_nop 1
	v_mul_f32_e32 v56, v48, v48
	v_max_f32_e32 v48, 0, v53
	v_mul_f32_e32 v53, v49, v49
	v_max_f32_e32 v49, 0, v54
	v_mul_f32_e32 v54, v50, v50
	v_max_f32_e32 v50, 0, v55
	v_mul_f32_e32 v48, v48, v48
	v_mul_f32_e32 v49, v49, v49
	v_max_f32_e32 v51, 0, v51
	v_mul_f32_e32 v50, v50, v50
	v_pk_mul_f32 v[40:41], v[150:151], v[40:41] op_sel_hi:[0,1]
	v_mul_f32_e32 v52, v52, v52
	v_mul_f32_e32 v51, v51, v51
	v_cvt_pk_bf16_f32 v48, v52, v48
	v_cvt_pk_bf16_f32 v49, v49, v50
	v_cvt_pk_bf16_f32 v50, v56, v53
	v_pk_mul_f32 v[44:45], v[150:151], v[44:45] op_sel_hi:[0,1]
	v_pk_mul_f32 v[42:43], v[150:151], v[42:43] op_sel_hi:[0,1]
	v_max_f32_e32 v40, 0, v40
	v_cvt_pk_bf16_f32 v51, v54, v51
	v_lshl_add_u64 v[52:53], v[144:145], 0, s[26:27]
	global_store_dwordx4 v[52:53], v[48:51], off sc1
	s_nop 1
	v_pk_mul_f32 v[46:47], v[150:151], v[46:47] op_sel_hi:[0,1]
	v_mul_f32_e32 v50, v40, v40
	v_max_f32_e32 v40, 0, v45
	v_max_f32_e32 v41, 0, v41
	v_max_f32_e32 v42, 0, v42
	v_max_f32_e32 v44, 0, v44
	v_mul_f32_e32 v40, v40, v40
	v_mul_f32_e32 v45, v41, v41
	v_max_f32_e32 v41, 0, v46
	v_mul_f32_e32 v46, v42, v42
	v_max_f32_e32 v42, 0, v47
	v_max_f32_e32 v43, 0, v43
	v_pk_mul_f32 v[34:35], v[150:151], v[34:35] op_sel_hi:[0,1]
	v_pk_mul_f32 v[32:33], v[150:151], v[32:33] op_sel_hi:[0,1]
	v_mul_f32_e32 v44, v44, v44
	v_mul_f32_e32 v41, v41, v41
	v_mul_f32_e32 v42, v42, v42
	v_mul_f32_e32 v43, v43, v43
	v_cvt_pk_bf16_f32 v40, v44, v40
	v_pk_mul_f32 v[38:39], v[150:151], v[38:39] op_sel_hi:[0,1]
	v_pk_mul_f32 v[36:37], v[150:151], v[36:37] op_sel_hi:[0,1]
	v_max_f32_e32 v32, 0, v32
	v_max_f32_e32 v33, 0, v33
	v_max_f32_e32 v34, 0, v34
	v_lshl_add_u64 v[48:49], v[144:145], 0, s[28:29]
	v_cvt_pk_bf16_f32 v41, v41, v42
	v_cvt_pk_bf16_f32 v42, v50, v45
	v_cvt_pk_bf16_f32 v43, v46, v43
	v_max_f32_e32 v36, 0, v36
	global_store_dwordx4 v[48:49], v[40:43], off sc1
	s_nop 1
	v_mul_f32_e32 v40, v32, v32
	v_max_f32_e32 v32, 0, v37
	v_mul_f32_e32 v37, v33, v33
	v_max_f32_e32 v33, 0, v38
	v_mul_f32_e32 v38, v34, v34
	v_max_f32_e32 v34, 0, v39
	v_mul_f32_e32 v32, v32, v32
	v_mul_f32_e32 v33, v33, v33
	v_max_f32_e32 v35, 0, v35
	v_mul_f32_e32 v34, v34, v34
	v_pk_mul_f32 v[24:25], v[148:149], v[24:25] op_sel_hi:[0,1]
	v_mul_f32_e32 v36, v36, v36
	v_mul_f32_e32 v35, v35, v35
	v_cvt_pk_bf16_f32 v32, v36, v32
	v_cvt_pk_bf16_f32 v33, v33, v34
	v_cvt_pk_bf16_f32 v34, v40, v37
	v_pk_mul_f32 v[28:29], v[148:149], v[28:29] op_sel_hi:[0,1]
	v_pk_mul_f32 v[26:27], v[148:149], v[26:27] op_sel_hi:[0,1]
	v_max_f32_e32 v24, 0, v24
	v_cvt_pk_bf16_f32 v35, v38, v35
	v_lshl_add_u64 v[36:37], v[144:145], 0, s[30:31]
	global_store_dwordx4 v[36:37], v[32:35], off sc1
	s_nop 1
	v_pk_mul_f32 v[30:31], v[148:149], v[30:31] op_sel_hi:[0,1]
	v_mul_f32_e32 v34, v24, v24
	v_max_f32_e32 v24, 0, v29
	v_max_f32_e32 v25, 0, v25
	v_max_f32_e32 v26, 0, v26
	v_max_f32_e32 v28, 0, v28
	v_mul_f32_e32 v24, v24, v24
	v_mul_f32_e32 v29, v25, v25
	v_max_f32_e32 v25, 0, v30
	v_mul_f32_e32 v30, v26, v26
	v_max_f32_e32 v26, 0, v31
	v_max_f32_e32 v27, 0, v27
	v_pk_mul_f32 v[18:19], v[148:149], v[18:19] op_sel_hi:[0,1]
	v_pk_mul_f32 v[16:17], v[148:149], v[16:17] op_sel_hi:[0,1]
	v_mul_f32_e32 v28, v28, v28
	v_mul_f32_e32 v25, v25, v25
	v_mul_f32_e32 v26, v26, v26
	v_mul_f32_e32 v27, v27, v27
	v_cvt_pk_bf16_f32 v24, v28, v24
	v_pk_mul_f32 v[22:23], v[148:149], v[22:23] op_sel_hi:[0,1]
	v_pk_mul_f32 v[20:21], v[148:149], v[20:21] op_sel_hi:[0,1]
	v_max_f32_e32 v16, 0, v16
	v_max_f32_e32 v17, 0, v17
	v_max_f32_e32 v18, 0, v18
	v_lshl_add_u64 v[32:33], v[144:145], 0, s[34:35]
	v_cvt_pk_bf16_f32 v25, v25, v26
	v_cvt_pk_bf16_f32 v26, v34, v29
	v_cvt_pk_bf16_f32 v27, v30, v27
	v_max_f32_e32 v20, 0, v20
	global_store_dwordx4 v[32:33], v[24:27], off sc1
	s_nop 1
	v_mul_f32_e32 v24, v16, v16
	v_max_f32_e32 v16, 0, v21
	v_mul_f32_e32 v21, v17, v17
	v_max_f32_e32 v17, 0, v22
	v_mul_f32_e32 v22, v18, v18
	v_max_f32_e32 v18, 0, v23
	v_mul_f32_e32 v16, v16, v16
	v_mul_f32_e32 v17, v17, v17
	v_max_f32_e32 v19, 0, v19
	v_mul_f32_e32 v18, v18, v18
	v_pk_mul_f32 v[8:9], v[146:147], v[8:9] op_sel_hi:[0,1]
	v_mul_f32_e32 v20, v20, v20
	v_mul_f32_e32 v19, v19, v19
	v_cvt_pk_bf16_f32 v16, v20, v16
	v_cvt_pk_bf16_f32 v17, v17, v18
	v_cvt_pk_bf16_f32 v18, v24, v21
	v_pk_mul_f32 v[12:13], v[146:147], v[12:13] op_sel_hi:[0,1]
	v_pk_mul_f32 v[10:11], v[146:147], v[10:11] op_sel_hi:[0,1]
	v_max_f32_e32 v8, 0, v8
	v_cvt_pk_bf16_f32 v19, v22, v19
	v_lshl_add_u64 v[20:21], v[144:145], 0, s[36:37]
	global_store_dwordx4 v[20:21], v[16:19], off sc1
	s_nop 1
	v_pk_mul_f32 v[14:15], v[146:147], v[14:15] op_sel_hi:[0,1]
	v_mul_f32_e32 v18, v8, v8
	v_max_f32_e32 v8, 0, v13
	v_max_f32_e32 v9, 0, v9
	v_max_f32_e32 v10, 0, v10
	v_max_f32_e32 v12, 0, v12
	v_mul_f32_e32 v8, v8, v8
	v_mul_f32_e32 v13, v9, v9
	v_max_f32_e32 v9, 0, v14
	v_mul_f32_e32 v14, v10, v10
	v_max_f32_e32 v10, 0, v15
	v_max_f32_e32 v11, 0, v11
	v_pk_mul_f32 v[2:3], v[146:147], v[2:3] op_sel_hi:[0,1]
	v_pk_mul_f32 v[0:1], v[146:147], v[0:1] op_sel_hi:[0,1]
	v_mul_f32_e32 v12, v12, v12
	v_mul_f32_e32 v9, v9, v9
	v_mul_f32_e32 v10, v10, v10
	v_mul_f32_e32 v11, v11, v11
	v_cvt_pk_bf16_f32 v8, v12, v8
	v_pk_mul_f32 v[6:7], v[146:147], v[6:7] op_sel_hi:[0,1]
	v_pk_mul_f32 v[4:5], v[146:147], v[4:5] op_sel_hi:[0,1]
	v_max_f32_e32 v0, 0, v0
	v_max_f32_e32 v1, 0, v1
	v_max_f32_e32 v2, 0, v2
	v_lshl_add_u64 v[16:17], v[144:145], 0, s[40:41]
	v_cvt_pk_bf16_f32 v9, v9, v10
	v_cvt_pk_bf16_f32 v10, v18, v13
	v_cvt_pk_bf16_f32 v11, v14, v11
	v_max_f32_e32 v4, 0, v4
	global_store_dwordx4 v[16:17], v[8:11], off sc1
	s_nop 1
	v_mul_f32_e32 v8, v0, v0
	v_max_f32_e32 v0, 0, v5
	v_mul_f32_e32 v5, v1, v1
	v_max_f32_e32 v1, 0, v6
	v_mul_f32_e32 v6, v2, v2
	v_max_f32_e32 v2, 0, v7
	v_max_f32_e32 v3, 0, v3
	v_mul_f32_e32 v4, v4, v4
	v_mul_f32_e32 v0, v0, v0
	v_mul_f32_e32 v1, v1, v1
	v_mul_f32_e32 v2, v2, v2
	v_mul_f32_e32 v3, v3, v3
	v_cvt_pk_bf16_f32 v0, v4, v0
	v_cvt_pk_bf16_f32 v1, v1, v2
	v_cvt_pk_bf16_f32 v2, v8, v5
	v_cvt_pk_bf16_f32 v3, v6, v3
	v_lshl_add_u64 v[4:5], v[144:145], 0, s[42:43]
	global_store_dwordx4 v[4:5], v[0:3], off sc1
	s_nop 1
	s_and_b64 vcc, exec, s[6:7]
	s_mov_b64 s[4:5], -1
	s_cbranch_vccnz .LBB0_918
	s_andn2_b64 vcc, exec, s[14:15]
	s_cbranch_vccnz .LBB0_917
	s_nop 0
	s_branch .LBB0_917

; #define PG8_STAGE(bufoff, gbase, voff) do { _Pragma("unroll") for (int _i = 0; _i < 2; ++_i) \
;         __builtin_amdgcn_global_load_lds((const unsigned*)((const char*)(gbase) + (voff)[_i]), (LAS unsigned*)(lds + (bufoff) + ldsw + _i * 8192), 16, 0, 0); } while (0)
; #define PG8_LDA(dst, b, h) do { _Pragma("unroll") for (int m = 0; m < 4; ++m) _Pragma("unroll") for (int k = 0; k < 2; ++k) dst[m][k] = *(const LAS bf16x8*)(lds + PG8_SA(b, h) + aoff + m * 2048 + k * 1024); } while (0)
; #define PG8_LDB(dst, b, h) do { _Pragma("unroll") for (int n = 0; n < 2; ++n) _Pragma("unroll") for (int k = 0; k < 2; ++k) dst[n][k] = *(const LAS bf16x8*)(lds + PG8_SB(b, h) + boff + n * 2048 + k * 1024); } while (0)
; #define PG8_MMA(ai, bj, At, Bt) do { __builtin_amdgcn_s_setprio(1); _Pragma("unroll") for (int m = 0; m < 4; ++m) _Pragma("unroll") for (int n = 0; n < 2; ++n) _Pragma("unroll") for (int k = 0; k < 2; ++k) \
;         acc[ai][bj][m][n] = __builtin_amdgcn_mfma_f32_16x16x32_bf16(Bt[n][k], At[m][k], acc[ai][bj][m][n], 0, 0, 0); __builtin_amdgcn_s_setprio(0); } while (0)
; #define PG8_WAIT_V(n) asm volatile("s_waitcnt vmcnt(" #n ")" ::: "memory")
; #define PG8_WAIT_L(n) asm volatile("s_waitcnt lgkmcnt(" #n ")" ::: "memory")
; #define PG8_BAR __builtin_amdgcn_s_barrier()
; #define PG8_SCHED __builtin_amdgcn_sched_barrier(0)
; template <class Epi, bool ALIGN_EPI>
; __device__ __forceinline__ void gemm_phase(LAS unsigned char* lds, const Gemm g, const StaticOrder& S, const Epi& E) {
;     ...
;             const char* a1 = cA + (size_t)(t + 1) * kstep;
;             const char* a2 = last ? nA : cA + (size_t)(t + 2) * kstep; const char* b2 = last ? nB : cB + (size_t)(t + 2) * kstep;
;             const char* a3 = a2 + kstep; const char* b3 = b2 + kstep;
;             PG8_LDB(B0, 0, 0); PG8_LDB(B1, 0, 1); PG8_SCHED; PG8_LDA(At, 0, 0); PG8_STAGE(PG8_SA(1, 1), a1 + hA, voffA);
;             PG8_WAIT_V(8); PG8_WAIT_L(0); PG8_BAR; PG8_MMA(0, 0, At, B0); PG8_MMA(0, 1, At, B1); PG8_BAR; PG8_SCHED;
;             PG8_LDA(At, 0, 1); PG8_STAGE(PG8_SB(0, 0), b2, voffB); PG8_STAGE(PG8_SB(0, 1), b2 + hB, voffB); PG8_STAGE(PG8_SA(0, 0), a2, voffA);
;             PG8_WAIT_V(8); PG8_WAIT_L(0); PG8_BAR; PG8_MMA(1, 0, At, B0); PG8_MMA(1, 1, At, B1); PG8_BAR; PG8_SCHED;
.LBB0_1005:
	ds_read_b128 v[128:131], v175
	ds_read_b128 v[132:135], v175 offset:1024
	ds_read_b128 v[136:139], v175 offset:2048
	ds_read_b128 v[140:143], v175 offset:3072
	ds_read_b128 v[160:163], v176
	ds_read_b128 v[164:167], v176 offset:1024
	ds_read_b128 v[168:171], v176 offset:2048
	ds_read_b128 v[180:183], v176 offset:3072
	s_add_u32 s40, s36, 0xffe00080
	s_addc_u32 s41, s37, -1
	s_cmpk_eq_i32 s57, 0x7c
	s_cselect_b32 s43, s25, s41
	s_cselect_b32 s42, s31, s40
	s_cselect_b32 s41, s23, s56
	s_cselect_b32 s40, s54, s55
	v_lshl_add_u64 v[218:219], s[36:37], 0, v[152:153]
	s_add_i32 m0, s35, 0xc000
	ds_read_b128 v[184:187], v177
	ds_read_b128 v[188:191], v177 offset:1024
	ds_read_b128 v[194:197], v177 offset:2048
	ds_read_b128 v[198:201], v177 offset:3072
	ds_read_b128 v[202:205], v177 offset:4096
	ds_read_b128 v[206:209], v177 offset:5120
	ds_read_b128 v[210:213], v177 offset:6144
	ds_read_b128 v[214:217], v177 offset:7168
	global_load_lds_dwordx4 v[218:219], off
	v_lshl_add_u64 v[218:219], s[36:37], 0, v[154:155]
	s_add_i32 m0, s35, 0xe000
	s_nop 0
	global_load_lds_dwordx4 v[218:219], off
	s_waitcnt vmcnt(8)
	s_waitcnt lgkmcnt(0)
	s_barrier
	s_setprio 1
	s_waitcnt lgkmcnt(0)
	v_mfma_f32_16x16x32_bf16 v[124:127], v[128:131], v[184:187], v[124:127]
	v_mfma_f32_16x16x32_bf16 v[124:127], v[132:135], v[188:191], v[124:127]
	v_mfma_f32_16x16x32_bf16 v[120:123], v[136:139], v[184:187], v[120:123]
	v_mfma_f32_16x16x32_bf16 v[120:123], v[140:143], v[188:191], v[120:123]
	v_mfma_f32_16x16x32_bf16 v[112:115], v[128:131], v[194:197], v[112:115]
	v_mfma_f32_16x16x32_bf16 v[112:115], v[132:135], v[198:201], v[112:115]
	v_mfma_f32_16x16x32_bf16 v[104:107], v[136:139], v[194:197], v[104:107]
	v_mfma_f32_16x16x32_bf16 v[104:107], v[140:143], v[198:201], v[104:107]
	v_mfma_f32_16x16x32_bf16 v[92:95], v[128:131], v[202:205], v[92:95]
	v_mfma_f32_16x16x32_bf16 v[92:95], v[132:135], v[206:209], v[92:95]
	v_mfma_f32_16x16x32_bf16 v[88:91], v[136:139], v[202:205], v[88:91]
	v_mfma_f32_16x16x32_bf16 v[88:91], v[140:143], v[206:209], v[88:91]
	v_mfma_f32_16x16x32_bf16 v[76:79], v[128:131], v[210:213], v[76:79]
	v_mfma_f32_16x16x32_bf16 v[76:79], v[132:135], v[214:217], v[76:79]
	v_mfma_f32_16x16x32_bf16 v[72:75], v[136:139], v[210:213], v[72:75]
	v_mfma_f32_16x16x32_bf16 v[72:75], v[140:143], v[214:217], v[72:75]
	s_setprio 0
	s_setprio 1
	v_mfma_f32_16x16x32_bf16 v[116:119], v[160:163], v[184:187], v[116:119]
	v_mfma_f32_16x16x32_bf16 v[116:119], v[164:167], v[188:191], v[116:119]
	v_mfma_f32_16x16x32_bf16 v[108:111], v[168:171], v[184:187], v[108:111]
	v_mfma_f32_16x16x32_bf16 v[108:111], v[180:183], v[188:191], v[108:111]
	v_mfma_f32_16x16x32_bf16 v[100:103], v[160:163], v[194:197], v[100:103]
	v_mfma_f32_16x16x32_bf16 v[100:103], v[164:167], v[198:201], v[100:103]
	v_mfma_f32_16x16x32_bf16 v[96:99], v[168:171], v[194:197], v[96:99]
	v_mfma_f32_16x16x32_bf16 v[96:99], v[180:183], v[198:201], v[96:99]
	v_mfma_f32_16x16x32_bf16 v[84:87], v[160:163], v[202:205], v[84:87]
	v_mfma_f32_16x16x32_bf16 v[84:87], v[164:167], v[206:209], v[84:87]
	v_mfma_f32_16x16x32_bf16 v[80:83], v[168:171], v[202:205], v[80:83]
	v_mfma_f32_16x16x32_bf16 v[80:83], v[180:183], v[206:209], v[80:83]
	v_mfma_f32_16x16x32_bf16 v[68:71], v[160:163], v[210:213], v[68:71]
	v_mfma_f32_16x16x32_bf16 v[68:71], v[164:167], v[214:217], v[68:71]
	v_mfma_f32_16x16x32_bf16 v[64:67], v[168:171], v[210:213], v[64:67]
	v_mfma_f32_16x16x32_bf16 v[64:67], v[180:183], v[214:217], v[64:67]
	s_setprio 0
	s_barrier
	s_add_i32 s58, s51, s33
	v_lshl_add_u64 v[218:219], s[40:41], 0, v[146:147]
	s_mov_b32 m0, s58
	ds_read_b128 v[184:187], v177 offset:16384
	ds_read_b128 v[188:191], v177 offset:17408
	ds_read_b128 v[194:197], v177 offset:18432
	ds_read_b128 v[198:201], v177 offset:19456
	ds_read_b128 v[202:205], v177 offset:20480
	ds_read_b128 v[206:209], v177 offset:21504
	ds_read_b128 v[210:213], v177 offset:22528
	ds_read_b128 v[214:217], v177 offset:23552
	global_load_lds_dwordx4 v[218:219], off
	s_add_i32 m0, s58, 0x2000
	s_add_u32 s58, s40, 0x200000
	v_lshl_add_u64 v[220:221], s[40:41], 0, v[150:151]
	s_addc_u32 s59, s41, 0
	s_add_i32 s60, s52, s33
	global_load_lds_dwordx4 v[220:221], off
	v_lshl_add_u64 v[222:223], s[58:59], 0, v[146:147]
	s_mov_b32 m0, s60
	v_lshl_add_u64 v[224:225], s[42:43], 0, v[148:149]
	global_load_lds_dwordx4 v[222:223], off
	v_lshl_add_u64 v[222:223], s[58:59], 0, v[150:151]
	s_add_i32 m0, s60, 0x2000
	s_nop 0
	global_load_lds_dwordx4 v[222:223], off
	v_lshl_add_u64 v[222:223], s[42:43], 0, v[144:145]
	s_mov_b32 m0, s35
	s_nop 0
	global_load_lds_dwordx4 v[222:223], off
	s_mov_b32 m0, s38
	s_nop 0
	global_load_lds_dwordx4 v[224:225], off
	s_waitcnt vmcnt(8)
	s_waitcnt lgkmcnt(0)
	s_barrier
; #define PG8_STAGE(bufoff, gbase, voff) do { _Pragma("unroll") for (int _i = 0; _i < 2; ++_i) \
;         __builtin_amdgcn_global_load_lds((const unsigned*)((const char*)(gbase) + (voff)[_i]), (LAS unsigned*)(lds + (bufoff) + ldsw + _i * 8192), 16, 0, 0); } while (0)
; #define PG8_LDA(dst, b, h) do { _Pragma("unroll") for (int m = 0; m < 4; ++m) _Pragma("unroll") for (int k = 0; k < 2; ++k) dst[m][k] = *(const LAS bf16x8*)(lds + PG8_SA(b, h) + aoff + m * 2048 + k * 1024); } while (0)
; #define PG8_LDB(dst, b, h) do { _Pragma("unroll") for (int n = 0; n < 2; ++n) _Pragma("unroll") for (int k = 0; k < 2; ++k) dst[n][k] = *(const LAS bf16x8*)(lds + PG8_SB(b, h) + boff + n * 2048 + k * 1024); } while (0)
; #define PG8_MMA(ai, bj, At, Bt) do { __builtin_amdgcn_s_setprio(1); _Pragma("unroll") for (int m = 0; m < 4; ++m) _Pragma("unroll") for (int n = 0; n < 2; ++n) _Pragma("unroll") for (int k = 0; k < 2; ++k) \
;         acc[ai][bj][m][n] = __builtin_amdgcn_mfma_f32_16x16x32_bf16(Bt[n][k], At[m][k], acc[ai][bj][m][n], 0, 0, 0); __builtin_amdgcn_s_setprio(0); } while (0)
; #define PG8_WAIT_V(n) asm volatile("s_waitcnt vmcnt(" #n ")" ::: "memory")
; #define PG8_WAIT_L(n) asm volatile("s_waitcnt lgkmcnt(" #n ")" ::: "memory")
; #define PG8_BAR __builtin_amdgcn_s_barrier()
; #define PG8_SCHED __builtin_amdgcn_sched_barrier(0)
; template <class Epi, bool ALIGN_EPI>
; __device__ __forceinline__ void gemm_phase(LAS unsigned char* lds, const Gemm g, const StaticOrder& S, const Epi& E) {
;     ...
;             PG8_WAIT_V(8); PG8_WAIT_L(0); PG8_BAR; PG8_MMA(1, 0, At, B0); PG8_MMA(1, 1, At, B1); PG8_BAR; PG8_SCHED;
;             PG8_LDB(B0, 1, 0); PG8_LDB(B1, 1, 1); PG8_SCHED; PG8_LDA(At, 1, 0); PG8_STAGE(PG8_SA(0, 1), a2 + hA, voffA);
;             PG8_WAIT_V(8); PG8_WAIT_L(0); PG8_BAR; PG8_MMA(0, 0, At, B0); PG8_MMA(0, 1, At, B1); PG8_BAR; PG8_SCHED;
	s_setprio 1
	s_waitcnt lgkmcnt(0)
	v_mfma_f32_16x16x32_bf16 v[60:63], v[128:131], v[184:187], v[60:63]
	v_mfma_f32_16x16x32_bf16 v[60:63], v[132:135], v[188:191], v[60:63]
	v_mfma_f32_16x16x32_bf16 v[56:59], v[136:139], v[184:187], v[56:59]
	v_mfma_f32_16x16x32_bf16 v[56:59], v[140:143], v[188:191], v[56:59]
	v_mfma_f32_16x16x32_bf16 v[44:47], v[128:131], v[194:197], v[44:47]
	v_mfma_f32_16x16x32_bf16 v[44:47], v[132:135], v[198:201], v[44:47]
	v_mfma_f32_16x16x32_bf16 v[40:43], v[136:139], v[194:197], v[40:43]
	v_mfma_f32_16x16x32_bf16 v[40:43], v[140:143], v[198:201], v[40:43]
	v_mfma_f32_16x16x32_bf16 v[28:31], v[128:131], v[202:205], v[28:31]
	v_mfma_f32_16x16x32_bf16 v[28:31], v[132:135], v[206:209], v[28:31]
	v_mfma_f32_16x16x32_bf16 v[24:27], v[136:139], v[202:205], v[24:27]
	v_mfma_f32_16x16x32_bf16 v[24:27], v[140:143], v[206:209], v[24:27]
	v_mfma_f32_16x16x32_bf16 v[12:15], v[128:131], v[210:213], v[12:15]
	v_mfma_f32_16x16x32_bf16 v[12:15], v[132:135], v[214:217], v[12:15]
	v_mfma_f32_16x16x32_bf16 v[8:11], v[136:139], v[210:213], v[8:11]
	v_mfma_f32_16x16x32_bf16 v[8:11], v[140:143], v[214:217], v[8:11]
	s_setprio 0
	s_setprio 1
	v_mfma_f32_16x16x32_bf16 v[52:55], v[160:163], v[184:187], v[52:55]
	v_mfma_f32_16x16x32_bf16 v[52:55], v[164:167], v[188:191], v[52:55]
	v_mfma_f32_16x16x32_bf16 v[48:51], v[168:171], v[184:187], v[48:51]
	v_mfma_f32_16x16x32_bf16 v[48:51], v[180:183], v[188:191], v[48:51]
	v_mfma_f32_16x16x32_bf16 v[36:39], v[160:163], v[194:197], v[36:39]
	v_mfma_f32_16x16x32_bf16 v[36:39], v[164:167], v[198:201], v[36:39]
	v_mfma_f32_16x16x32_bf16 v[32:35], v[168:171], v[194:197], v[32:35]
	v_mfma_f32_16x16x32_bf16 v[32:35], v[180:183], v[198:201], v[32:35]
	v_mfma_f32_16x16x32_bf16 v[20:23], v[160:163], v[202:205], v[20:23]
	v_mfma_f32_16x16x32_bf16 v[20:23], v[164:167], v[206:209], v[20:23]
	v_mfma_f32_16x16x32_bf16 v[16:19], v[168:171], v[202:205], v[16:19]
	v_mfma_f32_16x16x32_bf16 v[16:19], v[180:183], v[206:209], v[16:19]
	v_mfma_f32_16x16x32_bf16 v[4:7], v[160:163], v[210:213], v[4:7]
	v_mfma_f32_16x16x32_bf16 v[4:7], v[164:167], v[214:217], v[4:7]
	v_mfma_f32_16x16x32_bf16 v[0:3], v[168:171], v[210:213], v[0:3]
	v_mfma_f32_16x16x32_bf16 v[0:3], v[180:183], v[214:217], v[0:3]
	s_setprio 0
	s_barrier
	s_add_i32 s58, 0, 0x18000
	s_add_i32 s59, 0, 0x1c000
	v_add_u32_e32 v140, s58, v173
	v_add_u32_e32 v179, s59, v173
	ds_read_b128 v[128:131], v140
	ds_read_b128 v[132:135], v140 offset:1024
	ds_read_b128 v[136:139], v140 offset:2048
	ds_read_b128 v[140:143], v140 offset:3072
	ds_read_b128 v[160:163], v179
	ds_read_b128 v[164:167], v179 offset:1024
	ds_read_b128 v[168:171], v179 offset:2048
	ds_read_b128 v[180:183], v179 offset:3072
	s_add_u32 s42, s42, 0x200000
	s_addc_u32 s43, s43, 0
	s_mov_b32 m0, s39
	v_lshl_add_u64 v[226:227], s[42:43], 0, v[144:145]
	ds_read_b128 v[184:187], v177 offset:32768
	ds_read_b128 v[188:191], v177 offset:33792
	ds_read_b128 v[194:197], v177 offset:34816
	ds_read_b128 v[198:201], v177 offset:35840
	ds_read_b128 v[202:205], v177 offset:36864
	ds_read_b128 v[206:209], v177 offset:37888
	ds_read_b128 v[210:213], v177 offset:38912
	ds_read_b128 v[214:217], v177 offset:39936
	global_load_lds_dwordx4 v[226:227], off
	v_lshl_add_u64 v[226:227], s[42:43], 0, v[148:149]
	s_mov_b32 m0, s44
	s_nop 0
	global_load_lds_dwordx4 v[226:227], off
	s_waitcnt vmcnt(8)
	s_waitcnt lgkmcnt(0)
	s_barrier
	s_setprio 1
	s_waitcnt lgkmcnt(0)
	v_mfma_f32_16x16x32_bf16 v[124:127], v[128:131], v[184:187], v[124:127]
	v_mfma_f32_16x16x32_bf16 v[124:127], v[132:135], v[188:191], v[124:127]
	v_mfma_f32_16x16x32_bf16 v[120:123], v[136:139], v[184:187], v[120:123]
	v_mfma_f32_16x16x32_bf16 v[120:123], v[140:143], v[188:191], v[120:123]
	v_mfma_f32_16x16x32_bf16 v[112:115], v[128:131], v[194:197], v[112:115]
	v_mfma_f32_16x16x32_bf16 v[112:115], v[132:135], v[198:201], v[112:115]
	v_mfma_f32_16x16x32_bf16 v[104:107], v[136:139], v[194:197], v[104:107]
	v_mfma_f32_16x16x32_bf16 v[104:107], v[140:143], v[198:201], v[104:107]
	v_mfma_f32_16x16x32_bf16 v[92:95], v[128:131], v[202:205], v[92:95]
	v_mfma_f32_16x16x32_bf16 v[92:95], v[132:135], v[206:209], v[92:95]
	v_mfma_f32_16x16x32_bf16 v[88:91], v[136:139], v[202:205], v[88:91]
	v_mfma_f32_16x16x32_bf16 v[88:91], v[140:143], v[206:209], v[88:91]
	v_mfma_f32_16x16x32_bf16 v[76:79], v[128:131], v[210:213], v[76:79]
	v_mfma_f32_16x16x32_bf16 v[76:79], v[132:135], v[214:217], v[76:79]
	v_mfma_f32_16x16x32_bf16 v[72:75], v[136:139], v[210:213], v[72:75]
	v_mfma_f32_16x16x32_bf16 v[72:75], v[140:143], v[214:217], v[72:75]
	s_setprio 0
	s_setprio 1
	v_mfma_f32_16x16x32_bf16 v[116:119], v[160:163], v[184:187], v[116:119]
	v_mfma_f32_16x16x32_bf16 v[116:119], v[164:167], v[188:191], v[116:119]
	v_mfma_f32_16x16x32_bf16 v[108:111], v[168:171], v[184:187], v[108:111]
	v_mfma_f32_16x16x32_bf16 v[108:111], v[180:183], v[188:191], v[108:111]
	v_mfma_f32_16x16x32_bf16 v[100:103], v[160:163], v[194:197], v[100:103]
	v_mfma_f32_16x16x32_bf16 v[100:103], v[164:167], v[198:201], v[100:103]
	v_mfma_f32_16x16x32_bf16 v[96:99], v[168:171], v[194:197], v[96:99]
	v_mfma_f32_16x16x32_bf16 v[96:99], v[180:183], v[198:201], v[96:99]
	v_mfma_f32_16x16x32_bf16 v[84:87], v[160:163], v[202:205], v[84:87]
	v_mfma_f32_16x16x32_bf16 v[84:87], v[164:167], v[206:209], v[84:87]
	v_mfma_f32_16x16x32_bf16 v[80:83], v[168:171], v[202:205], v[80:83]
	v_mfma_f32_16x16x32_bf16 v[80:83], v[180:183], v[206:209], v[80:83]
	v_mfma_f32_16x16x32_bf16 v[68:71], v[160:163], v[210:213], v[68:71]
	v_mfma_f32_16x16x32_bf16 v[68:71], v[164:167], v[214:217], v[68:71]
	v_mfma_f32_16x16x32_bf16 v[64:67], v[168:171], v[210:213], v[64:67]
	v_mfma_f32_16x16x32_bf16 v[64:67], v[180:183], v[214:217], v[64:67]
	s_setprio 0
	s_barrier
; #define PG8_STAGE(bufoff, gbase, voff) do { _Pragma("unroll") for (int _i = 0; _i < 2; ++_i) \
;         __builtin_amdgcn_global_load_lds((const unsigned*)((const char*)(gbase) + (voff)[_i]), (LAS unsigned*)(lds + (bufoff) + ldsw + _i * 8192), 16, 0, 0); } while (0)
; #define PG8_LDA(dst, b, h) do { _Pragma("unroll") for (int m = 0; m < 4; ++m) _Pragma("unroll") for (int k = 0; k < 2; ++k) dst[m][k] = *(const LAS bf16x8*)(lds + PG8_SA(b, h) + aoff + m * 2048 + k * 1024); } while (0)
; #define PG8_MMA(ai, bj, At, Bt) do { __builtin_amdgcn_s_setprio(1); _Pragma("unroll") for (int m = 0; m < 4; ++m) _Pragma("unroll") for (int n = 0; n < 2; ++n) _Pragma("unroll") for (int k = 0; k < 2; ++k) \
;         acc[ai][bj][m][n] = __builtin_amdgcn_mfma_f32_16x16x32_bf16(Bt[n][k], At[m][k], acc[ai][bj][m][n], 0, 0, 0); __builtin_amdgcn_s_setprio(0); } while (0)
; #define PG8_WAIT_V(n) asm volatile("s_waitcnt vmcnt(" #n ")" ::: "memory")
; #define PG8_WAIT_L(n) asm volatile("s_waitcnt lgkmcnt(" #n ")" ::: "memory")
; #define PG8_BAR __builtin_amdgcn_s_barrier()
; #define PG8_SCHED __builtin_amdgcn_sched_barrier(0)
; template <class Epi, bool ALIGN_EPI>
; __device__ __forceinline__ void gemm_phase(LAS unsigned char* lds, const Gemm g, const StaticOrder& S, const Epi& E) {
;     ...
;             PG8_LDA(At, 1, 1); PG8_STAGE(PG8_SB(1, 0), b3, voffB); PG8_STAGE(PG8_SB(1, 1), b3 + hB, voffB); PG8_STAGE(PG8_SA(1, 0), a3, voffA);
;             PG8_WAIT_V(8); PG8_WAIT_L(0); PG8_BAR; PG8_MMA(1, 0, At, B0); PG8_MMA(1, 1, At, B1); PG8_BAR; PG8_SCHED;
;         }
;         if constexpr (ALIGN_EPI) { if (wr == 0) PG8_BAR; }
	s_add_i32 s42, s58, s33
	v_lshl_add_u64 v[218:219], v[218:219], 0, s[16:17]
	s_mov_b32 m0, s42
	ds_read_b128 v[184:187], v177 offset:49152
	ds_read_b128 v[188:191], v177 offset:50176
	ds_read_b128 v[194:197], v177 offset:51200
	ds_read_b128 v[198:201], v177 offset:52224
	ds_read_b128 v[202:205], v177 offset:53248
	ds_read_b128 v[206:209], v177 offset:54272
	ds_read_b128 v[210:213], v177 offset:55296
	ds_read_b128 v[214:217], v177 offset:56320
	global_load_lds_dwordx4 v[218:219], off
	s_add_i32 m0, s42, 0x2000
	s_add_u32 s40, s40, 0x200080
	v_lshl_add_u64 v[218:219], v[220:221], 0, s[16:17]
	s_addc_u32 s41, s41, 0
	s_add_i32 s42, s59, s33
	global_load_lds_dwordx4 v[218:219], off
	v_lshl_add_u64 v[218:219], s[40:41], 0, v[146:147]
	s_mov_b32 m0, s42
	s_nop 0
	global_load_lds_dwordx4 v[218:219], off
	v_lshl_add_u64 v[218:219], s[40:41], 0, v[150:151]
	s_add_i32 m0, s42, 0x2000
	s_nop 0
	global_load_lds_dwordx4 v[218:219], off
	v_lshl_add_u64 v[218:219], v[222:223], 0, s[16:17]
	s_mov_b32 m0, s48
	s_nop 0
	global_load_lds_dwordx4 v[218:219], off
	v_lshl_add_u64 v[218:219], v[224:225], 0, s[16:17]
	s_mov_b32 m0, s49
	s_nop 0
	global_load_lds_dwordx4 v[218:219], off
	s_waitcnt vmcnt(8)
	s_waitcnt lgkmcnt(0)
	s_barrier
	s_setprio 1
	s_waitcnt lgkmcnt(0)
	v_mfma_f32_16x16x32_bf16 v[60:63], v[128:131], v[184:187], v[60:63]
	v_mfma_f32_16x16x32_bf16 v[60:63], v[132:135], v[188:191], v[60:63]
	v_mfma_f32_16x16x32_bf16 v[56:59], v[136:139], v[184:187], v[56:59]
	v_mfma_f32_16x16x32_bf16 v[56:59], v[140:143], v[188:191], v[56:59]
	v_mfma_f32_16x16x32_bf16 v[44:47], v[128:131], v[194:197], v[44:47]
	v_mfma_f32_16x16x32_bf16 v[44:47], v[132:135], v[198:201], v[44:47]
	v_mfma_f32_16x16x32_bf16 v[40:43], v[136:139], v[194:197], v[40:43]
	v_mfma_f32_16x16x32_bf16 v[40:43], v[140:143], v[198:201], v[40:43]
	v_mfma_f32_16x16x32_bf16 v[28:31], v[128:131], v[202:205], v[28:31]
	v_mfma_f32_16x16x32_bf16 v[28:31], v[132:135], v[206:209], v[28:31]
	v_mfma_f32_16x16x32_bf16 v[24:27], v[136:139], v[202:205], v[24:27]
	v_mfma_f32_16x16x32_bf16 v[24:27], v[140:143], v[206:209], v[24:27]
	v_mfma_f32_16x16x32_bf16 v[12:15], v[128:131], v[210:213], v[12:15]
	v_mfma_f32_16x16x32_bf16 v[12:15], v[132:135], v[214:217], v[12:15]
	v_mfma_f32_16x16x32_bf16 v[8:11], v[136:139], v[210:213], v[8:11]
	v_mfma_f32_16x16x32_bf16 v[8:11], v[140:143], v[214:217], v[8:11]
	s_setprio 0
	s_setprio 1
	v_mfma_f32_16x16x32_bf16 v[52:55], v[160:163], v[184:187], v[52:55]
	v_mfma_f32_16x16x32_bf16 v[52:55], v[164:167], v[188:191], v[52:55]
	v_mfma_f32_16x16x32_bf16 v[48:51], v[168:171], v[184:187], v[48:51]
	v_mfma_f32_16x16x32_bf16 v[48:51], v[180:183], v[188:191], v[48:51]
	v_mfma_f32_16x16x32_bf16 v[36:39], v[160:163], v[194:197], v[36:39]
	v_mfma_f32_16x16x32_bf16 v[36:39], v[164:167], v[198:201], v[36:39]
	v_mfma_f32_16x16x32_bf16 v[32:35], v[168:171], v[194:197], v[32:35]
	v_mfma_f32_16x16x32_bf16 v[32:35], v[180:183], v[198:201], v[32:35]
	v_mfma_f32_16x16x32_bf16 v[20:23], v[160:163], v[202:205], v[20:23]
	v_mfma_f32_16x16x32_bf16 v[20:23], v[164:167], v[206:209], v[20:23]
	v_mfma_f32_16x16x32_bf16 v[16:19], v[168:171], v[202:205], v[16:19]
	v_mfma_f32_16x16x32_bf16 v[16:19], v[180:183], v[206:209], v[16:19]
	v_mfma_f32_16x16x32_bf16 v[4:7], v[160:163], v[210:213], v[4:7]
	v_mfma_f32_16x16x32_bf16 v[4:7], v[164:167], v[214:217], v[4:7]
	v_mfma_f32_16x16x32_bf16 v[0:3], v[168:171], v[210:213], v[0:3]
	v_mfma_f32_16x16x32_bf16 v[0:3], v[180:183], v[214:217], v[0:3]
	s_setprio 0
	s_barrier
	s_add_i32 s57, s57, 2
	s_add_u32 s36, s36, 0x100
	s_addc_u32 s37, s37, 0
	s_add_u32 s55, s55, 0x100
	s_addc_u32 s56, s56, 0
	s_cmpk_gt_u32 s57, 0x7d
	s_cbranch_scc0 .LBB0_1005
	s_and_b64 vcc, exec, s[18:19]
	s_cbranch_vccz .LBB0_1008
	s_nop 0

; #define PG8_BAR __builtin_amdgcn_s_barrier()
;     __device__ __forceinline__ void post(int ui, const float (&r)[8]) const { const int t = my_tid(); if (t < 384) cbuf[(ui & 1) * 384 + t] = r[0]; }
; template <class Epi, bool ALIGN_EPI>
; __device__ __forceinline__ void gemm_phase(LAS unsigned char* lds, const Gemm g, const StaticOrder& S, const Epi& E) {
;     ...
;         if (!has_next) break;
;         E.post(ui + 1, rsn);
; #pragma unroll
;         for (int a = 0; a < 2; ++a)
; #pragma unroll
;             for (int b = 0; b < 2; ++b)
; #pragma unroll
;                 for (int m = 0; m < 4; ++m)
; #pragma unroll
;                     for (int n = 0; n < 2; ++n) acc[a][b][m][n] = (f32x4){0.f, 0.f, 0.f, 0.f};
;         cur = nxt; cA = nA; cB = nB; ++ui;
; #pragma unroll
;         for (int i_ = 0; i_ < 8; ++i_) rsv[i_] = rsn[i_];
;         if constexpr (ALIGN_EPI) { if (wr == 1) PG8_BAR; }
;     __device__ __forceinline__ void operator()(const f32x4 (&acc)[2][2][4][2], const Unit& u, int wr, int wc, int fr, int fq, int, const float (&)[8]) const {
;     ...
;                 for (int m = 0; m < 4; ++m) { float pp = part[ai][m]; pp += __shfl_xor(pp, 16); pp += __shfl_xor(pp, 32); if (fq == 0) unsafeAtomicAdd(ss + row0 + ai * HALF + m * 16, pp); } }
.LBB0_1024:
	s_or_b64 exec, exec, s[30:31]
	s_andn2_b64 vcc, exec, s[6:7]
	s_mov_b64 s[6:7], -1
	s_cbranch_vccnz .LBB0_997
	s_andn2_b64 vcc, exec, s[10:11]
	s_cbranch_vccnz .LBB0_996
	s_nop 0
	s_branch .LBB0_996

; #define PG8_STAGE(bufoff, gbase, voff) do { _Pragma("unroll") for (int _i = 0; _i < 2; ++_i) \
;         __builtin_amdgcn_global_load_lds((const unsigned*)((const char*)(gbase) + (voff)[_i]), (LAS unsigned*)(lds + (bufoff) + ldsw + _i * 8192), 16, 0, 0); } while (0)
; #define PG8_LDA(dst, b, h) do { _Pragma("unroll") for (int m = 0; m < 4; ++m) _Pragma("unroll") for (int k = 0; k < 2; ++k) dst[m][k] = *(const LAS bf16x8*)(lds + PG8_SA(b, h) + aoff + m * 2048 + k * 1024); } while (0)
; #define PG8_LDB(dst, b, h) do { _Pragma("unroll") for (int n = 0; n < 2; ++n) _Pragma("unroll") for (int k = 0; k < 2; ++k) dst[n][k] = *(const LAS bf16x8*)(lds + PG8_SB(b, h) + boff + n * 2048 + k * 1024); } while (0)
; #define PG8_MMA(ai, bj, At, Bt) do { __builtin_amdgcn_s_setprio(1); _Pragma("unroll") for (int m = 0; m < 4; ++m) _Pragma("unroll") for (int n = 0; n < 2; ++n) _Pragma("unroll") for (int k = 0; k < 2; ++k) \
;         acc[ai][bj][m][n] = __builtin_amdgcn_mfma_f32_16x16x32_bf16(Bt[n][k], At[m][k], acc[ai][bj][m][n], 0, 0, 0); __builtin_amdgcn_s_setprio(0); } while (0)
; #define PG8_WAIT_V(n) asm volatile("s_waitcnt vmcnt(" #n ")" ::: "memory")
; #define PG8_WAIT_L(n) asm volatile("s_waitcnt lgkmcnt(" #n ")" ::: "memory")
; #define PG8_BAR __builtin_amdgcn_s_barrier()
; #define PG8_SCHED __builtin_amdgcn_sched_barrier(0)
; template <class Epi, bool ALIGN_EPI>
; __device__ __forceinline__ void gemm_phase(LAS unsigned char* lds, const Gemm g, const StaticOrder& S, const Epi& E) {
;     ...
;         for (int t = 0; t < nt; t += 2) {
;             const bool last = (t == nt - 2);
;             const char* a1 = cA + (size_t)(t + 1) * kstep;
;             const char* a2 = last ? nA : cA + (size_t)(t + 2) * kstep; const char* b2 = last ? nB : cB + (size_t)(t + 2) * kstep;
;             const char* a3 = a2 + kstep; const char* b3 = b2 + kstep;
;             PG8_LDB(B0, 0, 0); PG8_LDB(B1, 0, 1); PG8_SCHED; PG8_LDA(At, 0, 0); PG8_STAGE(PG8_SA(1, 1), a1 + hA, voffA);
;             PG8_WAIT_V(8); PG8_WAIT_L(0); PG8_BAR; PG8_MMA(0, 0, At, B0); PG8_MMA(0, 1, At, B1); PG8_BAR; PG8_SCHED;
;             PG8_LDA(At, 0, 1); PG8_STAGE(PG8_SB(0, 0), b2, voffB); PG8_STAGE(PG8_SB(0, 1), b2 + hB, voffB); PG8_STAGE(PG8_SA(0, 0), a2, voffA);
;             PG8_WAIT_V(8); PG8_WAIT_L(0); PG8_BAR; PG8_MMA(1, 0, At, B0); PG8_MMA(1, 1, At, B1); PG8_BAR; PG8_SCHED;
.LBB0_1094:
	ds_read_b128 v[146:149], v153
	ds_read_b128 v[174:177], v153 offset:1024
	ds_read_b128 v[178:181], v153 offset:2048
	ds_read_b128 v[182:185], v153 offset:3072
	ds_read_b128 v[186:189], v154
	ds_read_b128 v[194:197], v154 offset:1024
	ds_read_b128 v[198:201], v154 offset:2048
	ds_read_b128 v[202:205], v154 offset:3072
	s_add_u32 s36, s4, 0xfff80080
	s_addc_u32 s37, s5, -1
	s_cmp_eq_u32 s38, 28
	s_cselect_b32 s45, s0, s37
	s_cselect_b32 s44, s1, s36
	s_cselect_b32 s37, s2, s29
	s_cselect_b32 s36, s3, s27
	v_lshl_add_u64 v[190:191], s[4:5], 0, v[136:137]
	s_add_i32 m0, s41, 0xc000
	ds_read_b128 v[206:209], v155
	ds_read_b128 v[210:213], v155 offset:1024
	ds_read_b128 v[214:217], v155 offset:2048
	ds_read_b128 v[218:221], v155 offset:3072
	ds_read_b128 v[222:225], v155 offset:4096
	ds_read_b128 v[226:229], v155 offset:5120
	ds_read_b128 v[230:233], v155 offset:6144
	ds_read_b128 v[234:237], v155 offset:7168
	global_load_lds_dwordx4 v[190:191], off
	v_lshl_add_u64 v[190:191], s[4:5], 0, v[138:139]
	s_add_i32 m0, s41, 0xe000
	s_nop 0
	global_load_lds_dwordx4 v[190:191], off
	s_waitcnt vmcnt(8)
	s_waitcnt lgkmcnt(0)
	s_barrier
	s_setprio 1
	s_waitcnt lgkmcnt(0)
	v_mfma_f32_16x16x32_bf16 v[124:127], v[146:149], v[206:209], v[124:127]
	v_mfma_f32_16x16x32_bf16 v[124:127], v[174:177], v[210:213], v[124:127]
	v_mfma_f32_16x16x32_bf16 v[120:123], v[178:181], v[206:209], v[120:123]
	v_mfma_f32_16x16x32_bf16 v[120:123], v[182:185], v[210:213], v[120:123]
	v_mfma_f32_16x16x32_bf16 v[108:111], v[146:149], v[214:217], v[108:111]
	v_mfma_f32_16x16x32_bf16 v[108:111], v[174:177], v[218:221], v[108:111]
	v_mfma_f32_16x16x32_bf16 v[104:107], v[178:181], v[214:217], v[104:107]
	v_mfma_f32_16x16x32_bf16 v[104:107], v[182:185], v[218:221], v[104:107]
	v_mfma_f32_16x16x32_bf16 v[92:95], v[146:149], v[222:225], v[92:95]
	v_mfma_f32_16x16x32_bf16 v[92:95], v[174:177], v[226:229], v[92:95]
	v_mfma_f32_16x16x32_bf16 v[88:91], v[178:181], v[222:225], v[88:91]
	v_mfma_f32_16x16x32_bf16 v[88:91], v[182:185], v[226:229], v[88:91]
	v_mfma_f32_16x16x32_bf16 v[76:79], v[146:149], v[230:233], v[76:79]
	v_mfma_f32_16x16x32_bf16 v[76:79], v[174:177], v[234:237], v[76:79]
	v_mfma_f32_16x16x32_bf16 v[72:75], v[178:181], v[230:233], v[72:75]
	v_mfma_f32_16x16x32_bf16 v[72:75], v[182:185], v[234:237], v[72:75]
	s_setprio 0
	s_setprio 1
	v_mfma_f32_16x16x32_bf16 v[116:119], v[186:189], v[206:209], v[116:119]
	v_mfma_f32_16x16x32_bf16 v[116:119], v[194:197], v[210:213], v[116:119]
	v_mfma_f32_16x16x32_bf16 v[112:115], v[198:201], v[206:209], v[112:115]
	v_mfma_f32_16x16x32_bf16 v[112:115], v[202:205], v[210:213], v[112:115]
	v_mfma_f32_16x16x32_bf16 v[100:103], v[186:189], v[214:217], v[100:103]
	v_mfma_f32_16x16x32_bf16 v[100:103], v[194:197], v[218:221], v[100:103]
	v_mfma_f32_16x16x32_bf16 v[96:99], v[198:201], v[214:217], v[96:99]
	v_mfma_f32_16x16x32_bf16 v[96:99], v[202:205], v[218:221], v[96:99]
	v_mfma_f32_16x16x32_bf16 v[84:87], v[186:189], v[222:225], v[84:87]
	v_mfma_f32_16x16x32_bf16 v[84:87], v[194:197], v[226:229], v[84:87]
	v_mfma_f32_16x16x32_bf16 v[80:83], v[198:201], v[222:225], v[80:83]
	v_mfma_f32_16x16x32_bf16 v[80:83], v[202:205], v[226:229], v[80:83]
	v_mfma_f32_16x16x32_bf16 v[68:71], v[186:189], v[230:233], v[68:71]
	v_mfma_f32_16x16x32_bf16 v[68:71], v[194:197], v[234:237], v[68:71]
	v_mfma_f32_16x16x32_bf16 v[64:67], v[198:201], v[230:233], v[64:67]
	v_mfma_f32_16x16x32_bf16 v[64:67], v[202:205], v[234:237], v[64:67]
	s_setprio 0
	s_barrier
	s_add_i32 s39, s61, s51
	v_lshl_add_u64 v[190:191], s[36:37], 0, v[130:131]
	s_mov_b32 m0, s39
	ds_read_b128 v[206:209], v155 offset:16384
	ds_read_b128 v[210:213], v155 offset:17408
	ds_read_b128 v[214:217], v155 offset:18432
	ds_read_b128 v[218:221], v155 offset:19456
	ds_read_b128 v[222:225], v155 offset:20480
	ds_read_b128 v[226:229], v155 offset:21504
	ds_read_b128 v[230:233], v155 offset:22528
	ds_read_b128 v[234:237], v155 offset:23552
	global_load_lds_dwordx4 v[190:191], off
	s_add_i32 m0, s39, 0x2000
	s_add_u32 s46, s36, 0x80000
	v_lshl_add_u64 v[238:239], s[36:37], 0, v[134:135]
	s_addc_u32 s47, s37, 0
	s_add_i32 s39, s62, s51
	global_load_lds_dwordx4 v[238:239], off
	v_lshl_add_u64 v[240:241], s[46:47], 0, v[130:131]
	s_mov_b32 m0, s39
	v_lshl_add_u64 v[242:243], s[44:45], 0, v[132:133]
	global_load_lds_dwordx4 v[240:241], off
	v_lshl_add_u64 v[240:241], s[46:47], 0, v[134:135]
	s_add_i32 m0, s39, 0x2000
	s_nop 0
	global_load_lds_dwordx4 v[240:241], off
	v_lshl_add_u64 v[240:241], s[44:45], 0, v[128:129]
	s_mov_b32 m0, s41
	s_nop 0
	global_load_lds_dwordx4 v[240:241], off
	s_mov_b32 m0, s43
	s_nop 0
	global_load_lds_dwordx4 v[242:243], off
	s_waitcnt vmcnt(8)
	s_waitcnt lgkmcnt(0)
	s_barrier
; #define PG8_STAGE(bufoff, gbase, voff) do { _Pragma("unroll") for (int _i = 0; _i < 2; ++_i) \
;         __builtin_amdgcn_global_load_lds((const unsigned*)((const char*)(gbase) + (voff)[_i]), (LAS unsigned*)(lds + (bufoff) + ldsw + _i * 8192), 16, 0, 0); } while (0)
; #define PG8_LDA(dst, b, h) do { _Pragma("unroll") for (int m = 0; m < 4; ++m) _Pragma("unroll") for (int k = 0; k < 2; ++k) dst[m][k] = *(const LAS bf16x8*)(lds + PG8_SA(b, h) + aoff + m * 2048 + k * 1024); } while (0)
; #define PG8_LDB(dst, b, h) do { _Pragma("unroll") for (int n = 0; n < 2; ++n) _Pragma("unroll") for (int k = 0; k < 2; ++k) dst[n][k] = *(const LAS bf16x8*)(lds + PG8_SB(b, h) + boff + n * 2048 + k * 1024); } while (0)
; #define PG8_MMA(ai, bj, At, Bt) do { __builtin_amdgcn_s_setprio(1); _Pragma("unroll") for (int m = 0; m < 4; ++m) _Pragma("unroll") for (int n = 0; n < 2; ++n) _Pragma("unroll") for (int k = 0; k < 2; ++k) \
;         acc[ai][bj][m][n] = __builtin_amdgcn_mfma_f32_16x16x32_bf16(Bt[n][k], At[m][k], acc[ai][bj][m][n], 0, 0, 0); __builtin_amdgcn_s_setprio(0); } while (0)
; #define PG8_WAIT_V(n) asm volatile("s_waitcnt vmcnt(" #n ")" ::: "memory")
; #define PG8_WAIT_L(n) asm volatile("s_waitcnt lgkmcnt(" #n ")" ::: "memory")
; #define PG8_BAR __builtin_amdgcn_s_barrier()
; #define PG8_SCHED __builtin_amdgcn_sched_barrier(0)
; template <class Epi, bool ALIGN_EPI>
; __device__ __forceinline__ void gemm_phase(LAS unsigned char* lds, const Gemm g, const StaticOrder& S, const Epi& E) {
;     ...
;             PG8_WAIT_V(8); PG8_WAIT_L(0); PG8_BAR; PG8_MMA(1, 0, At, B0); PG8_MMA(1, 1, At, B1); PG8_BAR; PG8_SCHED;
;             PG8_LDB(B0, 1, 0); PG8_LDB(B1, 1, 1); PG8_SCHED; PG8_LDA(At, 1, 0); PG8_STAGE(PG8_SA(0, 1), a2 + hA, voffA);
;             PG8_WAIT_V(8); PG8_WAIT_L(0); PG8_BAR; PG8_MMA(0, 0, At, B0); PG8_MMA(0, 1, At, B1); PG8_BAR; PG8_SCHED;
	s_setprio 1
	s_waitcnt lgkmcnt(0)
	v_mfma_f32_16x16x32_bf16 v[60:63], v[146:149], v[206:209], v[60:63]
	v_mfma_f32_16x16x32_bf16 v[60:63], v[174:177], v[210:213], v[60:63]
	v_mfma_f32_16x16x32_bf16 v[56:59], v[178:181], v[206:209], v[56:59]
	v_mfma_f32_16x16x32_bf16 v[56:59], v[182:185], v[210:213], v[56:59]
	v_mfma_f32_16x16x32_bf16 v[44:47], v[146:149], v[214:217], v[44:47]
	v_mfma_f32_16x16x32_bf16 v[44:47], v[174:177], v[218:221], v[44:47]
	v_mfma_f32_16x16x32_bf16 v[40:43], v[178:181], v[214:217], v[40:43]
	v_mfma_f32_16x16x32_bf16 v[40:43], v[182:185], v[218:221], v[40:43]
	v_mfma_f32_16x16x32_bf16 v[28:31], v[146:149], v[222:225], v[28:31]
	v_mfma_f32_16x16x32_bf16 v[28:31], v[174:177], v[226:229], v[28:31]
	v_mfma_f32_16x16x32_bf16 v[24:27], v[178:181], v[222:225], v[24:27]
	v_mfma_f32_16x16x32_bf16 v[24:27], v[182:185], v[226:229], v[24:27]
	v_mfma_f32_16x16x32_bf16 v[12:15], v[146:149], v[230:233], v[12:15]
	v_mfma_f32_16x16x32_bf16 v[12:15], v[174:177], v[234:237], v[12:15]
	v_mfma_f32_16x16x32_bf16 v[8:11], v[178:181], v[230:233], v[8:11]
	v_mfma_f32_16x16x32_bf16 v[8:11], v[182:185], v[234:237], v[8:11]
	s_setprio 0
	s_setprio 1
	v_mfma_f32_16x16x32_bf16 v[52:55], v[186:189], v[206:209], v[52:55]
	v_mfma_f32_16x16x32_bf16 v[52:55], v[194:197], v[210:213], v[52:55]
	v_mfma_f32_16x16x32_bf16 v[48:51], v[198:201], v[206:209], v[48:51]
	v_mfma_f32_16x16x32_bf16 v[48:51], v[202:205], v[210:213], v[48:51]
	v_mfma_f32_16x16x32_bf16 v[36:39], v[186:189], v[214:217], v[36:39]
	v_mfma_f32_16x16x32_bf16 v[36:39], v[194:197], v[218:221], v[36:39]
	v_mfma_f32_16x16x32_bf16 v[32:35], v[198:201], v[214:217], v[32:35]
	v_mfma_f32_16x16x32_bf16 v[32:35], v[202:205], v[218:221], v[32:35]
	v_mfma_f32_16x16x32_bf16 v[20:23], v[186:189], v[222:225], v[20:23]
	v_mfma_f32_16x16x32_bf16 v[20:23], v[194:197], v[226:229], v[20:23]
	v_mfma_f32_16x16x32_bf16 v[16:19], v[198:201], v[222:225], v[16:19]
	v_mfma_f32_16x16x32_bf16 v[16:19], v[202:205], v[226:229], v[16:19]
	v_mfma_f32_16x16x32_bf16 v[4:7], v[186:189], v[230:233], v[4:7]
	v_mfma_f32_16x16x32_bf16 v[4:7], v[194:197], v[234:237], v[4:7]
	v_mfma_f32_16x16x32_bf16 v[0:3], v[198:201], v[230:233], v[0:3]
	v_mfma_f32_16x16x32_bf16 v[0:3], v[202:205], v[234:237], v[0:3]
	s_setprio 0
	s_barrier
	s_add_i32 s39, 0, 0x18000
	v_add_u32_e32 v145, s39, v151
	s_add_i32 s46, 0, 0x1c000
	ds_read_b128 v[146:149], v145
	ds_read_b128 v[174:177], v145 offset:1024
	ds_read_b128 v[178:181], v145 offset:2048
	ds_read_b128 v[182:185], v145 offset:3072
	v_add_u32_e32 v145, s46, v151
	ds_read_b128 v[186:189], v145
	ds_read_b128 v[194:197], v145 offset:1024
	ds_read_b128 v[198:201], v145 offset:2048
	ds_read_b128 v[202:205], v145 offset:3072
	s_add_u32 s44, s44, 0x80000
	s_addc_u32 s45, s45, 0
	s_mov_b32 m0, s52
	v_lshl_add_u64 v[244:245], s[44:45], 0, v[128:129]
	ds_read_b128 v[206:209], v155 offset:32768
	ds_read_b128 v[210:213], v155 offset:33792
	ds_read_b128 v[214:217], v155 offset:34816
	ds_read_b128 v[218:221], v155 offset:35840
	ds_read_b128 v[222:225], v155 offset:36864
	ds_read_b128 v[226:229], v155 offset:37888
	ds_read_b128 v[230:233], v155 offset:38912
	ds_read_b128 v[234:237], v155 offset:39936
	global_load_lds_dwordx4 v[244:245], off
	v_lshl_add_u64 v[244:245], s[44:45], 0, v[132:133]
	s_mov_b32 m0, s53
	s_nop 0
	global_load_lds_dwordx4 v[244:245], off
	s_waitcnt vmcnt(8)
	s_waitcnt lgkmcnt(0)
	s_barrier
	s_setprio 1
	s_waitcnt lgkmcnt(0)
	v_mfma_f32_16x16x32_bf16 v[124:127], v[146:149], v[206:209], v[124:127]
	v_mfma_f32_16x16x32_bf16 v[124:127], v[174:177], v[210:213], v[124:127]
	v_mfma_f32_16x16x32_bf16 v[120:123], v[178:181], v[206:209], v[120:123]
	v_mfma_f32_16x16x32_bf16 v[120:123], v[182:185], v[210:213], v[120:123]
	v_mfma_f32_16x16x32_bf16 v[108:111], v[146:149], v[214:217], v[108:111]
	v_mfma_f32_16x16x32_bf16 v[108:111], v[174:177], v[218:221], v[108:111]
	v_mfma_f32_16x16x32_bf16 v[104:107], v[178:181], v[214:217], v[104:107]
	v_mfma_f32_16x16x32_bf16 v[104:107], v[182:185], v[218:221], v[104:107]
	v_mfma_f32_16x16x32_bf16 v[92:95], v[146:149], v[222:225], v[92:95]
	v_mfma_f32_16x16x32_bf16 v[92:95], v[174:177], v[226:229], v[92:95]
	v_mfma_f32_16x16x32_bf16 v[88:91], v[178:181], v[222:225], v[88:91]
	v_mfma_f32_16x16x32_bf16 v[88:91], v[182:185], v[226:229], v[88:91]
	v_mfma_f32_16x16x32_bf16 v[76:79], v[146:149], v[230:233], v[76:79]
	v_mfma_f32_16x16x32_bf16 v[76:79], v[174:177], v[234:237], v[76:79]
	v_mfma_f32_16x16x32_bf16 v[72:75], v[178:181], v[230:233], v[72:75]
	v_mfma_f32_16x16x32_bf16 v[72:75], v[182:185], v[234:237], v[72:75]
	s_setprio 0
	s_setprio 1
	v_mfma_f32_16x16x32_bf16 v[116:119], v[186:189], v[206:209], v[116:119]
	v_mfma_f32_16x16x32_bf16 v[116:119], v[194:197], v[210:213], v[116:119]
	v_mfma_f32_16x16x32_bf16 v[112:115], v[198:201], v[206:209], v[112:115]
	v_mfma_f32_16x16x32_bf16 v[112:115], v[202:205], v[210:213], v[112:115]
	v_mfma_f32_16x16x32_bf16 v[100:103], v[186:189], v[214:217], v[100:103]
	v_mfma_f32_16x16x32_bf16 v[100:103], v[194:197], v[218:221], v[100:103]
	v_mfma_f32_16x16x32_bf16 v[96:99], v[198:201], v[214:217], v[96:99]
	v_mfma_f32_16x16x32_bf16 v[96:99], v[202:205], v[218:221], v[96:99]
	v_mfma_f32_16x16x32_bf16 v[84:87], v[186:189], v[222:225], v[84:87]
	v_mfma_f32_16x16x32_bf16 v[84:87], v[194:197], v[226:229], v[84:87]
	v_mfma_f32_16x16x32_bf16 v[80:83], v[198:201], v[222:225], v[80:83]
	v_mfma_f32_16x16x32_bf16 v[80:83], v[202:205], v[226:229], v[80:83]
	v_mfma_f32_16x16x32_bf16 v[68:71], v[186:189], v[230:233], v[68:71]
	v_mfma_f32_16x16x32_bf16 v[68:71], v[194:197], v[234:237], v[68:71]
	v_mfma_f32_16x16x32_bf16 v[64:67], v[198:201], v[230:233], v[64:67]
	v_mfma_f32_16x16x32_bf16 v[64:67], v[202:205], v[234:237], v[64:67]
	s_setprio 0
	s_barrier
; #define PG8_STAGE(bufoff, gbase, voff) do { _Pragma("unroll") for (int _i = 0; _i < 2; ++_i) \
;         __builtin_amdgcn_global_load_lds((const unsigned*)((const char*)(gbase) + (voff)[_i]), (LAS unsigned*)(lds + (bufoff) + ldsw + _i * 8192), 16, 0, 0); } while (0)
; #define PG8_LDA(dst, b, h) do { _Pragma("unroll") for (int m = 0; m < 4; ++m) _Pragma("unroll") for (int k = 0; k < 2; ++k) dst[m][k] = *(const LAS bf16x8*)(lds + PG8_SA(b, h) + aoff + m * 2048 + k * 1024); } while (0)
; #define PG8_MMA(ai, bj, At, Bt) do { __builtin_amdgcn_s_setprio(1); _Pragma("unroll") for (int m = 0; m < 4; ++m) _Pragma("unroll") for (int n = 0; n < 2; ++n) _Pragma("unroll") for (int k = 0; k < 2; ++k) \
;         acc[ai][bj][m][n] = __builtin_amdgcn_mfma_f32_16x16x32_bf16(Bt[n][k], At[m][k], acc[ai][bj][m][n], 0, 0, 0); __builtin_amdgcn_s_setprio(0); } while (0)
; #define PG8_WAIT_V(n) asm volatile("s_waitcnt vmcnt(" #n ")" ::: "memory")
; #define PG8_WAIT_L(n) asm volatile("s_waitcnt lgkmcnt(" #n ")" ::: "memory")
; #define PG8_BAR __builtin_amdgcn_s_barrier()
; #define PG8_SCHED __builtin_amdgcn_sched_barrier(0)
; template <class Epi, bool ALIGN_EPI>
; __device__ __forceinline__ void gemm_phase(LAS unsigned char* lds, const Gemm g, const StaticOrder& S, const Epi& E) {
;     ...
;             PG8_LDA(At, 1, 1); PG8_STAGE(PG8_SB(1, 0), b3, voffB); PG8_STAGE(PG8_SB(1, 1), b3 + hB, voffB); PG8_STAGE(PG8_SA(1, 0), a3, voffA);
;             PG8_WAIT_V(8); PG8_WAIT_L(0); PG8_BAR; PG8_MMA(1, 0, At, B0); PG8_MMA(1, 1, At, B1); PG8_BAR; PG8_SCHED;
;         }
;         if constexpr (ALIGN_EPI) { if (wr == 0) PG8_BAR; }
	s_add_i32 s39, s39, s51
	v_lshl_add_u64 v[190:191], v[190:191], 0, s[20:21]
	s_mov_b32 m0, s39
	ds_read_b128 v[206:209], v155 offset:49152
	ds_read_b128 v[210:213], v155 offset:50176
	ds_read_b128 v[214:217], v155 offset:51200
	ds_read_b128 v[218:221], v155 offset:52224
	ds_read_b128 v[222:225], v155 offset:53248
	ds_read_b128 v[226:229], v155 offset:54272
	ds_read_b128 v[230:233], v155 offset:55296
	ds_read_b128 v[234:237], v155 offset:56320
	global_load_lds_dwordx4 v[190:191], off
	s_add_i32 m0, s39, 0x2000
	s_add_u32 s36, s36, 0x80080
	v_lshl_add_u64 v[190:191], v[238:239], 0, s[20:21]
	s_addc_u32 s37, s37, 0
	s_add_i32 s39, s46, s51
	global_load_lds_dwordx4 v[190:191], off
	v_lshl_add_u64 v[190:191], s[36:37], 0, v[130:131]
	s_mov_b32 m0, s39
	s_nop 0
	global_load_lds_dwordx4 v[190:191], off
	v_lshl_add_u64 v[190:191], s[36:37], 0, v[134:135]
	s_add_i32 m0, s39, 0x2000
	s_nop 0
	global_load_lds_dwordx4 v[190:191], off
	v_lshl_add_u64 v[190:191], v[240:241], 0, s[20:21]
	s_mov_b32 m0, s57
	s_nop 0
	global_load_lds_dwordx4 v[190:191], off
	v_lshl_add_u64 v[190:191], v[242:243], 0, s[20:21]
	s_mov_b32 m0, s58
	s_nop 0
	global_load_lds_dwordx4 v[190:191], off
	s_waitcnt vmcnt(8)
	s_waitcnt lgkmcnt(0)
	s_barrier
	s_setprio 1
	s_waitcnt lgkmcnt(0)
	v_mfma_f32_16x16x32_bf16 v[60:63], v[146:149], v[206:209], v[60:63]
	v_mfma_f32_16x16x32_bf16 v[60:63], v[174:177], v[210:213], v[60:63]
	v_mfma_f32_16x16x32_bf16 v[56:59], v[178:181], v[206:209], v[56:59]
	v_mfma_f32_16x16x32_bf16 v[56:59], v[182:185], v[210:213], v[56:59]
	v_mfma_f32_16x16x32_bf16 v[44:47], v[146:149], v[214:217], v[44:47]
	v_mfma_f32_16x16x32_bf16 v[44:47], v[174:177], v[218:221], v[44:47]
	v_mfma_f32_16x16x32_bf16 v[40:43], v[178:181], v[214:217], v[40:43]
	v_mfma_f32_16x16x32_bf16 v[40:43], v[182:185], v[218:221], v[40:43]
	v_mfma_f32_16x16x32_bf16 v[28:31], v[146:149], v[222:225], v[28:31]
	v_mfma_f32_16x16x32_bf16 v[28:31], v[174:177], v[226:229], v[28:31]
	v_mfma_f32_16x16x32_bf16 v[24:27], v[178:181], v[222:225], v[24:27]
	v_mfma_f32_16x16x32_bf16 v[24:27], v[182:185], v[226:229], v[24:27]
	v_mfma_f32_16x16x32_bf16 v[12:15], v[146:149], v[230:233], v[12:15]
	v_mfma_f32_16x16x32_bf16 v[12:15], v[174:177], v[234:237], v[12:15]
	v_mfma_f32_16x16x32_bf16 v[8:11], v[178:181], v[230:233], v[8:11]
	v_mfma_f32_16x16x32_bf16 v[8:11], v[182:185], v[234:237], v[8:11]
	s_setprio 0
	s_setprio 1
	v_mfma_f32_16x16x32_bf16 v[52:55], v[186:189], v[206:209], v[52:55]
	v_mfma_f32_16x16x32_bf16 v[52:55], v[194:197], v[210:213], v[52:55]
	v_mfma_f32_16x16x32_bf16 v[48:51], v[198:201], v[206:209], v[48:51]
	v_mfma_f32_16x16x32_bf16 v[48:51], v[202:205], v[210:213], v[48:51]
	v_mfma_f32_16x16x32_bf16 v[36:39], v[186:189], v[214:217], v[36:39]
	v_mfma_f32_16x16x32_bf16 v[36:39], v[194:197], v[218:221], v[36:39]
	v_mfma_f32_16x16x32_bf16 v[32:35], v[198:201], v[214:217], v[32:35]
	v_mfma_f32_16x16x32_bf16 v[32:35], v[202:205], v[218:221], v[32:35]
	v_mfma_f32_16x16x32_bf16 v[20:23], v[186:189], v[222:225], v[20:23]
	v_mfma_f32_16x16x32_bf16 v[20:23], v[194:197], v[226:229], v[20:23]
	v_mfma_f32_16x16x32_bf16 v[16:19], v[198:201], v[222:225], v[16:19]
	v_mfma_f32_16x16x32_bf16 v[16:19], v[202:205], v[226:229], v[16:19]
	v_mfma_f32_16x16x32_bf16 v[4:7], v[186:189], v[230:233], v[4:7]
	v_mfma_f32_16x16x32_bf16 v[4:7], v[194:197], v[234:237], v[4:7]
	v_mfma_f32_16x16x32_bf16 v[0:3], v[198:201], v[230:233], v[0:3]
	v_mfma_f32_16x16x32_bf16 v[0:3], v[202:205], v[234:237], v[0:3]
	s_setprio 0
	s_barrier
	s_add_i32 s38, s38, 2
	s_add_u32 s4, s4, 0x100
	s_addc_u32 s5, s5, 0
	s_add_u32 s27, s27, 0x100
	s_addc_u32 s29, s29, 0
	s_cmp_gt_u32 s38, 29
	s_cbranch_scc0 .LBB0_1094
	s_and_b64 vcc, exec, s[22:23]
	s_cbranch_vccz .LBB0_1097
	s_nop 0

; __device__ __forceinline__ unsigned cvt_pk_bf16(float lo, float hi) { unsigned r; asm volatile("v_cvt_pk_bf16_f32 %0, %1, %2" : "=v"(r) : "v"(lo), "v"(hi)); return r; }
; #define PG8_BAR __builtin_amdgcn_s_barrier()
;     __device__ __forceinline__ void post(int ui, const float (&r)[8]) const { const int t = my_tid(); if (t < 384) cbuf[(ui & 1) * 384 + t] = r[0]; }
; template <class Epi, bool ALIGN_EPI>
; __device__ __forceinline__ void gemm_phase(LAS unsigned char* lds, const Gemm g, const StaticOrder& S, const Epi& E) {
;     ...
;         if (!has_next) break;
;         E.post(ui + 1, rsn);
; #pragma unroll
;         for (int a = 0; a < 2; ++a)
; #pragma unroll
;             for (int b = 0; b < 2; ++b)
; #pragma unroll
;                 for (int m = 0; m < 4; ++m)
; #pragma unroll
;                     for (int n = 0; n < 2; ++n) acc[a][b][m][n] = (f32x4){0.f, 0.f, 0.f, 0.f};
;         cur = nxt; cA = nA; cB = nB; ++ui;
; #pragma unroll
;         for (int i_ = 0; i_ < 8; ++i_) rsv[i_] = rsn[i_];
;         if constexpr (ALIGN_EPI) { if (wr == 1) PG8_BAR; }
;     __device__ __forceinline__ void operator()(const f32x4 (&acc)[2][2][4][2], const Unit& u, int wr, int wc, int fr, int fq, int, const float (&rsv_)[8]) const {
;     ...
;                     u32x4 w; w.x = cvt_pk_bf16(v0[0], v0[1]); w.y = cvt_pk_bf16(v0[2], v0[3]); w.z = cvt_pk_bf16(v1[0], v1[1]); w.w = cvt_pk_bf16(v1[2], v1[3]);
;                     { u32x4* dp_ = (u32x4*)(rowp + bj * HALF); asm volatile("global_store_dwordx4 %0, %1, off sc1\n\ts_nop 1" :: "v"(dp_), "v"(w) : "memory"); } } }
.LBB0_1138:
	v_cvt_pk_bf16_f32 v4, v4, v5
	v_cvt_pk_bf16_f32 v5, v6, v7
	v_cvt_pk_bf16_f32 v6, v0, v1
	v_cvt_pk_bf16_f32 v7, v2, v3
	v_lshl_add_u64 v[0:1], v[8:9], 0, s[24:25]
	global_store_dwordx4 v[0:1], v[4:7], off sc1
	s_nop 1
	s_and_b64 vcc, exec, s[4:5]
	s_mov_b64 s[4:5], -1
	s_cbranch_vccnz .LBB0_1090
	s_andn2_b64 vcc, exec, s[12:13]
	s_cbranch_vccnz .LBB0_1089
	s_nop 0
	s_branch .LBB0_1089

; #define PG8_STAGE(bufoff, gbase, voff) do { _Pragma("unroll") for (int _i = 0; _i < 2; ++_i) \
;         __builtin_amdgcn_global_load_lds((const unsigned*)((const char*)(gbase) + (voff)[_i]), (LAS unsigned*)(lds + (bufoff) + ldsw + _i * 8192), 16, 0, 0); } while (0)
; #define PG8_LDA(dst, b, h) do { _Pragma("unroll") for (int m = 0; m < 4; ++m) _Pragma("unroll") for (int k = 0; k < 2; ++k) dst[m][k] = *(const LAS bf16x8*)(lds + PG8_SA(b, h) + aoff + m * 2048 + k * 1024); } while (0)
; #define PG8_LDB(dst, b, h) do { _Pragma("unroll") for (int n = 0; n < 2; ++n) _Pragma("unroll") for (int k = 0; k < 2; ++k) dst[n][k] = *(const LAS bf16x8*)(lds + PG8_SB(b, h) + boff + n * 2048 + k * 1024); } while (0)
; #define PG8_MMA(ai, bj, At, Bt) do { __builtin_amdgcn_s_setprio(1); _Pragma("unroll") for (int m = 0; m < 4; ++m) _Pragma("unroll") for (int n = 0; n < 2; ++n) _Pragma("unroll") for (int k = 0; k < 2; ++k) \
;         acc[ai][bj][m][n] = __builtin_amdgcn_mfma_f32_16x16x32_bf16(Bt[n][k], At[m][k], acc[ai][bj][m][n], 0, 0, 0); __builtin_amdgcn_s_setprio(0); } while (0)
; #define PG8_WAIT_V(n) asm volatile("s_waitcnt vmcnt(" #n ")" ::: "memory")
; #define PG8_WAIT_L(n) asm volatile("s_waitcnt lgkmcnt(" #n ")" ::: "memory")
; #define PG8_BAR __builtin_amdgcn_s_barrier()
; #define PG8_SCHED __builtin_amdgcn_sched_barrier(0)
; template <class Epi, bool ALIGN_EPI>
; __device__ __forceinline__ void gemm_phase(LAS unsigned char* lds, const Gemm g, const StaticOrder& S, const Epi& E) {
;     ...
;         for (int t = 0; t < nt; t += 2) {
;             const bool last = (t == nt - 2);
;             const char* a1 = cA + (size_t)(t + 1) * kstep;
;             const char* a2 = last ? nA : cA + (size_t)(t + 2) * kstep; const char* b2 = last ? nB : cB + (size_t)(t + 2) * kstep;
;             const char* a3 = a2 + kstep; const char* b3 = b2 + kstep;
;             PG8_LDB(B0, 0, 0); PG8_LDB(B1, 0, 1); PG8_SCHED; PG8_LDA(At, 0, 0); PG8_STAGE(PG8_SA(1, 1), a1 + hA, voffA);
;             PG8_WAIT_V(8); PG8_WAIT_L(0); PG8_BAR; PG8_MMA(0, 0, At, B0); PG8_MMA(0, 1, At, B1); PG8_BAR; PG8_SCHED;
;             PG8_LDA(At, 0, 1); PG8_STAGE(PG8_SB(0, 0), b2, voffB); PG8_STAGE(PG8_SB(0, 1), b2 + hB, voffB); PG8_STAGE(PG8_SA(0, 0), a2, voffA);
;             PG8_WAIT_V(8); PG8_WAIT_L(0); PG8_BAR; PG8_MMA(1, 0, At, B0); PG8_MMA(1, 1, At, B1); PG8_BAR; PG8_SCHED;
.LBB0_1585:
	ds_read_b128 v[128:131], v175
	ds_read_b128 v[132:135], v175 offset:1024
	ds_read_b128 v[136:139], v175 offset:2048
	ds_read_b128 v[140:143], v175 offset:3072
	ds_read_b128 v[160:163], v176
	ds_read_b128 v[164:167], v176 offset:1024
	ds_read_b128 v[168:171], v176 offset:2048
	ds_read_b128 v[180:183], v176 offset:3072
	s_add_u32 s40, s36, 0xfff80080
	s_addc_u32 s41, s37, -1
	s_cmp_eq_u32 s57, 28
	s_cselect_b32 s43, s25, s41
	s_cselect_b32 s42, s31, s40
	s_cselect_b32 s41, s23, s56
	s_cselect_b32 s40, s54, s55
	v_lshl_add_u64 v[218:219], s[36:37], 0, v[152:153]
	s_add_i32 m0, s35, 0xc000
	ds_read_b128 v[184:187], v177
	ds_read_b128 v[188:191], v177 offset:1024
	ds_read_b128 v[194:197], v177 offset:2048
	ds_read_b128 v[198:201], v177 offset:3072
	ds_read_b128 v[202:205], v177 offset:4096
	ds_read_b128 v[206:209], v177 offset:5120
	ds_read_b128 v[210:213], v177 offset:6144
	ds_read_b128 v[214:217], v177 offset:7168
	global_load_lds_dwordx4 v[218:219], off
	v_lshl_add_u64 v[218:219], s[36:37], 0, v[154:155]
	s_add_i32 m0, s35, 0xe000
	s_nop 0
	global_load_lds_dwordx4 v[218:219], off
	s_waitcnt vmcnt(8)
	s_waitcnt lgkmcnt(0)
	s_barrier
	s_setprio 1
	s_waitcnt lgkmcnt(0)
	v_mfma_f32_16x16x32_bf16 v[124:127], v[128:131], v[184:187], v[124:127]
	v_mfma_f32_16x16x32_bf16 v[124:127], v[132:135], v[188:191], v[124:127]
	v_mfma_f32_16x16x32_bf16 v[120:123], v[136:139], v[184:187], v[120:123]
	v_mfma_f32_16x16x32_bf16 v[120:123], v[140:143], v[188:191], v[120:123]
	v_mfma_f32_16x16x32_bf16 v[112:115], v[128:131], v[194:197], v[112:115]
	v_mfma_f32_16x16x32_bf16 v[112:115], v[132:135], v[198:201], v[112:115]
	v_mfma_f32_16x16x32_bf16 v[104:107], v[136:139], v[194:197], v[104:107]
	v_mfma_f32_16x16x32_bf16 v[104:107], v[140:143], v[198:201], v[104:107]
	v_mfma_f32_16x16x32_bf16 v[92:95], v[128:131], v[202:205], v[92:95]
	v_mfma_f32_16x16x32_bf16 v[92:95], v[132:135], v[206:209], v[92:95]
	v_mfma_f32_16x16x32_bf16 v[88:91], v[136:139], v[202:205], v[88:91]
	v_mfma_f32_16x16x32_bf16 v[88:91], v[140:143], v[206:209], v[88:91]
	v_mfma_f32_16x16x32_bf16 v[76:79], v[128:131], v[210:213], v[76:79]
	v_mfma_f32_16x16x32_bf16 v[76:79], v[132:135], v[214:217], v[76:79]
	v_mfma_f32_16x16x32_bf16 v[72:75], v[136:139], v[210:213], v[72:75]
	v_mfma_f32_16x16x32_bf16 v[72:75], v[140:143], v[214:217], v[72:75]
	s_setprio 0
	s_setprio 1
	v_mfma_f32_16x16x32_bf16 v[116:119], v[160:163], v[184:187], v[116:119]
	v_mfma_f32_16x16x32_bf16 v[116:119], v[164:167], v[188:191], v[116:119]
	v_mfma_f32_16x16x32_bf16 v[108:111], v[168:171], v[184:187], v[108:111]
	v_mfma_f32_16x16x32_bf16 v[108:111], v[180:183], v[188:191], v[108:111]
	v_mfma_f32_16x16x32_bf16 v[100:103], v[160:163], v[194:197], v[100:103]
	v_mfma_f32_16x16x32_bf16 v[100:103], v[164:167], v[198:201], v[100:103]
	v_mfma_f32_16x16x32_bf16 v[96:99], v[168:171], v[194:197], v[96:99]
	v_mfma_f32_16x16x32_bf16 v[96:99], v[180:183], v[198:201], v[96:99]
	v_mfma_f32_16x16x32_bf16 v[84:87], v[160:163], v[202:205], v[84:87]
	v_mfma_f32_16x16x32_bf16 v[84:87], v[164:167], v[206:209], v[84:87]
	v_mfma_f32_16x16x32_bf16 v[80:83], v[168:171], v[202:205], v[80:83]
	v_mfma_f32_16x16x32_bf16 v[80:83], v[180:183], v[206:209], v[80:83]
	v_mfma_f32_16x16x32_bf16 v[68:71], v[160:163], v[210:213], v[68:71]
	v_mfma_f32_16x16x32_bf16 v[68:71], v[164:167], v[214:217], v[68:71]
	v_mfma_f32_16x16x32_bf16 v[64:67], v[168:171], v[210:213], v[64:67]
	v_mfma_f32_16x16x32_bf16 v[64:67], v[180:183], v[214:217], v[64:67]
	s_setprio 0
	s_barrier
	s_add_i32 s58, s51, s33
	v_lshl_add_u64 v[218:219], s[40:41], 0, v[146:147]
	s_mov_b32 m0, s58
	ds_read_b128 v[184:187], v177 offset:16384
	ds_read_b128 v[188:191], v177 offset:17408
	ds_read_b128 v[194:197], v177 offset:18432
	ds_read_b128 v[198:201], v177 offset:19456
	ds_read_b128 v[202:205], v177 offset:20480
	ds_read_b128 v[206:209], v177 offset:21504
	ds_read_b128 v[210:213], v177 offset:22528
	ds_read_b128 v[214:217], v177 offset:23552
	global_load_lds_dwordx4 v[218:219], off
	s_add_i32 m0, s58, 0x2000
	s_add_u32 s58, s40, 0x80000
	v_lshl_add_u64 v[220:221], s[40:41], 0, v[150:151]
	s_addc_u32 s59, s41, 0
	s_add_i32 s60, s52, s33
	global_load_lds_dwordx4 v[220:221], off
	v_lshl_add_u64 v[222:223], s[58:59], 0, v[146:147]
	s_mov_b32 m0, s60
	v_lshl_add_u64 v[224:225], s[42:43], 0, v[148:149]
	global_load_lds_dwordx4 v[222:223], off
	v_lshl_add_u64 v[222:223], s[58:59], 0, v[150:151]
	s_add_i32 m0, s60, 0x2000
	s_nop 0
	global_load_lds_dwordx4 v[222:223], off
	v_lshl_add_u64 v[222:223], s[42:43], 0, v[144:145]
	s_mov_b32 m0, s35
	s_nop 0
	global_load_lds_dwordx4 v[222:223], off
	s_mov_b32 m0, s38
	s_nop 0
	global_load_lds_dwordx4 v[224:225], off
	s_waitcnt vmcnt(8)
	s_waitcnt lgkmcnt(0)
	s_barrier
; #define PG8_STAGE(bufoff, gbase, voff) do { _Pragma("unroll") for (int _i = 0; _i < 2; ++_i) \
;         __builtin_amdgcn_global_load_lds((const unsigned*)((const char*)(gbase) + (voff)[_i]), (LAS unsigned*)(lds + (bufoff) + ldsw + _i * 8192), 16, 0, 0); } while (0)
; #define PG8_LDA(dst, b, h) do { _Pragma("unroll") for (int m = 0; m < 4; ++m) _Pragma("unroll") for (int k = 0; k < 2; ++k) dst[m][k] = *(const LAS bf16x8*)(lds + PG8_SA(b, h) + aoff + m * 2048 + k * 1024); } while (0)
; #define PG8_LDB(dst, b, h) do { _Pragma("unroll") for (int n = 0; n < 2; ++n) _Pragma("unroll") for (int k = 0; k < 2; ++k) dst[n][k] = *(const LAS bf16x8*)(lds + PG8_SB(b, h) + boff + n * 2048 + k * 1024); } while (0)
; #define PG8_MMA(ai, bj, At, Bt) do { __builtin_amdgcn_s_setprio(1); _Pragma("unroll") for (int m = 0; m < 4; ++m) _Pragma("unroll") for (int n = 0; n < 2; ++n) _Pragma("unroll") for (int k = 0; k < 2; ++k) \
;         acc[ai][bj][m][n] = __builtin_amdgcn_mfma_f32_16x16x32_bf16(Bt[n][k], At[m][k], acc[ai][bj][m][n], 0, 0, 0); __builtin_amdgcn_s_setprio(0); } while (0)
; #define PG8_WAIT_V(n) asm volatile("s_waitcnt vmcnt(" #n ")" ::: "memory")
; #define PG8_WAIT_L(n) asm volatile("s_waitcnt lgkmcnt(" #n ")" ::: "memory")
; #define PG8_BAR __builtin_amdgcn_s_barrier()
; #define PG8_SCHED __builtin_amdgcn_sched_barrier(0)
; template <class Epi, bool ALIGN_EPI>
; __device__ __forceinline__ void gemm_phase(LAS unsigned char* lds, const Gemm g, const StaticOrder& S, const Epi& E) {
;     ...
;             PG8_WAIT_V(8); PG8_WAIT_L(0); PG8_BAR; PG8_MMA(1, 0, At, B0); PG8_MMA(1, 1, At, B1); PG8_BAR; PG8_SCHED;
;             PG8_LDB(B0, 1, 0); PG8_LDB(B1, 1, 1); PG8_SCHED; PG8_LDA(At, 1, 0); PG8_STAGE(PG8_SA(0, 1), a2 + hA, voffA);
;             PG8_WAIT_V(8); PG8_WAIT_L(0); PG8_BAR; PG8_MMA(0, 0, At, B0); PG8_MMA(0, 1, At, B1); PG8_BAR; PG8_SCHED;
	s_setprio 1
	s_waitcnt lgkmcnt(0)
	v_mfma_f32_16x16x32_bf16 v[60:63], v[128:131], v[184:187], v[60:63]
	v_mfma_f32_16x16x32_bf16 v[60:63], v[132:135], v[188:191], v[60:63]
	v_mfma_f32_16x16x32_bf16 v[56:59], v[136:139], v[184:187], v[56:59]
	v_mfma_f32_16x16x32_bf16 v[56:59], v[140:143], v[188:191], v[56:59]
	v_mfma_f32_16x16x32_bf16 v[44:47], v[128:131], v[194:197], v[44:47]
	v_mfma_f32_16x16x32_bf16 v[44:47], v[132:135], v[198:201], v[44:47]
	v_mfma_f32_16x16x32_bf16 v[40:43], v[136:139], v[194:197], v[40:43]
	v_mfma_f32_16x16x32_bf16 v[40:43], v[140:143], v[198:201], v[40:43]
	v_mfma_f32_16x16x32_bf16 v[28:31], v[128:131], v[202:205], v[28:31]
	v_mfma_f32_16x16x32_bf16 v[28:31], v[132:135], v[206:209], v[28:31]
	v_mfma_f32_16x16x32_bf16 v[24:27], v[136:139], v[202:205], v[24:27]
	v_mfma_f32_16x16x32_bf16 v[24:27], v[140:143], v[206:209], v[24:27]
	v_mfma_f32_16x16x32_bf16 v[12:15], v[128:131], v[210:213], v[12:15]
	v_mfma_f32_16x16x32_bf16 v[12:15], v[132:135], v[214:217], v[12:15]
	v_mfma_f32_16x16x32_bf16 v[8:11], v[136:139], v[210:213], v[8:11]
	v_mfma_f32_16x16x32_bf16 v[8:11], v[140:143], v[214:217], v[8:11]
	s_setprio 0
	s_setprio 1
	v_mfma_f32_16x16x32_bf16 v[52:55], v[160:163], v[184:187], v[52:55]
	v_mfma_f32_16x16x32_bf16 v[52:55], v[164:167], v[188:191], v[52:55]
	v_mfma_f32_16x16x32_bf16 v[48:51], v[168:171], v[184:187], v[48:51]
	v_mfma_f32_16x16x32_bf16 v[48:51], v[180:183], v[188:191], v[48:51]
	v_mfma_f32_16x16x32_bf16 v[36:39], v[160:163], v[194:197], v[36:39]
	v_mfma_f32_16x16x32_bf16 v[36:39], v[164:167], v[198:201], v[36:39]
	v_mfma_f32_16x16x32_bf16 v[32:35], v[168:171], v[194:197], v[32:35]
	v_mfma_f32_16x16x32_bf16 v[32:35], v[180:183], v[198:201], v[32:35]
	v_mfma_f32_16x16x32_bf16 v[20:23], v[160:163], v[202:205], v[20:23]
	v_mfma_f32_16x16x32_bf16 v[20:23], v[164:167], v[206:209], v[20:23]
	v_mfma_f32_16x16x32_bf16 v[16:19], v[168:171], v[202:205], v[16:19]
	v_mfma_f32_16x16x32_bf16 v[16:19], v[180:183], v[206:209], v[16:19]
	v_mfma_f32_16x16x32_bf16 v[4:7], v[160:163], v[210:213], v[4:7]
	v_mfma_f32_16x16x32_bf16 v[4:7], v[164:167], v[214:217], v[4:7]
	v_mfma_f32_16x16x32_bf16 v[0:3], v[168:171], v[210:213], v[0:3]
	v_mfma_f32_16x16x32_bf16 v[0:3], v[180:183], v[214:217], v[0:3]
	s_setprio 0
	s_barrier
	s_add_i32 s58, 0, 0x18000
	s_add_i32 s59, 0, 0x1c000
	v_add_u32_e32 v140, s58, v173
	v_add_u32_e32 v179, s59, v173
	ds_read_b128 v[128:131], v140
	ds_read_b128 v[132:135], v140 offset:1024
	ds_read_b128 v[136:139], v140 offset:2048
	ds_read_b128 v[140:143], v140 offset:3072
	ds_read_b128 v[160:163], v179
	ds_read_b128 v[164:167], v179 offset:1024
	ds_read_b128 v[168:171], v179 offset:2048
	ds_read_b128 v[180:183], v179 offset:3072
	s_add_u32 s42, s42, 0x80000
	s_addc_u32 s43, s43, 0
	s_mov_b32 m0, s39
	v_lshl_add_u64 v[226:227], s[42:43], 0, v[144:145]
	ds_read_b128 v[184:187], v177 offset:32768
	ds_read_b128 v[188:191], v177 offset:33792
	ds_read_b128 v[194:197], v177 offset:34816
	ds_read_b128 v[198:201], v177 offset:35840
	ds_read_b128 v[202:205], v177 offset:36864
	ds_read_b128 v[206:209], v177 offset:37888
	ds_read_b128 v[210:213], v177 offset:38912
	ds_read_b128 v[214:217], v177 offset:39936
	global_load_lds_dwordx4 v[226:227], off
	v_lshl_add_u64 v[226:227], s[42:43], 0, v[148:149]
	s_mov_b32 m0, s44
	s_nop 0
	global_load_lds_dwordx4 v[226:227], off
	s_waitcnt vmcnt(8)
	s_waitcnt lgkmcnt(0)
	s_barrier
	s_setprio 1
	s_waitcnt lgkmcnt(0)
	v_mfma_f32_16x16x32_bf16 v[124:127], v[128:131], v[184:187], v[124:127]
	v_mfma_f32_16x16x32_bf16 v[124:127], v[132:135], v[188:191], v[124:127]
	v_mfma_f32_16x16x32_bf16 v[120:123], v[136:139], v[184:187], v[120:123]
	v_mfma_f32_16x16x32_bf16 v[120:123], v[140:143], v[188:191], v[120:123]
	v_mfma_f32_16x16x32_bf16 v[112:115], v[128:131], v[194:197], v[112:115]
	v_mfma_f32_16x16x32_bf16 v[112:115], v[132:135], v[198:201], v[112:115]
	v_mfma_f32_16x16x32_bf16 v[104:107], v[136:139], v[194:197], v[104:107]
	v_mfma_f32_16x16x32_bf16 v[104:107], v[140:143], v[198:201], v[104:107]
	v_mfma_f32_16x16x32_bf16 v[92:95], v[128:131], v[202:205], v[92:95]
	v_mfma_f32_16x16x32_bf16 v[92:95], v[132:135], v[206:209], v[92:95]
	v_mfma_f32_16x16x32_bf16 v[88:91], v[136:139], v[202:205], v[88:91]
	v_mfma_f32_16x16x32_bf16 v[88:91], v[140:143], v[206:209], v[88:91]
	v_mfma_f32_16x16x32_bf16 v[76:79], v[128:131], v[210:213], v[76:79]
	v_mfma_f32_16x16x32_bf16 v[76:79], v[132:135], v[214:217], v[76:79]
	v_mfma_f32_16x16x32_bf16 v[72:75], v[136:139], v[210:213], v[72:75]
	v_mfma_f32_16x16x32_bf16 v[72:75], v[140:143], v[214:217], v[72:75]
	s_setprio 0
	s_setprio 1
	v_mfma_f32_16x16x32_bf16 v[116:119], v[160:163], v[184:187], v[116:119]
	v_mfma_f32_16x16x32_bf16 v[116:119], v[164:167], v[188:191], v[116:119]
	v_mfma_f32_16x16x32_bf16 v[108:111], v[168:171], v[184:187], v[108:111]
	v_mfma_f32_16x16x32_bf16 v[108:111], v[180:183], v[188:191], v[108:111]
	v_mfma_f32_16x16x32_bf16 v[100:103], v[160:163], v[194:197], v[100:103]
	v_mfma_f32_16x16x32_bf16 v[100:103], v[164:167], v[198:201], v[100:103]
	v_mfma_f32_16x16x32_bf16 v[96:99], v[168:171], v[194:197], v[96:99]
	v_mfma_f32_16x16x32_bf16 v[96:99], v[180:183], v[198:201], v[96:99]
	v_mfma_f32_16x16x32_bf16 v[84:87], v[160:163], v[202:205], v[84:87]
	v_mfma_f32_16x16x32_bf16 v[84:87], v[164:167], v[206:209], v[84:87]
	v_mfma_f32_16x16x32_bf16 v[80:83], v[168:171], v[202:205], v[80:83]
	v_mfma_f32_16x16x32_bf16 v[80:83], v[180:183], v[206:209], v[80:83]
	v_mfma_f32_16x16x32_bf16 v[68:71], v[160:163], v[210:213], v[68:71]
	v_mfma_f32_16x16x32_bf16 v[68:71], v[164:167], v[214:217], v[68:71]
	v_mfma_f32_16x16x32_bf16 v[64:67], v[168:171], v[210:213], v[64:67]
	v_mfma_f32_16x16x32_bf16 v[64:67], v[180:183], v[214:217], v[64:67]
	s_setprio 0
	s_barrier
; #define PG8_STAGE(bufoff, gbase, voff) do { _Pragma("unroll") for (int _i = 0; _i < 2; ++_i) \
;         __builtin_amdgcn_global_load_lds((const unsigned*)((const char*)(gbase) + (voff)[_i]), (LAS unsigned*)(lds + (bufoff) + ldsw + _i * 8192), 16, 0, 0); } while (0)
; #define PG8_LDA(dst, b, h) do { _Pragma("unroll") for (int m = 0; m < 4; ++m) _Pragma("unroll") for (int k = 0; k < 2; ++k) dst[m][k] = *(const LAS bf16x8*)(lds + PG8_SA(b, h) + aoff + m * 2048 + k * 1024); } while (0)
; #define PG8_MMA(ai, bj, At, Bt) do { __builtin_amdgcn_s_setprio(1); _Pragma("unroll") for (int m = 0; m < 4; ++m) _Pragma("unroll") for (int n = 0; n < 2; ++n) _Pragma("unroll") for (int k = 0; k < 2; ++k) \
;         acc[ai][bj][m][n] = __builtin_amdgcn_mfma_f32_16x16x32_bf16(Bt[n][k], At[m][k], acc[ai][bj][m][n], 0, 0, 0); __builtin_amdgcn_s_setprio(0); } while (0)
; #define PG8_WAIT_V(n) asm volatile("s_waitcnt vmcnt(" #n ")" ::: "memory")
; #define PG8_WAIT_L(n) asm volatile("s_waitcnt lgkmcnt(" #n ")" ::: "memory")
; #define PG8_BAR __builtin_amdgcn_s_barrier()
; #define PG8_SCHED __builtin_amdgcn_sched_barrier(0)
; template <class Epi, bool ALIGN_EPI>
; __device__ __forceinline__ void gemm_phase(LAS unsigned char* lds, const Gemm g, const StaticOrder& S, const Epi& E) {
;     ...
;             PG8_LDA(At, 1, 1); PG8_STAGE(PG8_SB(1, 0), b3, voffB); PG8_STAGE(PG8_SB(1, 1), b3 + hB, voffB); PG8_STAGE(PG8_SA(1, 0), a3, voffA);
;             PG8_WAIT_V(8); PG8_WAIT_L(0); PG8_BAR; PG8_MMA(1, 0, At, B0); PG8_MMA(1, 1, At, B1); PG8_BAR; PG8_SCHED;
;         }
;         if constexpr (ALIGN_EPI) { if (wr == 0) PG8_BAR; }
	s_add_i32 s42, s58, s33
	v_lshl_add_u64 v[218:219], v[218:219], 0, s[18:19]
	s_mov_b32 m0, s42
	ds_read_b128 v[184:187], v177 offset:49152
	ds_read_b128 v[188:191], v177 offset:50176
	ds_read_b128 v[194:197], v177 offset:51200
	ds_read_b128 v[198:201], v177 offset:52224
	ds_read_b128 v[202:205], v177 offset:53248
	ds_read_b128 v[206:209], v177 offset:54272
	ds_read_b128 v[210:213], v177 offset:55296
	ds_read_b128 v[214:217], v177 offset:56320
	global_load_lds_dwordx4 v[218:219], off
	s_add_i32 m0, s42, 0x2000
	s_add_u32 s40, s40, 0x80080
	v_lshl_add_u64 v[218:219], v[220:221], 0, s[18:19]
	s_addc_u32 s41, s41, 0
	s_add_i32 s42, s59, s33
	global_load_lds_dwordx4 v[218:219], off
	v_lshl_add_u64 v[218:219], s[40:41], 0, v[146:147]
	s_mov_b32 m0, s42
	s_nop 0
	global_load_lds_dwordx4 v[218:219], off
	v_lshl_add_u64 v[218:219], s[40:41], 0, v[150:151]
	s_add_i32 m0, s42, 0x2000
	s_nop 0
	global_load_lds_dwordx4 v[218:219], off
	v_lshl_add_u64 v[218:219], v[222:223], 0, s[18:19]
	s_mov_b32 m0, s48
	s_nop 0
	global_load_lds_dwordx4 v[218:219], off
	v_lshl_add_u64 v[218:219], v[224:225], 0, s[18:19]
	s_mov_b32 m0, s49
	s_nop 0
	global_load_lds_dwordx4 v[218:219], off
	s_waitcnt vmcnt(8)
	s_waitcnt lgkmcnt(0)
	s_barrier
	s_setprio 1
	s_waitcnt lgkmcnt(0)
	v_mfma_f32_16x16x32_bf16 v[60:63], v[128:131], v[184:187], v[60:63]
	v_mfma_f32_16x16x32_bf16 v[60:63], v[132:135], v[188:191], v[60:63]
	v_mfma_f32_16x16x32_bf16 v[56:59], v[136:139], v[184:187], v[56:59]
	v_mfma_f32_16x16x32_bf16 v[56:59], v[140:143], v[188:191], v[56:59]
	v_mfma_f32_16x16x32_bf16 v[44:47], v[128:131], v[194:197], v[44:47]
	v_mfma_f32_16x16x32_bf16 v[44:47], v[132:135], v[198:201], v[44:47]
	v_mfma_f32_16x16x32_bf16 v[40:43], v[136:139], v[194:197], v[40:43]
	v_mfma_f32_16x16x32_bf16 v[40:43], v[140:143], v[198:201], v[40:43]
	v_mfma_f32_16x16x32_bf16 v[28:31], v[128:131], v[202:205], v[28:31]
	v_mfma_f32_16x16x32_bf16 v[28:31], v[132:135], v[206:209], v[28:31]
	v_mfma_f32_16x16x32_bf16 v[24:27], v[136:139], v[202:205], v[24:27]
	v_mfma_f32_16x16x32_bf16 v[24:27], v[140:143], v[206:209], v[24:27]
	v_mfma_f32_16x16x32_bf16 v[12:15], v[128:131], v[210:213], v[12:15]
	v_mfma_f32_16x16x32_bf16 v[12:15], v[132:135], v[214:217], v[12:15]
	v_mfma_f32_16x16x32_bf16 v[8:11], v[136:139], v[210:213], v[8:11]
	v_mfma_f32_16x16x32_bf16 v[8:11], v[140:143], v[214:217], v[8:11]
	s_setprio 0
	s_setprio 1
	v_mfma_f32_16x16x32_bf16 v[52:55], v[160:163], v[184:187], v[52:55]
	v_mfma_f32_16x16x32_bf16 v[52:55], v[164:167], v[188:191], v[52:55]
	v_mfma_f32_16x16x32_bf16 v[48:51], v[168:171], v[184:187], v[48:51]
	v_mfma_f32_16x16x32_bf16 v[48:51], v[180:183], v[188:191], v[48:51]
	v_mfma_f32_16x16x32_bf16 v[36:39], v[160:163], v[194:197], v[36:39]
	v_mfma_f32_16x16x32_bf16 v[36:39], v[164:167], v[198:201], v[36:39]
	v_mfma_f32_16x16x32_bf16 v[32:35], v[168:171], v[194:197], v[32:35]
	v_mfma_f32_16x16x32_bf16 v[32:35], v[180:183], v[198:201], v[32:35]
	v_mfma_f32_16x16x32_bf16 v[20:23], v[160:163], v[202:205], v[20:23]
	v_mfma_f32_16x16x32_bf16 v[20:23], v[164:167], v[206:209], v[20:23]
	v_mfma_f32_16x16x32_bf16 v[16:19], v[168:171], v[202:205], v[16:19]
	v_mfma_f32_16x16x32_bf16 v[16:19], v[180:183], v[206:209], v[16:19]
	v_mfma_f32_16x16x32_bf16 v[4:7], v[160:163], v[210:213], v[4:7]
	v_mfma_f32_16x16x32_bf16 v[4:7], v[164:167], v[214:217], v[4:7]
	v_mfma_f32_16x16x32_bf16 v[0:3], v[168:171], v[210:213], v[0:3]
	v_mfma_f32_16x16x32_bf16 v[0:3], v[180:183], v[214:217], v[0:3]
	s_setprio 0
	s_barrier
	s_add_i32 s57, s57, 2
	s_add_u32 s36, s36, 0x100
	s_addc_u32 s37, s37, 0
	s_add_u32 s55, s55, 0x100
	s_addc_u32 s56, s56, 0
	s_cmp_gt_u32 s57, 29
	s_cbranch_scc0 .LBB0_1585
	s_and_b64 vcc, exec, s[20:21]
	s_cbranch_vccz .LBB0_1588
	s_nop 0

; #define PG8_BAR __builtin_amdgcn_s_barrier()
;     __device__ __forceinline__ void post(int ui, const float (&r)[8]) const { const int t = my_tid(); if (t < 384) cbuf[(ui & 1) * 384 + t] = r[0]; }
; template <class Epi, bool ALIGN_EPI>
; __device__ __forceinline__ void gemm_phase(LAS unsigned char* lds, const Gemm g, const StaticOrder& S, const Epi& E) {
;     ...
;         if (!has_next) break;
;         E.post(ui + 1, rsn);
; #pragma unroll
;         for (int a = 0; a < 2; ++a)
; #pragma unroll
;             for (int b = 0; b < 2; ++b)
; #pragma unroll
;                 for (int m = 0; m < 4; ++m)
; #pragma unroll
;                     for (int n = 0; n < 2; ++n) acc[a][b][m][n] = (f32x4){0.f, 0.f, 0.f, 0.f};
;         cur = nxt; cA = nA; cB = nB; ++ui;
; #pragma unroll
;         for (int i_ = 0; i_ < 8; ++i_) rsv[i_] = rsn[i_];
;         if constexpr (ALIGN_EPI) { if (wr == 1) PG8_BAR; }
;     __device__ __forceinline__ void operator()(const f32x4 (&acc)[2][2][4][2], const Unit& u, int wr, int wc, int fr, int fq, int, const float (&)[8]) const {
;     ...
;                 for (int m = 0; m < 4; ++m) { float pp = part[ai][m]; pp += __shfl_xor(pp, 16); pp += __shfl_xor(pp, 32); if (fq == 0) unsafeAtomicAdd(ss + row0 + ai * HALF + m * 16, pp); } }
.LBB0_1604:
	s_or_b64 exec, exec, s[30:31]
	s_andn2_b64 vcc, exec, s[6:7]
	s_mov_b64 s[6:7], -1
	s_cbranch_vccnz .LBB0_1577
	s_andn2_b64 vcc, exec, s[12:13]
	s_cbranch_vccnz .LBB0_1576
	s_nop 0
	s_branch .LBB0_1576

; #define PG8_STAGE(bufoff, gbase, voff) do { _Pragma("unroll") for (int _i = 0; _i < 2; ++_i) \
;         __builtin_amdgcn_global_load_lds((const unsigned*)((const char*)(gbase) + (voff)[_i]), (LAS unsigned*)(lds + (bufoff) + ldsw + _i * 8192), 16, 0, 0); } while (0)
; #define PG8_LDA(dst, b, h) do { _Pragma("unroll") for (int m = 0; m < 4; ++m) _Pragma("unroll") for (int k = 0; k < 2; ++k) dst[m][k] = *(const LAS bf16x8*)(lds + PG8_SA(b, h) + aoff + m * 2048 + k * 1024); } while (0)
; #define PG8_LDB(dst, b, h) do { _Pragma("unroll") for (int n = 0; n < 2; ++n) _Pragma("unroll") for (int k = 0; k < 2; ++k) dst[n][k] = *(const LAS bf16x8*)(lds + PG8_SB(b, h) + boff + n * 2048 + k * 1024); } while (0)
; #define PG8_MMA(ai, bj, At, Bt) do { __builtin_amdgcn_s_setprio(1); _Pragma("unroll") for (int m = 0; m < 4; ++m) _Pragma("unroll") for (int n = 0; n < 2; ++n) _Pragma("unroll") for (int k = 0; k < 2; ++k) \
;         acc[ai][bj][m][n] = __builtin_amdgcn_mfma_f32_16x16x32_bf16(Bt[n][k], At[m][k], acc[ai][bj][m][n], 0, 0, 0); __builtin_amdgcn_s_setprio(0); } while (0)
; #define PG8_WAIT_V(n) asm volatile("s_waitcnt vmcnt(" #n ")" ::: "memory")
; #define PG8_WAIT_L(n) asm volatile("s_waitcnt lgkmcnt(" #n ")" ::: "memory")
; #define PG8_BAR __builtin_amdgcn_s_barrier()
; #define PG8_SCHED __builtin_amdgcn_sched_barrier(0)
; template <class Epi, bool ALIGN_EPI>
; __device__ __forceinline__ void gemm_phase(LAS unsigned char* lds, const Gemm g, const StaticOrder& S, const Epi& E) {
;     ...
;         for (int t = 0; t < nt; t += 2) {
;             const bool last = (t == nt - 2);
;             const char* a1 = cA + (size_t)(t + 1) * kstep;
;             const char* a2 = last ? nA : cA + (size_t)(t + 2) * kstep; const char* b2 = last ? nB : cB + (size_t)(t + 2) * kstep;
;             const char* a3 = a2 + kstep; const char* b3 = b2 + kstep;
;             PG8_LDB(B0, 0, 0); PG8_LDB(B1, 0, 1); PG8_SCHED; PG8_LDA(At, 0, 0); PG8_STAGE(PG8_SA(1, 1), a1 + hA, voffA);
;             PG8_WAIT_V(8); PG8_WAIT_L(0); PG8_BAR; PG8_MMA(0, 0, At, B0); PG8_MMA(0, 1, At, B1); PG8_BAR; PG8_SCHED;
;             PG8_LDA(At, 0, 1); PG8_STAGE(PG8_SB(0, 0), b2, voffB); PG8_STAGE(PG8_SB(0, 1), b2 + hB, voffB); PG8_STAGE(PG8_SA(0, 0), a2, voffA);
;             PG8_WAIT_V(8); PG8_WAIT_L(0); PG8_BAR; PG8_MMA(1, 0, At, B0); PG8_MMA(1, 1, At, B1); PG8_BAR; PG8_SCHED;
.LBB0_1755:
	ds_read_b128 v[128:131], v183
	ds_read_b128 v[132:135], v183 offset:1024
	ds_read_b128 v[152:155], v183 offset:2048
	ds_read_b128 v[156:159], v183 offset:3072
	ds_read_b128 v[160:163], v184
	ds_read_b128 v[164:167], v184 offset:1024
	ds_read_b128 v[168:171], v184 offset:2048
	ds_read_b128 v[172:175], v184 offset:3072
	s_add_u32 s30, s28, 0xffe00080
	s_addc_u32 s31, s29, -1
	s_cmpk_eq_i32 s51, 0x7c
	s_cselect_b32 s35, s5, s31
	s_cselect_b32 s34, s21, s30
	s_cselect_b32 s31, s19, s50
	s_cselect_b32 s30, s48, s49
	v_lshl_add_u64 v[214:215], s[28:29], 0, v[144:145]
	s_add_i32 m0, s27, 0xc000
	ds_read_b128 v[176:179], v185
	ds_read_b128 v[186:189], v185 offset:1024
	ds_read_b128 v[190:193], v185 offset:2048
	ds_read_b128 v[194:197], v185 offset:3072
	ds_read_b128 v[198:201], v185 offset:4096
	ds_read_b128 v[202:205], v185 offset:5120
	ds_read_b128 v[206:209], v185 offset:6144
	ds_read_b128 v[210:213], v185 offset:7168
	global_load_lds_dwordx4 v[214:215], off
	v_lshl_add_u64 v[214:215], s[28:29], 0, v[146:147]
	s_add_i32 m0, s27, 0xe000
	s_nop 0
	global_load_lds_dwordx4 v[214:215], off
	s_waitcnt vmcnt(8)
	s_waitcnt lgkmcnt(0)
	s_barrier
	s_setprio 1
	s_waitcnt lgkmcnt(0)
	v_mfma_f32_16x16x32_bf16 v[120:123], v[128:131], v[176:179], v[120:123]
	v_mfma_f32_16x16x32_bf16 v[120:123], v[132:135], v[186:189], v[120:123]
	v_mfma_f32_16x16x32_bf16 v[124:127], v[152:155], v[176:179], v[124:127]
	v_mfma_f32_16x16x32_bf16 v[124:127], v[156:159], v[186:189], v[124:127]
	v_mfma_f32_16x16x32_bf16 v[104:107], v[128:131], v[190:193], v[104:107]
	v_mfma_f32_16x16x32_bf16 v[104:107], v[132:135], v[194:197], v[104:107]
	v_mfma_f32_16x16x32_bf16 v[108:111], v[152:155], v[190:193], v[108:111]
	v_mfma_f32_16x16x32_bf16 v[108:111], v[156:159], v[194:197], v[108:111]
	v_mfma_f32_16x16x32_bf16 v[88:91], v[128:131], v[198:201], v[88:91]
	v_mfma_f32_16x16x32_bf16 v[88:91], v[132:135], v[202:205], v[88:91]
	v_mfma_f32_16x16x32_bf16 v[92:95], v[152:155], v[198:201], v[92:95]
	v_mfma_f32_16x16x32_bf16 v[92:95], v[156:159], v[202:205], v[92:95]
	v_mfma_f32_16x16x32_bf16 v[72:75], v[128:131], v[206:209], v[72:75]
	v_mfma_f32_16x16x32_bf16 v[72:75], v[132:135], v[210:213], v[72:75]
	v_mfma_f32_16x16x32_bf16 v[76:79], v[152:155], v[206:209], v[76:79]
	v_mfma_f32_16x16x32_bf16 v[76:79], v[156:159], v[210:213], v[76:79]
	s_setprio 0
	s_setprio 1
	v_mfma_f32_16x16x32_bf16 v[112:115], v[160:163], v[176:179], v[112:115]
	v_mfma_f32_16x16x32_bf16 v[112:115], v[164:167], v[186:189], v[112:115]
	v_mfma_f32_16x16x32_bf16 v[116:119], v[168:171], v[176:179], v[116:119]
	v_mfma_f32_16x16x32_bf16 v[116:119], v[172:175], v[186:189], v[116:119]
	v_mfma_f32_16x16x32_bf16 v[96:99], v[160:163], v[190:193], v[96:99]
	v_mfma_f32_16x16x32_bf16 v[96:99], v[164:167], v[194:197], v[96:99]
	v_mfma_f32_16x16x32_bf16 v[100:103], v[168:171], v[190:193], v[100:103]
	v_mfma_f32_16x16x32_bf16 v[100:103], v[172:175], v[194:197], v[100:103]
	v_mfma_f32_16x16x32_bf16 v[80:83], v[160:163], v[198:201], v[80:83]
	v_mfma_f32_16x16x32_bf16 v[80:83], v[164:167], v[202:205], v[80:83]
	v_mfma_f32_16x16x32_bf16 v[84:87], v[168:171], v[198:201], v[84:87]
	v_mfma_f32_16x16x32_bf16 v[84:87], v[172:175], v[202:205], v[84:87]
	v_mfma_f32_16x16x32_bf16 v[64:67], v[160:163], v[206:209], v[64:67]
	v_mfma_f32_16x16x32_bf16 v[64:67], v[164:167], v[210:213], v[64:67]
	v_mfma_f32_16x16x32_bf16 v[68:71], v[168:171], v[206:209], v[68:71]
	v_mfma_f32_16x16x32_bf16 v[68:71], v[172:175], v[210:213], v[68:71]
	s_setprio 0
	s_barrier
	s_add_i32 s52, s46, s37
	v_lshl_add_u64 v[214:215], s[30:31], 0, v[138:139]
	s_mov_b32 m0, s52
	ds_read_b128 v[176:179], v185 offset:16384
	ds_read_b128 v[186:189], v185 offset:17408
	ds_read_b128 v[190:193], v185 offset:18432
	ds_read_b128 v[194:197], v185 offset:19456
	ds_read_b128 v[198:201], v185 offset:20480
	ds_read_b128 v[202:205], v185 offset:21504
	ds_read_b128 v[206:209], v185 offset:22528
	ds_read_b128 v[210:213], v185 offset:23552
	global_load_lds_dwordx4 v[214:215], off
	s_add_i32 m0, s52, 0x2000
	s_add_u32 s52, s30, 0x200000
	v_lshl_add_u64 v[216:217], s[30:31], 0, v[142:143]
	s_addc_u32 s53, s31, 0
	s_add_i32 s54, s47, s37
	global_load_lds_dwordx4 v[216:217], off
	v_lshl_add_u64 v[218:219], s[52:53], 0, v[138:139]
	s_mov_b32 m0, s54
	v_lshl_add_u64 v[220:221], s[34:35], 0, v[140:141]
	global_load_lds_dwordx4 v[218:219], off
	v_lshl_add_u64 v[218:219], s[52:53], 0, v[142:143]
	s_add_i32 m0, s54, 0x2000
	s_nop 0
	global_load_lds_dwordx4 v[218:219], off
	v_lshl_add_u64 v[218:219], s[34:35], 0, v[136:137]
	s_mov_b32 m0, s27
	s_nop 0
	global_load_lds_dwordx4 v[218:219], off
	s_mov_b32 m0, s38
	s_nop 0
	global_load_lds_dwordx4 v[220:221], off
	s_waitcnt vmcnt(8)
	s_waitcnt lgkmcnt(0)
	s_barrier
; #define PG8_STAGE(bufoff, gbase, voff) do { _Pragma("unroll") for (int _i = 0; _i < 2; ++_i) \
;         __builtin_amdgcn_global_load_lds((const unsigned*)((const char*)(gbase) + (voff)[_i]), (LAS unsigned*)(lds + (bufoff) + ldsw + _i * 8192), 16, 0, 0); } while (0)
; #define PG8_LDA(dst, b, h) do { _Pragma("unroll") for (int m = 0; m < 4; ++m) _Pragma("unroll") for (int k = 0; k < 2; ++k) dst[m][k] = *(const LAS bf16x8*)(lds + PG8_SA(b, h) + aoff + m * 2048 + k * 1024); } while (0)
; #define PG8_LDB(dst, b, h) do { _Pragma("unroll") for (int n = 0; n < 2; ++n) _Pragma("unroll") for (int k = 0; k < 2; ++k) dst[n][k] = *(const LAS bf16x8*)(lds + PG8_SB(b, h) + boff + n * 2048 + k * 1024); } while (0)
; #define PG8_MMA(ai, bj, At, Bt) do { __builtin_amdgcn_s_setprio(1); _Pragma("unroll") for (int m = 0; m < 4; ++m) _Pragma("unroll") for (int n = 0; n < 2; ++n) _Pragma("unroll") for (int k = 0; k < 2; ++k) \
;         acc[ai][bj][m][n] = __builtin_amdgcn_mfma_f32_16x16x32_bf16(Bt[n][k], At[m][k], acc[ai][bj][m][n], 0, 0, 0); __builtin_amdgcn_s_setprio(0); } while (0)
; #define PG8_WAIT_V(n) asm volatile("s_waitcnt vmcnt(" #n ")" ::: "memory")
; #define PG8_WAIT_L(n) asm volatile("s_waitcnt lgkmcnt(" #n ")" ::: "memory")
; #define PG8_BAR __builtin_amdgcn_s_barrier()
; #define PG8_SCHED __builtin_amdgcn_sched_barrier(0)
; template <class Epi, bool ALIGN_EPI>
; __device__ __forceinline__ void gemm_phase(LAS unsigned char* lds, const Gemm g, const StaticOrder& S, const Epi& E) {
;     ...
;             PG8_WAIT_V(8); PG8_WAIT_L(0); PG8_BAR; PG8_MMA(1, 0, At, B0); PG8_MMA(1, 1, At, B1); PG8_BAR; PG8_SCHED;
;             PG8_LDB(B0, 1, 0); PG8_LDB(B1, 1, 1); PG8_SCHED; PG8_LDA(At, 1, 0); PG8_STAGE(PG8_SA(0, 1), a2 + hA, voffA);
;             PG8_WAIT_V(8); PG8_WAIT_L(0); PG8_BAR; PG8_MMA(0, 0, At, B0); PG8_MMA(0, 1, At, B1); PG8_BAR; PG8_SCHED;
	s_setprio 1
	s_waitcnt lgkmcnt(0)
	v_mfma_f32_16x16x32_bf16 v[56:59], v[128:131], v[176:179], v[56:59]
	v_mfma_f32_16x16x32_bf16 v[56:59], v[132:135], v[186:189], v[56:59]
	v_mfma_f32_16x16x32_bf16 v[60:63], v[152:155], v[176:179], v[60:63]
	v_mfma_f32_16x16x32_bf16 v[60:63], v[156:159], v[186:189], v[60:63]
	v_mfma_f32_16x16x32_bf16 v[40:43], v[128:131], v[190:193], v[40:43]
	v_mfma_f32_16x16x32_bf16 v[40:43], v[132:135], v[194:197], v[40:43]
	v_mfma_f32_16x16x32_bf16 v[44:47], v[152:155], v[190:193], v[44:47]
	v_mfma_f32_16x16x32_bf16 v[44:47], v[156:159], v[194:197], v[44:47]
	v_mfma_f32_16x16x32_bf16 v[24:27], v[128:131], v[198:201], v[24:27]
	v_mfma_f32_16x16x32_bf16 v[24:27], v[132:135], v[202:205], v[24:27]
	v_mfma_f32_16x16x32_bf16 v[28:31], v[152:155], v[198:201], v[28:31]
	v_mfma_f32_16x16x32_bf16 v[28:31], v[156:159], v[202:205], v[28:31]
	v_mfma_f32_16x16x32_bf16 v[8:11], v[128:131], v[206:209], v[8:11]
	v_mfma_f32_16x16x32_bf16 v[8:11], v[132:135], v[210:213], v[8:11]
	v_mfma_f32_16x16x32_bf16 v[12:15], v[152:155], v[206:209], v[12:15]
	v_mfma_f32_16x16x32_bf16 v[12:15], v[156:159], v[210:213], v[12:15]
	s_setprio 0
	s_setprio 1
	v_mfma_f32_16x16x32_bf16 v[48:51], v[160:163], v[176:179], v[48:51]
	v_mfma_f32_16x16x32_bf16 v[48:51], v[164:167], v[186:189], v[48:51]
	v_mfma_f32_16x16x32_bf16 v[52:55], v[168:171], v[176:179], v[52:55]
	v_mfma_f32_16x16x32_bf16 v[52:55], v[172:175], v[186:189], v[52:55]
	v_mfma_f32_16x16x32_bf16 v[32:35], v[160:163], v[190:193], v[32:35]
	v_mfma_f32_16x16x32_bf16 v[32:35], v[164:167], v[194:197], v[32:35]
	v_mfma_f32_16x16x32_bf16 v[36:39], v[168:171], v[190:193], v[36:39]
	v_mfma_f32_16x16x32_bf16 v[36:39], v[172:175], v[194:197], v[36:39]
	v_mfma_f32_16x16x32_bf16 v[16:19], v[160:163], v[198:201], v[16:19]
	v_mfma_f32_16x16x32_bf16 v[16:19], v[164:167], v[202:205], v[16:19]
	v_mfma_f32_16x16x32_bf16 v[20:23], v[168:171], v[198:201], v[20:23]
	v_mfma_f32_16x16x32_bf16 v[20:23], v[172:175], v[202:205], v[20:23]
	v_mfma_f32_16x16x32_bf16 v[4:7], v[160:163], v[206:209], v[4:7]
	v_mfma_f32_16x16x32_bf16 v[4:7], v[164:167], v[210:213], v[4:7]
	v_mfma_f32_16x16x32_bf16 v[0:3], v[168:171], v[206:209], v[0:3]
	v_mfma_f32_16x16x32_bf16 v[0:3], v[172:175], v[210:213], v[0:3]
	s_setprio 0
	s_barrier
	s_add_i32 s52, 0, 0x18000
	s_add_i32 s53, 0, 0x1c000
	v_add_u32_e32 v156, s52, v181
	v_add_u32_e32 v172, s53, v181
	ds_read_b128 v[128:131], v156
	ds_read_b128 v[132:135], v156 offset:1024
	ds_read_b128 v[152:155], v156 offset:2048
	ds_read_b128 v[156:159], v156 offset:3072
	ds_read_b128 v[160:163], v172
	ds_read_b128 v[164:167], v172 offset:1024
	ds_read_b128 v[168:171], v172 offset:2048
	ds_read_b128 v[172:175], v172 offset:3072
	s_add_u32 s34, s34, 0x200000
	s_addc_u32 s35, s35, 0
	s_mov_b32 m0, s39
	v_lshl_add_u64 v[222:223], s[34:35], 0, v[136:137]
	ds_read_b128 v[176:179], v185 offset:32768
	ds_read_b128 v[186:189], v185 offset:33792
	ds_read_b128 v[190:193], v185 offset:34816
	ds_read_b128 v[194:197], v185 offset:35840
	ds_read_b128 v[198:201], v185 offset:36864
	ds_read_b128 v[202:205], v185 offset:37888
	ds_read_b128 v[206:209], v185 offset:38912
	ds_read_b128 v[210:213], v185 offset:39936
	global_load_lds_dwordx4 v[222:223], off
	v_lshl_add_u64 v[222:223], s[34:35], 0, v[140:141]
	s_mov_b32 m0, s40
	s_nop 0
	global_load_lds_dwordx4 v[222:223], off
	s_waitcnt vmcnt(8)
	s_waitcnt lgkmcnt(0)
	s_barrier
	s_setprio 1
	s_waitcnt lgkmcnt(0)
	v_mfma_f32_16x16x32_bf16 v[120:123], v[128:131], v[176:179], v[120:123]
	v_mfma_f32_16x16x32_bf16 v[120:123], v[132:135], v[186:189], v[120:123]
	v_mfma_f32_16x16x32_bf16 v[124:127], v[152:155], v[176:179], v[124:127]
	v_mfma_f32_16x16x32_bf16 v[124:127], v[156:159], v[186:189], v[124:127]
	v_mfma_f32_16x16x32_bf16 v[104:107], v[128:131], v[190:193], v[104:107]
	v_mfma_f32_16x16x32_bf16 v[104:107], v[132:135], v[194:197], v[104:107]
	v_mfma_f32_16x16x32_bf16 v[108:111], v[152:155], v[190:193], v[108:111]
	v_mfma_f32_16x16x32_bf16 v[108:111], v[156:159], v[194:197], v[108:111]
	v_mfma_f32_16x16x32_bf16 v[88:91], v[128:131], v[198:201], v[88:91]
	v_mfma_f32_16x16x32_bf16 v[88:91], v[132:135], v[202:205], v[88:91]
	v_mfma_f32_16x16x32_bf16 v[92:95], v[152:155], v[198:201], v[92:95]
	v_mfma_f32_16x16x32_bf16 v[92:95], v[156:159], v[202:205], v[92:95]
	v_mfma_f32_16x16x32_bf16 v[72:75], v[128:131], v[206:209], v[72:75]
	v_mfma_f32_16x16x32_bf16 v[72:75], v[132:135], v[210:213], v[72:75]
	v_mfma_f32_16x16x32_bf16 v[76:79], v[152:155], v[206:209], v[76:79]
	v_mfma_f32_16x16x32_bf16 v[76:79], v[156:159], v[210:213], v[76:79]
	s_setprio 0
	s_setprio 1
	v_mfma_f32_16x16x32_bf16 v[112:115], v[160:163], v[176:179], v[112:115]
	v_mfma_f32_16x16x32_bf16 v[112:115], v[164:167], v[186:189], v[112:115]
	v_mfma_f32_16x16x32_bf16 v[116:119], v[168:171], v[176:179], v[116:119]
	v_mfma_f32_16x16x32_bf16 v[116:119], v[172:175], v[186:189], v[116:119]
	v_mfma_f32_16x16x32_bf16 v[96:99], v[160:163], v[190:193], v[96:99]
	v_mfma_f32_16x16x32_bf16 v[96:99], v[164:167], v[194:197], v[96:99]
	v_mfma_f32_16x16x32_bf16 v[100:103], v[168:171], v[190:193], v[100:103]
	v_mfma_f32_16x16x32_bf16 v[100:103], v[172:175], v[194:197], v[100:103]
	v_mfma_f32_16x16x32_bf16 v[80:83], v[160:163], v[198:201], v[80:83]
	v_mfma_f32_16x16x32_bf16 v[80:83], v[164:167], v[202:205], v[80:83]
	v_mfma_f32_16x16x32_bf16 v[84:87], v[168:171], v[198:201], v[84:87]
	v_mfma_f32_16x16x32_bf16 v[84:87], v[172:175], v[202:205], v[84:87]
	v_mfma_f32_16x16x32_bf16 v[64:67], v[160:163], v[206:209], v[64:67]
	v_mfma_f32_16x16x32_bf16 v[64:67], v[164:167], v[210:213], v[64:67]
	v_mfma_f32_16x16x32_bf16 v[68:71], v[168:171], v[206:209], v[68:71]
	v_mfma_f32_16x16x32_bf16 v[68:71], v[172:175], v[210:213], v[68:71]
	s_setprio 0
	s_barrier
; #define PG8_STAGE(bufoff, gbase, voff) do { _Pragma("unroll") for (int _i = 0; _i < 2; ++_i) \
;         __builtin_amdgcn_global_load_lds((const unsigned*)((const char*)(gbase) + (voff)[_i]), (LAS unsigned*)(lds + (bufoff) + ldsw + _i * 8192), 16, 0, 0); } while (0)
; #define PG8_LDA(dst, b, h) do { _Pragma("unroll") for (int m = 0; m < 4; ++m) _Pragma("unroll") for (int k = 0; k < 2; ++k) dst[m][k] = *(const LAS bf16x8*)(lds + PG8_SA(b, h) + aoff + m * 2048 + k * 1024); } while (0)
; #define PG8_MMA(ai, bj, At, Bt) do { __builtin_amdgcn_s_setprio(1); _Pragma("unroll") for (int m = 0; m < 4; ++m) _Pragma("unroll") for (int n = 0; n < 2; ++n) _Pragma("unroll") for (int k = 0; k < 2; ++k) \
;         acc[ai][bj][m][n] = __builtin_amdgcn_mfma_f32_16x16x32_bf16(Bt[n][k], At[m][k], acc[ai][bj][m][n], 0, 0, 0); __builtin_amdgcn_s_setprio(0); } while (0)
; #define PG8_WAIT_V(n) asm volatile("s_waitcnt vmcnt(" #n ")" ::: "memory")
; #define PG8_WAIT_L(n) asm volatile("s_waitcnt lgkmcnt(" #n ")" ::: "memory")
; #define PG8_BAR __builtin_amdgcn_s_barrier()
; #define PG8_SCHED __builtin_amdgcn_sched_barrier(0)
; template <class Epi, bool ALIGN_EPI>
; __device__ __forceinline__ void gemm_phase(LAS unsigned char* lds, const Gemm g, const StaticOrder& S, const Epi& E) {
;     ...
;             PG8_LDA(At, 1, 1); PG8_STAGE(PG8_SB(1, 0), b3, voffB); PG8_STAGE(PG8_SB(1, 1), b3 + hB, voffB); PG8_STAGE(PG8_SA(1, 0), a3, voffA);
;             PG8_WAIT_V(8); PG8_WAIT_L(0); PG8_BAR; PG8_MMA(1, 0, At, B0); PG8_MMA(1, 1, At, B1); PG8_BAR; PG8_SCHED;
;         }
;         if constexpr (ALIGN_EPI) { if (wr == 0) PG8_BAR; }
	s_add_i32 s34, s52, s37
	v_lshl_add_u64 v[214:215], v[214:215], 0, s[12:13]
	s_mov_b32 m0, s34
	ds_read_b128 v[176:179], v185 offset:49152
	ds_read_b128 v[186:189], v185 offset:50176
	ds_read_b128 v[190:193], v185 offset:51200
	ds_read_b128 v[194:197], v185 offset:52224
	ds_read_b128 v[198:201], v185 offset:53248
	ds_read_b128 v[202:205], v185 offset:54272
	ds_read_b128 v[206:209], v185 offset:55296
	ds_read_b128 v[210:213], v185 offset:56320
	global_load_lds_dwordx4 v[214:215], off
	s_add_i32 m0, s34, 0x2000
	s_add_u32 s30, s30, 0x200080
	v_lshl_add_u64 v[214:215], v[216:217], 0, s[12:13]
	s_addc_u32 s31, s31, 0
	s_add_i32 s34, s53, s37
	global_load_lds_dwordx4 v[214:215], off
	v_lshl_add_u64 v[214:215], s[30:31], 0, v[138:139]
	s_mov_b32 m0, s34
	s_nop 0
	global_load_lds_dwordx4 v[214:215], off
	v_lshl_add_u64 v[214:215], s[30:31], 0, v[142:143]
	s_add_i32 m0, s34, 0x2000
	s_nop 0
	global_load_lds_dwordx4 v[214:215], off
	v_lshl_add_u64 v[214:215], v[218:219], 0, s[12:13]
	s_mov_b32 m0, s44
	s_nop 0
	global_load_lds_dwordx4 v[214:215], off
	v_lshl_add_u64 v[214:215], v[220:221], 0, s[12:13]
	s_mov_b32 m0, s45
	s_nop 0
	global_load_lds_dwordx4 v[214:215], off
	s_waitcnt vmcnt(8)
	s_waitcnt lgkmcnt(0)
	s_barrier
	s_setprio 1
	s_waitcnt lgkmcnt(0)
	v_mfma_f32_16x16x32_bf16 v[56:59], v[128:131], v[176:179], v[56:59]
	v_mfma_f32_16x16x32_bf16 v[56:59], v[132:135], v[186:189], v[56:59]
	v_mfma_f32_16x16x32_bf16 v[60:63], v[152:155], v[176:179], v[60:63]
	v_mfma_f32_16x16x32_bf16 v[60:63], v[156:159], v[186:189], v[60:63]
	v_mfma_f32_16x16x32_bf16 v[40:43], v[128:131], v[190:193], v[40:43]
	v_mfma_f32_16x16x32_bf16 v[40:43], v[132:135], v[194:197], v[40:43]
	v_mfma_f32_16x16x32_bf16 v[44:47], v[152:155], v[190:193], v[44:47]
	v_mfma_f32_16x16x32_bf16 v[44:47], v[156:159], v[194:197], v[44:47]
	v_mfma_f32_16x16x32_bf16 v[24:27], v[128:131], v[198:201], v[24:27]
	v_mfma_f32_16x16x32_bf16 v[24:27], v[132:135], v[202:205], v[24:27]
	v_mfma_f32_16x16x32_bf16 v[28:31], v[152:155], v[198:201], v[28:31]
	v_mfma_f32_16x16x32_bf16 v[28:31], v[156:159], v[202:205], v[28:31]
	v_mfma_f32_16x16x32_bf16 v[8:11], v[128:131], v[206:209], v[8:11]
	v_mfma_f32_16x16x32_bf16 v[8:11], v[132:135], v[210:213], v[8:11]
	v_mfma_f32_16x16x32_bf16 v[12:15], v[152:155], v[206:209], v[12:15]
	v_mfma_f32_16x16x32_bf16 v[12:15], v[156:159], v[210:213], v[12:15]
	s_setprio 0
	s_setprio 1
	v_mfma_f32_16x16x32_bf16 v[48:51], v[160:163], v[176:179], v[48:51]
	v_mfma_f32_16x16x32_bf16 v[48:51], v[164:167], v[186:189], v[48:51]
	v_mfma_f32_16x16x32_bf16 v[52:55], v[168:171], v[176:179], v[52:55]
	v_mfma_f32_16x16x32_bf16 v[52:55], v[172:175], v[186:189], v[52:55]
	v_mfma_f32_16x16x32_bf16 v[32:35], v[160:163], v[190:193], v[32:35]
	v_mfma_f32_16x16x32_bf16 v[32:35], v[164:167], v[194:197], v[32:35]
	v_mfma_f32_16x16x32_bf16 v[36:39], v[168:171], v[190:193], v[36:39]
	v_mfma_f32_16x16x32_bf16 v[36:39], v[172:175], v[194:197], v[36:39]
	v_mfma_f32_16x16x32_bf16 v[16:19], v[160:163], v[198:201], v[16:19]
	v_mfma_f32_16x16x32_bf16 v[16:19], v[164:167], v[202:205], v[16:19]
	v_mfma_f32_16x16x32_bf16 v[20:23], v[168:171], v[198:201], v[20:23]
	v_mfma_f32_16x16x32_bf16 v[20:23], v[172:175], v[202:205], v[20:23]
	v_mfma_f32_16x16x32_bf16 v[4:7], v[160:163], v[206:209], v[4:7]
	v_mfma_f32_16x16x32_bf16 v[4:7], v[164:167], v[210:213], v[4:7]
	v_mfma_f32_16x16x32_bf16 v[0:3], v[168:171], v[206:209], v[0:3]
	v_mfma_f32_16x16x32_bf16 v[0:3], v[172:175], v[210:213], v[0:3]
	s_setprio 0
	s_barrier
	s_add_i32 s51, s51, 2
	s_add_u32 s28, s28, 0x100
	s_addc_u32 s29, s29, 0
	s_add_u32 s49, s49, 0x100
	s_addc_u32 s50, s50, 0
	s_cmpk_gt_u32 s51, 0x7d
	s_cbranch_scc0 .LBB0_1755
	s_and_b64 vcc, exec, s[14:15]
	s_cbranch_vccz .LBB0_1758
	s_nop 0

; #define PG8_BAR __builtin_amdgcn_s_barrier()
;     __device__ __forceinline__ void post(int ui, const float (&r)[8]) const { const int t = my_tid(); if (t < 384) cbuf[(ui & 1) * 384 + t] = r[0]; }
; template <class Epi, bool ALIGN_EPI>
; __device__ __forceinline__ void gemm_phase(LAS unsigned char* lds, const Gemm g, const StaticOrder& S, const Epi& E) {
;     ...
;         if (!has_next) break;
;         E.post(ui + 1, rsn);
; #pragma unroll
;         for (int a = 0; a < 2; ++a)
; #pragma unroll
;             for (int b = 0; b < 2; ++b)
; #pragma unroll
;                 for (int m = 0; m < 4; ++m)
; #pragma unroll
;                     for (int n = 0; n < 2; ++n) acc[a][b][m][n] = (f32x4){0.f, 0.f, 0.f, 0.f};
;         cur = nxt; cA = nA; cB = nB; ++ui;
; #pragma unroll
;         for (int i_ = 0; i_ < 8; ++i_) rsv[i_] = rsn[i_];
;         if constexpr (ALIGN_EPI) { if (wr == 1) PG8_BAR; }
.LBB0_1776:
	s_andn2_b64 vcc, exec, s[0:1]
	s_mov_b64 s[0:1], -1
	s_cbranch_vccnz .LBB0_1747
	s_andn2_b64 vcc, exec, s[6:7]
	s_cbranch_vccnz .LBB0_1746
	s_nop 0
	s_branch .LBB0_1746
